# diff-attn: hand-scheduled far-tile path (LDS reads ahead, exp in MFMA gaps), flat->global, softmax ref shift to tab[255]
# speedup vs baseline: 1.0186x; 1.0186x over previous
;     __device__ __forceinline__ void operator()(const f32x4 (&acc)[2][2][4][2], const Unit& u, int wr, int wc, int fr, int fq) const {
;         const int row0 = u.pm * BM + wr * 64 + fr;
;         float rsv[2][4];
; #pragma unroll
;         for (int ai = 0; ai < 2; ++ai) {
; #pragma unroll
;             for (int m = 0; m < 4; ++m) {
;                 const int row = row0 + ai * HALF + m * 16;
;                 const f32x4 h0 = *((const f32x4*)(hss + (size_t)row * 16) + fq);
;                 float ss = (h0[0] + h0[1]) + (h0[2] + h0[3]);
;                 ss += __shfl_xor(ss, 16); ss += __shfl_xor(ss, 32);
;                 rsv[ai][m] = 1.0f / sqrtf(ss * (1.0f / 1024.0f) + 1e-6f);
;             }
;     ...
;                 } else {
;                     const int c0 = wc * 32 + 8 * fq;
;                     if (c0 < 72) {
;                         *(f32x4*)(misc + (size_t)row * 80 + c0) = acc[ai][0][m][0] * rs;
;                         *(f32x4*)(misc + (size_t)row * 80 + c0 + 4) = acc[ai][0][m][1] * rs;
;                     }
.LBB0_143:
	v_and_b32_e32 v148, 64, v216
	v_xor_b32_e32 v0, 16, v216
	v_add_u32_e32 v148, 64, v148
	v_cmp_lt_i32_e32 vcc, v0, v148
	v_lshl_add_u32 v160, s44, 8, v139
	v_ashrrev_i32_e32 v161, 31, v160
	v_cndmask_b32_e32 v0, v216, v0, vcc
	v_lshlrev_b32_e32 v173, 2, v0
	v_xor_b32_e32 v0, 32, v216
	v_cmp_lt_i32_e32 vcc, v0, v148
	v_lshlrev_b64 v[148:149], 6, v[160:161]
	v_lshl_add_u64 v[148:149], v[142:143], 0, v[148:149]
	global_load_dwordx4 v[148:151], v[148:149], off
	v_cndmask_b32_e32 v0, v216, v0, vcc
	v_lshlrev_b32_e32 v0, 2, v0
	v_or_b32_e32 v164, 16, v160
	v_ashrrev_i32_e32 v165, 31, v164
	v_or_b32_e32 v158, 32, v160
	v_ashrrev_i32_e32 v159, 31, v158
	v_or_b32_e32 v156, 48, v160
	v_ashrrev_i32_e32 v157, 31, v156
	v_add_u32_e32 v154, 0x80, v160
	v_ashrrev_i32_e32 v155, 31, v154
	s_cmp_gt_i32 s43, 15
	s_cselect_b64 s[8:9], -1, 0
	s_waitcnt vmcnt(0) lgkmcnt(0)
	v_add_f32_e32 v148, v148, v149
	v_add_f32_e32 v149, v150, v151
	v_add_f32_e32 v148, v148, v149
	ds_bpermute_b32 v149, v173, v148
	s_waitcnt lgkmcnt(0)
	v_add_f32_e32 v148, v148, v149
	ds_bpermute_b32 v149, v0, v148
	s_waitcnt lgkmcnt(0)
	v_add_f32_e32 v148, v148, v149
	v_fmamk_f32 v148, v148, 0x3a800000, v211
	v_cmp_gt_f32_e32 vcc, s55, v148
	v_mul_f32_e32 v149, 0x4f800000, v148
	s_nop 0
	v_cndmask_b32_e32 v148, v148, v149, vcc
	v_sqrt_f32_e32 v149, v148
	s_nop 0
	v_add_u32_e32 v150, -1, v149
	v_fma_f32 v151, -v150, v149, v148
	v_cmp_ge_f32_e64 s[0:1], 0, v151
	v_add_u32_e32 v151, 1, v149
	s_nop 0
	v_cndmask_b32_e64 v150, v149, v150, s[0:1]
	v_fma_f32 v149, -v151, v149, v148
	v_cmp_lt_f32_e64 s[0:1], 0, v149
	s_nop 1
	v_cndmask_b32_e64 v149, v150, v151, s[0:1]
	v_mul_f32_e32 v150, 0x37800000, v149
	v_cndmask_b32_e32 v149, v149, v150, vcc
	v_cmp_class_f32_e32 vcc, v148, v212
	s_nop 1
	v_cndmask_b32_e32 v148, v149, v148, vcc
	v_div_scale_f32 v149, s[0:1], v148, v148, 1.0
	v_rcp_f32_e32 v150, v149
	s_mov_b64 s[0:1], -1
	v_fma_f32 v151, -v149, v150, 1.0
	v_fmac_f32_e32 v150, v151, v150
	v_div_scale_f32 v151, vcc, 1.0, v148, 1.0
	v_mul_f32_e32 v152, v151, v150
	v_fma_f32 v153, -v149, v152, v151
	v_fmac_f32_e32 v152, v153, v150
	v_fma_f32 v149, -v149, v152, v151
	v_div_fmas_f32 v149, v149, v150, v152
	v_div_fixup_f32 v162, v149, v148, 1.0
	v_lshlrev_b64 v[148:149], 6, v[164:165]
	v_lshl_add_u64 v[148:149], v[142:143], 0, v[148:149]
	global_load_dwordx4 v[148:151], v[148:149], off
	v_add_u32_e32 v152, 0x90, v160
	v_ashrrev_i32_e32 v153, 31, v152
	s_and_b64 vcc, exec, s[8:9]
	s_waitcnt vmcnt(0) lgkmcnt(0)
	v_add_f32_e32 v148, v148, v149
	v_add_f32_e32 v149, v150, v151
	v_add_f32_e32 v148, v148, v149
	ds_bpermute_b32 v149, v173, v148
	s_waitcnt lgkmcnt(0)
	v_add_f32_e32 v171, v148, v149
	v_lshlrev_b64 v[148:149], 6, v[158:159]
	v_lshl_add_u64 v[148:149], v[142:143], 0, v[148:149]
	global_load_dwordx4 v[148:151], v[148:149], off
	ds_bpermute_b32 v172, v0, v171
	s_waitcnt vmcnt(0) lgkmcnt(0)
	v_add_f32_e32 v148, v148, v149
	v_add_f32_e32 v149, v150, v151
	v_add_f32_e32 v148, v148, v149
	ds_bpermute_b32 v149, v173, v148
	s_waitcnt lgkmcnt(0)
	v_add_f32_e32 v169, v148, v149
	v_lshlrev_b64 v[148:149], 6, v[156:157]
	v_lshl_add_u64 v[148:149], v[142:143], 0, v[148:149]
	global_load_dwordx4 v[148:151], v[148:149], off
	ds_bpermute_b32 v170, v0, v169
	s_waitcnt vmcnt(0) lgkmcnt(0)
	v_add_f32_e32 v148, v148, v149
	v_add_f32_e32 v149, v150, v151
	v_add_f32_e32 v148, v148, v149
	ds_bpermute_b32 v149, v173, v148
	s_waitcnt lgkmcnt(0)
	v_add_f32_e32 v167, v148, v149
	v_lshlrev_b64 v[148:149], 6, v[154:155]
	v_lshl_add_u64 v[148:149], v[142:143], 0, v[148:149]
	global_load_dwordx4 v[148:151], v[148:149], off
	ds_bpermute_b32 v168, v0, v167
	s_waitcnt vmcnt(0) lgkmcnt(0)
	v_add_f32_e32 v148, v148, v149
	v_add_f32_e32 v149, v150, v151
	v_add_f32_e32 v148, v148, v149
	ds_bpermute_b32 v149, v173, v148
	s_waitcnt lgkmcnt(0)
	v_add_f32_e32 v161, v148, v149
	v_lshlrev_b64 v[148:149], 6, v[152:153]
	v_lshl_add_u64 v[148:149], v[142:143], 0, v[148:149]
	global_load_dwordx4 v[148:151], v[148:149], off
	ds_bpermute_b32 v165, v0, v161
	s_waitcnt vmcnt(0) lgkmcnt(0)
	v_add_f32_e32 v148, v148, v149
	v_add_f32_e32 v149, v150, v151
	v_add_f32_e32 v148, v148, v149
	ds_bpermute_b32 v149, v173, v148
	v_add_u32_e32 v150, 0xa0, v160
	v_ashrrev_i32_e32 v151, 31, v150
	s_waitcnt lgkmcnt(0)
	v_add_f32_e32 v155, v148, v149
	v_lshlrev_b64 v[148:149], 6, v[150:151]
	v_lshl_add_u64 v[148:149], v[142:143], 0, v[148:149]
	global_load_dwordx4 v[174:177], v[148:149], off
	ds_bpermute_b32 v157, v0, v155
	s_waitcnt vmcnt(0) lgkmcnt(0)
	v_add_f32_e32 v148, v174, v175
	v_add_f32_e32 v149, v176, v177
	v_add_f32_e32 v148, v148, v149
	ds_bpermute_b32 v149, v173, v148
	s_waitcnt lgkmcnt(0)
	v_add_f32_e32 v151, v148, v149
	v_add_u32_e32 v148, 0xb0, v160
	v_ashrrev_i32_e32 v149, 31, v148
	v_lshlrev_b64 v[174:175], 6, v[148:149]
	v_lshl_add_u64 v[174:175], v[142:143], 0, v[174:175]
	global_load_dwordx4 v[174:177], v[174:175], off
	ds_bpermute_b32 v153, v0, v151
	s_waitcnt vmcnt(0) lgkmcnt(0)
	v_add_f32_e32 v149, v174, v175
	v_add_f32_e32 v159, v176, v177
	v_add_f32_e32 v149, v149, v159
	ds_bpermute_b32 v159, v173, v149
	s_waitcnt lgkmcnt(0)
	v_add_f32_e32 v149, v149, v159
	ds_bpermute_b32 v159, v0, v149
	s_cbranch_vccz .LBB0_147
	s_and_saveexec_b64 s[0:1], s[6:7]
	s_cbranch_execz .LBB0_146
	s_movk_i32 s17, 0x140
	v_pk_mul_f32 v[176:177], v[128:129], v[162:163] op_sel_hi:[1,0]
	v_pk_mul_f32 v[174:175], v[126:127], v[162:163] op_sel_hi:[1,0]
	v_mad_i64_i32 v[178:179], s[26:27], v160, s17, v[140:141]
	global_store_dwordx4 v[178:179], v[174:177], off
	s_nop 1
	v_pk_mul_f32 v[176:177], v[124:125], v[162:163] op_sel_hi:[1,0]
	v_pk_mul_f32 v[174:175], v[122:123], v[162:163] op_sel_hi:[1,0]
	global_store_dwordx4 v[178:179], v[174:177], off offset:16

; __device__ __forceinline__ unsigned cvt_pk_bf16(float lo, float hi) { unsigned r; asm volatile("v_cvt_pk_bf16_f32 %0, %1, %2" : "=v"(r) : "v"(lo), "v"(hi)); return r; }
;     __device__ __forceinline__ void operator()(const f32x4 (&acc)[2][2][4][2], const Unit& u, int wr, int wc, int fr, int fq) const {
;     ...
;                 const int row = row0 + ai * HALF + m * 16;
;                 const f32x4 h0 = *((const f32x4*)(hss + (size_t)row * 16) + fq);
;                 float ss = (h0[0] + h0[1]) + (h0[2] + h0[3]);
;                 ss += __shfl_xor(ss, 16); ss += __shfl_xor(ss, 32);
;                 rsv[ai][m] = 1.0f / sqrtf(ss * (1.0f / 1024.0f) + 1e-6f);
;     ...
;             for (int m = 0; m < 4; ++m) {
;                 const int row = row0 + ai * HALF + m * 16;
;                 const float rs = rsv[ai][m];
;                 if (u.pn < ntile_main) {
;                     bf16_t* rowp = P + (size_t)row * 4160 + u.pn * BM + wc * 32 + 8 * fq;
; #pragma unroll
;                     for (int bj = 0; bj < 2; ++bj) {
;                         const f32x4 v0 = acc[ai][bj][m][0] * rs, v1 = acc[ai][bj][m][1] * rs;
;                         u32x4 w; w.x = cvt_pk_bf16(v0[0], v0[1]); w.y = cvt_pk_bf16(v0[2], v0[3]); w.z = cvt_pk_bf16(v1[0], v1[1]); w.w = cvt_pk_bf16(v1[2], v1[3]);
;                         *(u32x4*)(rowp + bj * HALF) = w;
;                     }
.LBB0_147:
	s_andn2_b64 vcc, exec, s[0:1]
	v_lshlrev_b32_e32 v0, 1, v138
	s_cbranch_vccnz .LBB0_149
	v_mov_b64_e32 v[174:175], s[12:13]
	v_mad_i64_i32 v[174:175], s[0:1], v160, s76, v[174:175]
	s_lshl_b32 s0, s43, 8
	s_ashr_i32 s1, s0, 31
	v_lshl_add_u64 v[174:175], s[0:1], 1, v[174:175]
	s_lshl_b32 s92, s38, 1
	v_lshl_add_u64 v[174:175], v[174:175], 0, s[92:93]
	v_lshl_add_u64 v[174:175], v[174:175], 0, v[0:1]
	v_pk_mul_f32 v[128:129], v[128:129], v[162:163] op_sel_hi:[1,0]
	v_pk_mul_f32 v[126:127], v[126:127], v[162:163] op_sel_hi:[1,0]
	v_pk_mul_f32 v[176:177], v[124:125], v[162:163] op_sel_hi:[1,0]
	v_pk_mul_f32 v[124:125], v[122:123], v[162:163] op_sel_hi:[1,0]
	v_cvt_pk_bf16_f32 v122, v126, v127
	v_cvt_pk_bf16_f32 v123, v128, v129
	v_pk_mul_f32 v[120:121], v[120:121], v[162:163] op_sel_hi:[1,0]
	v_cvt_pk_bf16_f32 v124, v124, v125
	v_cvt_pk_bf16_f32 v125, v176, v177
	global_store_dwordx4 v[174:175], v[122:125], off
	v_pk_mul_f32 v[118:119], v[118:119], v[162:163] op_sel_hi:[1,0]
	s_nop 0
	v_pk_mul_f32 v[122:123], v[116:117], v[162:163] op_sel_hi:[1,0]
	v_pk_mul_f32 v[116:117], v[114:115], v[162:163] op_sel_hi:[1,0]
	v_cvt_pk_bf16_f32 v114, v118, v119
	v_cvt_pk_bf16_f32 v115, v120, v121
	s_nop 0
	v_cvt_pk_bf16_f32 v116, v116, v117
	v_cvt_pk_bf16_f32 v117, v122, v123
	global_store_dwordx4 v[174:175], v[114:117], off offset:256
.LBB0_149:
	s_nop 1
	v_add_f32_e32 v114, v171, v172
	v_fmamk_f32 v114, v114, 0x3a800000, v211
	v_mul_f32_e32 v115, 0x4f800000, v114
	v_cmp_gt_f32_e32 vcc, s55, v114
	s_nop 1
	v_cndmask_b32_e32 v114, v114, v115, vcc
	v_sqrt_f32_e32 v115, v114
	s_nop 0
	v_add_u32_e32 v116, -1, v115
	v_fma_f32 v118, -v116, v115, v114
	v_add_u32_e32 v117, 1, v115
	v_cmp_ge_f32_e64 s[0:1], 0, v118
	s_nop 1
	v_cndmask_b32_e64 v116, v115, v116, s[0:1]
	v_fma_f32 v115, -v117, v115, v114
	v_cmp_lt_f32_e64 s[0:1], 0, v115
	s_nop 1
	v_cndmask_b32_e64 v115, v116, v117, s[0:1]
	v_mul_f32_e32 v116, 0x37800000, v115
	v_cndmask_b32_e32 v115, v115, v116, vcc
	v_cmp_class_f32_e32 vcc, v114, v212
	s_nop 1
	v_cndmask_b32_e32 v114, v115, v114, vcc
	v_div_scale_f32 v115, s[0:1], v114, v114, 1.0
	v_rcp_f32_e32 v116, v115
	s_nop 0
	v_fma_f32 v117, -v115, v116, 1.0
	v_fmac_f32_e32 v116, v117, v116
	v_div_scale_f32 v117, vcc, 1.0, v114, 1.0
	v_mul_f32_e32 v118, v117, v116
	v_fma_f32 v119, -v115, v118, v117
	v_fmac_f32_e32 v118, v119, v116
	v_fma_f32 v115, -v115, v118, v117
	v_div_fmas_f32 v115, v115, v116, v118
	v_div_fixup_f32 v114, v115, v114, 1.0
	v_cndmask_b32_e64 v115, 0, 1, s[8:9]
	v_cmp_ne_u32_e64 s[0:1], 1, v115
	s_andn2_b64 vcc, exec, s[8:9]
	s_mov_b64 s[8:9], -1
	s_cbranch_vccnz .LBB0_153
	s_and_saveexec_b64 s[8:9], s[6:7]
	s_cbranch_execz .LBB0_152
	s_movk_i32 s17, 0x140
	v_pk_mul_f32 v[118:119], v[112:113], v[114:115] op_sel_hi:[1,0]
	v_pk_mul_f32 v[116:117], v[110:111], v[114:115] op_sel_hi:[1,0]
	v_mad_i64_i32 v[120:121], s[26:27], v164, s17, v[140:141]
	global_store_dwordx4 v[120:121], v[116:119], off
	s_nop 1
	v_pk_mul_f32 v[118:119], v[108:109], v[114:115] op_sel_hi:[1,0]
	v_pk_mul_f32 v[116:117], v[106:107], v[114:115] op_sel_hi:[1,0]
	global_store_dwordx4 v[120:121], v[116:119], off offset:16

; __device__ __forceinline__ unsigned cvt_pk_bf16(float lo, float hi) { unsigned r; asm volatile("v_cvt_pk_bf16_f32 %0, %1, %2" : "=v"(r) : "v"(lo), "v"(hi)); return r; }
;     __device__ __forceinline__ void operator()(const f32x4 (&acc)[2][2][4][2], const Unit& u, int wr, int wc, int fr, int fq) const {
;     ...
;                 const int row = row0 + ai * HALF + m * 16;
;                 const f32x4 h0 = *((const f32x4*)(hss + (size_t)row * 16) + fq);
;                 float ss = (h0[0] + h0[1]) + (h0[2] + h0[3]);
;                 ss += __shfl_xor(ss, 16); ss += __shfl_xor(ss, 32);
;                 rsv[ai][m] = 1.0f / sqrtf(ss * (1.0f / 1024.0f) + 1e-6f);
;     ...
;             for (int m = 0; m < 4; ++m) {
;                 const int row = row0 + ai * HALF + m * 16;
;                 const float rs = rsv[ai][m];
;                 if (u.pn < ntile_main) {
;                     bf16_t* rowp = P + (size_t)row * 4160 + u.pn * BM + wc * 32 + 8 * fq;
; #pragma unroll
;                     for (int bj = 0; bj < 2; ++bj) {
;                         const f32x4 v0 = acc[ai][bj][m][0] * rs, v1 = acc[ai][bj][m][1] * rs;
;                         u32x4 w; w.x = cvt_pk_bf16(v0[0], v0[1]); w.y = cvt_pk_bf16(v0[2], v0[3]); w.z = cvt_pk_bf16(v1[0], v1[1]); w.w = cvt_pk_bf16(v1[2], v1[3]);
;                         *(u32x4*)(rowp + bj * HALF) = w;
;                     }
;                 } else {
;                     const int c0 = wc * 32 + 8 * fq;
;                     if (c0 < 72) {
;                         *(f32x4*)(misc + (size_t)row * 80 + c0) = acc[ai][0][m][0] * rs;
;                         *(f32x4*)(misc + (size_t)row * 80 + c0 + 4) = acc[ai][0][m][1] * rs;
.LBB0_153:
	s_andn2_b64 vcc, exec, s[8:9]
	s_cbranch_vccnz .LBB0_155
	v_mov_b64_e32 v[116:117], s[12:13]
	v_mad_i64_i32 v[116:117], s[8:9], v164, s76, v[116:117]
	s_lshl_b32 s8, s43, 8
	s_ashr_i32 s9, s8, 31
	v_lshl_add_u64 v[116:117], s[8:9], 1, v[116:117]
	s_lshl_b32 s92, s38, 1
	v_lshl_add_u64 v[116:117], v[116:117], 0, s[92:93]
	v_lshl_add_u64 v[116:117], v[116:117], 0, v[0:1]
	v_pk_mul_f32 v[112:113], v[112:113], v[114:115] op_sel_hi:[1,0]
	v_pk_mul_f32 v[110:111], v[110:111], v[114:115] op_sel_hi:[1,0]
	v_pk_mul_f32 v[118:119], v[108:109], v[114:115] op_sel_hi:[1,0]
	v_pk_mul_f32 v[108:109], v[106:107], v[114:115] op_sel_hi:[1,0]
	v_cvt_pk_bf16_f32 v106, v110, v111
	v_cvt_pk_bf16_f32 v107, v112, v113
	v_pk_mul_f32 v[104:105], v[104:105], v[114:115] op_sel_hi:[1,0]
	v_cvt_pk_bf16_f32 v108, v108, v109
	v_cvt_pk_bf16_f32 v109, v118, v119
	global_store_dwordx4 v[116:117], v[106:109], off
	v_pk_mul_f32 v[102:103], v[102:103], v[114:115] op_sel_hi:[1,0]
	s_nop 0
	v_pk_mul_f32 v[106:107], v[100:101], v[114:115] op_sel_hi:[1,0]
	v_pk_mul_f32 v[100:101], v[98:99], v[114:115] op_sel_hi:[1,0]
	v_cvt_pk_bf16_f32 v98, v102, v103
	v_cvt_pk_bf16_f32 v99, v104, v105
	s_nop 0
	v_cvt_pk_bf16_f32 v100, v100, v101
	v_cvt_pk_bf16_f32 v101, v106, v107
	global_store_dwordx4 v[116:117], v[98:101], off offset:256
.LBB0_155:
	s_nop 1
	v_add_f32_e32 v98, v169, v170
	v_fmamk_f32 v98, v98, 0x3a800000, v211
	v_mul_f32_e32 v99, 0x4f800000, v98
	v_cmp_gt_f32_e32 vcc, s55, v98
	s_nop 1
	v_cndmask_b32_e32 v98, v98, v99, vcc
	v_sqrt_f32_e32 v99, v98
	s_nop 0
	v_add_u32_e32 v100, -1, v99
	v_fma_f32 v102, -v100, v99, v98
	v_add_u32_e32 v101, 1, v99
	v_cmp_ge_f32_e64 s[8:9], 0, v102
	s_nop 1
	v_cndmask_b32_e64 v100, v99, v100, s[8:9]
	v_fma_f32 v99, -v101, v99, v98
	v_cmp_lt_f32_e64 s[8:9], 0, v99
	s_nop 1
	v_cndmask_b32_e64 v99, v100, v101, s[8:9]
	v_mul_f32_e32 v100, 0x37800000, v99
	v_cndmask_b32_e32 v99, v99, v100, vcc
	v_cmp_class_f32_e32 vcc, v98, v212
	s_nop 1
	v_cndmask_b32_e32 v98, v99, v98, vcc
	v_div_scale_f32 v99, s[8:9], v98, v98, 1.0
	v_rcp_f32_e32 v100, v99
	s_mov_b64 s[8:9], -1
	v_fma_f32 v101, -v99, v100, 1.0
	v_fmac_f32_e32 v100, v101, v100
	v_div_scale_f32 v101, vcc, 1.0, v98, 1.0
	v_mul_f32_e32 v102, v101, v100
	v_fma_f32 v103, -v99, v102, v101
	v_fmac_f32_e32 v102, v103, v100
	v_fma_f32 v99, -v99, v102, v101
	v_div_fmas_f32 v99, v99, v100, v102
	v_div_fixup_f32 v98, v99, v98, 1.0
	s_and_b64 vcc, exec, s[0:1]
	s_cbranch_vccnz .LBB0_159
	s_and_saveexec_b64 s[8:9], s[6:7]
	s_cbranch_execz .LBB0_158
	s_movk_i32 s17, 0x140
	v_pk_mul_f32 v[102:103], v[96:97], v[98:99] op_sel_hi:[1,0]
	v_pk_mul_f32 v[100:101], v[94:95], v[98:99] op_sel_hi:[1,0]
	v_mad_i64_i32 v[104:105], s[26:27], v158, s17, v[140:141]
	global_store_dwordx4 v[104:105], v[100:103], off
	s_nop 1
	v_pk_mul_f32 v[102:103], v[92:93], v[98:99] op_sel_hi:[1,0]
	v_pk_mul_f32 v[100:101], v[90:91], v[98:99] op_sel_hi:[1,0]
	global_store_dwordx4 v[104:105], v[100:103], off offset:16

; __device__ __forceinline__ unsigned cvt_pk_bf16(float lo, float hi) { unsigned r; asm volatile("v_cvt_pk_bf16_f32 %0, %1, %2" : "=v"(r) : "v"(lo), "v"(hi)); return r; }
;     __device__ __forceinline__ void operator()(const f32x4 (&acc)[2][2][4][2], const Unit& u, int wr, int wc, int fr, int fq) const {
;     ...
;                 const int row = row0 + ai * HALF + m * 16;
;                 const f32x4 h0 = *((const f32x4*)(hss + (size_t)row * 16) + fq);
;                 float ss = (h0[0] + h0[1]) + (h0[2] + h0[3]);
;                 ss += __shfl_xor(ss, 16); ss += __shfl_xor(ss, 32);
;                 rsv[ai][m] = 1.0f / sqrtf(ss * (1.0f / 1024.0f) + 1e-6f);
;     ...
;             for (int m = 0; m < 4; ++m) {
;                 const int row = row0 + ai * HALF + m * 16;
;                 const float rs = rsv[ai][m];
;                 if (u.pn < ntile_main) {
;                     bf16_t* rowp = P + (size_t)row * 4160 + u.pn * BM + wc * 32 + 8 * fq;
; #pragma unroll
;                     for (int bj = 0; bj < 2; ++bj) {
;                         const f32x4 v0 = acc[ai][bj][m][0] * rs, v1 = acc[ai][bj][m][1] * rs;
;                         u32x4 w; w.x = cvt_pk_bf16(v0[0], v0[1]); w.y = cvt_pk_bf16(v0[2], v0[3]); w.z = cvt_pk_bf16(v1[0], v1[1]); w.w = cvt_pk_bf16(v1[2], v1[3]);
;                         *(u32x4*)(rowp + bj * HALF) = w;
;                     }
;                 } else {
;                     const int c0 = wc * 32 + 8 * fq;
;                     if (c0 < 72) {
;                         *(f32x4*)(misc + (size_t)row * 80 + c0) = acc[ai][0][m][0] * rs;
;                         *(f32x4*)(misc + (size_t)row * 80 + c0 + 4) = acc[ai][0][m][1] * rs;
.LBB0_159:
	s_andn2_b64 vcc, exec, s[8:9]
	s_cbranch_vccnz .LBB0_161
	v_mov_b64_e32 v[100:101], s[12:13]
	v_mad_i64_i32 v[100:101], s[8:9], v158, s76, v[100:101]
	s_lshl_b32 s8, s43, 8
	s_ashr_i32 s9, s8, 31
	v_lshl_add_u64 v[100:101], s[8:9], 1, v[100:101]
	s_lshl_b32 s92, s38, 1
	v_lshl_add_u64 v[100:101], v[100:101], 0, s[92:93]
	v_lshl_add_u64 v[100:101], v[100:101], 0, v[0:1]
	v_pk_mul_f32 v[96:97], v[96:97], v[98:99] op_sel_hi:[1,0]
	v_pk_mul_f32 v[94:95], v[94:95], v[98:99] op_sel_hi:[1,0]
	v_pk_mul_f32 v[102:103], v[92:93], v[98:99] op_sel_hi:[1,0]
	v_pk_mul_f32 v[92:93], v[90:91], v[98:99] op_sel_hi:[1,0]
	v_cvt_pk_bf16_f32 v90, v94, v95
	v_cvt_pk_bf16_f32 v91, v96, v97
	v_pk_mul_f32 v[88:89], v[88:89], v[98:99] op_sel_hi:[1,0]
	v_cvt_pk_bf16_f32 v92, v92, v93
	v_cvt_pk_bf16_f32 v93, v102, v103
	global_store_dwordx4 v[100:101], v[90:93], off
	v_pk_mul_f32 v[86:87], v[86:87], v[98:99] op_sel_hi:[1,0]
	s_nop 0
	v_pk_mul_f32 v[90:91], v[84:85], v[98:99] op_sel_hi:[1,0]
	v_pk_mul_f32 v[84:85], v[82:83], v[98:99] op_sel_hi:[1,0]
	v_cvt_pk_bf16_f32 v82, v86, v87
	v_cvt_pk_bf16_f32 v83, v88, v89
	s_nop 0
	v_cvt_pk_bf16_f32 v84, v84, v85
	v_cvt_pk_bf16_f32 v85, v90, v91
	global_store_dwordx4 v[100:101], v[82:85], off offset:256
.LBB0_161:
	s_nop 1
	v_add_f32_e32 v82, v167, v168
	v_fmamk_f32 v82, v82, 0x3a800000, v211
	v_mul_f32_e32 v83, 0x4f800000, v82
	v_cmp_gt_f32_e32 vcc, s55, v82
	s_nop 1
	v_cndmask_b32_e32 v82, v82, v83, vcc
	v_sqrt_f32_e32 v83, v82
	s_nop 0
	v_add_u32_e32 v84, -1, v83
	v_fma_f32 v86, -v84, v83, v82
	v_add_u32_e32 v85, 1, v83
	v_cmp_ge_f32_e64 s[8:9], 0, v86
	s_nop 1
	v_cndmask_b32_e64 v84, v83, v84, s[8:9]
	v_fma_f32 v83, -v85, v83, v82
	v_cmp_lt_f32_e64 s[8:9], 0, v83
	s_nop 1
	v_cndmask_b32_e64 v83, v84, v85, s[8:9]
	v_mul_f32_e32 v84, 0x37800000, v83
	v_cndmask_b32_e32 v83, v83, v84, vcc
	v_cmp_class_f32_e32 vcc, v82, v212
	s_nop 1
	v_cndmask_b32_e32 v82, v83, v82, vcc
	v_div_scale_f32 v83, s[8:9], v82, v82, 1.0
	v_rcp_f32_e32 v84, v83
	s_mov_b64 s[8:9], -1
	v_fma_f32 v85, -v83, v84, 1.0
	v_fmac_f32_e32 v84, v85, v84
	v_div_scale_f32 v85, vcc, 1.0, v82, 1.0
	v_mul_f32_e32 v86, v85, v84
	v_fma_f32 v87, -v83, v86, v85
	v_fmac_f32_e32 v86, v87, v84
	v_fma_f32 v83, -v83, v86, v85
	v_div_fmas_f32 v83, v83, v84, v86
	v_div_fixup_f32 v82, v83, v82, 1.0
	s_and_b64 vcc, exec, s[0:1]
	s_cbranch_vccnz .LBB0_165
	s_and_saveexec_b64 s[8:9], s[6:7]
	s_cbranch_execz .LBB0_164
	s_movk_i32 s17, 0x140
	v_pk_mul_f32 v[86:87], v[80:81], v[82:83] op_sel_hi:[1,0]
	v_pk_mul_f32 v[84:85], v[78:79], v[82:83] op_sel_hi:[1,0]
	v_mad_i64_i32 v[88:89], s[26:27], v156, s17, v[140:141]
	global_store_dwordx4 v[88:89], v[84:87], off
	s_nop 1
	v_pk_mul_f32 v[86:87], v[76:77], v[82:83] op_sel_hi:[1,0]
	v_pk_mul_f32 v[84:85], v[74:75], v[82:83] op_sel_hi:[1,0]
	global_store_dwordx4 v[88:89], v[84:87], off offset:16

; __device__ __forceinline__ unsigned cvt_pk_bf16(float lo, float hi) { unsigned r; asm volatile("v_cvt_pk_bf16_f32 %0, %1, %2" : "=v"(r) : "v"(lo), "v"(hi)); return r; }
;     __device__ __forceinline__ void operator()(const f32x4 (&acc)[2][2][4][2], const Unit& u, int wr, int wc, int fr, int fq) const {
;     ...
;                 const int row = row0 + ai * HALF + m * 16;
;                 const f32x4 h0 = *((const f32x4*)(hss + (size_t)row * 16) + fq);
;                 float ss = (h0[0] + h0[1]) + (h0[2] + h0[3]);
;                 ss += __shfl_xor(ss, 16); ss += __shfl_xor(ss, 32);
;                 rsv[ai][m] = 1.0f / sqrtf(ss * (1.0f / 1024.0f) + 1e-6f);
;     ...
;             for (int m = 0; m < 4; ++m) {
;                 const int row = row0 + ai * HALF + m * 16;
;                 const float rs = rsv[ai][m];
;                 if (u.pn < ntile_main) {
;                     bf16_t* rowp = P + (size_t)row * 4160 + u.pn * BM + wc * 32 + 8 * fq;
; #pragma unroll
;                     for (int bj = 0; bj < 2; ++bj) {
;                         const f32x4 v0 = acc[ai][bj][m][0] * rs, v1 = acc[ai][bj][m][1] * rs;
;                         u32x4 w; w.x = cvt_pk_bf16(v0[0], v0[1]); w.y = cvt_pk_bf16(v0[2], v0[3]); w.z = cvt_pk_bf16(v1[0], v1[1]); w.w = cvt_pk_bf16(v1[2], v1[3]);
;                         *(u32x4*)(rowp + bj * HALF) = w;
;                     }
;                 } else {
;                     const int c0 = wc * 32 + 8 * fq;
;                     if (c0 < 72) {
;                         *(f32x4*)(misc + (size_t)row * 80 + c0) = acc[ai][0][m][0] * rs;
;                         *(f32x4*)(misc + (size_t)row * 80 + c0 + 4) = acc[ai][0][m][1] * rs;
.LBB0_165:
	s_andn2_b64 vcc, exec, s[8:9]
	s_cbranch_vccnz .LBB0_167
	v_mov_b64_e32 v[84:85], s[12:13]
	v_mad_i64_i32 v[84:85], s[8:9], v156, s76, v[84:85]
	s_lshl_b32 s8, s43, 8
	s_ashr_i32 s9, s8, 31
	v_lshl_add_u64 v[84:85], s[8:9], 1, v[84:85]
	s_lshl_b32 s92, s38, 1
	v_lshl_add_u64 v[84:85], v[84:85], 0, s[92:93]
	v_lshl_add_u64 v[84:85], v[84:85], 0, v[0:1]
	v_pk_mul_f32 v[80:81], v[80:81], v[82:83] op_sel_hi:[1,0]
	v_pk_mul_f32 v[78:79], v[78:79], v[82:83] op_sel_hi:[1,0]
	v_pk_mul_f32 v[86:87], v[76:77], v[82:83] op_sel_hi:[1,0]
	v_pk_mul_f32 v[76:77], v[74:75], v[82:83] op_sel_hi:[1,0]
	v_cvt_pk_bf16_f32 v74, v78, v79
	v_cvt_pk_bf16_f32 v75, v80, v81
	v_pk_mul_f32 v[72:73], v[72:73], v[82:83] op_sel_hi:[1,0]
	v_cvt_pk_bf16_f32 v76, v76, v77
	v_cvt_pk_bf16_f32 v77, v86, v87
	global_store_dwordx4 v[84:85], v[74:77], off
	v_pk_mul_f32 v[70:71], v[70:71], v[82:83] op_sel_hi:[1,0]
	s_nop 0
	v_pk_mul_f32 v[74:75], v[68:69], v[82:83] op_sel_hi:[1,0]
	v_pk_mul_f32 v[68:69], v[66:67], v[82:83] op_sel_hi:[1,0]
	v_cvt_pk_bf16_f32 v66, v70, v71
	v_cvt_pk_bf16_f32 v67, v72, v73
	s_nop 0
	v_cvt_pk_bf16_f32 v68, v68, v69
	v_cvt_pk_bf16_f32 v69, v74, v75
	global_store_dwordx4 v[84:85], v[66:69], off offset:256
.LBB0_167:
	s_nop 1
	v_add_f32_e32 v66, v161, v165
	v_fmamk_f32 v66, v66, 0x3a800000, v211
	v_mul_f32_e32 v67, 0x4f800000, v66
	v_cmp_gt_f32_e32 vcc, s55, v66
	s_nop 1
	v_cndmask_b32_e32 v66, v66, v67, vcc
	v_sqrt_f32_e32 v67, v66
	s_nop 0
	v_add_u32_e32 v68, -1, v67
	v_fma_f32 v70, -v68, v67, v66
	v_add_u32_e32 v69, 1, v67
	v_cmp_ge_f32_e64 s[8:9], 0, v70
	s_nop 1
	v_cndmask_b32_e64 v68, v67, v68, s[8:9]
	v_fma_f32 v67, -v69, v67, v66
	v_cmp_lt_f32_e64 s[8:9], 0, v67
	s_nop 1
	v_cndmask_b32_e64 v67, v68, v69, s[8:9]
	v_mul_f32_e32 v68, 0x37800000, v67
	v_cndmask_b32_e32 v67, v67, v68, vcc
	v_cmp_class_f32_e32 vcc, v66, v212
	s_nop 1
	v_cndmask_b32_e32 v66, v67, v66, vcc
	v_div_scale_f32 v67, s[8:9], v66, v66, 1.0
	v_rcp_f32_e32 v68, v67
	s_mov_b64 s[8:9], -1
	v_fma_f32 v69, -v67, v68, 1.0
	v_fmac_f32_e32 v68, v69, v68
	v_div_scale_f32 v69, vcc, 1.0, v66, 1.0
	v_mul_f32_e32 v70, v69, v68
	v_fma_f32 v71, -v67, v70, v69
	v_fmac_f32_e32 v70, v71, v68
	v_fma_f32 v67, -v67, v70, v69
	v_div_fmas_f32 v67, v67, v68, v70
	v_div_fixup_f32 v66, v67, v66, 1.0
	s_and_b64 vcc, exec, s[0:1]
	s_cbranch_vccnz .LBB0_171
	s_and_saveexec_b64 s[8:9], s[6:7]
	s_cbranch_execz .LBB0_170
	s_movk_i32 s17, 0x140
	v_pk_mul_f32 v[70:71], v[64:65], v[66:67] op_sel_hi:[1,0]
	v_pk_mul_f32 v[68:69], v[62:63], v[66:67] op_sel_hi:[1,0]
	v_mad_i64_i32 v[72:73], s[26:27], v154, s17, v[140:141]
	global_store_dwordx4 v[72:73], v[68:71], off
	s_nop 1
	v_pk_mul_f32 v[70:71], v[60:61], v[66:67] op_sel_hi:[1,0]
	v_pk_mul_f32 v[68:69], v[58:59], v[66:67] op_sel_hi:[1,0]
	global_store_dwordx4 v[72:73], v[68:71], off offset:16

; __device__ __forceinline__ unsigned cvt_pk_bf16(float lo, float hi) { unsigned r; asm volatile("v_cvt_pk_bf16_f32 %0, %1, %2" : "=v"(r) : "v"(lo), "v"(hi)); return r; }
;     __device__ __forceinline__ void operator()(const f32x4 (&acc)[2][2][4][2], const Unit& u, int wr, int wc, int fr, int fq) const {
;     ...
;                 const int row = row0 + ai * HALF + m * 16;
;                 const f32x4 h0 = *((const f32x4*)(hss + (size_t)row * 16) + fq);
;                 float ss = (h0[0] + h0[1]) + (h0[2] + h0[3]);
;                 ss += __shfl_xor(ss, 16); ss += __shfl_xor(ss, 32);
;                 rsv[ai][m] = 1.0f / sqrtf(ss * (1.0f / 1024.0f) + 1e-6f);
;     ...
;             for (int m = 0; m < 4; ++m) {
;                 const int row = row0 + ai * HALF + m * 16;
;                 const float rs = rsv[ai][m];
;                 if (u.pn < ntile_main) {
;                     bf16_t* rowp = P + (size_t)row * 4160 + u.pn * BM + wc * 32 + 8 * fq;
; #pragma unroll
;                     for (int bj = 0; bj < 2; ++bj) {
;                         const f32x4 v0 = acc[ai][bj][m][0] * rs, v1 = acc[ai][bj][m][1] * rs;
;                         u32x4 w; w.x = cvt_pk_bf16(v0[0], v0[1]); w.y = cvt_pk_bf16(v0[2], v0[3]); w.z = cvt_pk_bf16(v1[0], v1[1]); w.w = cvt_pk_bf16(v1[2], v1[3]);
;                         *(u32x4*)(rowp + bj * HALF) = w;
;                     }
;                 } else {
;                     const int c0 = wc * 32 + 8 * fq;
;                     if (c0 < 72) {
;                         *(f32x4*)(misc + (size_t)row * 80 + c0) = acc[ai][0][m][0] * rs;
;                         *(f32x4*)(misc + (size_t)row * 80 + c0 + 4) = acc[ai][0][m][1] * rs;
.LBB0_171:
	s_andn2_b64 vcc, exec, s[8:9]
	s_cbranch_vccnz .LBB0_173
	v_mov_b64_e32 v[68:69], s[12:13]
	v_mad_i64_i32 v[68:69], s[8:9], v154, s76, v[68:69]
	s_lshl_b32 s8, s43, 8
	s_ashr_i32 s9, s8, 31
	v_lshl_add_u64 v[68:69], s[8:9], 1, v[68:69]
	s_lshl_b32 s92, s38, 1
	v_lshl_add_u64 v[68:69], v[68:69], 0, s[92:93]
	v_lshl_add_u64 v[68:69], v[68:69], 0, v[0:1]
	v_pk_mul_f32 v[64:65], v[64:65], v[66:67] op_sel_hi:[1,0]
	v_pk_mul_f32 v[62:63], v[62:63], v[66:67] op_sel_hi:[1,0]
	v_pk_mul_f32 v[70:71], v[60:61], v[66:67] op_sel_hi:[1,0]
	v_pk_mul_f32 v[60:61], v[58:59], v[66:67] op_sel_hi:[1,0]
	v_cvt_pk_bf16_f32 v58, v62, v63
	v_cvt_pk_bf16_f32 v59, v64, v65
	v_pk_mul_f32 v[56:57], v[56:57], v[66:67] op_sel_hi:[1,0]
	v_cvt_pk_bf16_f32 v60, v60, v61
	v_cvt_pk_bf16_f32 v61, v70, v71
	global_store_dwordx4 v[68:69], v[58:61], off
	v_pk_mul_f32 v[54:55], v[54:55], v[66:67] op_sel_hi:[1,0]
	s_nop 0
	v_pk_mul_f32 v[58:59], v[52:53], v[66:67] op_sel_hi:[1,0]
	v_pk_mul_f32 v[52:53], v[50:51], v[66:67] op_sel_hi:[1,0]
	v_cvt_pk_bf16_f32 v50, v54, v55
	v_cvt_pk_bf16_f32 v51, v56, v57
	s_nop 0
	v_cvt_pk_bf16_f32 v52, v52, v53
	v_cvt_pk_bf16_f32 v53, v58, v59
	global_store_dwordx4 v[68:69], v[50:53], off offset:256
.LBB0_173:
	s_nop 1
	v_add_f32_e32 v50, v155, v157
	v_fmamk_f32 v50, v50, 0x3a800000, v211
	v_mul_f32_e32 v51, 0x4f800000, v50
	v_cmp_gt_f32_e32 vcc, s55, v50
	s_nop 1
	v_cndmask_b32_e32 v50, v50, v51, vcc
	v_sqrt_f32_e32 v51, v50
	s_nop 0
	v_add_u32_e32 v52, -1, v51
	v_fma_f32 v54, -v52, v51, v50
	v_add_u32_e32 v53, 1, v51
	v_cmp_ge_f32_e64 s[8:9], 0, v54
	s_nop 1
	v_cndmask_b32_e64 v52, v51, v52, s[8:9]
	v_fma_f32 v51, -v53, v51, v50
	v_cmp_lt_f32_e64 s[8:9], 0, v51
	s_nop 1
	v_cndmask_b32_e64 v51, v52, v53, s[8:9]
	v_mul_f32_e32 v52, 0x37800000, v51
	v_cndmask_b32_e32 v51, v51, v52, vcc
	v_cmp_class_f32_e32 vcc, v50, v212
	s_nop 1
	v_cndmask_b32_e32 v50, v51, v50, vcc
	v_div_scale_f32 v51, s[8:9], v50, v50, 1.0
	v_rcp_f32_e32 v52, v51
	s_mov_b64 s[8:9], -1
	v_fma_f32 v53, -v51, v52, 1.0
	v_fmac_f32_e32 v52, v53, v52
	v_div_scale_f32 v53, vcc, 1.0, v50, 1.0
	v_mul_f32_e32 v54, v53, v52
	v_fma_f32 v55, -v51, v54, v53
	v_fmac_f32_e32 v54, v55, v52
	v_fma_f32 v51, -v51, v54, v53
	v_div_fmas_f32 v51, v51, v52, v54
	v_div_fixup_f32 v50, v51, v50, 1.0
	s_and_b64 vcc, exec, s[0:1]
	s_cbranch_vccnz .LBB0_177
	s_and_saveexec_b64 s[8:9], s[6:7]
	s_cbranch_execz .LBB0_176
	s_movk_i32 s17, 0x140
	v_pk_mul_f32 v[54:55], v[48:49], v[50:51] op_sel_hi:[1,0]
	v_pk_mul_f32 v[52:53], v[46:47], v[50:51] op_sel_hi:[1,0]
	v_mad_i64_i32 v[56:57], s[26:27], v152, s17, v[140:141]
	global_store_dwordx4 v[56:57], v[52:55], off
	s_nop 1
	v_pk_mul_f32 v[54:55], v[44:45], v[50:51] op_sel_hi:[1,0]
	v_pk_mul_f32 v[52:53], v[42:43], v[50:51] op_sel_hi:[1,0]
	global_store_dwordx4 v[56:57], v[52:55], off offset:16

; __device__ __forceinline__ unsigned cvt_pk_bf16(float lo, float hi) { unsigned r; asm volatile("v_cvt_pk_bf16_f32 %0, %1, %2" : "=v"(r) : "v"(lo), "v"(hi)); return r; }
;     __device__ __forceinline__ void operator()(const f32x4 (&acc)[2][2][4][2], const Unit& u, int wr, int wc, int fr, int fq) const {
;     ...
;                 const int row = row0 + ai * HALF + m * 16;
;                 const f32x4 h0 = *((const f32x4*)(hss + (size_t)row * 16) + fq);
;                 float ss = (h0[0] + h0[1]) + (h0[2] + h0[3]);
;                 ss += __shfl_xor(ss, 16); ss += __shfl_xor(ss, 32);
;                 rsv[ai][m] = 1.0f / sqrtf(ss * (1.0f / 1024.0f) + 1e-6f);
;     ...
;             for (int m = 0; m < 4; ++m) {
;                 const int row = row0 + ai * HALF + m * 16;
;                 const float rs = rsv[ai][m];
;                 if (u.pn < ntile_main) {
;                     bf16_t* rowp = P + (size_t)row * 4160 + u.pn * BM + wc * 32 + 8 * fq;
; #pragma unroll
;                     for (int bj = 0; bj < 2; ++bj) {
;                         const f32x4 v0 = acc[ai][bj][m][0] * rs, v1 = acc[ai][bj][m][1] * rs;
;                         u32x4 w; w.x = cvt_pk_bf16(v0[0], v0[1]); w.y = cvt_pk_bf16(v0[2], v0[3]); w.z = cvt_pk_bf16(v1[0], v1[1]); w.w = cvt_pk_bf16(v1[2], v1[3]);
;                         *(u32x4*)(rowp + bj * HALF) = w;
;                     }
;                 } else {
;                     const int c0 = wc * 32 + 8 * fq;
;                     if (c0 < 72) {
;                         *(f32x4*)(misc + (size_t)row * 80 + c0) = acc[ai][0][m][0] * rs;
;                         *(f32x4*)(misc + (size_t)row * 80 + c0 + 4) = acc[ai][0][m][1] * rs;
.LBB0_177:
	s_andn2_b64 vcc, exec, s[8:9]
	s_cbranch_vccnz .LBB0_179
	v_mov_b64_e32 v[52:53], s[12:13]
	v_mad_i64_i32 v[52:53], s[8:9], v152, s76, v[52:53]
	s_lshl_b32 s8, s43, 8
	s_ashr_i32 s9, s8, 31
	v_lshl_add_u64 v[52:53], s[8:9], 1, v[52:53]
	s_lshl_b32 s92, s38, 1
	v_lshl_add_u64 v[52:53], v[52:53], 0, s[92:93]
	v_lshl_add_u64 v[52:53], v[52:53], 0, v[0:1]
	v_pk_mul_f32 v[48:49], v[48:49], v[50:51] op_sel_hi:[1,0]
	v_pk_mul_f32 v[46:47], v[46:47], v[50:51] op_sel_hi:[1,0]
	v_pk_mul_f32 v[54:55], v[44:45], v[50:51] op_sel_hi:[1,0]
	v_pk_mul_f32 v[44:45], v[42:43], v[50:51] op_sel_hi:[1,0]
	v_cvt_pk_bf16_f32 v42, v46, v47
	v_cvt_pk_bf16_f32 v43, v48, v49
	v_pk_mul_f32 v[40:41], v[40:41], v[50:51] op_sel_hi:[1,0]
	v_cvt_pk_bf16_f32 v44, v44, v45
	v_cvt_pk_bf16_f32 v45, v54, v55
	global_store_dwordx4 v[52:53], v[42:45], off
	v_pk_mul_f32 v[38:39], v[38:39], v[50:51] op_sel_hi:[1,0]
	s_nop 0
	v_pk_mul_f32 v[42:43], v[36:37], v[50:51] op_sel_hi:[1,0]
	v_pk_mul_f32 v[36:37], v[34:35], v[50:51] op_sel_hi:[1,0]
	v_cvt_pk_bf16_f32 v34, v38, v39
	v_cvt_pk_bf16_f32 v35, v40, v41
	s_nop 0
	v_cvt_pk_bf16_f32 v36, v36, v37
	v_cvt_pk_bf16_f32 v37, v42, v43
	global_store_dwordx4 v[52:53], v[34:37], off offset:256
.LBB0_179:
	s_nop 1
	v_add_f32_e32 v34, v151, v153
	v_fmamk_f32 v34, v34, 0x3a800000, v211
	v_mul_f32_e32 v35, 0x4f800000, v34
	v_cmp_gt_f32_e32 vcc, s55, v34
	s_nop 1
	v_cndmask_b32_e32 v34, v34, v35, vcc
	v_sqrt_f32_e32 v35, v34
	s_nop 0
	v_add_u32_e32 v36, -1, v35
	v_fma_f32 v38, -v36, v35, v34
	v_add_u32_e32 v37, 1, v35
	v_cmp_ge_f32_e64 s[8:9], 0, v38
	s_nop 1
	v_cndmask_b32_e64 v36, v35, v36, s[8:9]
	v_fma_f32 v35, -v37, v35, v34
	v_cmp_lt_f32_e64 s[8:9], 0, v35
	s_nop 1
	v_cndmask_b32_e64 v35, v36, v37, s[8:9]
	v_mul_f32_e32 v36, 0x37800000, v35
	v_cndmask_b32_e32 v35, v35, v36, vcc
	v_cmp_class_f32_e32 vcc, v34, v212
	s_nop 1
	v_cndmask_b32_e32 v34, v35, v34, vcc
	v_div_scale_f32 v35, s[8:9], v34, v34, 1.0
	v_rcp_f32_e32 v36, v35
	s_mov_b64 s[8:9], -1
	v_fma_f32 v37, -v35, v36, 1.0
	v_fmac_f32_e32 v36, v37, v36
	v_div_scale_f32 v37, vcc, 1.0, v34, 1.0
	v_mul_f32_e32 v38, v37, v36
	v_fma_f32 v39, -v35, v38, v37
	v_fmac_f32_e32 v38, v39, v36
	v_fma_f32 v35, -v35, v38, v37
	v_div_fmas_f32 v35, v35, v36, v38
	v_div_fixup_f32 v34, v35, v34, 1.0
	s_and_b64 vcc, exec, s[0:1]
	s_cbranch_vccnz .LBB0_183
	s_and_saveexec_b64 s[8:9], s[6:7]
	s_cbranch_execz .LBB0_182
	s_movk_i32 s17, 0x140
	v_pk_mul_f32 v[38:39], v[32:33], v[34:35] op_sel_hi:[1,0]
	v_pk_mul_f32 v[36:37], v[30:31], v[34:35] op_sel_hi:[1,0]
	v_mad_i64_i32 v[40:41], s[26:27], v150, s17, v[140:141]
	global_store_dwordx4 v[40:41], v[36:39], off
	s_nop 1
	v_pk_mul_f32 v[38:39], v[28:29], v[34:35] op_sel_hi:[1,0]
	v_pk_mul_f32 v[36:37], v[26:27], v[34:35] op_sel_hi:[1,0]
	global_store_dwordx4 v[40:41], v[36:39], off offset:16

; __device__ __forceinline__ unsigned cvt_pk_bf16(float lo, float hi) { unsigned r; asm volatile("v_cvt_pk_bf16_f32 %0, %1, %2" : "=v"(r) : "v"(lo), "v"(hi)); return r; }
;     __device__ __forceinline__ void operator()(const f32x4 (&acc)[2][2][4][2], const Unit& u, int wr, int wc, int fr, int fq) const {
;     ...
;                 const int row = row0 + ai * HALF + m * 16;
;                 const f32x4 h0 = *((const f32x4*)(hss + (size_t)row * 16) + fq);
;                 float ss = (h0[0] + h0[1]) + (h0[2] + h0[3]);
;                 ss += __shfl_xor(ss, 16); ss += __shfl_xor(ss, 32);
;                 rsv[ai][m] = 1.0f / sqrtf(ss * (1.0f / 1024.0f) + 1e-6f);
;     ...
;             for (int m = 0; m < 4; ++m) {
;                 const int row = row0 + ai * HALF + m * 16;
;                 const float rs = rsv[ai][m];
;                 if (u.pn < ntile_main) {
;                     bf16_t* rowp = P + (size_t)row * 4160 + u.pn * BM + wc * 32 + 8 * fq;
; #pragma unroll
;                     for (int bj = 0; bj < 2; ++bj) {
;                         const f32x4 v0 = acc[ai][bj][m][0] * rs, v1 = acc[ai][bj][m][1] * rs;
;                         u32x4 w; w.x = cvt_pk_bf16(v0[0], v0[1]); w.y = cvt_pk_bf16(v0[2], v0[3]); w.z = cvt_pk_bf16(v1[0], v1[1]); w.w = cvt_pk_bf16(v1[2], v1[3]);
;                         *(u32x4*)(rowp + bj * HALF) = w;
;                     }
;                 } else {
;                     const int c0 = wc * 32 + 8 * fq;
;                     if (c0 < 72) {
;                         *(f32x4*)(misc + (size_t)row * 80 + c0) = acc[ai][0][m][0] * rs;
;                         *(f32x4*)(misc + (size_t)row * 80 + c0 + 4) = acc[ai][0][m][1] * rs;
.LBB0_183:
	s_andn2_b64 vcc, exec, s[8:9]
	s_cbranch_vccnz .LBB0_185
	v_mov_b64_e32 v[36:37], s[12:13]
	v_mad_i64_i32 v[36:37], s[8:9], v150, s76, v[36:37]
	s_lshl_b32 s8, s43, 8
	s_ashr_i32 s9, s8, 31
	v_lshl_add_u64 v[36:37], s[8:9], 1, v[36:37]
	s_lshl_b32 s92, s38, 1
	v_lshl_add_u64 v[36:37], v[36:37], 0, s[92:93]
	v_lshl_add_u64 v[36:37], v[36:37], 0, v[0:1]
	v_pk_mul_f32 v[32:33], v[32:33], v[34:35] op_sel_hi:[1,0]
	v_pk_mul_f32 v[30:31], v[30:31], v[34:35] op_sel_hi:[1,0]
	v_pk_mul_f32 v[38:39], v[28:29], v[34:35] op_sel_hi:[1,0]
	v_pk_mul_f32 v[28:29], v[26:27], v[34:35] op_sel_hi:[1,0]
	v_cvt_pk_bf16_f32 v26, v30, v31
	v_cvt_pk_bf16_f32 v27, v32, v33
	v_pk_mul_f32 v[24:25], v[24:25], v[34:35] op_sel_hi:[1,0]
	v_cvt_pk_bf16_f32 v28, v28, v29
	v_cvt_pk_bf16_f32 v29, v38, v39
	global_store_dwordx4 v[36:37], v[26:29], off
	v_pk_mul_f32 v[22:23], v[22:23], v[34:35] op_sel_hi:[1,0]
	s_nop 0
	v_pk_mul_f32 v[26:27], v[20:21], v[34:35] op_sel_hi:[1,0]
	v_pk_mul_f32 v[20:21], v[18:19], v[34:35] op_sel_hi:[1,0]
	v_cvt_pk_bf16_f32 v18, v22, v23
	v_cvt_pk_bf16_f32 v19, v24, v25
	s_nop 0
	v_cvt_pk_bf16_f32 v20, v20, v21
	v_cvt_pk_bf16_f32 v21, v26, v27
	global_store_dwordx4 v[36:37], v[18:21], off offset:256
.LBB0_185:
	s_waitcnt lgkmcnt(0)
	s_nop 0
	v_add_f32_e32 v18, v149, v159
	v_fmamk_f32 v18, v18, 0x3a800000, v211
	v_mul_f32_e32 v19, 0x4f800000, v18
	v_cmp_gt_f32_e32 vcc, s55, v18
	s_nop 1
	v_cndmask_b32_e32 v18, v18, v19, vcc
	v_sqrt_f32_e32 v19, v18
	s_nop 0
	v_add_u32_e32 v20, -1, v19
	v_fma_f32 v22, -v20, v19, v18
	v_add_u32_e32 v21, 1, v19
	v_cmp_ge_f32_e64 s[8:9], 0, v22
	s_nop 1
	v_cndmask_b32_e64 v20, v19, v20, s[8:9]
	v_fma_f32 v19, -v21, v19, v18
	v_cmp_lt_f32_e64 s[8:9], 0, v19
	s_nop 1
	v_cndmask_b32_e64 v19, v20, v21, s[8:9]
	v_mul_f32_e32 v20, 0x37800000, v19
	v_cndmask_b32_e32 v19, v19, v20, vcc
	v_cmp_class_f32_e32 vcc, v18, v212
	s_nop 1
	v_cndmask_b32_e32 v18, v19, v18, vcc
	v_div_scale_f32 v19, s[8:9], v18, v18, 1.0
	v_rcp_f32_e32 v20, v19
	s_nop 0
	v_fma_f32 v21, -v19, v20, 1.0
	v_fmac_f32_e32 v20, v21, v20
	v_div_scale_f32 v21, vcc, 1.0, v18, 1.0
	v_mul_f32_e32 v22, v21, v20
	v_fma_f32 v23, -v19, v22, v21
	v_fmac_f32_e32 v22, v23, v20
	v_fma_f32 v19, -v19, v22, v21
	v_div_fmas_f32 v19, v19, v20, v22
	v_div_fixup_f32 v18, v19, v18, 1.0
	s_and_b64 vcc, exec, s[0:1]
	s_mov_b64 s[0:1], -1
	s_cbranch_vccnz .LBB0_189
	s_and_saveexec_b64 s[0:1], s[6:7]
	s_cbranch_execz .LBB0_188
	s_movk_i32 s8, 0x140
	v_pk_mul_f32 v[22:23], v[16:17], v[18:19] op_sel_hi:[1,0]
	v_pk_mul_f32 v[20:21], v[14:15], v[18:19] op_sel_hi:[1,0]
	v_mad_i64_i32 v[24:25], s[8:9], v148, s8, v[140:141]
	global_store_dwordx4 v[24:25], v[20:23], off
	s_nop 1
	v_pk_mul_f32 v[22:23], v[12:13], v[18:19] op_sel_hi:[1,0]
	v_pk_mul_f32 v[20:21], v[10:11], v[18:19] op_sel_hi:[1,0]
	global_store_dwordx4 v[24:25], v[20:23], off offset:16

; __device__ __forceinline__ unsigned cvt_pk_bf16(float lo, float hi) { unsigned r; asm volatile("v_cvt_pk_bf16_f32 %0, %1, %2" : "=v"(r) : "v"(lo), "v"(hi)); return r; }
;     __device__ __forceinline__ void operator()(const f32x4 (&acc)[2][2][4][2], const Unit& u, int wr, int wc, int fr, int fq) const {
;     ...
;                 if (u.pn < ntile_main) {
;                     bf16_t* rowp = P + (size_t)row * 4160 + u.pn * BM + wc * 32 + 8 * fq;
; #pragma unroll
;                     for (int bj = 0; bj < 2; ++bj) {
;                         const f32x4 v0 = acc[ai][bj][m][0] * rs, v1 = acc[ai][bj][m][1] * rs;
;                         u32x4 w; w.x = cvt_pk_bf16(v0[0], v0[1]); w.y = cvt_pk_bf16(v0[2], v0[3]); w.z = cvt_pk_bf16(v1[0], v1[1]); w.w = cvt_pk_bf16(v1[2], v1[3]);
;                         *(u32x4*)(rowp + bj * HALF) = w;
;                     }
.LBB0_189:
	s_andn2_b64 vcc, exec, s[0:1]
	s_cbranch_vccnz .LBB0_191
	v_mov_b64_e32 v[20:21], s[12:13]
	v_mad_i64_i32 v[20:21], s[0:1], v148, s76, v[20:21]
	s_lshl_b32 s0, s43, 8
	s_ashr_i32 s1, s0, 31
	v_lshl_add_u64 v[20:21], s[0:1], 1, v[20:21]
	s_lshl_b32 s92, s38, 1
	v_lshl_add_u64 v[20:21], v[20:21], 0, s[92:93]
	v_lshl_add_u64 v[20:21], v[20:21], 0, v[0:1]
	v_pk_mul_f32 v[16:17], v[16:17], v[18:19] op_sel_hi:[1,0]
	v_pk_mul_f32 v[14:15], v[14:15], v[18:19] op_sel_hi:[1,0]
	v_pk_mul_f32 v[22:23], v[12:13], v[18:19] op_sel_hi:[1,0]
	v_pk_mul_f32 v[12:13], v[10:11], v[18:19] op_sel_hi:[1,0]
	v_cvt_pk_bf16_f32 v10, v14, v15
	v_cvt_pk_bf16_f32 v11, v16, v17
	v_pk_mul_f32 v[8:9], v[8:9], v[18:19] op_sel_hi:[1,0]
	v_cvt_pk_bf16_f32 v12, v12, v13
	v_cvt_pk_bf16_f32 v13, v22, v23
	global_store_dwordx4 v[20:21], v[10:13], off
	v_pk_mul_f32 v[6:7], v[6:7], v[18:19] op_sel_hi:[1,0]
	s_nop 0
	v_pk_mul_f32 v[10:11], v[4:5], v[18:19] op_sel_hi:[1,0]
	v_pk_mul_f32 v[4:5], v[2:3], v[18:19] op_sel_hi:[1,0]
	v_cvt_pk_bf16_f32 v2, v6, v7
	v_cvt_pk_bf16_f32 v3, v8, v9
	s_nop 0
	v_cvt_pk_bf16_f32 v4, v4, v5
	v_cvt_pk_bf16_f32 v5, v10, v11
	global_store_dwordx4 v[20:21], v[2:5], off offset:256

; template <int MODE>
; __device__ __forceinline__ void attn_item(const AttnP& p, int b, int h, int qb, LAS unsigned char* lds) {
;     ...
;     const int tok0 = b * SEQ, q0 = qb * 256, qw = q0 + 32 * w, qrow = qw + ln;
;     const bf16_t* P = p.P;
;     bf16x8 Qf[NC][4];
; #pragma unroll
;     for (int c = 0; c < NC; ++c) {
;         u32x4 raw[4]; float ss = 0.f;
; #pragma unroll
;         for (int ks = 0; ks < 4; ++ks) {
;             raw[ks] = *(const u32x4*)(P + (size_t)(tok0 + qrow) * PP + qcol + c * 64 + ks * 16 + hh * 8);
; #pragma unroll
;             for (int e = 0; e < 4; ++e) { const float lo = bflo(raw[ks][e]), hi = bfhi(raw[ks][e]); ss += lo * lo + hi * hi; }
;         }
;         float sc = 0.125f * LOG2E;
;         if (MODE != 1) { ss += __shfl_xor(ss, 32); sc *= 1.0f / sqrtf(ss * (1.0f / 64.0f) + 1e-6f); }
; #pragma unroll
;         for (int ks = 0; ks < 4; ++ks) {
;             u32x4 o;
; #pragma unroll
;             for (int e = 0; e < 4; ++e) {
;                 float lo = bflo(raw[ks][e]) * sc, hi = bfhi(raw[ks][e]) * sc;
;                 if (MODE != 1) {
;                     const int d = ks * 16 + hh * 8 + 2 * e;
;                     const float* gq = p.qk_gain + ((MODE == 0) ? 0 : 128); const float* gk = gq + 64;
;                     lo *= gq[d] * gk[d]; hi *= gq[d + 1] * gk[d + 1];
;                 }
;                 o[e] = pk2(lo, hi);
;             }
;             Qf[c][ks] = __builtin_bit_cast(bf16x8, o);
;             if (QPARK) *(LAS u32x4*)(lds + QP_OFF + w * 8192 + ((c * 4 + ks) * 64 + lane) * 16) = o;
;         }
;     }
;     if (MODE == 0) { LAS float* tab = (LAS float*)(lds + TAB_OFF); if (tid < 256) tab[tid] = p.biasT[h * 256 + tid]; }
;     LAS unsigned* flags = (LAS unsigned*)(lds + FLAG_OFF);
;     if (MODE == 1 && tid < 16) flags[tid] = 0u;
;     f32x16 O[NC][DV / 32];
; #pragma unroll
;     for (int c = 0; c < NC; ++c)
; #pragma unroll
; __global__ void __launch_bounds__(512) hymba_fwd(Args a) {
;     ...
;                 const int idx = next_item(ctl + pb + 1, qslot);
;                 if (idx >= 256 + 1024) break;
;                 if (idx < 256) {
;     ...
;                     scan_pass1(sp, idx >> 5, (idx >> 2) & 7, idx & 3, lds);
;     ...
;                 } else {
;                     const int ci = idx - 256, qb = 15 - (ci >> 6), bh = ci & 63;
;     ...
;                     attn_item<2>(ap, bh >> 3, bh & 7, qb, lds);
.LBB0_211:
	s_waitcnt lgkmcnt(0)
	s_barrier
	s_mov_b64 s[0:1], exec
	v_readlane_b32 s2, v253, 0
	v_readlane_b32 s3, v253, 1
	s_and_b64 s[2:3], s[0:1], s[2:3]
	s_mov_b64 exec, s[2:3]
	s_cbranch_execz .LBB0_213
	v_readlane_b32 s2, v252, 3
	v_readlane_b32 s3, v252, 4
	s_waitcnt vmcnt(0)
	s_nop 0
	v_mov_b64_e32 v[2:3], s[2:3]
	global_atomic_add v0, v[2:3], v213, off offset:8 sc0
	v_readlane_b32 s2, v254, 19
	s_nop 1
	v_mov_b32_e32 v2, s2
	s_waitcnt vmcnt(0) lgkmcnt(0)
	ds_write_b32 v2, v0
.LBB0_213:
	s_or_b64 exec, exec, s[0:1]
	v_readlane_b32 s0, v254, 19
	s_waitcnt lgkmcnt(0)
	s_barrier
	v_mov_b32_e32 v0, s0
	ds_read_b32 v0, v0
	s_movk_i32 s0, 0x4ff
	s_waitcnt lgkmcnt(0)
	v_cmp_lt_i32_e32 vcc, s0, v0
	v_readfirstlane_b32 s3, v0
	s_mov_b64 s[0:1], -1
	s_cbranch_vccnz .LBB0_210
	s_cmpk_gt_i32 s3, 0xff
	v_writelane_b32 v252, s3, 9
	s_cbranch_scc0 .LBB0_243
	s_add_i32 s0, s3, 0xffffff00
	v_mov_b32_e32 v123, v210
	s_lshr_b32 s22, s0, 6
	s_sub_i32 s2, 15, s22
	v_readfirstlane_b32 s5, v123
	s_lshl_b32 s0, s3, 9
	s_ashr_i32 s1, s5, 1
	s_and_b32 s26, s0, 0x7000
	s_lshl_b32 s0, s2, 8
	s_and_b32 s27, s1, 0xffffffe0
	v_and_b32_e32 v122, 31, v123
	s_add_i32 s27, s27, s0
	v_or_b32_e32 v115, s27, v122
	s_and_b32 s4, s3, 7
	v_add_u32_e32 v0, s26, v115
	s_waitcnt vmcnt(0)
	v_mov_b64_e32 v[2:3], s[68:69]
	v_bfe_u32 v124, v123, 5, 1
	v_mad_i64_i32 v[2:3], s[0:1], v0, s76, v[2:3]
	s_lshl_b32 s92, s4, 7
	v_lshl_add_u64 v[2:3], v[2:3], 0, s[92:93]
	v_lshlrev_b32_e32 v88, 4, v124
	v_mov_b32_e32 v89, v1
	v_lshl_add_u64 v[2:3], v[2:3], 0, v[88:89]
	global_load_dwordx4 v[64:67], v[2:3], off offset:96
	global_load_dwordx4 v[68:71], v[2:3], off offset:64
	global_load_dwordx4 v[100:103], v[2:3], off offset:32
	global_load_dwordx4 v[116:119], v[2:3], off
	v_and_b32_e32 v0, 64, v216
	v_xor_b32_e32 v2, 32, v216
	v_add_u32_e32 v0, 64, v0
	v_cmp_lt_i32_e32 vcc, v2, v0
	v_and_b32_e32 v22, 32, v123
	s_waitcnt vmcnt(0) lgkmcnt(0)
	v_and_b32_e32 v85, 0xffff0000, v65
	v_cndmask_b32_e32 v2, v216, v2, vcc
	v_lshlrev_b32_e32 v114, 2, v2
	global_load_dwordx4 v[2:5], v22, s[90:91] offset:720
	global_load_dwordx4 v[26:29], v22, s[90:91] offset:704
	global_load_dwordx4 v[6:9], v22, s[90:91] offset:976
	global_load_dwordx4 v[34:37], v22, s[90:91] offset:960
	global_load_dwordx4 v[38:41], v22, s[90:91] offset:656
	global_load_dwordx4 v[30:33], v22, s[90:91] offset:640
	global_load_dwordx4 v[46:49], v22, s[90:91] offset:912
	global_load_dwordx4 v[42:45], v22, s[90:91] offset:896
	global_load_dwordx4 v[58:61], v22, s[90:91] offset:592
	global_load_dwordx4 v[10:13], v22, s[90:91] offset:576
	global_load_dwordx4 v[72:75], v22, s[90:91] offset:848
	global_load_dwordx4 v[14:17], v22, s[90:91] offset:832
	global_load_dwordx4 v[50:53], v22, s[90:91] offset:528
	global_load_dwordx4 v[18:21], v22, s[90:91] offset:512
	global_load_dwordx4 v[54:57], v22, s[90:91] offset:784
	s_nop 0
	global_load_dwordx4 v[22:25], v22, s[90:91] offset:768
	v_and_b32_e32 v83, 0xffff0000, v71
	v_and_b32_e32 v87, 0xffff0000, v67
	v_lshlrev_b32_e32 v84, 16, v64
	v_and_b32_e32 v111, 0xffff0000, v64
	v_lshlrev_b32_e32 v82, 16, v70
	v_and_b32_e32 v109, 0xffff0000, v70
	v_mov_b32_e32 v110, v85
	v_mov_b32_e32 v108, v83
	v_lshlrev_b32_e32 v86, 16, v66
	v_and_b32_e32 v113, 0xffff0000, v66
	v_lshlrev_b32_e32 v90, 16, v65
	v_lshlrev_b32_e32 v92, 16, v71
	v_mov_b32_e32 v112, v87
	v_mov_b32_e32 v91, v84
	v_mov_b32_e32 v93, v82
	v_pk_mul_f32 v[104:105], v[110:111], v[110:111]
	v_pk_mul_f32 v[106:107], v[108:109], v[108:109]
	v_lshlrev_b32_e32 v62, 16, v67
	v_lshlrev_b32_e32 v96, 16, v103
	v_and_b32_e32 v97, 0xffff0000, v103
	v_lshlrev_b32_e32 v78, 16, v102
	v_and_b32_e32 v79, 0xffff0000, v102
	v_mov_b32_e32 v63, v86
	v_pk_mul_f32 v[102:103], v[112:113], v[112:113]
	v_pk_fma_f32 v[130:131], v[90:91], v[90:91], v[104:105]
	v_pk_fma_f32 v[132:133], v[92:93], v[92:93], v[106:107]
	v_lshlrev_b32_e32 v104, 16, v117
	v_and_b32_e32 v105, 0xffff0000, v117
	v_lshlrev_b32_e32 v106, 16, v116
	v_and_b32_e32 v107, 0xffff0000, v116
	v_pk_fma_f32 v[128:129], v[62:63], v[62:63], v[102:103]
	v_lshlrev_b32_e32 v102, 16, v118
	v_and_b32_e32 v103, 0xffff0000, v118
	v_pk_mul_f32 v[136:137], v[104:105], v[104:105]
	v_pk_mul_f32 v[116:117], v[106:107], v[106:107]
	v_lshlrev_b32_e32 v98, 16, v101
	v_and_b32_e32 v99, 0xffff0000, v101
	v_lshlrev_b32_e32 v76, 16, v100
	v_and_b32_e32 v77, 0xffff0000, v100
	v_lshlrev_b32_e32 v100, 16, v119
	v_and_b32_e32 v101, 0xffff0000, v119
	v_pk_mul_f32 v[118:119], v[102:103], v[102:103]
	v_add_f32_e32 v89, v136, v137
	v_add_f32_e32 v91, v116, v117
	v_pk_mul_f32 v[134:135], v[100:101], v[100:101]
	v_add_f32_e32 v89, v91, v89
	v_add_f32_e32 v91, v118, v119
	v_pk_mul_f32 v[126:127], v[76:77], v[76:77]
	v_add_f32_e32 v63, v134, v135
	v_add_f32_e32 v89, v91, v89
	v_pk_mul_f32 v[120:121], v[98:99], v[98:99]
	v_add_f32_e32 v63, v63, v89
	v_add_f32_e32 v89, v126, v127
	v_pk_mul_f32 v[70:71], v[78:79], v[78:79]
	v_add_f32_e32 v63, v89, v63
	v_add_f32_e32 v89, v120, v121
	v_lshlrev_b32_e32 v94, 16, v69
	v_and_b32_e32 v95, 0xffff0000, v69
	v_lshlrev_b32_e32 v80, 16, v68
	v_and_b32_e32 v81, 0xffff0000, v68
	v_pk_mul_f32 v[68:69], v[96:97], v[96:97]
	v_add_f32_e32 v63, v89, v63
	v_add_f32_e32 v70, v70, v71
	v_pk_mul_f32 v[66:67], v[80:81], v[80:81]
	v_add_f32_e32 v63, v70, v63
	v_add_f32_e32 v68, v68, v69
	v_pk_mul_f32 v[64:65], v[94:95], v[94:95]
	v_add_f32_e32 v63, v68, v63
	v_add_f32_e32 v66, v66, v67
	v_add_f32_e32 v63, v66, v63
	v_add_f32_e32 v64, v64, v65
	v_add_f32_e32 v63, v64, v63
	v_add_f32_e32 v63, v133, v63
	v_add_f32_e32 v63, v132, v63
	v_add_f32_e32 v63, v131, v63
	v_add_f32_e32 v63, v130, v63
	v_add_f32_e32 v63, v129, v63
	v_add_f32_e32 v125, v128, v63
	ds_bpermute_b32 v126, v114, v125
	v_cmp_gt_i32_e32 vcc, 4, v123
	s_and_saveexec_b64 s[0:1], vcc
	v_lshl_add_u32 v63, v123, 2, 0
	ds_write_b32 v63, v1 offset:44672
	s_or_b64 exec, exec, s[0:1]
	v_and_b32_e32 v89, 63, v123
	v_lshlrev_b32_e32 v63, 2, v89
	global_load_dword v64, v63, s[90:91] offset:512
	v_xor_b32_e32 v67, 1, v216
	global_load_dword v63, v63, s[90:91] offset:768
	v_cmp_lt_i32_e32 vcc, v67, v0
	s_lshl_b32 s18, s4, 2
	v_readlane_b32 s0, v254, 61
	v_cndmask_b32_e32 v67, v216, v67, vcc
	v_lshlrev_b32_e32 v67, 2, v67
	s_lshl_b32 s28, s2, 2
	v_readlane_b32 s1, v254, 62
	s_or_b32 s29, s28, 3
	v_ashrrev_i32_e32 v127, 3, v123
	s_lshl_b32 s20, s4, 6
	s_lshl_b32 s92, s20, 1
	v_mov_b32_e32 v112, 0
	s_waitcnt vmcnt(1)
; template <int MODE>
; __device__ __forceinline__ void attn_item(const AttnP& p, int b, int h, int qb, LAS unsigned char* lds) {
;     ...
;         float gq_ = fabsf(p.qk_gain[128 + lane]), gk_ = fabsf(p.qk_gain[192 + lane]);
; #pragma unroll
;         for (int o_ = 1; o_ < 64; o_ <<= 1) { gq_ = fmaxf(gq_, __shfl_xor(gq_, o_)); gk_ = fmaxf(gk_, __shfl_xor(gk_, o_)); }
;         qk2 = 8.0f * gq_ * gk_ * LOG2E * 1.02f;
;     }
;     const float fb = (MODE == 2) ? p.fbias[h] : 0.f;
;     const int jt_max = qb * 4 + 3;
;     u32x4 kreg[NC], vreg[NC]; float cfreg = 0.f;
	v_and_b32_e32 v65, 0x7fffffff, v64
	ds_bpermute_b32 v65, v67, v65
	s_waitcnt vmcnt(0)
	v_and_b32_e32 v66, 0x7fffffff, v63
	v_max_f32_e64 v64, |v64|, |v64|
	v_max_f32_e64 v63, |v63|, |v63|
	s_waitcnt lgkmcnt(0)
	v_max_f32_e32 v65, v65, v65
	v_max_f32_e32 v64, v64, v65
	ds_bpermute_b32 v65, v67, v66
	s_waitcnt lgkmcnt(0)
	v_max_f32_e32 v65, v65, v65
	v_max_f32_e32 v63, v63, v65
	v_xor_b32_e32 v65, 2, v216
	v_cmp_lt_i32_e32 vcc, v65, v0
	s_nop 1
	v_cndmask_b32_e32 v65, v216, v65, vcc
	v_lshlrev_b32_e32 v65, 2, v65
	ds_bpermute_b32 v66, v65, v64
	ds_bpermute_b32 v65, v65, v63
	s_waitcnt lgkmcnt(1)
	v_max_f32_e32 v66, v66, v66
	s_waitcnt lgkmcnt(0)
	v_max_f32_e32 v65, v65, v65
	v_max_f32_e32 v63, v63, v65
	v_xor_b32_e32 v65, 4, v216
	v_cmp_lt_i32_e32 vcc, v65, v0
	v_max_f32_e32 v64, v64, v66
	s_nop 0
	v_cndmask_b32_e32 v65, v216, v65, vcc
	v_lshlrev_b32_e32 v65, 2, v65
	ds_bpermute_b32 v66, v65, v64
	ds_bpermute_b32 v65, v65, v63
	s_waitcnt lgkmcnt(1)
	v_max_f32_e32 v66, v66, v66
	s_waitcnt lgkmcnt(0)
	v_max_f32_e32 v65, v65, v65
	v_max_f32_e32 v63, v63, v65
	v_xor_b32_e32 v65, 8, v216
	v_cmp_lt_i32_e32 vcc, v65, v0
	v_max_f32_e32 v64, v64, v66
	s_nop 0
	v_cndmask_b32_e32 v65, v216, v65, vcc
	v_lshlrev_b32_e32 v65, 2, v65
	ds_bpermute_b32 v66, v65, v64
	ds_bpermute_b32 v65, v65, v63
	s_waitcnt lgkmcnt(1)
	v_max_f32_e32 v66, v66, v66
	s_waitcnt lgkmcnt(0)
	v_max_f32_e32 v65, v65, v65
	v_max_f32_e32 v65, v63, v65
	v_xor_b32_e32 v63, 16, v216
	v_cmp_lt_i32_e32 vcc, v63, v0
	v_max_f32_e32 v64, v64, v66
	s_nop 0
	v_cndmask_b32_e32 v0, v216, v63, vcc
	v_lshlrev_b32_e32 v0, 2, v0
	ds_bpermute_b32 v63, v0, v64
	ds_bpermute_b32 v0, v0, v65
	s_waitcnt lgkmcnt(1)
	v_max_f32_e32 v63, v63, v63
	s_waitcnt lgkmcnt(0)
	v_max_f32_e32 v0, v0, v0
	v_max_f32_e32 v91, v65, v0
	v_mov_b32_e32 v0, s18
	global_load_dword v110, v0, s[0:1]
	s_lshl_b32 s0, s29, 6
	s_or_b32 s6, s0, s26
	v_max_f32_e32 v63, v64, v63
	v_add_u32_e32 v0, s6, v127
	v_mov_b64_e32 v[64:65], s[68:69]
	v_mad_i64_i32 v[64:65], s[0:1], v0, s76, v[64:65]
	v_lshlrev_b32_e32 v0, 3, v123
	v_and_b32_e32 v108, 56, v0
	v_lshlrev_b32_e32 v0, 1, v108
	v_lshl_add_u64 v[64:65], v[64:65], 0, v[0:1]
	v_lshl_add_u64 v[68:69], v[64:65], 0, s[92:93]
	global_load_dwordx4 v[64:67], v[68:69], off offset:1024
	ds_bpermute_b32 v121, v114, v63
	ds_bpermute_b32 v93, v114, v91
	s_cmp_lt_u32 s5, 64
	s_cselect_b64 s[2:3], -1, 0
	s_cmp_gt_u32 s5, 63
	s_cselect_b64 s[0:1], -1, 0
	s_and_b64 vcc, exec, s[0:1]
	s_cbranch_vccnz .LBB0_219
	v_or_b32_e32 v70, s6, v89
	v_mul_u32_u24_e32 v70, 0x50, v70
	v_or_b32_e32 v70, s4, v70
	v_lshl_add_u32 v70, v70, 2, v217
	v_mov_b32_e32 v71, v1
	v_lshl_add_u64 v[70:71], s[84:85], 0, v[70:71]
	global_load_dword v112, v[70:71], off
.LBB0_219:
	s_nop 0
	global_load_dwordx4 v[68:71], v[68:69], off offset:2048
	s_waitcnt vmcnt(0) lgkmcnt(0)
	v_and_b32_e32 v119, 0xffff0000, v67
	v_and_b32_e32 v131, 0xffff0000, v66
	v_lshlrev_b32_e32 v118, 16, v67
	v_lshlrev_b32_e32 v130, 16, v66
	v_mov_b32_e32 v132, v119
	v_mov_b32_e32 v133, v131
	v_mov_b32_e32 v128, v118
	v_mov_b32_e32 v129, v130
	v_pk_mul_f32 v[132:133], v[132:133], v[132:133]
	v_and_b32_e32 v135, 0xffff0000, v64
	v_pk_fma_f32 v[128:129], v[128:129], v[128:129], v[132:133]
	v_and_b32_e32 v133, 0xffff0000, v65
	v_lshlrev_b32_e32 v132, 16, v65
	v_lshlrev_b32_e32 v134, 16, v64
	v_mov_b32_e32 v138, v135
	v_mov_b32_e32 v139, v133
	v_mov_b32_e32 v136, v134
	v_mov_b32_e32 v137, v132
	v_pk_mul_f32 v[138:139], v[138:139], v[138:139]
	v_mad_u64_u32 v[116:117], s[4:5], v127, s72, v[108:109]
	v_pk_fma_f32 v[136:137], v[136:137], v[136:137], v[138:139]
	v_lshlrev_b32_e32 v108, 1, v116
	v_add_f32_e32 v120, v136, v137
	v_add_f32_e32 v120, v129, v120
	v_add_f32_e32 v120, v128, v120
	v_mul_lo_u32 v117, v127, 24
	v_add_lshl_u32 v116, v116, v117, 1
	v_add_f32_dpp v120, v120, v120 quad_perm:[1,0,3,2] row_mask:0xf bank_mask:0xf bound_ctrl:1
	v_add_u32_e32 v117, 0, v108
	s_mov_b64 s[4:5], -1
	v_add_f32_dpp v120, v120, v120 quad_perm:[2,3,0,1] row_mask:0xf bank_mask:0xf bound_ctrl:1
	s_andn2_b64 vcc, exec, s[0:1]
	s_nop 0
	v_add_f32_dpp v120, v120, v120 row_half_mirror row_mask:0xf bank_mask:0xf bound_ctrl:1
	v_fmamk_f32 v120, v120, 0x3c800000, v211
	v_rsq_f32_e32 v120, v120
	s_nop 0
	v_pk_mul_f32 v[128:129], v[120:121], v[134:135] op_sel_hi:[0,1]
	v_pk_mul_f32 v[132:133], v[120:121], v[132:133] op_sel_hi:[0,1]
	v_pk_mul_f32 v[130:131], v[120:121], v[130:131] op_sel_hi:[0,1]
	v_pk_mul_f32 v[118:119], v[120:121], v[118:119] op_sel_hi:[0,1]
	v_cvt_pk_bf16_f32 v128, v128, v129
	v_cvt_pk_bf16_f32 v129, v132, v133
	v_cvt_pk_bf16_f32 v130, v130, v131
	v_cvt_pk_bf16_f32 v131, v118, v119
	v_add_u32_e32 v118, 0, v116
	ds_write_b128 v117, v[128:131]
	ds_write_b128 v118, v[68:71] offset:9216
	v_lshlrev_b32_e32 v117, 2, v216
	v_and_b32_e32 v128, 63, v216
	v_or_b32_e32 v129, 0x80, v117
	v_and_b32_e32 v131, 0x100, v117
	s_cbranch_vccnz .LBB0_221
	v_and_b32_e32 v130, 63, v216
	v_or_b32_e32 v118, 0x80, v117
	v_and_b32_e32 v119, 0x100, v117
	s_mov_b64 s[4:5], 0

; #define ATT_LOADK(jt) do { _Pragma("unroll") for (int i_ = 0; i_ < NC; ++i_) { const int key_ = tid >> 3, dch_ = (tid & 7) + 8 * i_; \
;             const bf16_t* rp_ = P + (size_t)(tok0 + (jt) * 64 + key_) * PP + dch_ * 8; kreg[i_] = *(const u32x4*)(rp_ + kcol); } \
;         if (MODE == 2 && w == 0) cfreg = p.misc[(size_t)(tok0 + (jt) * 64 + lane) * MISCP + 64 + h]; } while (0)
; #define ATT_LOADV(jt) do { _Pragma("unroll") for (int i_ = 0; i_ < NC; ++i_) { const int key_ = tid >> 3, dch_ = (tid & 7) + 8 * i_; \
;             const bf16_t* rp_ = P + (size_t)(tok0 + (jt) * 64 + key_) * PP + dch_ * 8; vreg[i_] = *(const u32x4*)(rp_ + vcol); } } while (0)
; template <int MODE>
; __device__ __forceinline__ void attn_item(const AttnP& p, int b, int h, int qb, LAS unsigned char* lds) {
;     ...
;     for (int it = 0; it <= jt_max; ++it) {
;         const int jt = jt_max - it, k0 = jt * 64, buf = it & 1;
;         const bool has_next = it < jt_max;
;         if (has_next) { ATT_LOADK(jt - 1); ATT_LOADV(jt - 1); }
.LBB0_228:
	s_cmp_lt_u32 s30, s29
	v_cndmask_b32_e64 v2, 0, 1, s[2:3]
	s_cselect_b64 s[22:23], -1, 0
	s_cmp_ge_u32 s30, s29
	v_cmp_ne_u32_e64 s[14:15], 1, v2
	s_cbranch_scc1 .LBB0_232
	v_add_u32_e32 v2, s33, v106
	v_add_u32_e32 v2, 0xffffff81, v2
	v_mad_i64_i32 v[2:3], s[24:25], v2, s76, v[90:91]
	s_waitcnt vmcnt(0)
	global_load_dwordx4 v[64:67], v[2:3], off offset:1024
	s_and_b64 vcc, exec, s[14:15]
	s_cbranch_vccnz .LBB0_231
	v_ashrrev_i32_e32 v93, 31, v92
	v_lshl_add_u64 v[4:5], s[18:19], 0, v[92:93]
	global_load_dword v112, v[4:5], off offset:256
.LBB0_231:
	global_load_dwordx4 v[68:71], v[2:3], off offset:2048

; __device__ __forceinline__ unsigned pk2(float lo, float hi) { f32x2 v = {lo, hi}; bf16x2_t b = __builtin_convertvector(v, bf16x2_t); return __builtin_bit_cast(unsigned, b); }
; __device__ __forceinline__ float bflo(unsigned u) { return __uint_as_float(u << 16); }
; __device__ __forceinline__ float bfhi(unsigned u) { return __uint_as_float(u & 0xffff0000u); }
; __device__ __forceinline__ float silu(float g) { return g * __builtin_amdgcn_rcpf(1.0f + __expf(-g)); }
; template <int MODE>
; __device__ __forceinline__ void attn_item(const AttnP& p, int b, int h, int qb, LAS unsigned char* lds) {
;     ...
;     float inv0 = 1.f, inv1 = 0.f;
;     if (MODE != 1) { float l0 = lsum[0]; l0 += __shfl_xor(l0, 32); inv0 = 1.0f / l0; }
;     if (MODE == 0) { float l1 = lsum[NC - 1]; l1 += __shfl_xor(l1, 32); inv1 = p.lam / l1; }
;     float ss = 0.f;
; #pragma unroll
;     for (int d = 0; d < DV / 32; ++d)
; #pragma unroll
;         for (int i = 0; i < 16; ++i) {
;             float o = O[0][d][i] * inv0;
;             if (MODE == 0) o -= O[NC - 1][d][i] * inv1;
;             O[0][d][i] = o; ss += o * o;
;         }
;     ss += __shfl_xor(ss, 32);
;     float rn = 1.0f / sqrtf(ss * (1.0f / DV) + 1e-6f);
;     if (MODE == 0) rn *= p.oml;
;     int qrow_e = qrow; asm volatile("" : "+v"(qrow_e));
;     const size_t trow = (size_t)(tok0 + qrow_e);
; #pragma unroll
;     for (int d = 0; d < DV / 32; ++d)
; #pragma unroll
;         for (int g = 0; g < 4; ++g) {
;             const int dd = d * 32 + 8 * g + 4 * hh;
;             const u32x2 gr = *(const u32x2*)(P + trow * PP + gcol + dd);
;             const f32x4 og = *(const f32x4*)(p.out_gain + gaincol + dd);
;             const float o0 = O[0][d][4 * g] * rn * og[0] * silu(bflo(gr.x)), o1 = O[0][d][4 * g + 1] * rn * og[1] * silu(bfhi(gr.x));
;             const float o2 = O[0][d][4 * g + 2] * rn * og[2] * silu(bflo(gr.y)), o3 = O[0][d][4 * g + 3] * rn * og[3] * silu(bfhi(gr.y));
;             u32x2 wv; wv.x = pk2(o0, o1); wv.y = pk2(o2, o3);
;             *(u32x2*)(p.mixed + trow * 1024 + mixcol + dd) = wv;
;         }
.LBB0_242:
	ds_bpermute_b32 v2, v114, v0
	s_lshl_b32 s2, s20, 2
	s_bitset1_b32 s2, 12
	s_waitcnt lgkmcnt(0)
	v_add_f32_e32 v0, v0, v2
	v_div_scale_f32 v2, s[0:1], v0, v0, 1.0
	v_rcp_f32_e32 v3, v2
	s_nop 0
	v_fma_f32 v4, -v2, v3, 1.0
	v_fmac_f32_e32 v3, v4, v3
	v_div_scale_f32 v4, vcc, 1.0, v0, 1.0
	v_mul_f32_e32 v5, v4, v3
	v_fma_f32 v6, -v2, v5, v4
	v_fmac_f32_e32 v5, v6, v3
	v_fma_f32 v2, -v2, v5, v4
	v_div_fmas_f32 v2, v2, v3, v5
	v_div_fixup_f32 v56, v2, v0, 1.0
	v_add_u32_e32 v2, s26, v115
	v_mov_b64_e32 v[4:5], s[68:69]
	v_mad_i64_i32 v[4:5], s[0:1], v2, s76, v[4:5]
	v_lshl_add_u64 v[4:5], v[4:5], 0, s[92:93]
	v_lshlrev_b32_e32 v0, 1, v94
	v_lshl_add_u64 v[12:13], v[4:5], 0, v[0:1]
	global_load_dwordx2 v[50:51], v[12:13], off offset:3072
	global_load_dwordx2 v[54:55], v[12:13], off offset:3088
	s_waitcnt vmcnt(0)
	global_load_dwordx2 v[66:67], v[12:13], off offset:3104
	global_load_dwordx2 v[74:75], v[12:13], off offset:3120
	v_readlane_b32 s0, v254, 54
	v_readlane_b32 s1, v254, 55
	s_add_u32 s2, s0, s2
	v_ashrrev_i32_e32 v3, 31, v2
	s_addc_u32 s3, s1, 0
	v_readlane_b32 s0, v254, 40
	v_lshlrev_b64 v[10:11], 11, v[2:3]
	v_readlane_b32 s1, v254, 41
	global_load_dwordx2 v[76:77], v[12:13], off offset:3136
	global_load_dwordx2 v[86:87], v[12:13], off offset:3152
	v_lshl_add_u64 v[10:11], s[0:1], 0, v[10:11]
	v_lshl_add_u64 v[10:11], v[10:11], 0, s[92:93]
	v_lshl_add_u64 v[10:11], v[10:11], 0, v[0:1]
	v_pk_mul_f32 v[14:15], v[26:27], v[56:57] op_sel_hi:[1,0]
	v_pk_mul_f32 v[8:9], v[28:29], v[56:57] op_sel_hi:[1,0]
	v_pk_mul_f32 v[6:7], v[30:31], v[56:57] op_sel_hi:[1,0]
	v_lshlrev_b32_e32 v57, 2, v94
	global_load_dwordx4 v[2:5], v57, s[2:3]
	v_pk_mul_f32 v[32:33], v[32:33], v[56:57] op_sel_hi:[1,0]
	v_pk_mul_f32 v[34:35], v[34:35], v[56:57] op_sel_hi:[1,0]
	v_pk_mul_f32 v[64:65], v[32:33], v[32:33]
	v_pk_mul_f32 v[62:63], v[34:35], v[34:35]
	v_pk_mul_f32 v[36:37], v[36:37], v[56:57] op_sel_hi:[1,0]
	v_pk_mul_f32 v[38:39], v[38:39], v[56:57] op_sel_hi:[1,0]
	v_pk_mul_f32 v[72:73], v[36:37], v[36:37]
	v_pk_mul_f32 v[70:71], v[38:39], v[38:39]
	v_pk_mul_f32 v[42:43], v[42:43], v[56:57] op_sel_hi:[1,0]
	v_pk_mul_f32 v[46:47], v[46:47], v[56:57] op_sel_hi:[1,0]
	v_pk_mul_f32 v[78:79], v[42:43], v[42:43]
	v_pk_mul_f32 v[88:89], v[46:47], v[46:47]
	v_pk_mul_f32 v[16:17], v[16:17], v[56:57] op_sel_hi:[1,0]
	v_pk_mul_f32 v[18:19], v[18:19], v[56:57] op_sel_hi:[1,0]
	v_pk_mul_f32 v[94:95], v[16:17], v[16:17]
	v_pk_mul_f32 v[92:93], v[18:19], v[18:19]
	v_pk_mul_f32 v[22:23], v[22:23], v[56:57] op_sel_hi:[1,0]
	v_pk_mul_f32 v[24:25], v[24:25], v[56:57] op_sel_hi:[1,0]
	v_pk_mul_f32 v[96:97], v[22:23], v[22:23]
	v_pk_mul_f32 v[100:101], v[24:25], v[24:25]
	v_pk_mul_f32 v[26:27], v[14:15], v[14:15]
	v_pk_mul_f32 v[28:29], v[8:9], v[8:9]
	v_pk_mul_f32 v[30:31], v[6:7], v[6:7]
	s_waitcnt lgkmcnt(0)
	v_lshlrev_b32_e32 v48, 16, v50
	v_and_b32_e32 v49, 0xffff0000, v50
	v_mul_f32_e32 v50, 0xbfb8aa3b, v48
	v_exp_f32_e32 v50, v50
	s_nop 0
	v_add_f32_e32 v50, 1.0, v50
	v_rcp_f32_e32 v52, v50
	v_mul_f32_e32 v50, 0xbfb8aa3b, v49
	v_exp_f32_e32 v50, v50
	s_nop 0
	v_add_f32_e32 v50, 1.0, v50
	v_rcp_f32_e32 v53, v50
	v_lshlrev_b32_e32 v50, 16, v51
	v_and_b32_e32 v51, 0xffff0000, v51
	v_pk_mul_f32 v[48:49], v[52:53], v[48:49]
	v_mul_f32_e32 v52, 0xbfb8aa3b, v50
	v_mul_f32_e32 v53, 0xbfb8aa3b, v51
	v_exp_f32_e32 v52, v52
	v_exp_f32_e32 v53, v53
	v_add_f32_e32 v52, 1.0, v52
	v_add_f32_e32 v53, 1.0, v53
	v_rcp_f32_e32 v52, v52
	v_rcp_f32_e32 v53, v53
	s_nop 0
	v_pk_mul_f32 v[50:51], v[52:53], v[50:51]
	v_lshlrev_b32_e32 v52, 16, v54
	v_mul_f32_e32 v0, 0xbfb8aa3b, v52
	v_exp_f32_e32 v0, v0
	v_and_b32_e32 v53, 0xffff0000, v54
	v_lshlrev_b32_e32 v54, 16, v55
	v_and_b32_e32 v55, 0xffff0000, v55
	v_add_f32_e32 v0, 1.0, v0
	v_rcp_f32_e32 v58, v0
	v_mul_f32_e32 v0, 0xbfb8aa3b, v53
	v_exp_f32_e32 v0, v0
	s_nop 0
	v_add_f32_e32 v0, 1.0, v0
	v_rcp_f32_e32 v59, v0
	v_mul_f32_e32 v0, 0xbfb8aa3b, v54
	v_exp_f32_e32 v0, v0
	v_pk_mul_f32 v[52:53], v[58:59], v[52:53]
	v_add_f32_e32 v0, 1.0, v0
	v_rcp_f32_e32 v58, v0
	v_mul_f32_e32 v0, 0xbfb8aa3b, v55
	v_exp_f32_e32 v0, v0
	s_nop 0
	v_add_f32_e32 v0, 1.0, v0
	v_rcp_f32_e32 v59, v0
	s_nop 0
	v_pk_mul_f32 v[54:55], v[58:59], v[54:55]
	v_pk_mul_f32 v[58:59], v[40:41], v[56:57] op_sel_hi:[1,0]
	s_waitcnt vmcnt(0)
; __device__ __forceinline__ unsigned pk2(float lo, float hi) { f32x2 v = {lo, hi}; bf16x2_t b = __builtin_convertvector(v, bf16x2_t); return __builtin_bit_cast(unsigned, b); }
; __device__ __forceinline__ float bflo(unsigned u) { return __uint_as_float(u << 16); }
; __device__ __forceinline__ float bfhi(unsigned u) { return __uint_as_float(u & 0xffff0000u); }
; __device__ __forceinline__ float silu(float g) { return g * __builtin_amdgcn_rcpf(1.0f + __expf(-g)); }
; template <int MODE>
; __device__ __forceinline__ void attn_item(const AttnP& p, int b, int h, int qb, LAS unsigned char* lds) {
;     ...
;     float ss = 0.f;
; #pragma unroll
;     for (int d = 0; d < DV / 32; ++d)
; #pragma unroll
;         for (int i = 0; i < 16; ++i) {
;             float o = O[0][d][i] * inv0;
;             if (MODE == 0) o -= O[NC - 1][d][i] * inv1;
;             O[0][d][i] = o; ss += o * o;
;         }
;     ss += __shfl_xor(ss, 32);
;     float rn = 1.0f / sqrtf(ss * (1.0f / DV) + 1e-6f);
;     if (MODE == 0) rn *= p.oml;
;     int qrow_e = qrow; asm volatile("" : "+v"(qrow_e));
;     const size_t trow = (size_t)(tok0 + qrow_e);
; #pragma unroll
;     for (int d = 0; d < DV / 32; ++d)
; #pragma unroll
;         for (int g = 0; g < 4; ++g) {
;             const int dd = d * 32 + 8 * g + 4 * hh;
;             const u32x2 gr = *(const u32x2*)(P + trow * PP + gcol + dd);
;             const f32x4 og = *(const f32x4*)(p.out_gain + gaincol + dd);
;             const float o0 = O[0][d][4 * g] * rn * og[0] * silu(bflo(gr.x)), o1 = O[0][d][4 * g + 1] * rn * og[1] * silu(bfhi(gr.x));
;             const float o2 = O[0][d][4 * g + 2] * rn * og[2] * silu(bflo(gr.y)), o3 = O[0][d][4 * g + 3] * rn * og[3] * silu(bfhi(gr.y));
;             u32x2 wv; wv.x = pk2(o0, o1); wv.y = pk2(o2, o3);
;             *(u32x2*)(p.mixed + trow * 1024 + mixcol + dd) = wv;
	v_lshlrev_b32_e32 v40, 16, v66
	v_mul_f32_e32 v0, 0xbfb8aa3b, v40
	v_exp_f32_e32 v0, v0
	v_and_b32_e32 v41, 0xffff0000, v66
	v_pk_mul_f32 v[80:81], v[58:59], v[58:59]
	v_add_f32_e32 v0, 1.0, v0
	v_rcp_f32_e32 v60, v0
	v_mul_f32_e32 v0, 0xbfb8aa3b, v41
	v_exp_f32_e32 v0, v0
	s_nop 0
	v_add_f32_e32 v0, 1.0, v0
	v_rcp_f32_e32 v61, v0
	s_nop 0
	v_pk_mul_f32 v[60:61], v[60:61], v[40:41]
	v_lshlrev_b32_e32 v40, 16, v67
	v_mul_f32_e32 v0, 0xbfb8aa3b, v40
	v_exp_f32_e32 v0, v0
	v_and_b32_e32 v41, 0xffff0000, v67
	v_add_f32_e32 v0, 1.0, v0
	v_rcp_f32_e32 v66, v0
	v_mul_f32_e32 v0, 0xbfb8aa3b, v41
	v_exp_f32_e32 v0, v0
	s_nop 0
	v_add_f32_e32 v0, 1.0, v0
	v_rcp_f32_e32 v67, v0
	s_nop 0
	v_pk_mul_f32 v[40:41], v[66:67], v[40:41]
	v_pk_mul_f32 v[66:67], v[44:45], v[56:57] op_sel_hi:[1,0]
	v_lshlrev_b32_e32 v44, 16, v74
	v_mul_f32_e32 v0, 0xbfb8aa3b, v44
	v_exp_f32_e32 v0, v0
	v_and_b32_e32 v45, 0xffff0000, v74
	v_pk_mul_f32 v[90:91], v[66:67], v[66:67]
	v_add_f32_e32 v0, 1.0, v0
	v_rcp_f32_e32 v68, v0
	v_mul_f32_e32 v0, 0xbfb8aa3b, v45
	v_exp_f32_e32 v0, v0
	s_nop 0
	v_add_f32_e32 v0, 1.0, v0
	v_rcp_f32_e32 v69, v0
	s_nop 0
	v_pk_mul_f32 v[68:69], v[68:69], v[44:45]
	v_lshlrev_b32_e32 v44, 16, v75
	v_mul_f32_e32 v0, 0xbfb8aa3b, v44
	v_exp_f32_e32 v0, v0
	v_and_b32_e32 v45, 0xffff0000, v75
	v_add_f32_e32 v0, 1.0, v0
	v_rcp_f32_e32 v74, v0
	v_mul_f32_e32 v0, 0xbfb8aa3b, v45
	v_exp_f32_e32 v0, v0
	s_nop 0
	v_add_f32_e32 v0, 1.0, v0
	v_rcp_f32_e32 v75, v0
	s_nop 0
	v_pk_mul_f32 v[44:45], v[74:75], v[44:45]
	v_lshlrev_b32_e32 v74, 16, v76
	v_mul_f32_e32 v0, 0xbfb8aa3b, v74
	v_exp_f32_e32 v0, v0
	v_and_b32_e32 v75, 0xffff0000, v76
	v_lshlrev_b32_e32 v76, 16, v77
	v_and_b32_e32 v77, 0xffff0000, v77
	v_add_f32_e32 v0, 1.0, v0
	v_rcp_f32_e32 v82, v0
	v_mul_f32_e32 v0, 0xbfb8aa3b, v75
	v_exp_f32_e32 v0, v0
	s_nop 0
	v_add_f32_e32 v0, 1.0, v0
	v_rcp_f32_e32 v83, v0
	v_mul_f32_e32 v0, 0xbfb8aa3b, v76
	v_exp_f32_e32 v0, v0
	v_pk_mul_f32 v[74:75], v[82:83], v[74:75]
	v_add_f32_e32 v0, 1.0, v0
	v_rcp_f32_e32 v82, v0
	v_mul_f32_e32 v0, 0xbfb8aa3b, v77
	v_exp_f32_e32 v0, v0
	s_nop 0
	v_add_f32_e32 v0, 1.0, v0
	v_rcp_f32_e32 v83, v0
	s_nop 0
	v_pk_mul_f32 v[76:77], v[82:83], v[76:77]
	v_pk_mul_f32 v[82:83], v[20:21], v[56:57] op_sel_hi:[1,0]
	v_lshlrev_b32_e32 v20, 16, v86
	v_mul_f32_e32 v0, 0xbfb8aa3b, v20
	v_exp_f32_e32 v0, v0
	v_and_b32_e32 v21, 0xffff0000, v86
	v_pk_mul_f32 v[98:99], v[82:83], v[82:83]
	v_add_f32_e32 v0, 1.0, v0
	v_rcp_f32_e32 v84, v0
	v_mul_f32_e32 v0, 0xbfb8aa3b, v21
	v_exp_f32_e32 v0, v0
	s_nop 0
	v_add_f32_e32 v0, 1.0, v0
	v_rcp_f32_e32 v85, v0
	s_nop 0
	v_pk_mul_f32 v[84:85], v[84:85], v[20:21]
	v_lshlrev_b32_e32 v20, 16, v87
	v_mul_f32_e32 v0, 0xbfb8aa3b, v20
	v_exp_f32_e32 v0, v0
	v_and_b32_e32 v21, 0xffff0000, v87
	v_add_f32_e32 v0, 1.0, v0
	v_rcp_f32_e32 v86, v0
	v_mul_f32_e32 v0, 0xbfb8aa3b, v21
	v_exp_f32_e32 v0, v0
	s_nop 0
	v_add_f32_e32 v0, 1.0, v0
	v_rcp_f32_e32 v87, v0
	v_add_f32_e32 v0, v64, v65
	v_add_f32_e32 v0, v62, v0
	v_add_f32_e32 v0, v63, v0
	v_add_f32_e32 v0, v72, v0
	v_add_f32_e32 v0, v73, v0
	v_add_f32_e32 v0, v70, v0
	v_add_f32_e32 v0, v71, v0
	v_add_f32_e32 v0, v80, v0
	v_add_f32_e32 v0, v81, v0
	v_add_f32_e32 v0, v78, v0
	v_add_f32_e32 v0, v79, v0
	v_add_f32_e32 v0, v90, v0
	v_add_f32_e32 v0, v91, v0
	v_add_f32_e32 v0, v88, v0
	v_add_f32_e32 v0, v89, v0
	v_add_f32_e32 v0, v94, v0
	v_add_f32_e32 v0, v95, v0
	v_add_f32_e32 v0, v92, v0
	v_add_f32_e32 v0, v93, v0
	v_add_f32_e32 v0, v98, v0
	v_add_f32_e32 v0, v99, v0
	v_add_f32_e32 v0, v96, v0
	v_add_f32_e32 v0, v97, v0
	v_add_f32_e32 v0, v100, v0
	v_add_f32_e32 v0, v101, v0
	v_add_f32_e32 v0, v26, v0
	v_add_f32_e32 v0, v27, v0
	v_add_f32_e32 v0, v28, v0
	v_add_f32_e32 v0, v29, v0
	v_add_f32_e32 v0, v30, v0
	v_add_f32_e32 v0, v31, v0
	ds_bpermute_b32 v26, v114, v0
	v_pk_mul_f32 v[86:87], v[86:87], v[20:21]
	global_load_dwordx2 v[20:21], v[12:13], off offset:3168
	s_waitcnt lgkmcnt(0)
	v_add_f32_e32 v0, v0, v26
	v_fmamk_f32 v0, v0, 0x3c800000, v211
	v_cmp_gt_f32_e32 vcc, s55, v0
	v_mul_f32_e32 v26, 0x4f800000, v0
	s_nop 0
	v_cndmask_b32_e32 v0, v0, v26, vcc
	v_sqrt_f32_e32 v26, v0
	s_nop 0
	v_add_u32_e32 v27, -1, v26
	v_fma_f32 v28, -v27, v26, v0
	v_cmp_ge_f32_e64 s[0:1], 0, v28
	v_add_u32_e32 v28, 1, v26
	s_nop 0
	v_cndmask_b32_e64 v27, v26, v27, s[0:1]
	v_fma_f32 v26, -v28, v26, v0
	v_cmp_lt_f32_e64 s[0:1], 0, v26
	s_nop 1
	v_cndmask_b32_e64 v26, v27, v28, s[0:1]
	v_mul_f32_e32 v27, 0x37800000, v26
	v_cndmask_b32_e32 v26, v26, v27, vcc
	v_cmp_class_f32_e32 vcc, v0, v212
	s_nop 1
	v_cndmask_b32_e32 v0, v26, v0, vcc
	v_div_scale_f32 v26, s[0:1], v0, v0, 1.0
	v_rcp_f32_e32 v27, v26
	s_mov_b64 s[0:1], 0
	v_fma_f32 v28, -v26, v27, 1.0
	v_fmac_f32_e32 v27, v28, v27
	v_div_scale_f32 v28, vcc, 1.0, v0, 1.0
	v_mul_f32_e32 v29, v28, v27
	v_fma_f32 v30, -v26, v29, v28
	v_fmac_f32_e32 v29, v30, v27
	v_fma_f32 v26, -v26, v29, v28
	v_div_fmas_f32 v26, v26, v27, v29
	v_div_fixup_f32 v0, v26, v0, 1.0
	v_pk_mul_f32 v[26:27], v[32:33], v[0:1] op_sel_hi:[1,0]
	v_pk_mul_f32 v[16:17], v[16:17], v[0:1] op_sel_hi:[1,0]
	v_pk_mul_f32 v[2:3], v[2:3], v[26:27]
	v_pk_mul_f32 v[26:27], v[34:35], v[0:1] op_sel_hi:[1,0]
	v_pk_mul_f32 v[2:3], v[48:49], v[2:3]
	v_pk_mul_f32 v[4:5], v[4:5], v[26:27]
	v_cvt_pk_bf16_f32 v2, v2, v3
	v_pk_mul_f32 v[4:5], v[50:51], v[4:5]
	v_pk_mul_f32 v[26:27], v[36:37], v[0:1] op_sel_hi:[1,0]
	v_cvt_pk_bf16_f32 v3, v4, v5
	global_store_dwordx2 v[10:11], v[2:3], off
	global_load_dwordx4 v[2:5], v57, s[2:3] offset:32
	v_pk_mul_f32 v[14:15], v[14:15], v[0:1] op_sel_hi:[1,0]
	v_pk_mul_f32 v[8:9], v[8:9], v[0:1] op_sel_hi:[1,0]
	v_pk_mul_f32 v[6:7], v[6:7], v[0:1] op_sel_hi:[1,0]
	s_waitcnt vmcnt(0)
; __device__ __forceinline__ unsigned pk2(float lo, float hi) { f32x2 v = {lo, hi}; bf16x2_t b = __builtin_convertvector(v, bf16x2_t); return __builtin_bit_cast(unsigned, b); }
; __device__ __forceinline__ float bflo(unsigned u) { return __uint_as_float(u << 16); }
; __device__ __forceinline__ float bfhi(unsigned u) { return __uint_as_float(u & 0xffff0000u); }
; __device__ __forceinline__ float silu(float g) { return g * __builtin_amdgcn_rcpf(1.0f + __expf(-g)); }
; template <int MODE>
; __device__ __forceinline__ void attn_item(const AttnP& p, int b, int h, int qb, LAS unsigned char* lds) {
;     ...
;     for (int d = 0; d < DV / 32; ++d)
; #pragma unroll
;         for (int g = 0; g < 4; ++g) {
;             const int dd = d * 32 + 8 * g + 4 * hh;
;             const u32x2 gr = *(const u32x2*)(P + trow * PP + gcol + dd);
;             const f32x4 og = *(const f32x4*)(p.out_gain + gaincol + dd);
;             const float o0 = O[0][d][4 * g] * rn * og[0] * silu(bflo(gr.x)), o1 = O[0][d][4 * g + 1] * rn * og[1] * silu(bfhi(gr.x));
;             const float o2 = O[0][d][4 * g + 2] * rn * og[2] * silu(bflo(gr.y)), o3 = O[0][d][4 * g + 3] * rn * og[3] * silu(bfhi(gr.y));
;             u32x2 wv; wv.x = pk2(o0, o1); wv.y = pk2(o2, o3);
;             *(u32x2*)(p.mixed + trow * 1024 + mixcol + dd) = wv;
;         }
	v_pk_mul_f32 v[2:3], v[2:3], v[26:27]
	v_pk_mul_f32 v[26:27], v[38:39], v[0:1] op_sel_hi:[1,0]
	v_pk_mul_f32 v[2:3], v[52:53], v[2:3]
	v_pk_mul_f32 v[4:5], v[4:5], v[26:27]
	v_cvt_pk_bf16_f32 v2, v2, v3
	v_pk_mul_f32 v[4:5], v[54:55], v[4:5]
	v_pk_mul_f32 v[26:27], v[58:59], v[0:1] op_sel_hi:[1,0]
	v_cvt_pk_bf16_f32 v3, v4, v5
	global_store_dwordx2 v[10:11], v[2:3], off offset:16
	global_load_dwordx4 v[2:5], v57, s[2:3] offset:64
	s_waitcnt vmcnt(0)
	v_pk_mul_f32 v[2:3], v[2:3], v[26:27]
	v_pk_mul_f32 v[26:27], v[42:43], v[0:1] op_sel_hi:[1,0]
	v_pk_mul_f32 v[2:3], v[60:61], v[2:3]
	v_pk_mul_f32 v[4:5], v[4:5], v[26:27]
	v_cvt_pk_bf16_f32 v2, v2, v3
	v_pk_mul_f32 v[4:5], v[40:41], v[4:5]
	v_pk_mul_f32 v[26:27], v[66:67], v[0:1] op_sel_hi:[1,0]
	v_cvt_pk_bf16_f32 v3, v4, v5
	global_store_dwordx2 v[10:11], v[2:3], off offset:32
	global_load_dwordx4 v[2:5], v57, s[2:3] offset:96
	s_waitcnt vmcnt(0)
	v_pk_mul_f32 v[2:3], v[2:3], v[26:27]
	v_pk_mul_f32 v[26:27], v[46:47], v[0:1] op_sel_hi:[1,0]
	v_pk_mul_f32 v[2:3], v[68:69], v[2:3]
	v_pk_mul_f32 v[4:5], v[4:5], v[26:27]
	v_cvt_pk_bf16_f32 v2, v2, v3
	v_pk_mul_f32 v[4:5], v[44:45], v[4:5]
	s_nop 0
	v_cvt_pk_bf16_f32 v3, v4, v5
	global_store_dwordx2 v[10:11], v[2:3], off offset:48
	global_load_dwordx4 v[2:5], v57, s[2:3] offset:128
	s_waitcnt vmcnt(0)
	v_pk_mul_f32 v[2:3], v[2:3], v[16:17]
	v_pk_mul_f32 v[16:17], v[18:19], v[0:1] op_sel_hi:[1,0]
	v_pk_mul_f32 v[2:3], v[74:75], v[2:3]
	v_pk_mul_f32 v[4:5], v[4:5], v[16:17]
	v_cvt_pk_bf16_f32 v2, v2, v3
	v_pk_mul_f32 v[4:5], v[76:77], v[4:5]
	v_pk_mul_f32 v[16:17], v[82:83], v[0:1] op_sel_hi:[1,0]
	v_cvt_pk_bf16_f32 v3, v4, v5
	global_store_dwordx2 v[10:11], v[2:3], off offset:64
	global_load_dwordx4 v[2:5], v57, s[2:3] offset:160
	s_waitcnt vmcnt(0)
	v_pk_mul_f32 v[2:3], v[2:3], v[16:17]
	v_pk_mul_f32 v[16:17], v[22:23], v[0:1] op_sel_hi:[1,0]
	v_pk_mul_f32 v[2:3], v[84:85], v[2:3]
	v_pk_mul_f32 v[4:5], v[4:5], v[16:17]
	v_cvt_pk_bf16_f32 v2, v2, v3
	v_pk_mul_f32 v[4:5], v[86:87], v[4:5]
	v_lshlrev_b32_e32 v16, 16, v20
	v_cvt_pk_bf16_f32 v3, v4, v5
	global_store_dwordx2 v[10:11], v[2:3], off offset:80
	global_load_dwordx4 v[2:5], v57, s[2:3] offset:192
	v_and_b32_e32 v17, 0xffff0000, v20
	v_mul_f32_e32 v18, 0xbfb8aa3b, v16
	v_mul_f32_e32 v19, 0xbfb8aa3b, v17
	v_exp_f32_e32 v18, v18
	v_exp_f32_e32 v19, v19
	v_pk_mul_f32 v[22:23], v[24:25], v[0:1] op_sel_hi:[1,0]
	v_add_f32_e32 v18, 1.0, v18
	v_add_f32_e32 v19, 1.0, v19
	v_rcp_f32_e32 v18, v18
	v_rcp_f32_e32 v19, v19
	s_waitcnt vmcnt(0)
	v_pk_mul_f32 v[2:3], v[2:3], v[22:23]
	v_pk_mul_f32 v[16:17], v[18:19], v[16:17]
	v_pk_mul_f32 v[4:5], v[4:5], v[14:15]
	v_pk_mul_f32 v[2:3], v[16:17], v[2:3]
	v_lshlrev_b32_e32 v16, 16, v21
	v_and_b32_e32 v17, 0xffff0000, v21
	v_mul_f32_e32 v18, 0xbfb8aa3b, v16
	v_mul_f32_e32 v14, 0xbfb8aa3b, v17
	v_exp_f32_e32 v18, v18
	v_exp_f32_e32 v14, v14
	v_cvt_pk_bf16_f32 v2, v2, v3
	v_add_f32_e32 v18, 1.0, v18
	v_add_f32_e32 v14, 1.0, v14
	v_rcp_f32_e32 v18, v18
	v_rcp_f32_e32 v19, v14
	s_nop 0
	v_pk_mul_f32 v[14:15], v[18:19], v[16:17]
	s_nop 0
	v_pk_mul_f32 v[4:5], v[14:15], v[4:5]
	s_nop 0
	v_cvt_pk_bf16_f32 v3, v4, v5
	global_store_dwordx2 v[10:11], v[2:3], off offset:96
	global_load_dwordx2 v[2:3], v[12:13], off offset:3184
	s_nop 0
	global_load_dwordx4 v[12:15], v57, s[2:3] offset:224
	v_readlane_b32 s3, v252, 9
	s_waitcnt vmcnt(0) lgkmcnt(0)
	v_lshlrev_b32_e32 v4, 16, v2
	v_and_b32_e32 v5, 0xffff0000, v2
	v_mul_f32_e32 v2, 0xbfb8aa3b, v4
	v_exp_f32_e32 v2, v2
	v_pk_mul_f32 v[8:9], v[12:13], v[8:9]
	v_pk_mul_f32 v[6:7], v[14:15], v[6:7]
	v_add_f32_e32 v2, 1.0, v2
	v_rcp_f32_e32 v16, v2
	v_mul_f32_e32 v2, 0xbfb8aa3b, v5
	v_exp_f32_e32 v2, v2
	s_nop 0
	v_add_f32_e32 v2, 1.0, v2
	v_rcp_f32_e32 v17, v2
	v_lshlrev_b32_e32 v2, 16, v3
	v_and_b32_e32 v3, 0xffff0000, v3
	v_mul_f32_e32 v0, 0xbfb8aa3b, v3
	v_pk_mul_f32 v[4:5], v[16:17], v[4:5]
	v_exp_f32_e32 v0, v0
	v_pk_mul_f32 v[4:5], v[4:5], v[8:9]
	v_mul_f32_e32 v8, 0xbfb8aa3b, v2
	v_exp_f32_e32 v8, v8
	v_add_f32_e32 v0, 1.0, v0
	v_rcp_f32_e32 v9, v0
	v_cvt_pk_bf16_f32 v4, v4, v5
	v_add_f32_e32 v8, 1.0, v8
	v_rcp_f32_e32 v8, v8
	s_nop 0
	v_pk_mul_f32 v[2:3], v[8:9], v[2:3]
	s_nop 0
	v_pk_mul_f32 v[2:3], v[2:3], v[6:7]
	s_nop 0
	v_cvt_pk_bf16_f32 v5, v2, v3
	global_store_dwordx2 v[10:11], v[4:5], off offset:112

; __device__ __forceinline__ void scan_pass1(const ScanP& sp, int b, int h, int seg, LAS unsigned char* lds) {
;     ...
;     SCAN_PREFETCH((size_t)(tok0 + seg * 1024 + tt), (seg * 1024 + tt) > 0);
.LBB0_249:
	s_or_b64 exec, exec, s[0:1]
	v_readlane_b32 s0, v252, 9
	s_and_b32 s1, s0, 3
	s_lshl_b32 s0, s0, 7
	s_and_b32 s0, s0, 0xfffff000
	v_and_b32_e32 v37, 15, v36
	s_lshl_b32 s2, s1, 10
	v_ashrrev_i32_e32 v38, 4, v36
	v_lshlrev_b32_e32 v39, 2, v37
	s_or_b32 s0, s2, s0
	v_or_b32_e32 v8, s4, v39
	v_add_u32_e32 v161, s0, v38
	s_waitcnt vmcnt(0)
	v_mov_b64_e32 v[2:3], s[84:85]
	s_movk_i32 s0, 0x140
	v_mov_b64_e32 v[4:5], s[68:69]
	v_writelane_b32 v252, s1, 10
	v_mad_i64_i32 v[6:7], s[0:1], v161, s0, v[2:3]
	v_mad_i64_i32 v[4:5], s[0:1], v161, s76, v[4:5]
	v_lshlrev_b32_e32 v120, 1, v8
	v_mov_b32_e32 v121, v1
	v_lshlrev_b32_e32 v0, 4, v37
	v_lshl_add_u64 v[8:9], v[4:5], 0, v[120:121]
	s_mov_b64 s[0:1], 0x1000
	v_lshl_add_u64 v[2:3], v[6:7], 0, v[0:1]
	v_lshl_add_u64 v[4:5], v[8:9], 0, s[0:1]
	v_add_co_u32_e32 v8, vcc, 0x1000, v8
	s_waitcnt lgkmcnt(0)
	s_barrier
	v_addc_co_u32_e32 v9, vcc, 0, v9, vcc
	global_load_dwordx4 v[84:87], v[2:3], off
	global_load_dwordx2 v[142:143], v[8:9], off
	global_load_dwordx2 v[140:141], v[4:5], off offset:1024
	global_load_dwordx2 v[138:139], v[4:5], off offset:2048
	v_add_u32_e32 v0, s2, v38
	v_mov_b32_e32 v2, v1
	v_mov_b32_e32 v3, v1
	v_cmp_lt_i32_e32 vcc, 0, v0
	v_mov_b32_e32 v0, v1
	v_mov_b32_e32 v146, v1
	v_mov_b32_e32 v147, v1
	v_mov_b64_e32 v[90:91], v[2:3]
	v_lshlrev_b32_e32 v122, 2, v39
	v_mov_b64_e32 v[148:149], v[146:147]
	v_mov_b64_e32 v[144:145], v[146:147]
	v_mov_b64_e32 v[88:89], v[0:1]
	s_and_saveexec_b64 s[0:1], vcc
	s_cbranch_execz .LBB0_251
	v_mov_b32_e32 v123, v1
	v_lshl_add_u64 v[2:3], v[6:7], 0, v[122:123]
	v_add_co_u32_e32 v2, vcc, 0xfffffec0, v2
	s_nop 1
	v_addc_co_u32_e32 v3, vcc, -1, v3, vcc
	v_add_co_u32_e32 v6, vcc, 0xffffdf80, v4
	s_nop 1
	v_addc_co_u32_e32 v7, vcc, -1, v5, vcc
	global_load_dwordx4 v[88:91], v[2:3], off
	global_load_dwordx2 v[144:145], v[6:7], off
	v_add_co_u32_e32 v2, vcc, 0xffffe380, v4
	s_nop 1
	v_addc_co_u32_e32 v3, vcc, -1, v5, vcc
	v_add_co_u32_e32 v4, vcc, 0xffffe780, v4
	s_nop 1
	v_addc_co_u32_e32 v5, vcc, -1, v5, vcc
	global_load_dwordx2 v[148:149], v[2:3], off
	global_load_dwordx2 v[146:147], v[4:5], off

; #define LAS __attribute__((address_space(3)))
; __device__ __forceinline__ unsigned pk2(float lo, float hi) { f32x2 v = {lo, hi}; bf16x2_t b = __builtin_convertvector(v, bf16x2_t); return __builtin_bit_cast(unsigned, b); }
; __device__ __forceinline__ float bflo(unsigned u) { return __uint_as_float(u << 16); }
; __device__ __forceinline__ float bfhi(unsigned u) { return __uint_as_float(u & 0xffff0000u); }
; __device__ __forceinline__ void scan_pass1(const ScanP& sp, int b, int h, int seg, LAS unsigned char* lds) {
;     ...
;             { u32x2 o_; o_.x = pk2(s[0], s[1]); o_.y = pk2(s[2], s[3]); *(LAS u32x2*)(lds + O_LORA + (tt * 72 + j4) * 2) = o_; }
;         }
;         {
;             const u32x2 rc = n_rc, kc = n_kc, vc = n_vc, rq = n_rq, kq = n_kq, vq = n_vq;
;             const f32x4 rcf = {bflo(rc.x), bfhi(rc.x), bflo(rc.y), bfhi(rc.y)}, rqf = {bflo(rq.x), bfhi(rq.x), bflo(rq.y), bfhi(rq.y)};
;             const f32x4 kcf = {bflo(kc.x), bfhi(kc.x), bflo(kc.y), bfhi(kc.y)}, kqf = {bflo(kq.x), bfhi(kq.x), bflo(kq.y), bfhi(kq.y)};
;             const f32x4 vcf = {bflo(vc.x), bfhi(vc.x), bflo(vc.y), bfhi(vc.y)}, vqf = {bflo(vq.x), bfhi(vq.x), bflo(vq.y), bfhi(vq.y)};
;             r4 = rcf + (rqf - rcf) * PARV(0); k4 = kcf + (kqf - kcf) * PARV(1); v4 = vcf + (vqf - vcf) * PARV(2);
;         }
;         if (chunk + 1 < 32) SCAN_PREFETCH(tok + 32, 1);
.LBB0_289:
	s_or_b64 exec, exec, s[0:1]
	v_cvt_pk_bf16_f32 v68, v68, v69
	v_cvt_pk_bf16_f32 v69, v2, v3
	v_add_u32_e32 v0, 0, v163
	ds_write_b64 v0, v[68:69] offset:16384
	ds_read_b128 v[108:111], v168
	ds_read_b128 v[104:107], v169
	ds_read_b128 v[100:103], v170
	s_cmp_eq_u32 s22, 31
	v_mov_b64_e32 v[158:159], v[146:147]
	v_mov_b64_e32 v[156:157], v[148:149]
	v_mov_b64_e32 v[154:155], v[144:145]
	v_mov_b64_e32 v[152:153], v[138:139]
	v_mov_b64_e32 v[150:151], v[140:141]
	v_mov_b64_e32 v[2:3], v[142:143]
	s_cbranch_scc1 .LBB0_291
	v_lshl_add_u32 v68, s22, 5, v161
	v_ashrrev_i32_e32 v69, 31, v68
	v_lshl_add_u64 v[2:3], v[68:69], 0, 32
	s_movk_i32 s23, 0x140
	v_mad_u64_u32 v[70:71], s[0:1], v2, s23, v[124:125]
	v_mad_i32_i24 v71, v3, s23, v71
	global_load_dwordx4 v[84:87], v[70:71], off
	v_mov_b64_e32 v[70:71], s[68:69]
	v_mad_u64_u32 v[70:71], s[0:1], v2, s76, v[70:71]
	v_mad_i32_i24 v71, v3, s76, v71
	v_mov_b32_e32 v121, v1
	v_lshl_add_u64 v[70:71], v[70:71], 0, v[120:121]
	s_mov_b64 s[0:1], 0x1000
	v_add_co_u32_e32 v2, vcc, s21, v70
	v_lshl_add_u64 v[72:73], v[70:71], 0, s[0:1]
	s_nop 0
	v_addc_co_u32_e32 v3, vcc, 0, v71, vcc
	global_load_dwordx2 v[2:3], v[2:3], off
	s_nop 0
	global_load_dwordx2 v[150:151], v[72:73], off offset:1024
	global_load_dwordx2 v[152:153], v[72:73], off offset:2048
	v_mov_b64_e32 v[72:73], s[84:85]
	v_mad_i64_i32 v[68:69], s[0:1], v68, s23, v[72:73]
	v_mov_b32_e32 v123, v1
	v_lshl_add_u64 v[68:69], v[68:69], 0, v[122:123]
	s_movk_i32 s0, 0x2000
	v_add_co_u32_e32 v68, vcc, s0, v68
	s_nop 1
	v_addc_co_u32_e32 v69, vcc, 0, v69, vcc
	v_add_co_u32_e32 v72, vcc, 0xffffef80, v70
	s_nop 1
	v_addc_co_u32_e32 v73, vcc, -1, v71, vcc
	global_load_dwordx4 v[88:91], v[68:69], off offset:1728
	global_load_dwordx2 v[154:155], v[72:73], off
	v_add_co_u32_e32 v68, vcc, 0xfffff380, v70
	s_nop 1
	v_addc_co_u32_e32 v69, vcc, -1, v71, vcc
	v_add_co_u32_e32 v70, vcc, 0xfffff780, v70
	s_nop 1
	v_addc_co_u32_e32 v71, vcc, -1, v71, vcc
	global_load_dwordx2 v[156:157], v[68:69], off
	global_load_dwordx2 v[158:159], v[70:71], off

; #define LAS __attribute__((address_space(3)))
; __device__ __forceinline__ unsigned pk2(float lo, float hi) { f32x2 v = {lo, hi}; bf16x2_t b = __builtin_convertvector(v, bf16x2_t); return __builtin_bit_cast(unsigned, b); }
; __device__ __forceinline__ void scan_pass1(const ScanP& sp, int b, int h, int seg, LAS unsigned char* lds) {
;     ...
;         __syncthreads();
;         {
;             const f32x4 y = *(const LAS f32x4*)(yb + tt * 64 + j4);
;             const f32x4 q = *(const LAS f32x4*)(qb + tt * 64 + j4);
;             u32x2 o; o.x = pk2(y[0], y[1]); o.y = pk2(y[2], y[3]);
;             *(u32x2*)(sp.mixed + (size_t)tokc_i * 1024 + 512 + ch) = o;
;             o.x = pk2(q[0], q[1]); o.y = pk2(q[2], q[3]);
;             *(u32x2*)(sp.Q + (size_t)tokc_i * 512 + ch) = o;
;             if (jg == 0) sp.bon[(size_t)tokc_i * 8 + h] = bon_c;
;         }
.LBB0_315:
	s_waitcnt lgkmcnt(0)
	s_barrier
	ds_read_b128 v[70:73], v179
	ds_read_b128 v[74:77], v180
	v_lshl_add_u32 v68, s83, 5, v161
	v_ashrrev_i32_e32 v69, 31, v68
	s_waitcnt lgkmcnt(0)
	v_cvt_pk_bf16_f32 v70, v70, v71
	v_cvt_pk_bf16_f32 v71, v72, v73
	v_lshlrev_b64 v[72:73], 11, v[68:69]
	v_lshl_add_u64 v[72:73], v[128:129], 0, v[72:73]
	global_store_dwordx2 v[72:73], v[70:71], off offset:1024
	v_lshlrev_b64 v[72:73], 10, v[68:69]
	v_cvt_pk_bf16_f32 v70, v74, v75
	v_cvt_pk_bf16_f32 v71, v76, v77
	v_lshl_add_u64 v[72:73], v[126:127], 0, v[72:73]
	global_store_dwordx2 v[72:73], v[70:71], off
	s_and_saveexec_b64 s[0:1], s[10:11]
	s_cbranch_execz .LBB0_317
	v_lshlrev_b64 v[68:69], 5, v[68:69]
	v_lshl_add_u64 v[68:69], s[94:95], 0, v[68:69]
	global_store_dword v[68:69], v187, off

; __device__ __forceinline__ int crow(int r, int hi) { return (r & 3) + 8 * (r >> 2) + 4 * hi; }
; __device__ __forceinline__ void scan_pass1(const ScanP& sp, int b, int h, int seg, LAS unsigned char* lds) {
;     ...
;     if (w < 4) {
;         int le_ = lane; asm volatile("" : "+v"(le_));
;         const int ln = le_ & 31, hh = le_ >> 5, icol = 32 * (w & 1) + ln;
;         float* dst = ((w < 2) ? sp.HE : sp.PE) + (size_t)((b * 8 + h) * 4 + seg) * 4096;
; #pragma unroll
;         for (int jb = 0; jb < 2; ++jb)
; #pragma unroll
;             for (int r = 0; r < 16; ++r) dst[(32 * jb + crow(r, hh)) * 64 + icol] = Hacc[jb][r];
;     }
.LBB0_320:
	v_readlane_b32 s42, v252, 5
	s_and_b64 vcc, exec, s[88:89]
	s_movk_i32 s72, 0x48
	v_readlane_b32 s43, v252, 6
	v_readlane_b32 s39, v252, 7
	v_readlane_b32 s41, v252, 8
	v_readlane_b32 s4, v252, 9
	s_cbranch_vccz .LBB0_209
	s_and_b64 s[0:1], s[54:55], exec
	v_readlane_b32 s0, v254, 57
	v_readlane_b32 s1, v254, 59
	s_cselect_b32 s2, s0, s1
	v_readlane_b32 s0, v254, 56
	v_readlane_b32 s1, v254, 58
	s_cselect_b32 s3, s0, s1
	s_and_b32 s0, s4, 0xffffffe0
	v_readlane_b32 s1, v252, 11
	s_or_b32 s0, s1, s0
	v_readlane_b32 s1, v252, 10
	s_or_b32 s0, s0, s1
	s_ashr_i32 s1, s0, 31
	s_waitcnt vmcnt(0)
	v_lshlrev_b32_e32 v2, 3, v160
	v_and_or_b32 v0, v160, 31, s82
	s_lshl_b64 s[0:1], s[0:1], 14
	v_and_b32_e32 v38, 0xffffff00, v2
	s_add_u32 s0, s3, s0
	v_or_b32_e32 v2, v38, v0
	s_addc_u32 s1, s2, s1
	v_ashrrev_i32_e32 v3, 31, v2
	v_lshl_add_u64 v[36:37], v[2:3], 2, s[0:1]
	v_ashrrev_i32_e32 v3, 31, v38
	v_lshl_add_u64 v[2:3], v[2:3], 2, s[0:1]
	global_store_dword v[36:37], v20, off
	global_store_dword v[2:3], v21, off offset:256
	global_store_dword v[2:3], v22, off offset:512
	global_store_dword v[2:3], v23, off offset:768
	v_add_u32_e32 v22, 0x200, v38
	v_or_b32_e32 v2, v22, v0
	v_ashrrev_i32_e32 v3, 31, v2
	v_lshl_add_u64 v[2:3], v[2:3], 2, s[0:1]
	v_add_u32_e32 v23, 0x240, v38
	global_store_dword v[2:3], v24, off
	v_or_b32_e32 v2, v23, v0
	v_ashrrev_i32_e32 v3, 31, v2
	v_lshl_add_u64 v[2:3], v[2:3], 2, s[0:1]
	v_add_u32_e32 v24, 0x280, v38
	global_store_dword v[2:3], v25, off
	v_or_b32_e32 v2, v24, v0
	v_ashrrev_i32_e32 v3, 31, v2
	v_lshl_add_u64 v[2:3], v[2:3], 2, s[0:1]
	v_add_u32_e32 v25, 0x2c0, v38
	global_store_dword v[2:3], v26, off
	v_or_b32_e32 v2, v25, v0
	v_ashrrev_i32_e32 v3, 31, v2
	v_lshl_add_u64 v[2:3], v[2:3], 2, s[0:1]
	v_add_u32_e32 v26, 0x400, v38
	global_store_dword v[2:3], v27, off
	v_or_b32_e32 v2, v26, v0
	v_ashrrev_i32_e32 v3, 31, v2
	v_lshl_add_u64 v[2:3], v[2:3], 2, s[0:1]
	v_add_u32_e32 v27, 0x440, v38
	global_store_dword v[2:3], v28, off
	v_or_b32_e32 v2, v27, v0
	v_ashrrev_i32_e32 v3, 31, v2
	v_lshl_add_u64 v[2:3], v[2:3], 2, s[0:1]
	v_add_u32_e32 v28, 0x480, v38
	global_store_dword v[2:3], v29, off
	v_or_b32_e32 v2, v28, v0
	v_ashrrev_i32_e32 v3, 31, v2
	v_lshl_add_u64 v[2:3], v[2:3], 2, s[0:1]
	v_add_u32_e32 v29, 0x4c0, v38
	global_store_dword v[2:3], v30, off
	v_or_b32_e32 v2, v29, v0
	v_ashrrev_i32_e32 v3, 31, v2
	v_lshl_add_u64 v[2:3], v[2:3], 2, s[0:1]
	v_add_u32_e32 v30, 0x600, v38
	global_store_dword v[2:3], v31, off
	v_or_b32_e32 v2, v30, v0
	v_ashrrev_i32_e32 v3, 31, v2
	v_lshl_add_u64 v[2:3], v[2:3], 2, s[0:1]
	v_add_u32_e32 v31, 0x640, v38
	global_store_dword v[2:3], v32, off
	v_or_b32_e32 v2, v31, v0
	v_ashrrev_i32_e32 v3, 31, v2
	v_lshl_add_u64 v[2:3], v[2:3], 2, s[0:1]
	v_add_u32_e32 v32, 0x680, v38
	global_store_dword v[2:3], v33, off
	v_or_b32_e32 v2, v32, v0
	v_ashrrev_i32_e32 v3, 31, v2
	v_lshl_add_u64 v[2:3], v[2:3], 2, s[0:1]
	v_add_u32_e32 v33, 0x6c0, v38
	global_store_dword v[2:3], v34, off
	v_or_b32_e32 v2, v33, v0
	v_ashrrev_i32_e32 v3, 31, v2
	v_lshl_add_u64 v[2:3], v[2:3], 2, s[0:1]
	v_or_b32_e32 v0, 0x800, v0
	global_store_dword v[2:3], v35, off
	v_add_u32_e32 v2, v0, v38
	v_ashrrev_i32_e32 v3, 31, v2
	v_lshl_add_u64 v[20:21], v[2:3], 2, s[0:1]
	global_store_dword v[20:21], v4, off
	v_or_b32_e32 v20, 64, v2
	v_or_b32_e32 v4, 0x80, v2
	v_or_b32_e32 v2, 0xc0, v2
	v_ashrrev_i32_e32 v3, 31, v2
	v_lshl_add_u64 v[2:3], v[2:3], 2, s[0:1]
	global_store_dword v[2:3], v7, off
	v_add_u32_e32 v2, v22, v0
	v_ashrrev_i32_e32 v3, 31, v2
	v_lshl_add_u64 v[2:3], v[2:3], 2, s[0:1]
	global_store_dword v[2:3], v8, off
	v_add_u32_e32 v2, v23, v0
	v_ashrrev_i32_e32 v21, 31, v20
	v_ashrrev_i32_e32 v3, 31, v2
	v_lshl_add_u64 v[20:21], v[20:21], 2, s[0:1]
	v_lshl_add_u64 v[2:3], v[2:3], 2, s[0:1]
	global_store_dword v[20:21], v5, off
	global_store_dword v[2:3], v9, off
	v_add_u32_e32 v2, v24, v0
	v_ashrrev_i32_e32 v5, 31, v4
	v_ashrrev_i32_e32 v3, 31, v2
	v_lshl_add_u64 v[4:5], v[4:5], 2, s[0:1]
	v_lshl_add_u64 v[2:3], v[2:3], 2, s[0:1]
	global_store_dword v[4:5], v6, off
	global_store_dword v[2:3], v10, off
	v_add_u32_e32 v2, v25, v0
	v_ashrrev_i32_e32 v3, 31, v2
	v_lshl_add_u64 v[2:3], v[2:3], 2, s[0:1]
	global_store_dword v[2:3], v11, off
	v_add_u32_e32 v2, v26, v0
	v_ashrrev_i32_e32 v3, 31, v2
	v_lshl_add_u64 v[2:3], v[2:3], 2, s[0:1]
	global_store_dword v[2:3], v12, off
	v_add_u32_e32 v2, v27, v0
	v_ashrrev_i32_e32 v3, 31, v2
	v_lshl_add_u64 v[2:3], v[2:3], 2, s[0:1]
	global_store_dword v[2:3], v13, off
	v_add_u32_e32 v2, v28, v0
	v_ashrrev_i32_e32 v3, 31, v2
	v_lshl_add_u64 v[2:3], v[2:3], 2, s[0:1]
	global_store_dword v[2:3], v14, off
	v_add_u32_e32 v2, v29, v0
	v_ashrrev_i32_e32 v3, 31, v2
	v_lshl_add_u64 v[2:3], v[2:3], 2, s[0:1]
	global_store_dword v[2:3], v15, off
	v_add_u32_e32 v2, v30, v0
	v_ashrrev_i32_e32 v3, 31, v2
	v_lshl_add_u64 v[2:3], v[2:3], 2, s[0:1]
	global_store_dword v[2:3], v16, off
	v_add_u32_e32 v2, v31, v0
	v_ashrrev_i32_e32 v3, 31, v2
	v_lshl_add_u64 v[2:3], v[2:3], 2, s[0:1]
	global_store_dword v[2:3], v17, off
	v_add_u32_e32 v2, v32, v0
	v_ashrrev_i32_e32 v3, 31, v2
	v_lshl_add_u64 v[2:3], v[2:3], 2, s[0:1]
	global_store_dword v[2:3], v18, off
	v_add_u32_e32 v2, v33, v0
	v_ashrrev_i32_e32 v3, 31, v2
	v_lshl_add_u64 v[2:3], v[2:3], 2, s[0:1]
	global_store_dword v[2:3], v19, off
	s_branch .LBB0_209
; __device__ __forceinline__ void xbar(unsigned* ctl, unsigned k, unsigned x, unsigned nloc, unsigned nx) {
;     asm volatile("s_waitcnt vmcnt(0)" ::: "memory");
;     __syncthreads();
;     if (threadIdx.x == 0) {
;         const unsigned old = __hip_atomic_fetch_add(ctl + 2048 + 64 * x, 1u, __ATOMIC_RELAXED, __HIP_MEMORY_SCOPE_AGENT);
;         if (old + 1u == nloc * (k + 1u)) {
;             __builtin_amdgcn_fence(__ATOMIC_RELEASE, "agent");
;             __hip_atomic_fetch_add(ctl + 3072, 1u, __ATOMIC_RELAXED, __HIP_MEMORY_SCOPE_AGENT);
;         }
;         const unsigned target = nx * (k + 1u);
;         while (__hip_atomic_load(ctl + 3072, __ATOMIC_RELAXED, __HIP_MEMORY_SCOPE_AGENT) < target) __builtin_amdgcn_s_sleep(1);
;     }
;     __syncthreads();
;     __builtin_amdgcn_fence(__ATOMIC_ACQUIRE, "agent");
;     asm volatile("s_waitcnt vmcnt(0)" ::: "memory");
; }
.LBB0_322:
	s_waitcnt vmcnt(0)
	s_waitcnt lgkmcnt(0)
	s_barrier
	s_mov_b64 s[0:1], exec
	v_readlane_b32 s2, v253, 0
	v_readlane_b32 s3, v253, 1
	v_readlane_b32 s80, v253, 6
	v_readlane_b32 s10, v254, 42
	v_readlane_b32 s12, v254, 50
	v_readlane_b32 s14, v254, 52
	s_and_b64 s[2:3], s[0:1], s[2:3]
	v_readlane_b32 s73, v254, 35
	v_readlane_b32 s81, v253, 7
	v_readlane_b32 s82, v253, 8
	v_readlane_b32 s83, v253, 9
	v_readlane_b32 s77, v254, 60
	v_readlane_b32 s84, v254, 63
	v_readlane_b32 s11, v254, 43
	v_readlane_b32 s13, v254, 51
	v_readlane_b32 s15, v254, 53
	v_readlane_b32 s16, v254, 56
	v_readlane_b32 s17, v254, 57
	v_readlane_b32 s85, v252, 0
	s_mov_b64 exec, s[2:3]
	s_cbranch_execz .LBB0_328
	v_readlane_b32 s2, v253, 49
	v_readlane_b32 s8, v252, 1
	v_readlane_b32 s3, v253, 50
	v_readlane_b32 s9, v252, 2
	s_add_u32 s2, s8, s2
	s_addc_u32 s3, s9, s3
	v_mov_b32_e32 v0, s2
	s_waitcnt vmcnt(0)
	v_add_co_u32_e32 v2, vcc, 0x2000, v0
	v_mov_b32_e32 v0, s3
	s_nop 0
	v_addc_co_u32_e32 v3, vcc, 0, v0, vcc
	global_atomic_add v0, v[2:3], v213, off sc0
	s_mul_i32 s4, s77, 6
	s_add_i32 s4, s4, 2
	v_readlane_b32 s2, v253, 10
	s_mul_i32 s2, s4, s2
	s_waitcnt vmcnt(0) lgkmcnt(0)
	v_add_u32_e32 v0, 1, v0
	v_cmp_eq_u32_e32 vcc, s2, v0
	s_and_saveexec_b64 s[2:3], vcc
	s_cbranch_execz .LBB0_325
	v_mov_b32_e32 v0, s8
	v_add_co_u32_e32 v2, vcc, 0x3000, v0
	v_mov_b32_e32 v0, s9
	s_nop 0
	v_addc_co_u32_e32 v3, vcc, 0, v0, vcc
	buffer_wbl2 sc1
	global_atomic_add v[2:3], v213, off
.LBB0_325:
	s_or_b64 exec, exec, s[2:3]
	v_mov_b32_e32 v0, s8
	v_add_co_u32_e32 v2, vcc, 0x3000, v0
	v_mov_b32_e32 v0, s9
	s_nop 0
	v_addc_co_u32_e32 v3, vcc, 0, v0, vcc
	global_load_dword v0, v[2:3], off sc1
	v_readlane_b32 s2, v253, 11
	s_mul_i32 s6, s4, s2
	s_add_u32 s2, s8, 0x3000
	s_addc_u32 s3, s9, 0
	s_waitcnt vmcnt(0) lgkmcnt(0)
	v_cmp_gt_u32_e32 vcc, s6, v0
	s_and_b64 exec, exec, vcc
	s_cbranch_execz .LBB0_328
	s_mov_b64 s[4:5], 0
.LBB0_327:
	v_mov_b64_e32 v[2:3], s[2:3]
	s_sleep 1
	global_load_dword v0, v[2:3], off sc1
	s_waitcnt vmcnt(0) lgkmcnt(0)
	v_readfirstlane_b32 s7, v0
	s_cmp_ge_u32 s7, s6
	s_cselect_b64 s[8:9], -1, 0
	s_and_b64 s[8:9], exec, s[8:9]
	s_or_b64 s[4:5], s[8:9], s[4:5]
	s_andn2_b64 exec, exec, s[4:5]
	s_cbranch_execnz .LBB0_327

; #define LAS __attribute__((address_space(3)))
; __device__ __forceinline__ int next_item(unsigned* ctr, LAS unsigned* slot) {
;     __syncthreads();
;     if (threadIdx.x == 0) *slot = atomicAdd(ctr, 1u);
;     __syncthreads();
;     return (int)*slot;
; }
; __global__ void __launch_bounds__(512) hymba_fwd(Args a) {
;     ...
;             for (;;) {
;                 const int idx = next_item(ctl + 32 + pb + 1, qslot);
;                 if (idx >= 256) break;
.LBB0_331:
	s_barrier
	s_mov_b64 s[0:1], exec
	v_readlane_b32 s2, v253, 0
	v_readlane_b32 s3, v253, 1
	s_and_b64 s[2:3], s[0:1], s[2:3]
	s_mov_b64 exec, s[2:3]
	s_cbranch_execz .LBB0_333
	v_readlane_b32 s2, v252, 3
	v_readlane_b32 s3, v252, 4
	s_nop 1
	v_mov_b64_e32 v[2:3], s[2:3]
	global_atomic_add v0, v[2:3], v213, off offset:136 sc0
	v_readlane_b32 s2, v254, 19
	s_nop 1
	v_mov_b32_e32 v2, s2
	s_waitcnt vmcnt(0) lgkmcnt(0)
	ds_write_b32 v2, v0

; #define LAS __attribute__((address_space(3)))
; __device__ __forceinline__ void scan_pass2(const ScanP& sp, int b, int h, int seg, LAS unsigned char* lds) {
;     ...
;     for (int s = 0; s < seg; ++s) {
;         const float* HE = sp.HE + (size_t)((b * 8 + h) * 4 + s) * 4096; const float* PE = sp.PE + (size_t)((b * 8 + h) * 4 + s) * 4096;
;         f32x4 a0 = *(const f32x4*)(HE + j * 64 + i8), a1 = *(const f32x4*)(HE + j * 64 + i8 + 4);
;         f32x4 pvr[16];
; #pragma unroll
;         for (int jq = 0; jq < 16; ++jq) pvr[jq] = *(const f32x4*)(PE + j * 64 + 4 * jq);
; #pragma unroll
;         for (int jq = 0; jq < 16; ++jq) {
; #pragma unroll
;             for (int q = 0; q < 4; ++q) {
;                 const f32x4 h0 = *(const LAS f32x4*)(Hc + (4 * jq + q) * 64 + i8), h1 = *(const LAS f32x4*)(Hc + (4 * jq + q) * 64 + i8 + 4);
;                 a0 += h0 * pvr[jq][q]; a1 += h1 * pvr[jq][q];
;             }
;         }
;         *(LAS f32x4*)(Hn + j * 64 + i8) = a0; *(LAS f32x4*)(Hn + j * 64 + i8 + 4) = a1;
.LBB0_338:
	v_lshl_add_u64 v[2:3], v[32:33], 0, v[0:1]
	global_load_dwordx4 v[38:41], v[2:3], off
	global_load_dwordx4 v[42:45], v[2:3], off offset:16
	v_add_co_u32_e32 v2, vcc, 0x400000, v32
	s_mov_b32 s6, s7
	s_nop 0
	v_addc_co_u32_e32 v3, vcc, 0, v33, vcc
	global_load_dwordx4 v[46:49], v[2:3], off
	global_load_dwordx4 v[50:53], v[2:3], off offset:16
	global_load_dwordx4 v[54:57], v[2:3], off offset:32
	global_load_dwordx4 v[58:61], v[2:3], off offset:48
	global_load_dwordx4 v[62:65], v[2:3], off offset:64
	global_load_dwordx4 v[66:69], v[2:3], off offset:80
	global_load_dwordx4 v[70:73], v[2:3], off offset:96
	global_load_dwordx4 v[74:77], v[2:3], off offset:112
	global_load_dwordx4 v[78:81], v[2:3], off offset:128
	global_load_dwordx4 v[26:29], v[2:3], off offset:144
	global_load_dwordx4 v[22:25], v[2:3], off offset:160
	global_load_dwordx4 v[18:21], v[2:3], off offset:176
	global_load_dwordx4 v[14:17], v[2:3], off offset:192
	global_load_dwordx4 v[10:13], v[2:3], off offset:208
	global_load_dwordx4 v[6:9], v[2:3], off offset:224
	s_nop 0
	global_load_dwordx4 v[2:5], v[2:3], off offset:240
	v_add_u32_e32 v31, s6, v37
	ds_read_b128 v[82:85], v31
	ds_read_b128 v[86:89], v31 offset:16
	s_mov_b32 s7, s5
	s_add_i32 s1, s1, -1
	s_mov_b64 s[8:9], 0x4000
	v_lshl_add_u64 v[32:33], v[32:33], 0, s[8:9]
	s_cmp_eq_u32 s1, 0
	s_mov_b32 s5, s6
	s_waitcnt vmcnt(0) lgkmcnt(0)
	v_pk_fma_f32 v[84:85], v[46:47], v[84:85], v[40:41] op_sel_hi:[0,1,1]
	v_pk_fma_f32 v[82:83], v[46:47], v[82:83], v[38:39] op_sel_hi:[0,1,1]
	v_pk_fma_f32 v[88:89], v[46:47], v[88:89], v[44:45] op_sel_hi:[0,1,1]
	v_pk_fma_f32 v[86:87], v[46:47], v[86:87], v[42:43] op_sel_hi:[0,1,1]
	ds_read_b128 v[38:41], v31 offset:256
	ds_read_b128 v[42:45], v31 offset:272
	s_waitcnt lgkmcnt(1)
	v_pk_fma_f32 v[84:85], v[46:47], v[40:41], v[84:85] op_sel:[1,0,0]
	v_pk_fma_f32 v[82:83], v[46:47], v[38:39], v[82:83] op_sel:[1,0,0]
	s_waitcnt lgkmcnt(0)
	v_pk_fma_f32 v[88:89], v[46:47], v[44:45], v[88:89] op_sel:[1,0,0]
	v_pk_fma_f32 v[46:47], v[46:47], v[42:43], v[86:87] op_sel:[1,0,0]
	ds_read_b128 v[38:41], v31 offset:512
	ds_read_b128 v[42:45], v31 offset:528
	s_waitcnt lgkmcnt(1)
	v_pk_fma_f32 v[84:85], v[48:49], v[40:41], v[84:85] op_sel_hi:[0,1,1]
	v_pk_fma_f32 v[82:83], v[48:49], v[38:39], v[82:83] op_sel_hi:[0,1,1]
	s_waitcnt lgkmcnt(0)
	v_pk_fma_f32 v[86:87], v[48:49], v[44:45], v[88:89] op_sel_hi:[0,1,1]
	v_pk_fma_f32 v[46:47], v[48:49], v[42:43], v[46:47] op_sel_hi:[0,1,1]
	ds_read_b128 v[38:41], v31 offset:768
	ds_read_b128 v[42:45], v31 offset:784
	v_mov_b32_e32 v48, v49
	s_waitcnt lgkmcnt(1)
	v_pk_fma_f32 v[84:85], v[48:49], v[40:41], v[84:85] op_sel_hi:[0,1,1]
	v_pk_fma_f32 v[82:83], v[48:49], v[38:39], v[82:83] op_sel_hi:[0,1,1]
	s_waitcnt lgkmcnt(0)
	v_pk_fma_f32 v[86:87], v[48:49], v[44:45], v[86:87] op_sel_hi:[0,1,1]
	v_pk_fma_f32 v[46:47], v[48:49], v[42:43], v[46:47] op_sel_hi:[0,1,1]
	ds_read_b128 v[38:41], v31 offset:1024
	ds_read_b128 v[42:45], v31 offset:1040
	s_waitcnt lgkmcnt(1)
	v_pk_fma_f32 v[48:49], v[50:51], v[40:41], v[84:85] op_sel_hi:[0,1,1]
	v_pk_fma_f32 v[82:83], v[50:51], v[38:39], v[82:83] op_sel_hi:[0,1,1]
	s_waitcnt lgkmcnt(0)
	v_pk_fma_f32 v[84:85], v[50:51], v[44:45], v[86:87] op_sel_hi:[0,1,1]
	v_pk_fma_f32 v[46:47], v[50:51], v[42:43], v[46:47] op_sel_hi:[0,1,1]
	ds_read_b128 v[38:41], v31 offset:1280
	ds_read_b128 v[42:45], v31 offset:1296
	s_waitcnt lgkmcnt(1)
	v_pk_fma_f32 v[48:49], v[50:51], v[40:41], v[48:49] op_sel:[1,0,0]
	v_pk_fma_f32 v[82:83], v[50:51], v[38:39], v[82:83] op_sel:[1,0,0]
	s_waitcnt lgkmcnt(0)
	v_pk_fma_f32 v[84:85], v[50:51], v[44:45], v[84:85] op_sel:[1,0,0]
	v_pk_fma_f32 v[46:47], v[50:51], v[42:43], v[46:47] op_sel:[1,0,0]
	ds_read_b128 v[38:41], v31 offset:1536
	ds_read_b128 v[42:45], v31 offset:1552
	s_waitcnt lgkmcnt(1)
	v_pk_fma_f32 v[48:49], v[52:53], v[40:41], v[48:49] op_sel_hi:[0,1,1]
	v_pk_fma_f32 v[50:51], v[52:53], v[38:39], v[82:83] op_sel_hi:[0,1,1]
	s_waitcnt lgkmcnt(0)
	v_pk_fma_f32 v[82:83], v[52:53], v[44:45], v[84:85] op_sel_hi:[0,1,1]
	v_pk_fma_f32 v[46:47], v[52:53], v[42:43], v[46:47] op_sel_hi:[0,1,1]
	ds_read_b128 v[38:41], v31 offset:1792
	ds_read_b128 v[42:45], v31 offset:1808
	v_mov_b32_e32 v52, v53
	s_waitcnt lgkmcnt(1)
	v_pk_fma_f32 v[48:49], v[52:53], v[40:41], v[48:49] op_sel_hi:[0,1,1]
	v_pk_fma_f32 v[50:51], v[52:53], v[38:39], v[50:51] op_sel_hi:[0,1,1]
	s_waitcnt lgkmcnt(0)
	v_pk_fma_f32 v[82:83], v[52:53], v[44:45], v[82:83] op_sel_hi:[0,1,1]
	v_pk_fma_f32 v[46:47], v[52:53], v[42:43], v[46:47] op_sel_hi:[0,1,1]
	ds_read_b128 v[38:41], v31 offset:2048
	ds_read_b128 v[42:45], v31 offset:2064
	s_waitcnt lgkmcnt(1)
	v_pk_fma_f32 v[48:49], v[54:55], v[40:41], v[48:49] op_sel_hi:[0,1,1]
	v_pk_fma_f32 v[50:51], v[54:55], v[38:39], v[50:51] op_sel_hi:[0,1,1]
	s_waitcnt lgkmcnt(0)
	v_pk_fma_f32 v[52:53], v[54:55], v[44:45], v[82:83] op_sel_hi:[0,1,1]
	v_pk_fma_f32 v[46:47], v[54:55], v[42:43], v[46:47] op_sel_hi:[0,1,1]
	ds_read_b128 v[38:41], v31 offset:2304
	ds_read_b128 v[42:45], v31 offset:2320
	s_waitcnt lgkmcnt(1)
	v_pk_fma_f32 v[48:49], v[54:55], v[40:41], v[48:49] op_sel:[1,0,0]
	v_pk_fma_f32 v[50:51], v[54:55], v[38:39], v[50:51] op_sel:[1,0,0]
	s_waitcnt lgkmcnt(0)
	v_pk_fma_f32 v[52:53], v[54:55], v[44:45], v[52:53] op_sel:[1,0,0]
	v_pk_fma_f32 v[46:47], v[54:55], v[42:43], v[46:47] op_sel:[1,0,0]
	ds_read_b128 v[38:41], v31 offset:2560
	ds_read_b128 v[42:45], v31 offset:2576
	v_mov_b32_e32 v54, v57
	s_waitcnt lgkmcnt(1)
	v_pk_fma_f32 v[48:49], v[56:57], v[40:41], v[48:49] op_sel_hi:[0,1,1]
	v_pk_fma_f32 v[50:51], v[56:57], v[38:39], v[50:51] op_sel_hi:[0,1,1]
	s_waitcnt lgkmcnt(0)
; #define LAS __attribute__((address_space(3)))
; __device__ __forceinline__ void scan_pass2(const ScanP& sp, int b, int h, int seg, LAS unsigned char* lds) {
;     ...
;         for (int jq = 0; jq < 16; ++jq) {
; #pragma unroll
;             for (int q = 0; q < 4; ++q) {
;                 const f32x4 h0 = *(const LAS f32x4*)(Hc + (4 * jq + q) * 64 + i8), h1 = *(const LAS f32x4*)(Hc + (4 * jq + q) * 64 + i8 + 4);
;                 a0 += h0 * pvr[jq][q]; a1 += h1 * pvr[jq][q];
;             }
;         }
	v_pk_fma_f32 v[52:53], v[56:57], v[44:45], v[52:53] op_sel_hi:[0,1,1]
	v_pk_fma_f32 v[46:47], v[56:57], v[42:43], v[46:47] op_sel_hi:[0,1,1]
	ds_read_b128 v[38:41], v31 offset:2816
	ds_read_b128 v[42:45], v31 offset:2832
	s_waitcnt lgkmcnt(1)
	v_pk_fma_f32 v[48:49], v[54:55], v[40:41], v[48:49] op_sel_hi:[0,1,1]
	v_pk_fma_f32 v[50:51], v[54:55], v[38:39], v[50:51] op_sel_hi:[0,1,1]
	s_waitcnt lgkmcnt(0)
	v_pk_fma_f32 v[52:53], v[54:55], v[44:45], v[52:53] op_sel_hi:[0,1,1]
	v_pk_fma_f32 v[46:47], v[54:55], v[42:43], v[46:47] op_sel_hi:[0,1,1]
	ds_read_b128 v[38:41], v31 offset:3072
	ds_read_b128 v[42:45], v31 offset:3088
	v_mov_b32_e32 v54, v61
	s_waitcnt lgkmcnt(1)
	v_pk_fma_f32 v[48:49], v[58:59], v[40:41], v[48:49] op_sel_hi:[0,1,1]
	v_pk_fma_f32 v[50:51], v[58:59], v[38:39], v[50:51] op_sel_hi:[0,1,1]
	s_waitcnt lgkmcnt(0)
	v_pk_fma_f32 v[52:53], v[58:59], v[44:45], v[52:53] op_sel_hi:[0,1,1]
	v_pk_fma_f32 v[46:47], v[58:59], v[42:43], v[46:47] op_sel_hi:[0,1,1]
	ds_read_b128 v[38:41], v31 offset:3328
	ds_read_b128 v[42:45], v31 offset:3344
	s_waitcnt lgkmcnt(1)
	v_pk_fma_f32 v[48:49], v[58:59], v[40:41], v[48:49] op_sel:[1,0,0]
	v_pk_fma_f32 v[50:51], v[58:59], v[38:39], v[50:51] op_sel:[1,0,0]
	s_waitcnt lgkmcnt(0)
	v_pk_fma_f32 v[52:53], v[58:59], v[44:45], v[52:53] op_sel:[1,0,0]
	v_pk_fma_f32 v[46:47], v[58:59], v[42:43], v[46:47] op_sel:[1,0,0]
	ds_read_b128 v[38:41], v31 offset:3584
	ds_read_b128 v[42:45], v31 offset:3600
	s_waitcnt lgkmcnt(1)
	v_pk_fma_f32 v[48:49], v[60:61], v[40:41], v[48:49] op_sel_hi:[0,1,1]
	v_pk_fma_f32 v[50:51], v[60:61], v[38:39], v[50:51] op_sel_hi:[0,1,1]
	s_waitcnt lgkmcnt(0)
	v_pk_fma_f32 v[52:53], v[60:61], v[44:45], v[52:53] op_sel_hi:[0,1,1]
	v_pk_fma_f32 v[46:47], v[60:61], v[42:43], v[46:47] op_sel_hi:[0,1,1]
	ds_read_b128 v[38:41], v31 offset:3840
	ds_read_b128 v[42:45], v31 offset:3856
	s_waitcnt lgkmcnt(1)
	v_pk_fma_f32 v[48:49], v[54:55], v[40:41], v[48:49] op_sel_hi:[0,1,1]
	v_pk_fma_f32 v[50:51], v[54:55], v[38:39], v[50:51] op_sel_hi:[0,1,1]
	s_waitcnt lgkmcnt(0)
	v_pk_fma_f32 v[52:53], v[54:55], v[44:45], v[52:53] op_sel_hi:[0,1,1]
	v_pk_fma_f32 v[46:47], v[54:55], v[42:43], v[46:47] op_sel_hi:[0,1,1]
	ds_read_b128 v[38:41], v31 offset:4096
	ds_read_b128 v[42:45], v31 offset:4112
	v_mov_b32_e32 v54, v65
	s_waitcnt lgkmcnt(1)
	v_pk_fma_f32 v[48:49], v[62:63], v[40:41], v[48:49] op_sel_hi:[0,1,1]
	v_pk_fma_f32 v[50:51], v[62:63], v[38:39], v[50:51] op_sel_hi:[0,1,1]
	s_waitcnt lgkmcnt(0)
	v_pk_fma_f32 v[52:53], v[62:63], v[44:45], v[52:53] op_sel_hi:[0,1,1]
	v_pk_fma_f32 v[46:47], v[62:63], v[42:43], v[46:47] op_sel_hi:[0,1,1]
	ds_read_b128 v[38:41], v31 offset:4352
	ds_read_b128 v[42:45], v31 offset:4368
	s_waitcnt lgkmcnt(1)
	v_pk_fma_f32 v[48:49], v[62:63], v[40:41], v[48:49] op_sel:[1,0,0]
	v_pk_fma_f32 v[50:51], v[62:63], v[38:39], v[50:51] op_sel:[1,0,0]
	s_waitcnt lgkmcnt(0)
	v_pk_fma_f32 v[52:53], v[62:63], v[44:45], v[52:53] op_sel:[1,0,0]
	v_pk_fma_f32 v[46:47], v[62:63], v[42:43], v[46:47] op_sel:[1,0,0]
	ds_read_b128 v[38:41], v31 offset:4608
	ds_read_b128 v[42:45], v31 offset:4624
	s_waitcnt lgkmcnt(1)
	v_pk_fma_f32 v[48:49], v[64:65], v[40:41], v[48:49] op_sel_hi:[0,1,1]
	v_pk_fma_f32 v[50:51], v[64:65], v[38:39], v[50:51] op_sel_hi:[0,1,1]
	s_waitcnt lgkmcnt(0)
	v_pk_fma_f32 v[52:53], v[64:65], v[44:45], v[52:53] op_sel_hi:[0,1,1]
	v_pk_fma_f32 v[46:47], v[64:65], v[42:43], v[46:47] op_sel_hi:[0,1,1]
	ds_read_b128 v[38:41], v31 offset:4864
	ds_read_b128 v[42:45], v31 offset:4880
	s_waitcnt lgkmcnt(1)
	v_pk_fma_f32 v[48:49], v[54:55], v[40:41], v[48:49] op_sel_hi:[0,1,1]
	v_pk_fma_f32 v[50:51], v[54:55], v[38:39], v[50:51] op_sel_hi:[0,1,1]
	s_waitcnt lgkmcnt(0)
	v_pk_fma_f32 v[52:53], v[54:55], v[44:45], v[52:53] op_sel_hi:[0,1,1]
	v_pk_fma_f32 v[46:47], v[54:55], v[42:43], v[46:47] op_sel_hi:[0,1,1]
	ds_read_b128 v[38:41], v31 offset:5120
	ds_read_b128 v[42:45], v31 offset:5136
	v_mov_b32_e32 v54, v69
	s_waitcnt lgkmcnt(1)
	v_pk_fma_f32 v[48:49], v[66:67], v[40:41], v[48:49] op_sel_hi:[0,1,1]
	v_pk_fma_f32 v[50:51], v[66:67], v[38:39], v[50:51] op_sel_hi:[0,1,1]
	s_waitcnt lgkmcnt(0)
	v_pk_fma_f32 v[52:53], v[66:67], v[44:45], v[52:53] op_sel_hi:[0,1,1]
	v_pk_fma_f32 v[46:47], v[66:67], v[42:43], v[46:47] op_sel_hi:[0,1,1]
	ds_read_b128 v[38:41], v31 offset:5376
	ds_read_b128 v[42:45], v31 offset:5392
	s_waitcnt lgkmcnt(1)
	v_pk_fma_f32 v[48:49], v[66:67], v[40:41], v[48:49] op_sel:[1,0,0]
	v_pk_fma_f32 v[50:51], v[66:67], v[38:39], v[50:51] op_sel:[1,0,0]
	s_waitcnt lgkmcnt(0)
	v_pk_fma_f32 v[52:53], v[66:67], v[44:45], v[52:53] op_sel:[1,0,0]
	v_pk_fma_f32 v[46:47], v[66:67], v[42:43], v[46:47] op_sel:[1,0,0]
	ds_read_b128 v[38:41], v31 offset:5632
	ds_read_b128 v[42:45], v31 offset:5648
	s_waitcnt lgkmcnt(1)
	v_pk_fma_f32 v[48:49], v[68:69], v[40:41], v[48:49] op_sel_hi:[0,1,1]
	v_pk_fma_f32 v[50:51], v[68:69], v[38:39], v[50:51] op_sel_hi:[0,1,1]
	s_waitcnt lgkmcnt(0)
	v_pk_fma_f32 v[52:53], v[68:69], v[44:45], v[52:53] op_sel_hi:[0,1,1]
	v_pk_fma_f32 v[46:47], v[68:69], v[42:43], v[46:47] op_sel_hi:[0,1,1]
	ds_read_b128 v[38:41], v31 offset:5888
	ds_read_b128 v[42:45], v31 offset:5904
	s_waitcnt lgkmcnt(1)
	v_pk_fma_f32 v[48:49], v[54:55], v[40:41], v[48:49] op_sel_hi:[0,1,1]
	v_pk_fma_f32 v[50:51], v[54:55], v[38:39], v[50:51] op_sel_hi:[0,1,1]
	s_waitcnt lgkmcnt(0)
	v_pk_fma_f32 v[52:53], v[54:55], v[44:45], v[52:53] op_sel_hi:[0,1,1]
	v_pk_fma_f32 v[46:47], v[54:55], v[42:43], v[46:47] op_sel_hi:[0,1,1]
	ds_read_b128 v[38:41], v31 offset:6144
	ds_read_b128 v[42:45], v31 offset:6160
	v_mov_b32_e32 v54, v73
	s_waitcnt lgkmcnt(1)
; #define LAS __attribute__((address_space(3)))
; __device__ __forceinline__ void scan_pass2(const ScanP& sp, int b, int h, int seg, LAS unsigned char* lds) {
;     ...
;         for (int jq = 0; jq < 16; ++jq) {
; #pragma unroll
;             for (int q = 0; q < 4; ++q) {
;                 const f32x4 h0 = *(const LAS f32x4*)(Hc + (4 * jq + q) * 64 + i8), h1 = *(const LAS f32x4*)(Hc + (4 * jq + q) * 64 + i8 + 4);
;                 a0 += h0 * pvr[jq][q]; a1 += h1 * pvr[jq][q];
;             }
;         }
	v_pk_fma_f32 v[48:49], v[70:71], v[40:41], v[48:49] op_sel_hi:[0,1,1]
	v_pk_fma_f32 v[50:51], v[70:71], v[38:39], v[50:51] op_sel_hi:[0,1,1]
	s_waitcnt lgkmcnt(0)
	v_pk_fma_f32 v[52:53], v[70:71], v[44:45], v[52:53] op_sel_hi:[0,1,1]
	v_pk_fma_f32 v[46:47], v[70:71], v[42:43], v[46:47] op_sel_hi:[0,1,1]
	ds_read_b128 v[38:41], v31 offset:6400
	ds_read_b128 v[42:45], v31 offset:6416
	s_waitcnt lgkmcnt(1)
	v_pk_fma_f32 v[48:49], v[70:71], v[40:41], v[48:49] op_sel:[1,0,0]
	v_pk_fma_f32 v[50:51], v[70:71], v[38:39], v[50:51] op_sel:[1,0,0]
	s_waitcnt lgkmcnt(0)
	v_pk_fma_f32 v[52:53], v[70:71], v[44:45], v[52:53] op_sel:[1,0,0]
	v_pk_fma_f32 v[46:47], v[70:71], v[42:43], v[46:47] op_sel:[1,0,0]
	ds_read_b128 v[38:41], v31 offset:6656
	ds_read_b128 v[42:45], v31 offset:6672
	s_waitcnt lgkmcnt(1)
	v_pk_fma_f32 v[48:49], v[72:73], v[40:41], v[48:49] op_sel_hi:[0,1,1]
	v_pk_fma_f32 v[50:51], v[72:73], v[38:39], v[50:51] op_sel_hi:[0,1,1]
	s_waitcnt lgkmcnt(0)
	v_pk_fma_f32 v[52:53], v[72:73], v[44:45], v[52:53] op_sel_hi:[0,1,1]
	v_pk_fma_f32 v[46:47], v[72:73], v[42:43], v[46:47] op_sel_hi:[0,1,1]
	ds_read_b128 v[38:41], v31 offset:6912
	ds_read_b128 v[42:45], v31 offset:6928
	s_waitcnt lgkmcnt(1)
	v_pk_fma_f32 v[48:49], v[54:55], v[40:41], v[48:49] op_sel_hi:[0,1,1]
	v_pk_fma_f32 v[50:51], v[54:55], v[38:39], v[50:51] op_sel_hi:[0,1,1]
	s_waitcnt lgkmcnt(0)
	v_pk_fma_f32 v[52:53], v[54:55], v[44:45], v[52:53] op_sel_hi:[0,1,1]
	v_pk_fma_f32 v[46:47], v[54:55], v[42:43], v[46:47] op_sel_hi:[0,1,1]
	ds_read_b128 v[38:41], v31 offset:7168
	ds_read_b128 v[42:45], v31 offset:7184
	v_mov_b32_e32 v54, v77
	s_waitcnt lgkmcnt(1)
	v_pk_fma_f32 v[48:49], v[74:75], v[40:41], v[48:49] op_sel_hi:[0,1,1]
	v_pk_fma_f32 v[50:51], v[74:75], v[38:39], v[50:51] op_sel_hi:[0,1,1]
	s_waitcnt lgkmcnt(0)
	v_pk_fma_f32 v[52:53], v[74:75], v[44:45], v[52:53] op_sel_hi:[0,1,1]
	v_pk_fma_f32 v[46:47], v[74:75], v[42:43], v[46:47] op_sel_hi:[0,1,1]
	ds_read_b128 v[38:41], v31 offset:7424
	ds_read_b128 v[42:45], v31 offset:7440
	s_waitcnt lgkmcnt(1)
	v_pk_fma_f32 v[48:49], v[74:75], v[40:41], v[48:49] op_sel:[1,0,0]
	v_pk_fma_f32 v[50:51], v[74:75], v[38:39], v[50:51] op_sel:[1,0,0]
	s_waitcnt lgkmcnt(0)
	v_pk_fma_f32 v[52:53], v[74:75], v[44:45], v[52:53] op_sel:[1,0,0]
	v_pk_fma_f32 v[46:47], v[74:75], v[42:43], v[46:47] op_sel:[1,0,0]
	ds_read_b128 v[38:41], v31 offset:7680
	ds_read_b128 v[42:45], v31 offset:7696
	s_waitcnt lgkmcnt(1)
	v_pk_fma_f32 v[48:49], v[76:77], v[40:41], v[48:49] op_sel_hi:[0,1,1]
	v_pk_fma_f32 v[50:51], v[76:77], v[38:39], v[50:51] op_sel_hi:[0,1,1]
	s_waitcnt lgkmcnt(0)
	v_pk_fma_f32 v[52:53], v[76:77], v[44:45], v[52:53] op_sel_hi:[0,1,1]
	v_pk_fma_f32 v[46:47], v[76:77], v[42:43], v[46:47] op_sel_hi:[0,1,1]
	ds_read_b128 v[38:41], v31 offset:7936
	ds_read_b128 v[42:45], v31 offset:7952
	s_waitcnt lgkmcnt(1)
	v_pk_fma_f32 v[48:49], v[54:55], v[40:41], v[48:49] op_sel_hi:[0,1,1]
	v_pk_fma_f32 v[50:51], v[54:55], v[38:39], v[50:51] op_sel_hi:[0,1,1]
	s_waitcnt lgkmcnt(0)
	v_pk_fma_f32 v[52:53], v[54:55], v[44:45], v[52:53] op_sel_hi:[0,1,1]
	v_pk_fma_f32 v[46:47], v[54:55], v[42:43], v[46:47] op_sel_hi:[0,1,1]
	ds_read_b128 v[38:41], v31 offset:8192
	ds_read_b128 v[42:45], v31 offset:8208
	v_mov_b32_e32 v54, v81
	s_waitcnt lgkmcnt(1)
	v_pk_fma_f32 v[48:49], v[78:79], v[40:41], v[48:49] op_sel_hi:[0,1,1]
	v_pk_fma_f32 v[50:51], v[78:79], v[38:39], v[50:51] op_sel_hi:[0,1,1]
	s_waitcnt lgkmcnt(0)
	v_pk_fma_f32 v[52:53], v[78:79], v[44:45], v[52:53] op_sel_hi:[0,1,1]
	v_pk_fma_f32 v[46:47], v[78:79], v[42:43], v[46:47] op_sel_hi:[0,1,1]
	ds_read_b128 v[38:41], v31 offset:8448
	ds_read_b128 v[42:45], v31 offset:8464
	s_waitcnt lgkmcnt(1)
	v_pk_fma_f32 v[48:49], v[78:79], v[40:41], v[48:49] op_sel:[1,0,0]
	v_pk_fma_f32 v[50:51], v[78:79], v[38:39], v[50:51] op_sel:[1,0,0]
	s_waitcnt lgkmcnt(0)
	v_pk_fma_f32 v[52:53], v[78:79], v[44:45], v[52:53] op_sel:[1,0,0]
	v_pk_fma_f32 v[46:47], v[78:79], v[42:43], v[46:47] op_sel:[1,0,0]
	ds_read_b128 v[38:41], v31 offset:8704
	ds_read_b128 v[42:45], v31 offset:8720
	s_waitcnt lgkmcnt(1)
	v_pk_fma_f32 v[48:49], v[80:81], v[40:41], v[48:49] op_sel_hi:[0,1,1]
	v_pk_fma_f32 v[50:51], v[80:81], v[38:39], v[50:51] op_sel_hi:[0,1,1]
	s_waitcnt lgkmcnt(0)
	v_pk_fma_f32 v[52:53], v[80:81], v[44:45], v[52:53] op_sel_hi:[0,1,1]
	v_pk_fma_f32 v[46:47], v[80:81], v[42:43], v[46:47] op_sel_hi:[0,1,1]
	ds_read_b128 v[38:41], v31 offset:8960
	ds_read_b128 v[42:45], v31 offset:8976
	s_waitcnt lgkmcnt(1)
	v_pk_fma_f32 v[48:49], v[54:55], v[40:41], v[48:49] op_sel_hi:[0,1,1]
	v_pk_fma_f32 v[50:51], v[54:55], v[38:39], v[50:51] op_sel_hi:[0,1,1]
	s_waitcnt lgkmcnt(0)
	v_pk_fma_f32 v[52:53], v[54:55], v[44:45], v[52:53] op_sel_hi:[0,1,1]
	v_pk_fma_f32 v[46:47], v[54:55], v[42:43], v[46:47] op_sel_hi:[0,1,1]
	ds_read_b128 v[38:41], v31 offset:9216
	ds_read_b128 v[42:45], v31 offset:9232
	s_waitcnt lgkmcnt(1)
	v_pk_fma_f32 v[48:49], v[26:27], v[40:41], v[48:49] op_sel_hi:[0,1,1]
	v_pk_fma_f32 v[50:51], v[26:27], v[38:39], v[50:51] op_sel_hi:[0,1,1]
	s_waitcnt lgkmcnt(0)
	v_pk_fma_f32 v[52:53], v[26:27], v[44:45], v[52:53] op_sel_hi:[0,1,1]
	v_pk_fma_f32 v[46:47], v[26:27], v[42:43], v[46:47] op_sel_hi:[0,1,1]
	ds_read_b128 v[38:41], v31 offset:9472
	ds_read_b128 v[42:45], v31 offset:9488
	s_waitcnt lgkmcnt(1)
	v_pk_fma_f32 v[48:49], v[26:27], v[40:41], v[48:49] op_sel:[1,0,0]
	v_pk_fma_f32 v[50:51], v[26:27], v[38:39], v[50:51] op_sel:[1,0,0]
	s_waitcnt lgkmcnt(0)
	v_pk_fma_f32 v[52:53], v[26:27], v[44:45], v[52:53] op_sel:[1,0,0]
	v_pk_fma_f32 v[26:27], v[26:27], v[42:43], v[46:47] op_sel:[1,0,0]
	ds_read_b128 v[38:41], v31 offset:9728
	ds_read_b128 v[42:45], v31 offset:9744
	s_waitcnt lgkmcnt(1)
; #define LAS __attribute__((address_space(3)))
; __device__ __forceinline__ void scan_pass2(const ScanP& sp, int b, int h, int seg, LAS unsigned char* lds) {
;     ...
;         for (int jq = 0; jq < 16; ++jq) {
; #pragma unroll
;             for (int q = 0; q < 4; ++q) {
;                 const f32x4 h0 = *(const LAS f32x4*)(Hc + (4 * jq + q) * 64 + i8), h1 = *(const LAS f32x4*)(Hc + (4 * jq + q) * 64 + i8 + 4);
;                 a0 += h0 * pvr[jq][q]; a1 += h1 * pvr[jq][q];
;             }
;         }
	v_pk_fma_f32 v[46:47], v[28:29], v[40:41], v[48:49] op_sel_hi:[0,1,1]
	v_pk_fma_f32 v[48:49], v[28:29], v[38:39], v[50:51] op_sel_hi:[0,1,1]
	s_waitcnt lgkmcnt(0)
	v_pk_fma_f32 v[50:51], v[28:29], v[44:45], v[52:53] op_sel_hi:[0,1,1]
	v_pk_fma_f32 v[26:27], v[28:29], v[42:43], v[26:27] op_sel_hi:[0,1,1]
	ds_read_b128 v[38:41], v31 offset:9984
	ds_read_b128 v[42:45], v31 offset:10000
	v_mov_b32_e32 v28, v29
	s_waitcnt lgkmcnt(1)
	v_pk_fma_f32 v[46:47], v[28:29], v[40:41], v[46:47] op_sel_hi:[0,1,1]
	v_pk_fma_f32 v[48:49], v[28:29], v[38:39], v[48:49] op_sel_hi:[0,1,1]
	s_waitcnt lgkmcnt(0)
	v_pk_fma_f32 v[44:45], v[28:29], v[44:45], v[50:51] op_sel_hi:[0,1,1]
	v_pk_fma_f32 v[42:43], v[28:29], v[42:43], v[26:27] op_sel_hi:[0,1,1]
	ds_read_b128 v[26:29], v31 offset:10240
	ds_read_b128 v[38:41], v31 offset:10256
	s_waitcnt lgkmcnt(1)
	v_pk_fma_f32 v[46:47], v[22:23], v[28:29], v[46:47] op_sel_hi:[0,1,1]
	v_pk_fma_f32 v[48:49], v[22:23], v[26:27], v[48:49] op_sel_hi:[0,1,1]
	s_waitcnt lgkmcnt(0)
	v_pk_fma_f32 v[44:45], v[22:23], v[40:41], v[44:45] op_sel_hi:[0,1,1]
	v_pk_fma_f32 v[42:43], v[22:23], v[38:39], v[42:43] op_sel_hi:[0,1,1]
	ds_read_b128 v[26:29], v31 offset:10496
	ds_read_b128 v[38:41], v31 offset:10512
	s_waitcnt lgkmcnt(1)
	v_pk_fma_f32 v[46:47], v[22:23], v[28:29], v[46:47] op_sel:[1,0,0]
	v_pk_fma_f32 v[48:49], v[22:23], v[26:27], v[48:49] op_sel:[1,0,0]
	s_waitcnt lgkmcnt(0)
	v_pk_fma_f32 v[44:45], v[22:23], v[40:41], v[44:45] op_sel:[1,0,0]
	v_pk_fma_f32 v[22:23], v[22:23], v[38:39], v[42:43] op_sel:[1,0,0]
	ds_read_b128 v[26:29], v31 offset:10752
	ds_read_b128 v[38:41], v31 offset:10768
	s_waitcnt lgkmcnt(1)
	v_pk_fma_f32 v[42:43], v[24:25], v[28:29], v[46:47] op_sel_hi:[0,1,1]
	v_pk_fma_f32 v[46:47], v[24:25], v[26:27], v[48:49] op_sel_hi:[0,1,1]
	s_waitcnt lgkmcnt(0)
	v_pk_fma_f32 v[44:45], v[24:25], v[40:41], v[44:45] op_sel_hi:[0,1,1]
	v_pk_fma_f32 v[22:23], v[24:25], v[38:39], v[22:23] op_sel_hi:[0,1,1]
	ds_read_b128 v[26:29], v31 offset:11008
	ds_read_b128 v[38:41], v31 offset:11024
	v_mov_b32_e32 v24, v25
	s_waitcnt lgkmcnt(1)
	v_pk_fma_f32 v[42:43], v[24:25], v[28:29], v[42:43] op_sel_hi:[0,1,1]
	v_pk_fma_f32 v[46:47], v[24:25], v[26:27], v[46:47] op_sel_hi:[0,1,1]
	s_waitcnt lgkmcnt(0)
	v_pk_fma_f32 v[40:41], v[24:25], v[40:41], v[44:45] op_sel_hi:[0,1,1]
	v_pk_fma_f32 v[38:39], v[24:25], v[38:39], v[22:23] op_sel_hi:[0,1,1]
	ds_read_b128 v[22:25], v31 offset:11264
	ds_read_b128 v[26:29], v31 offset:11280
	s_waitcnt lgkmcnt(1)
	v_pk_fma_f32 v[42:43], v[18:19], v[24:25], v[42:43] op_sel_hi:[0,1,1]
	v_pk_fma_f32 v[44:45], v[18:19], v[22:23], v[46:47] op_sel_hi:[0,1,1]
	s_waitcnt lgkmcnt(0)
	v_pk_fma_f32 v[40:41], v[18:19], v[28:29], v[40:41] op_sel_hi:[0,1,1]
	v_pk_fma_f32 v[38:39], v[18:19], v[26:27], v[38:39] op_sel_hi:[0,1,1]
	ds_read_b128 v[22:25], v31 offset:11520
	ds_read_b128 v[26:29], v31 offset:11536
	s_waitcnt lgkmcnt(1)
	v_pk_fma_f32 v[42:43], v[18:19], v[24:25], v[42:43] op_sel:[1,0,0]
	v_pk_fma_f32 v[44:45], v[18:19], v[22:23], v[44:45] op_sel:[1,0,0]
	s_waitcnt lgkmcnt(0)
	v_pk_fma_f32 v[40:41], v[18:19], v[28:29], v[40:41] op_sel:[1,0,0]
	v_pk_fma_f32 v[18:19], v[18:19], v[26:27], v[38:39] op_sel:[1,0,0]
	ds_read_b128 v[22:25], v31 offset:11776
	ds_read_b128 v[26:29], v31 offset:11792
	s_waitcnt lgkmcnt(1)
	v_pk_fma_f32 v[38:39], v[20:21], v[24:25], v[42:43] op_sel_hi:[0,1,1]
	v_pk_fma_f32 v[42:43], v[20:21], v[22:23], v[44:45] op_sel_hi:[0,1,1]
	s_waitcnt lgkmcnt(0)
	v_pk_fma_f32 v[40:41], v[20:21], v[28:29], v[40:41] op_sel_hi:[0,1,1]
	v_pk_fma_f32 v[18:19], v[20:21], v[26:27], v[18:19] op_sel_hi:[0,1,1]
	ds_read_b128 v[22:25], v31 offset:12032
	ds_read_b128 v[26:29], v31 offset:12048
	v_mov_b32_e32 v20, v21
	s_waitcnt lgkmcnt(1)
	v_pk_fma_f32 v[38:39], v[20:21], v[24:25], v[38:39] op_sel_hi:[0,1,1]
	v_pk_fma_f32 v[42:43], v[20:21], v[22:23], v[42:43] op_sel_hi:[0,1,1]
	s_waitcnt lgkmcnt(0)
	v_pk_fma_f32 v[28:29], v[20:21], v[28:29], v[40:41] op_sel_hi:[0,1,1]
	v_pk_fma_f32 v[26:27], v[20:21], v[26:27], v[18:19] op_sel_hi:[0,1,1]
	ds_read_b128 v[18:21], v31 offset:12288
	ds_read_b128 v[22:25], v31 offset:12304
	s_waitcnt lgkmcnt(1)
	v_pk_fma_f32 v[38:39], v[14:15], v[20:21], v[38:39] op_sel_hi:[0,1,1]
	v_pk_fma_f32 v[40:41], v[14:15], v[18:19], v[42:43] op_sel_hi:[0,1,1]
	s_waitcnt lgkmcnt(0)
	v_pk_fma_f32 v[28:29], v[14:15], v[24:25], v[28:29] op_sel_hi:[0,1,1]
	v_pk_fma_f32 v[26:27], v[14:15], v[22:23], v[26:27] op_sel_hi:[0,1,1]
	ds_read_b128 v[18:21], v31 offset:12544
	ds_read_b128 v[22:25], v31 offset:12560
	s_waitcnt lgkmcnt(1)
	v_pk_fma_f32 v[38:39], v[14:15], v[20:21], v[38:39] op_sel:[1,0,0]
	v_pk_fma_f32 v[40:41], v[14:15], v[18:19], v[40:41] op_sel:[1,0,0]
	s_waitcnt lgkmcnt(0)
	v_pk_fma_f32 v[28:29], v[14:15], v[24:25], v[28:29] op_sel:[1,0,0]
	v_pk_fma_f32 v[14:15], v[14:15], v[22:23], v[26:27] op_sel:[1,0,0]
	ds_read_b128 v[18:21], v31 offset:12800
	ds_read_b128 v[22:25], v31 offset:12816
	s_waitcnt lgkmcnt(1)
	v_pk_fma_f32 v[26:27], v[16:17], v[20:21], v[38:39] op_sel_hi:[0,1,1]
	v_pk_fma_f32 v[38:39], v[16:17], v[18:19], v[40:41] op_sel_hi:[0,1,1]
	s_waitcnt lgkmcnt(0)
	v_pk_fma_f32 v[28:29], v[16:17], v[24:25], v[28:29] op_sel_hi:[0,1,1]
	v_pk_fma_f32 v[14:15], v[16:17], v[22:23], v[14:15] op_sel_hi:[0,1,1]
	ds_read_b128 v[18:21], v31 offset:13056
	ds_read_b128 v[22:25], v31 offset:13072
	v_mov_b32_e32 v16, v17
	s_waitcnt lgkmcnt(1)
; #define LAS __attribute__((address_space(3)))
; __device__ __forceinline__ void scan_pass2(const ScanP& sp, int b, int h, int seg, LAS unsigned char* lds) {
;     ...
;         for (int jq = 0; jq < 16; ++jq) {
; #pragma unroll
;             for (int q = 0; q < 4; ++q) {
;                 const f32x4 h0 = *(const LAS f32x4*)(Hc + (4 * jq + q) * 64 + i8), h1 = *(const LAS f32x4*)(Hc + (4 * jq + q) * 64 + i8 + 4);
;                 a0 += h0 * pvr[jq][q]; a1 += h1 * pvr[jq][q];
;             }
;         }
;         *(LAS f32x4*)(Hn + j * 64 + i8) = a0; *(LAS f32x4*)(Hn + j * 64 + i8 + 4) = a1;
;         __syncthreads();
;         LAS float* t_ = Hc; Hc = Hn; Hn = t_;
	v_pk_fma_f32 v[26:27], v[16:17], v[20:21], v[26:27] op_sel_hi:[0,1,1]
	v_pk_fma_f32 v[38:39], v[16:17], v[18:19], v[38:39] op_sel_hi:[0,1,1]
	s_waitcnt lgkmcnt(0)
	v_pk_fma_f32 v[24:25], v[16:17], v[24:25], v[28:29] op_sel_hi:[0,1,1]
	v_pk_fma_f32 v[22:23], v[16:17], v[22:23], v[14:15] op_sel_hi:[0,1,1]
	ds_read_b128 v[14:17], v31 offset:13312
	ds_read_b128 v[18:21], v31 offset:13328
	s_waitcnt lgkmcnt(1)
	v_pk_fma_f32 v[26:27], v[10:11], v[16:17], v[26:27] op_sel_hi:[0,1,1]
	v_pk_fma_f32 v[28:29], v[10:11], v[14:15], v[38:39] op_sel_hi:[0,1,1]
	s_waitcnt lgkmcnt(0)
	v_pk_fma_f32 v[24:25], v[10:11], v[20:21], v[24:25] op_sel_hi:[0,1,1]
	v_pk_fma_f32 v[22:23], v[10:11], v[18:19], v[22:23] op_sel_hi:[0,1,1]
	ds_read_b128 v[14:17], v31 offset:13568
	ds_read_b128 v[18:21], v31 offset:13584
	s_waitcnt lgkmcnt(1)
	v_pk_fma_f32 v[26:27], v[10:11], v[16:17], v[26:27] op_sel:[1,0,0]
	v_pk_fma_f32 v[28:29], v[10:11], v[14:15], v[28:29] op_sel:[1,0,0]
	s_waitcnt lgkmcnt(0)
	v_pk_fma_f32 v[24:25], v[10:11], v[20:21], v[24:25] op_sel:[1,0,0]
	v_pk_fma_f32 v[10:11], v[10:11], v[18:19], v[22:23] op_sel:[1,0,0]
	ds_read_b128 v[14:17], v31 offset:13824
	ds_read_b128 v[18:21], v31 offset:13840
	s_waitcnt lgkmcnt(1)
	v_pk_fma_f32 v[22:23], v[12:13], v[16:17], v[26:27] op_sel_hi:[0,1,1]
	v_pk_fma_f32 v[26:27], v[12:13], v[14:15], v[28:29] op_sel_hi:[0,1,1]
	s_waitcnt lgkmcnt(0)
	v_pk_fma_f32 v[24:25], v[12:13], v[20:21], v[24:25] op_sel_hi:[0,1,1]
	v_pk_fma_f32 v[10:11], v[12:13], v[18:19], v[10:11] op_sel_hi:[0,1,1]
	ds_read_b128 v[14:17], v31 offset:14080
	ds_read_b128 v[18:21], v31 offset:14096
	v_mov_b32_e32 v12, v13
	s_waitcnt lgkmcnt(1)
	v_pk_fma_f32 v[22:23], v[12:13], v[16:17], v[22:23] op_sel_hi:[0,1,1]
	v_pk_fma_f32 v[26:27], v[12:13], v[14:15], v[26:27] op_sel_hi:[0,1,1]
	s_waitcnt lgkmcnt(0)
	v_pk_fma_f32 v[20:21], v[12:13], v[20:21], v[24:25] op_sel_hi:[0,1,1]
	v_pk_fma_f32 v[18:19], v[12:13], v[18:19], v[10:11] op_sel_hi:[0,1,1]
	ds_read_b128 v[10:13], v31 offset:14336
	ds_read_b128 v[14:17], v31 offset:14352
	s_waitcnt lgkmcnt(1)
	v_pk_fma_f32 v[22:23], v[6:7], v[12:13], v[22:23] op_sel_hi:[0,1,1]
	v_pk_fma_f32 v[24:25], v[6:7], v[10:11], v[26:27] op_sel_hi:[0,1,1]
	s_waitcnt lgkmcnt(0)
	v_pk_fma_f32 v[20:21], v[6:7], v[16:17], v[20:21] op_sel_hi:[0,1,1]
	v_pk_fma_f32 v[18:19], v[6:7], v[14:15], v[18:19] op_sel_hi:[0,1,1]
	ds_read_b128 v[10:13], v31 offset:14592
	ds_read_b128 v[14:17], v31 offset:14608
	s_waitcnt lgkmcnt(1)
	v_pk_fma_f32 v[22:23], v[6:7], v[12:13], v[22:23] op_sel:[1,0,0]
	v_pk_fma_f32 v[24:25], v[6:7], v[10:11], v[24:25] op_sel:[1,0,0]
	s_waitcnt lgkmcnt(0)
	v_pk_fma_f32 v[20:21], v[6:7], v[16:17], v[20:21] op_sel:[1,0,0]
	v_pk_fma_f32 v[6:7], v[6:7], v[14:15], v[18:19] op_sel:[1,0,0]
	ds_read_b128 v[10:13], v31 offset:14848
	ds_read_b128 v[14:17], v31 offset:14864
	s_waitcnt lgkmcnt(1)
	v_pk_fma_f32 v[18:19], v[8:9], v[12:13], v[22:23] op_sel_hi:[0,1,1]
	v_pk_fma_f32 v[22:23], v[8:9], v[10:11], v[24:25] op_sel_hi:[0,1,1]
	s_waitcnt lgkmcnt(0)
	v_pk_fma_f32 v[20:21], v[8:9], v[16:17], v[20:21] op_sel_hi:[0,1,1]
	v_pk_fma_f32 v[6:7], v[8:9], v[14:15], v[6:7] op_sel_hi:[0,1,1]
	ds_read_b128 v[10:13], v31 offset:15104
	ds_read_b128 v[14:17], v31 offset:15120
	v_mov_b32_e32 v8, v9
	s_waitcnt lgkmcnt(1)
	v_pk_fma_f32 v[18:19], v[8:9], v[12:13], v[18:19] op_sel_hi:[0,1,1]
	v_pk_fma_f32 v[22:23], v[8:9], v[10:11], v[22:23] op_sel_hi:[0,1,1]
	s_waitcnt lgkmcnt(0)
	v_pk_fma_f32 v[16:17], v[8:9], v[16:17], v[20:21] op_sel_hi:[0,1,1]
	v_pk_fma_f32 v[14:15], v[8:9], v[14:15], v[6:7] op_sel_hi:[0,1,1]
	ds_read_b128 v[6:9], v31 offset:15360
	ds_read_b128 v[10:13], v31 offset:15376
	s_waitcnt lgkmcnt(1)
	v_pk_fma_f32 v[18:19], v[2:3], v[8:9], v[18:19] op_sel_hi:[0,1,1]
	v_pk_fma_f32 v[20:21], v[2:3], v[6:7], v[22:23] op_sel_hi:[0,1,1]
	s_waitcnt lgkmcnt(0)
	v_pk_fma_f32 v[16:17], v[2:3], v[12:13], v[16:17] op_sel_hi:[0,1,1]
	v_pk_fma_f32 v[14:15], v[2:3], v[10:11], v[14:15] op_sel_hi:[0,1,1]
	ds_read_b128 v[6:9], v31 offset:15616
	ds_read_b128 v[10:13], v31 offset:15632
	v_mov_b32_e32 v22, v5
	s_waitcnt lgkmcnt(1)
	v_pk_fma_f32 v[18:19], v[2:3], v[8:9], v[18:19] op_sel:[1,0,0]
	v_pk_fma_f32 v[20:21], v[2:3], v[6:7], v[20:21] op_sel:[1,0,0]
	s_waitcnt lgkmcnt(0)
	v_pk_fma_f32 v[16:17], v[2:3], v[12:13], v[16:17] op_sel:[1,0,0]
	v_pk_fma_f32 v[2:3], v[2:3], v[10:11], v[14:15] op_sel:[1,0,0]
	ds_read_b128 v[6:9], v31 offset:15872
	ds_read_b128 v[10:13], v31 offset:15888
	s_waitcnt lgkmcnt(1)
	v_pk_fma_f32 v[14:15], v[4:5], v[8:9], v[18:19] op_sel_hi:[0,1,1]
	v_pk_fma_f32 v[18:19], v[4:5], v[6:7], v[20:21] op_sel_hi:[0,1,1]
	s_waitcnt lgkmcnt(0)
	v_pk_fma_f32 v[16:17], v[4:5], v[12:13], v[16:17] op_sel_hi:[0,1,1]
	v_pk_fma_f32 v[20:21], v[4:5], v[10:11], v[2:3] op_sel_hi:[0,1,1]
	ds_read_b128 v[6:9], v31 offset:16128
	ds_read_b128 v[10:13], v31 offset:16144
	s_waitcnt lgkmcnt(1)
	v_pk_fma_f32 v[2:3], v[22:23], v[6:7], v[18:19] op_sel_hi:[0,1,1]
	s_waitcnt lgkmcnt(0)
	v_pk_fma_f32 v[6:7], v[22:23], v[10:11], v[20:21] op_sel_hi:[0,1,1]
	v_lshlrev_b32_e32 v10, 2, v30
	v_pk_fma_f32 v[4:5], v[22:23], v[8:9], v[14:15] op_sel_hi:[0,1,1]
	v_add3_u32 v10, s7, v10, v37
	v_pk_fma_f32 v[8:9], v[22:23], v[12:13], v[16:17] op_sel_hi:[0,1,1]
	ds_write_b128 v10, v[2:5]
	ds_write_b128 v10, v[6:9] offset:16
	s_waitcnt lgkmcnt(0)
	s_barrier
	s_cbranch_scc0 .LBB0_338

; #define LAS __attribute__((address_space(3)))
; #define MFMA32(a, b, c) __builtin_amdgcn_mfma_f32_32x32x16_bf16((a), (b), (c), 0, 0, 0)
; __device__ __forceinline__ void scan_pass2(const ScanP& sp, int b, int h, int seg, LAS unsigned char* lds) {
;     ...
;     for (int c = w; c < 32; c += 8) {
;         const int t0 = seg * 1024 + c * 32;
; #pragma unroll
;         for (int ib = 0; ib < 2; ++ib) {
;             f32x16 acc;
; #pragma unroll
;             for (int i = 0; i < 16; ++i) acc[i] = 0.f;
; #pragma unroll
;             for (int ks = 0; ks < 4; ++ks) {
;                 const bf16x8 qa = *(const bf16x8*)(sp.Q + (size_t)(tok0 + t0 + ln) * 512 + h * 64 + ks * 16 + hh * 8);
;                 const bf16x8 hb = *(const LAS bf16x8*)(HiT + ((ib * 32 + ln) * 72 + ks * 16 + hh * 8) * 2);
;                 acc = MFMA32(qa, hb, acc);
;             }
; #pragma unroll
;             for (int r = 0; r < 16; ++r) ybw[crow(r, hh) * 64 + ib * 32 + ln] = acc[r];
;     ...
;             const int item = it * 64 + lane, tt = item >> 4, jg = item & 15, j4 = 4 * jg, ch = h * 64 + j4;
;             const int t = t0 + tt; const size_t tok = (size_t)(tok0 + t);
;             const u32x2 y0 = *(const u32x2*)(sp.mixed + tok * 1024 + 512 + ch);
;             const f32x4 dy = *(const LAS f32x4*)(ybw + tt * 64 + j4);
;             const f32x4 y = {bflo(y0.x) + dy[0], bfhi(y0.x) + dy[1], bflo(y0.y) + dy[2], bfhi(y0.y) + dy[3]};
;             const float mean = red16((y[0] + y[1]) + (y[2] + y[3])) * (1.0f / 64.0f);
;             const f32x4 dlt = y - mean;
;             const float var = red16((dlt[0] * dlt[0] + dlt[1] * dlt[1]) + (dlt[2] * dlt[2] + dlt[3] * dlt[3])) * (1.0f / 64.0f);
;             const float rs = __builtin_amdgcn_rsqf(var + 64e-5f);
;             const bf16_t* vp = sp.P + tok * PP + 3072 + ch;
;             const u32x2 vc = *(const u32x2*)vp; u32x2 vq = {0u, 0u}; if (t > 0) vq = *(const u32x2*)(vp - PP);
;             const f32x4 vcf = {bflo(vc.x), bfhi(vc.x), bflo(vc.y), bfhi(vc.y)}, vqf = {bflo(vq.x), bfhi(vq.x), bflo(vq.y), bfhi(vq.y)};
;             const f32x4 v4 = vcf + (vqf - vcf) * *(const LAS f32x4*)(par + j4);
;             const float bon = sp.bon[tok * 8 + h];
;             const u32x2 gr = *(const u32x2*)(sp.P + tok * PP + 3584 + ch);
;             const f32x4 yo = dlt * rs * *(const LAS f32x4*)(par + 64 + j4) + *(const LAS f32x4*)(par + 128 + j4) + v4 * bon;
.LBB0_342:
	s_lshl_b32 s2, s4, 5
	s_add_i32 s2, s2, s5
	v_add_u32_e32 v2, s2, v19
	v_ashrrev_i32_e32 v3, 31, v2
	v_lshlrev_b64 v[2:3], 10, v[2:3]
	v_lshl_add_u64 v[24:25], v[20:21], 0, v[2:3]
	global_load_dwordx4 v[2:5], v[24:25], off
	global_load_dwordx4 v[32:35], v[24:25], off offset:32
	ds_read_b128 v[6:9], v30 offset:32768
	ds_read_b128 v[36:39], v30 offset:32800
	s_mov_b32 s6, 0
	s_waitcnt vmcnt(0) lgkmcnt(0)
	v_mfma_f32_32x32x16_bf16 v[2:17], v[2:5], v[6:9], 0
	v_mfma_f32_32x32x16_bf16 v[2:17], v[32:35], v[36:39], v[2:17]
	global_load_dwordx4 v[32:35], v[24:25], off offset:64
	ds_read_b128 v[36:39], v30 offset:32832
	s_waitcnt vmcnt(0) lgkmcnt(0)
	v_mfma_f32_32x32x16_bf16 v[2:17], v[32:35], v[36:39], v[2:17]
	global_load_dwordx4 v[32:35], v[24:25], off offset:96
	ds_read_b128 v[36:39], v30 offset:32864
	s_waitcnt vmcnt(0) lgkmcnt(0)
	v_mfma_f32_32x32x16_bf16 v[2:17], v[32:35], v[36:39], v[2:17]
	s_nop 11
	ds_write_b32 v31, v2 offset:43008
	ds_write_b32 v31, v3 offset:43264
	ds_write_b32 v31, v4 offset:43520
	ds_write_b32 v31, v5 offset:43776
	ds_write_b32 v31, v6 offset:45056
	ds_write_b32 v31, v7 offset:45312
	ds_write_b32 v31, v8 offset:45568
	ds_write_b32 v31, v9 offset:45824
	ds_write_b32 v31, v10 offset:47104
	ds_write_b32 v31, v11 offset:47360
	ds_write_b32 v31, v12 offset:47616
	ds_write_b32 v31, v13 offset:47872
	ds_write_b32 v31, v14 offset:49152
	ds_write_b32 v31, v15 offset:49408
	ds_write_b32 v31, v16 offset:49664
	ds_write_b32 v31, v17 offset:49920
	global_load_dwordx4 v[2:5], v[24:25], off
	global_load_dwordx4 v[32:35], v[24:25], off offset:32
	ds_read_b128 v[6:9], v30 offset:37376
	ds_read_b128 v[36:39], v30 offset:37408
	s_waitcnt vmcnt(0) lgkmcnt(0)
	v_mfma_f32_32x32x16_bf16 v[2:17], v[2:5], v[6:9], 0
	v_mfma_f32_32x32x16_bf16 v[2:17], v[32:35], v[36:39], v[2:17]
	global_load_dwordx4 v[32:35], v[24:25], off offset:64
	ds_read_b128 v[36:39], v30 offset:37440
	s_waitcnt vmcnt(0) lgkmcnt(0)
	v_mfma_f32_32x32x16_bf16 v[2:17], v[32:35], v[36:39], v[2:17]
	global_load_dwordx4 v[32:35], v[24:25], off offset:96
	ds_read_b128 v[36:39], v30 offset:37472
	s_waitcnt vmcnt(0) lgkmcnt(0)
	v_mfma_f32_32x32x16_bf16 v[2:17], v[32:35], v[36:39], v[2:17]
	v_mov_b32_e32 v32, v29
	s_nop 10
	ds_write_b32 v31, v2 offset:43136
	ds_write_b32 v31, v3 offset:43392
	ds_write_b32 v31, v4 offset:43648
	ds_write_b32 v31, v5 offset:43904
	ds_write_b32 v31, v6 offset:45184
	ds_write_b32 v31, v7 offset:45440
	ds_write_b32 v31, v8 offset:45696
	ds_write_b32 v31, v9 offset:45952
	ds_write_b32 v31, v10 offset:47232
	ds_write_b32 v31, v11 offset:47488
	ds_write_b32 v31, v12 offset:47744
	ds_write_b32 v31, v13 offset:48000
	ds_write_b32 v31, v14 offset:49280
	ds_write_b32 v31, v15 offset:49536
	ds_write_b32 v31, v16 offset:49792
	ds_write_b32 v31, v17 offset:50048
	s_waitcnt lgkmcnt(0)
	s_branch .LBB0_344
.LBB0_343:
	s_or_b64 exec, exec, s[2:3]
	v_add_f32_e32 v16, v24, v25
	v_fmamk_f32 v16, v16, 0x3c800000, v214
	s_waitcnt vmcnt(0) lgkmcnt(0)
	v_lshlrev_b32_e32 v34, 16, v14
	v_and_b32_e32 v35, 0xffff0000, v14
	v_lshlrev_b32_e32 v36, 16, v15
	v_and_b32_e32 v37, 0xffff0000, v15
	v_lshlrev_b32_e32 v14, 16, v4
	v_and_b32_e32 v15, 0xffff0000, v4
	v_rsq_f32_e32 v24, v16
	v_sub_f32_e32 v39, v15, v35
	v_sub_f32_e32 v38, v14, v34
	ds_read_b128 v[14:17], v26 offset:41984
	v_lshlrev_b32_e32 v4, 16, v5
	v_and_b32_e32 v5, 0xffff0000, v5
	v_sub_f32_e32 v5, v5, v37
	v_sub_f32_e32 v4, v4, v36
	s_waitcnt lgkmcnt(0)
	v_pk_fma_f32 v[16:17], v[16:17], v[4:5], v[36:37]
	v_lshlrev_b64 v[4:5], 5, v[6:7]
	v_lshl_add_u64 v[4:5], s[0:1], 0, v[4:5]
	v_pk_fma_f32 v[14:15], v[14:15], v[38:39], v[34:35]
	global_load_dword v34, v[4:5], off
	v_lshl_add_u64 v[4:5], v[12:13], 0, v[0:1]
	v_add_co_u32_e32 v4, vcc, s21, v4
	v_pk_mul_f32 v[36:37], v[10:11], v[24:25] op_sel_hi:[1,0]
	s_nop 0
	v_addc_co_u32_e32 v5, vcc, 0, v5, vcc
	global_load_dwordx2 v[12:13], v[4:5], off offset:3072
	v_pk_mul_f32 v[24:25], v[8:9], v[24:25] op_sel_hi:[1,0]
	ds_read_b128 v[4:7], v26 offset:42240
	ds_read_b128 v[8:11], v26 offset:42496
	s_add_i32 s6, s6, 16
	v_add_u32_e32 v32, 0x1000, v32
	s_cmp_eq_u32 s6, 32
	s_waitcnt lgkmcnt(0)
	v_pk_fma_f32 v[4:5], v[24:25], v[4:5], v[8:9]
	v_pk_fma_f32 v[6:7], v[36:37], v[6:7], v[10:11]
	s_waitcnt vmcnt(0)
	v_pk_fma_f32 v[4:5], v[34:35], v[14:15], v[4:5] op_sel_hi:[0,1,1]
	v_pk_fma_f32 v[6:7], v[34:35], v[16:17], v[6:7] op_sel_hi:[0,1,1]
	v_lshlrev_b32_e32 v8, 16, v12
	v_mul_f32_e32 v0, 0xbfb8aa3b, v8
	v_exp_f32_e32 v0, v0
	v_and_b32_e32 v9, 0xffff0000, v12
	v_add_f32_e32 v0, 1.0, v0
	v_rcp_f32_e32 v10, v0
	v_mul_f32_e32 v0, 0xbfb8aa3b, v9
	v_exp_f32_e32 v0, v0
	s_nop 0
	v_add_f32_e32 v0, 1.0, v0
	v_rcp_f32_e32 v11, v0
	s_nop 0
	v_pk_mul_f32 v[8:9], v[10:11], v[8:9]
	s_nop 0
	v_pk_mul_f32 v[4:5], v[8:9], v[4:5]
	v_lshlrev_b32_e32 v8, 16, v13
	v_mul_f32_e32 v0, 0xbfb8aa3b, v8
	v_exp_f32_e32 v0, v0
	v_and_b32_e32 v9, 0xffff0000, v13
	v_cvt_pk_bf16_f32 v4, v4, v5
	v_add_f32_e32 v0, 1.0, v0
	v_rcp_f32_e32 v10, v0
	v_mul_f32_e32 v0, 0xbfb8aa3b, v9
	v_exp_f32_e32 v0, v0
	s_nop 0
	v_add_f32_e32 v0, 1.0, v0
	v_rcp_f32_e32 v11, v0
	s_nop 0
	v_pk_mul_f32 v[8:9], v[10:11], v[8:9]
	s_nop 0
	v_pk_mul_f32 v[6:7], v[8:9], v[6:7]
	s_nop 0
	v_cvt_pk_bf16_f32 v5, v6, v7
	global_store_dwordx2 v[2:3], v[4:5], off offset:1024
	s_cbranch_scc1 .LBB0_341
; #define LAS __attribute__((address_space(3)))
; __device__ __forceinline__ unsigned pk2(float lo, float hi) { f32x2 v = {lo, hi}; bf16x2_t b = __builtin_convertvector(v, bf16x2_t); return __builtin_bit_cast(unsigned, b); }
; __device__ __forceinline__ float bflo(unsigned u) { return __uint_as_float(u << 16); }
; __device__ __forceinline__ float bfhi(unsigned u) { return __uint_as_float(u & 0xffff0000u); }
; __device__ __forceinline__ float silu(float g) { return g * __builtin_amdgcn_rcpf(1.0f + __expf(-g)); }
; __device__ __forceinline__ void scan_pass2(const ScanP& sp, int b, int h, int seg, LAS unsigned char* lds) {
;     ...
;         for (int it = 0; it < 8; ++it) {
;             const int item = it * 64 + lane, tt = item >> 4, jg = item & 15, j4 = 4 * jg, ch = h * 64 + j4;
;             const int t = t0 + tt; const size_t tok = (size_t)(tok0 + t);
;             const u32x2 y0 = *(const u32x2*)(sp.mixed + tok * 1024 + 512 + ch);
;             const f32x4 dy = *(const LAS f32x4*)(ybw + tt * 64 + j4);
;             const f32x4 y = {bflo(y0.x) + dy[0], bfhi(y0.x) + dy[1], bflo(y0.y) + dy[2], bfhi(y0.y) + dy[3]};
;             const float mean = red16((y[0] + y[1]) + (y[2] + y[3])) * (1.0f / 64.0f);
;             const f32x4 dlt = y - mean;
;             const float var = red16((dlt[0] * dlt[0] + dlt[1] * dlt[1]) + (dlt[2] * dlt[2] + dlt[3] * dlt[3])) * (1.0f / 64.0f);
;             const float rs = __builtin_amdgcn_rsqf(var + 64e-5f);
;             const bf16_t* vp = sp.P + tok * PP + 3072 + ch;
;             const u32x2 vc = *(const u32x2*)vp; u32x2 vq = {0u, 0u}; if (t > 0) vq = *(const u32x2*)(vp - PP);
;             const f32x4 vcf = {bflo(vc.x), bfhi(vc.x), bflo(vc.y), bfhi(vc.y)}, vqf = {bflo(vq.x), bfhi(vq.x), bflo(vq.y), bfhi(vq.y)};
;             const f32x4 v4 = vcf + (vqf - vcf) * *(const LAS f32x4*)(par + j4);
;             const float bon = sp.bon[tok * 8 + h];
;             const u32x2 gr = *(const u32x2*)(sp.P + tok * PP + 3584 + ch);
;             const f32x4 yo = dlt * rs * *(const LAS f32x4*)(par + 64 + j4) + *(const LAS f32x4*)(par + 128 + j4) + v4 * bon;
;             u32x2 o; o.x = pk2(yo[0] * silu(bflo(gr.x)), yo[1] * silu(bfhi(gr.x))); o.y = pk2(yo[2] * silu(bflo(gr.y)), yo[3] * silu(bfhi(gr.y)));
;             *(u32x2*)(sp.mixed + tok * 1024 + 512 + ch) = o;
.LBB0_344:
	v_add_u32_e32 v2, s6, v28
	v_ashrrev_i32_e32 v3, 31, v2
	v_lshlrev_b64 v[4:5], 11, v[2:3]
	v_lshl_add_u64 v[6:7], v[22:23], 0, v[4:5]
	global_load_dwordx2 v[4:5], v[6:7], off offset:1024
	ds_read_b128 v[8:11], v32
	v_add_u32_e32 v33, s6, v27
	v_mov_b32_e32 v16, 0
	v_mov_b32_e32 v17, 0
	s_waitcnt vmcnt(0) lgkmcnt(0)
	v_lshlrev_b32_e32 v12, 16, v4
	v_and_b32_e32 v13, 0xffff0000, v4
	v_lshlrev_b32_e32 v4, 16, v5
	v_and_b32_e32 v5, 0xffff0000, v5
	v_pk_add_f32 v[8:9], v[8:9], v[12:13]
	v_pk_add_f32 v[10:11], v[10:11], v[4:5]
	v_mov_b32_e32 v4, v8
	v_mov_b32_e32 v5, v10
	v_mov_b32_e32 v12, v9
	v_mov_b32_e32 v13, v11
	v_pk_add_f32 v[4:5], v[4:5], v[12:13]
	v_mov_b64_e32 v[12:13], s[68:69]
	v_add_f32_e32 v0, v4, v5
	v_mad_i64_i32 v[12:13], s[2:3], v2, s76, v[12:13]
	s_nop 0
	v_add_f32_dpp v0, v0, v0 quad_perm:[1,0,3,2] row_mask:0xf bank_mask:0xf bound_ctrl:1
	s_nop 1
	v_add_f32_dpp v0, v0, v0 quad_perm:[2,3,0,1] row_mask:0xf bank_mask:0xf bound_ctrl:1
	s_nop 1
	v_add_f32_dpp v0, v0, v0 row_half_mirror row_mask:0xf bank_mask:0xf bound_ctrl:1
	s_nop 1
	v_add_f32_dpp v0, v0, v0 row_mirror row_mask:0xf bank_mask:0xf bound_ctrl:1
	v_fmamk_f32 v11, v0, 0xbc800000, v11
	v_fmamk_f32 v9, v0, 0xbc800000, v9
	v_fmac_f32_e32 v10, 0xbc800000, v0
	v_fmac_f32_e32 v8, 0xbc800000, v0
	v_mul_f32_e32 v0, v9, v9
	v_mul_f32_e32 v4, v11, v11
	v_fmac_f32_e32 v0, v8, v8
	v_fmac_f32_e32 v4, v10, v10
	v_add_f32_e32 v0, v0, v4
	v_mov_b32_e32 v4, 0
	s_nop 0
	v_add_f32_dpp v0, v0, v0 quad_perm:[1,0,3,2] row_mask:0xf bank_mask:0xf bound_ctrl:1
	s_nop 1
	v_add_f32_dpp v0, v0, v0 quad_perm:[2,3,0,1] row_mask:0xf bank_mask:0xf bound_ctrl:1
	s_nop 1
	v_add_f32_dpp v5, v0, v0 row_half_mirror row_mask:0xf bank_mask:0xf bound_ctrl:1
	v_lshlrev_b32_e32 v0, 1, v18
	v_lshl_add_u64 v[12:13], v[12:13], 0, v[0:1]
	v_add_co_u32_e32 v14, vcc, 0x1000, v12
	v_mov_b32_dpp v24, v5 row_mirror row_mask:0xf bank_mask:0xf bound_ctrl:1
	s_nop 0
	v_addc_co_u32_e32 v15, vcc, 0, v13, vcc
	global_load_dwordx2 v[14:15], v[14:15], off offset:2048
	v_cmp_lt_i32_e32 vcc, 0, v33
	s_and_saveexec_b64 s[2:3], vcc
	s_cbranch_execz .LBB0_346
	v_lshl_add_u64 v[16:17], v[12:13], 0, s[60:61]
	v_add_co_u32_e32 v16, vcc, 0xffffdf80, v16
	s_nop 1
	v_addc_co_u32_e32 v17, vcc, -1, v17, vcc
	global_load_dwordx2 v[16:17], v[16:17], off
.LBB0_346:
	s_or_b64 exec, exec, s[2:3]
	v_add_f32_e32 v5, v5, v24
	v_fmamk_f32 v5, v5, 0x3c800000, v214
	v_rsq_f32_e32 v24, v5
	s_waitcnt vmcnt(0) lgkmcnt(0)
	v_lshlrev_b32_e32 v34, 16, v14
	v_and_b32_e32 v35, 0xffff0000, v14
	v_lshlrev_b32_e32 v36, 16, v15
	v_and_b32_e32 v37, 0xffff0000, v15
	v_lshlrev_b32_e32 v5, 16, v16
	v_and_b32_e32 v14, 0xffff0000, v16
	v_lshlrev_b32_e32 v15, 16, v17
	v_and_b32_e32 v16, 0xffff0000, v17
	v_sub_f32_e32 v39, v16, v37
	v_sub_f32_e32 v38, v15, v36
	v_sub_f32_e32 v41, v14, v35
	ds_read_b128 v[14:17], v26 offset:41984
	v_sub_f32_e32 v40, v5, v34
	v_add_co_u32_e32 v12, vcc, s21, v12
	v_add_u32_e32 v5, 4, v33
	s_waitcnt lgkmcnt(0)
	v_pk_fma_f32 v[34:35], v[14:15], v[40:41], v[34:35]
	v_lshlrev_b64 v[14:15], 5, v[2:3]
	v_lshl_add_u64 v[14:15], s[0:1], 0, v[14:15]
	v_addc_co_u32_e32 v13, vcc, 0, v13, vcc
	v_pk_fma_f32 v[16:17], v[16:17], v[38:39], v[36:37]
	global_load_dword v36, v[14:15], off
	global_load_dwordx2 v[38:39], v[12:13], off offset:3072
	v_pk_mul_f32 v[40:41], v[10:11], v[24:25] op_sel_hi:[1,0]
	v_pk_mul_f32 v[24:25], v[8:9], v[24:25] op_sel_hi:[1,0]
	ds_read_b128 v[8:11], v26 offset:42240
	ds_read_b128 v[12:15], v26 offset:42496
	s_waitcnt lgkmcnt(0)
	v_pk_fma_f32 v[8:9], v[24:25], v[8:9], v[12:13]
	v_pk_fma_f32 v[10:11], v[40:41], v[10:11], v[14:15]
	s_waitcnt vmcnt(0)
	v_pk_fma_f32 v[8:9], v[36:37], v[34:35], v[8:9] op_sel_hi:[0,1,1]
	v_lshlrev_b32_e32 v12, 16, v38
	v_mul_f32_e32 v3, 0xbfb8aa3b, v12
	v_exp_f32_e32 v3, v3
	v_and_b32_e32 v13, 0xffff0000, v38
	v_pk_fma_f32 v[10:11], v[36:37], v[16:17], v[10:11] op_sel_hi:[0,1,1]
	v_add_f32_e32 v3, 1.0, v3
	v_rcp_f32_e32 v14, v3
	v_mul_f32_e32 v3, 0xbfb8aa3b, v13
	v_exp_f32_e32 v3, v3
	s_nop 0
	v_add_f32_e32 v3, 1.0, v3
	v_rcp_f32_e32 v15, v3
	s_nop 0
	v_pk_mul_f32 v[12:13], v[14:15], v[12:13]
	s_nop 0
	v_pk_mul_f32 v[8:9], v[12:13], v[8:9]
	v_lshlrev_b32_e32 v12, 16, v39
	v_mul_f32_e32 v3, 0xbfb8aa3b, v12
	v_exp_f32_e32 v3, v3
	v_and_b32_e32 v13, 0xffff0000, v39
	v_cvt_pk_bf16_f32 v8, v8, v9
	v_add_f32_e32 v3, 1.0, v3
	v_rcp_f32_e32 v14, v3
	v_mul_f32_e32 v3, 0xbfb8aa3b, v13
	v_exp_f32_e32 v3, v3
	s_nop 0
	v_add_f32_e32 v3, 1.0, v3
	v_rcp_f32_e32 v15, v3
	s_nop 0
	v_pk_mul_f32 v[12:13], v[14:15], v[12:13]
	s_nop 0
	v_pk_mul_f32 v[10:11], v[12:13], v[10:11]
	s_nop 0
	v_cvt_pk_bf16_f32 v9, v10, v11
	global_store_dwordx2 v[6:7], v[8:9], off offset:1024
	v_add_u32_e32 v8, 4, v2
	v_ashrrev_i32_e32 v9, 31, v8
	v_lshlrev_b64 v[6:7], 11, v[8:9]
	v_lshl_add_u64 v[6:7], v[22:23], 0, v[6:7]
	global_load_dwordx2 v[14:15], v[6:7], off offset:1024
	ds_read_b128 v[10:13], v32 offset:1024
	s_waitcnt vmcnt(0) lgkmcnt(0)
	v_lshlrev_b32_e32 v16, 16, v14
	v_and_b32_e32 v17, 0xffff0000, v14
	v_lshlrev_b32_e32 v14, 16, v15
	v_and_b32_e32 v15, 0xffff0000, v15
	v_pk_add_f32 v[10:11], v[10:11], v[16:17]
	v_pk_add_f32 v[12:13], v[12:13], v[14:15]
	v_mov_b32_e32 v14, v10
	v_mov_b32_e32 v15, v12
	v_mov_b32_e32 v16, v11
	v_mov_b32_e32 v17, v13
	v_pk_add_f32 v[14:15], v[14:15], v[16:17]
	s_nop 0
	v_add_f32_e32 v3, v14, v15
	s_nop 1
	v_add_f32_dpp v3, v3, v3 quad_perm:[1,0,3,2] row_mask:0xf bank_mask:0xf bound_ctrl:1
	s_nop 1
	v_add_f32_dpp v3, v3, v3 quad_perm:[2,3,0,1] row_mask:0xf bank_mask:0xf bound_ctrl:1
	s_nop 1
	v_add_f32_dpp v3, v3, v3 row_half_mirror row_mask:0xf bank_mask:0xf bound_ctrl:1
	s_nop 1
	v_add_f32_dpp v3, v3, v3 row_mirror row_mask:0xf bank_mask:0xf bound_ctrl:1
	v_fmamk_f32 v13, v3, 0xbc800000, v13
	v_fmamk_f32 v11, v3, 0xbc800000, v11
	v_fmac_f32_e32 v12, 0xbc800000, v3
	v_fmac_f32_e32 v10, 0xbc800000, v3
	v_mul_f32_e32 v3, v11, v11
	v_mul_f32_e32 v14, v13, v13
	v_fmac_f32_e32 v3, v10, v10
	v_fmac_f32_e32 v14, v12, v12
	v_add_f32_e32 v3, v3, v14
	v_mov_b64_e32 v[14:15], s[68:69]
	v_mad_i64_i32 v[14:15], s[2:3], v8, s76, v[14:15]
	v_lshl_add_u64 v[24:25], v[14:15], 0, v[0:1]
	v_add_co_u32_e32 v16, vcc, 0x1000, v24
	v_add_f32_dpp v3, v3, v3 quad_perm:[1,0,3,2] row_mask:0xf bank_mask:0xf bound_ctrl:1
	s_nop 0
	v_addc_co_u32_e32 v17, vcc, 0, v25, vcc
	global_load_dwordx2 v[16:17], v[16:17], off offset:2048
	v_add_f32_dpp v3, v3, v3 quad_perm:[2,3,0,1] row_mask:0xf bank_mask:0xf bound_ctrl:1
	v_cmp_lt_i32_e32 vcc, 0, v5
	v_mov_b32_e32 v5, 0
	v_add_f32_dpp v3, v3, v3 row_half_mirror row_mask:0xf bank_mask:0xf bound_ctrl:1
	s_nop 1
	v_mov_b32_dpp v34, v3 row_mirror row_mask:0xf bank_mask:0xf bound_ctrl:1
	s_and_saveexec_b64 s[2:3], vcc
	s_cbranch_execz .LBB0_348
	v_lshl_add_u64 v[4:5], v[24:25], 0, s[60:61]
	v_add_co_u32_e32 v4, vcc, 0xffffdf80, v4
	s_nop 1
	v_addc_co_u32_e32 v5, vcc, -1, v5, vcc
	global_load_dwordx2 v[4:5], v[4:5], off
; #define LAS __attribute__((address_space(3)))
; __device__ __forceinline__ unsigned pk2(float lo, float hi) { f32x2 v = {lo, hi}; bf16x2_t b = __builtin_convertvector(v, bf16x2_t); return __builtin_bit_cast(unsigned, b); }
; __device__ __forceinline__ float bflo(unsigned u) { return __uint_as_float(u << 16); }
; __device__ __forceinline__ float bfhi(unsigned u) { return __uint_as_float(u & 0xffff0000u); }
; __device__ __forceinline__ float silu(float g) { return g * __builtin_amdgcn_rcpf(1.0f + __expf(-g)); }
; __device__ __forceinline__ void scan_pass2(const ScanP& sp, int b, int h, int seg, LAS unsigned char* lds) {
;     ...
;         for (int it = 0; it < 8; ++it) {
;             const int item = it * 64 + lane, tt = item >> 4, jg = item & 15, j4 = 4 * jg, ch = h * 64 + j4;
;             const int t = t0 + tt; const size_t tok = (size_t)(tok0 + t);
;             const u32x2 y0 = *(const u32x2*)(sp.mixed + tok * 1024 + 512 + ch);
;             const f32x4 dy = *(const LAS f32x4*)(ybw + tt * 64 + j4);
;             const f32x4 y = {bflo(y0.x) + dy[0], bfhi(y0.x) + dy[1], bflo(y0.y) + dy[2], bfhi(y0.y) + dy[3]};
;             const float mean = red16((y[0] + y[1]) + (y[2] + y[3])) * (1.0f / 64.0f);
;             const f32x4 dlt = y - mean;
;             const float var = red16((dlt[0] * dlt[0] + dlt[1] * dlt[1]) + (dlt[2] * dlt[2] + dlt[3] * dlt[3])) * (1.0f / 64.0f);
;             const float rs = __builtin_amdgcn_rsqf(var + 64e-5f);
;             const bf16_t* vp = sp.P + tok * PP + 3072 + ch;
;             const u32x2 vc = *(const u32x2*)vp; u32x2 vq = {0u, 0u}; if (t > 0) vq = *(const u32x2*)(vp - PP);
;             const f32x4 vcf = {bflo(vc.x), bfhi(vc.x), bflo(vc.y), bfhi(vc.y)}, vqf = {bflo(vq.x), bfhi(vq.x), bflo(vq.y), bfhi(vq.y)};
;             const f32x4 v4 = vcf + (vqf - vcf) * *(const LAS f32x4*)(par + j4);
;             const float bon = sp.bon[tok * 8 + h];
;             const u32x2 gr = *(const u32x2*)(sp.P + tok * PP + 3584 + ch);
;             const f32x4 yo = dlt * rs * *(const LAS f32x4*)(par + 64 + j4) + *(const LAS f32x4*)(par + 128 + j4) + v4 * bon;
;             u32x2 o; o.x = pk2(yo[0] * silu(bflo(gr.x)), yo[1] * silu(bfhi(gr.x))); o.y = pk2(yo[2] * silu(bflo(gr.y)), yo[3] * silu(bfhi(gr.y)));
;             *(u32x2*)(sp.mixed + tok * 1024 + 512 + ch) = o;
.LBB0_348:
	s_or_b64 exec, exec, s[2:3]
	v_add_f32_e32 v3, v3, v34
	ds_read_b128 v[34:37], v26 offset:41984
	v_fmamk_f32 v3, v3, 0x3c800000, v214
	v_rsq_f32_e32 v24, v3
	s_waitcnt vmcnt(0) lgkmcnt(0)
	v_lshlrev_b32_e32 v38, 16, v16
	v_and_b32_e32 v39, 0xffff0000, v16
	v_lshlrev_b32_e32 v16, 16, v17
	v_and_b32_e32 v17, 0xffff0000, v17
	v_lshlrev_b32_e32 v3, 16, v4
	v_and_b32_e32 v25, 0xffff0000, v4
	v_lshlrev_b32_e32 v4, 16, v5
	v_and_b32_e32 v5, 0xffff0000, v5
	v_lshlrev_b64 v[8:9], 5, v[8:9]
	v_sub_f32_e32 v5, v5, v17
	v_sub_f32_e32 v4, v4, v16
	v_lshl_add_u64 v[8:9], s[0:1], 0, v[8:9]
	v_pk_fma_f32 v[4:5], v[36:37], v[4:5], v[16:17]
	global_load_dword v16, v[8:9], off
	v_lshl_add_u64 v[8:9], v[14:15], 0, v[0:1]
	v_add_co_u32_e32 v8, vcc, s21, v8
	v_sub_f32_e32 v41, v25, v39
	s_nop 0
	v_addc_co_u32_e32 v9, vcc, 0, v9, vcc
	global_load_dwordx2 v[36:37], v[8:9], off offset:3072
	v_sub_f32_e32 v40, v3, v38
	v_pk_fma_f32 v[34:35], v[34:35], v[40:41], v[38:39]
	v_pk_mul_f32 v[38:39], v[12:13], v[24:25] op_sel_hi:[1,0]
	v_pk_mul_f32 v[24:25], v[10:11], v[24:25] op_sel_hi:[1,0]
	ds_read_b128 v[8:11], v26 offset:42240
	ds_read_b128 v[12:15], v26 offset:42496
	s_waitcnt lgkmcnt(0)
	v_pk_fma_f32 v[10:11], v[38:39], v[10:11], v[14:15]
	v_pk_fma_f32 v[8:9], v[24:25], v[8:9], v[12:13]
	v_add_u32_e32 v24, 8, v33
	v_mov_b32_e32 v25, 0
	s_waitcnt vmcnt(0)
	v_pk_fma_f32 v[4:5], v[16:17], v[4:5], v[10:11] op_sel_hi:[0,1,1]
	v_pk_fma_f32 v[8:9], v[16:17], v[34:35], v[8:9] op_sel_hi:[0,1,1]
	v_lshlrev_b32_e32 v10, 16, v36
	v_mul_f32_e32 v3, 0xbfb8aa3b, v10
	v_exp_f32_e32 v3, v3
	v_and_b32_e32 v11, 0xffff0000, v36
	v_add_f32_e32 v3, 1.0, v3
	v_rcp_f32_e32 v12, v3
	v_mul_f32_e32 v3, 0xbfb8aa3b, v11
	v_exp_f32_e32 v3, v3
	s_nop 0
	v_add_f32_e32 v3, 1.0, v3
	v_rcp_f32_e32 v13, v3
	s_nop 0
	v_pk_mul_f32 v[10:11], v[12:13], v[10:11]
	s_nop 0
	v_pk_mul_f32 v[8:9], v[10:11], v[8:9]
	v_lshlrev_b32_e32 v10, 16, v37
	v_mul_f32_e32 v3, 0xbfb8aa3b, v10
	v_exp_f32_e32 v3, v3
	v_and_b32_e32 v11, 0xffff0000, v37
	v_cvt_pk_bf16_f32 v8, v8, v9
	v_add_f32_e32 v3, 1.0, v3
	v_rcp_f32_e32 v12, v3
	v_mul_f32_e32 v3, 0xbfb8aa3b, v11
	v_exp_f32_e32 v3, v3
	s_nop 0
	v_add_f32_e32 v3, 1.0, v3
	v_rcp_f32_e32 v13, v3
	s_nop 0
	v_pk_mul_f32 v[10:11], v[12:13], v[10:11]
	s_nop 0
	v_pk_mul_f32 v[4:5], v[10:11], v[4:5]
	s_nop 0
	v_cvt_pk_bf16_f32 v9, v4, v5
	global_store_dwordx2 v[6:7], v[8:9], off offset:1024
	v_add_u32_e32 v8, 8, v2
	v_ashrrev_i32_e32 v9, 31, v8
	v_lshlrev_b64 v[4:5], 11, v[8:9]
	v_lshl_add_u64 v[6:7], v[22:23], 0, v[4:5]
	global_load_dwordx2 v[4:5], v[6:7], off offset:1024
	ds_read_b128 v[10:13], v32 offset:2048
	s_waitcnt vmcnt(0) lgkmcnt(0)
	v_lshlrev_b32_e32 v14, 16, v4
	v_and_b32_e32 v15, 0xffff0000, v4
	v_lshlrev_b32_e32 v4, 16, v5
	v_and_b32_e32 v5, 0xffff0000, v5
	v_pk_add_f32 v[10:11], v[10:11], v[14:15]
	v_pk_add_f32 v[12:13], v[12:13], v[4:5]
	v_mov_b32_e32 v4, v10
	v_mov_b32_e32 v5, v12
	v_mov_b32_e32 v14, v11
	v_mov_b32_e32 v15, v13
	v_pk_add_f32 v[4:5], v[4:5], v[14:15]
	v_mov_b64_e32 v[14:15], s[68:69]
	v_mad_i64_i32 v[14:15], s[2:3], v8, s76, v[14:15]
	v_lshl_add_u64 v[14:15], v[14:15], 0, v[0:1]
	v_add_co_u32_e32 v16, vcc, 0x1000, v14
	v_add_f32_e32 v3, v4, v5
	s_nop 0
	v_addc_co_u32_e32 v17, vcc, 0, v15, vcc
	global_load_dwordx2 v[16:17], v[16:17], off offset:2048
	v_add_f32_dpp v3, v3, v3 quad_perm:[1,0,3,2] row_mask:0xf bank_mask:0xf bound_ctrl:1
	v_cmp_lt_i32_e32 vcc, 0, v24
	v_mov_b32_e32 v24, 0
	v_add_f32_dpp v3, v3, v3 quad_perm:[2,3,0,1] row_mask:0xf bank_mask:0xf bound_ctrl:1
	s_nop 1
	v_add_f32_dpp v3, v3, v3 row_half_mirror row_mask:0xf bank_mask:0xf bound_ctrl:1
	s_nop 1
	v_add_f32_dpp v3, v3, v3 row_mirror row_mask:0xf bank_mask:0xf bound_ctrl:1
	v_fmamk_f32 v13, v3, 0xbc800000, v13
	v_fmamk_f32 v11, v3, 0xbc800000, v11
	v_fmac_f32_e32 v12, 0xbc800000, v3
	v_fmac_f32_e32 v10, 0xbc800000, v3
	v_mul_f32_e32 v3, v11, v11
	v_mul_f32_e32 v4, v13, v13
	v_fmac_f32_e32 v3, v10, v10
	v_fmac_f32_e32 v4, v12, v12
	v_add_f32_e32 v3, v3, v4
	v_mov_b32_e32 v4, 0
	s_nop 0
	v_add_f32_dpp v3, v3, v3 quad_perm:[1,0,3,2] row_mask:0xf bank_mask:0xf bound_ctrl:1
	s_nop 1
	v_add_f32_dpp v3, v3, v3 quad_perm:[2,3,0,1] row_mask:0xf bank_mask:0xf bound_ctrl:1
	s_nop 1
	v_add_f32_dpp v3, v3, v3 row_half_mirror row_mask:0xf bank_mask:0xf bound_ctrl:1
	s_nop 1
	v_mov_b32_dpp v5, v3 row_mirror row_mask:0xf bank_mask:0xf bound_ctrl:1
	s_and_saveexec_b64 s[2:3], vcc
	s_cbranch_execz .LBB0_350
	v_lshl_add_u64 v[24:25], v[14:15], 0, s[60:61]
	v_add_co_u32_e32 v24, vcc, 0xffffdf80, v24
	s_nop 1
	v_addc_co_u32_e32 v25, vcc, -1, v25, vcc
	global_load_dwordx2 v[24:25], v[24:25], off
; #define LAS __attribute__((address_space(3)))
; __device__ __forceinline__ unsigned pk2(float lo, float hi) { f32x2 v = {lo, hi}; bf16x2_t b = __builtin_convertvector(v, bf16x2_t); return __builtin_bit_cast(unsigned, b); }
; __device__ __forceinline__ float bflo(unsigned u) { return __uint_as_float(u << 16); }
; __device__ __forceinline__ float bfhi(unsigned u) { return __uint_as_float(u & 0xffff0000u); }
; __device__ __forceinline__ float silu(float g) { return g * __builtin_amdgcn_rcpf(1.0f + __expf(-g)); }
; __device__ __forceinline__ void scan_pass2(const ScanP& sp, int b, int h, int seg, LAS unsigned char* lds) {
;     ...
;         for (int it = 0; it < 8; ++it) {
;             const int item = it * 64 + lane, tt = item >> 4, jg = item & 15, j4 = 4 * jg, ch = h * 64 + j4;
;             const int t = t0 + tt; const size_t tok = (size_t)(tok0 + t);
;             const u32x2 y0 = *(const u32x2*)(sp.mixed + tok * 1024 + 512 + ch);
;             const f32x4 dy = *(const LAS f32x4*)(ybw + tt * 64 + j4);
;             const f32x4 y = {bflo(y0.x) + dy[0], bfhi(y0.x) + dy[1], bflo(y0.y) + dy[2], bfhi(y0.y) + dy[3]};
;             const float mean = red16((y[0] + y[1]) + (y[2] + y[3])) * (1.0f / 64.0f);
;             const f32x4 dlt = y - mean;
;             const float var = red16((dlt[0] * dlt[0] + dlt[1] * dlt[1]) + (dlt[2] * dlt[2] + dlt[3] * dlt[3])) * (1.0f / 64.0f);
;             const float rs = __builtin_amdgcn_rsqf(var + 64e-5f);
;             const bf16_t* vp = sp.P + tok * PP + 3072 + ch;
;             const u32x2 vc = *(const u32x2*)vp; u32x2 vq = {0u, 0u}; if (t > 0) vq = *(const u32x2*)(vp - PP);
;             const f32x4 vcf = {bflo(vc.x), bfhi(vc.x), bflo(vc.y), bfhi(vc.y)}, vqf = {bflo(vq.x), bfhi(vq.x), bflo(vq.y), bfhi(vq.y)};
;             const f32x4 v4 = vcf + (vqf - vcf) * *(const LAS f32x4*)(par + j4);
;             const float bon = sp.bon[tok * 8 + h];
;             const u32x2 gr = *(const u32x2*)(sp.P + tok * PP + 3584 + ch);
;             const f32x4 yo = dlt * rs * *(const LAS f32x4*)(par + 64 + j4) + *(const LAS f32x4*)(par + 128 + j4) + v4 * bon;
;             u32x2 o; o.x = pk2(yo[0] * silu(bflo(gr.x)), yo[1] * silu(bfhi(gr.x))); o.y = pk2(yo[2] * silu(bflo(gr.y)), yo[3] * silu(bfhi(gr.y)));
;             *(u32x2*)(sp.mixed + tok * 1024 + 512 + ch) = o;
.LBB0_350:
	s_or_b64 exec, exec, s[2:3]
	ds_read_b128 v[34:37], v26 offset:41984
	v_add_f32_e32 v3, v3, v5
	v_fmamk_f32 v3, v3, 0x3c800000, v214
	v_rsq_f32_e32 v38, v3
	s_waitcnt vmcnt(0) lgkmcnt(0)
	v_lshlrev_b32_e32 v40, 16, v16
	v_and_b32_e32 v41, 0xffff0000, v16
	v_lshlrev_b32_e32 v16, 16, v17
	v_and_b32_e32 v17, 0xffff0000, v17
	v_lshlrev_b32_e32 v3, 16, v24
	v_and_b32_e32 v5, 0xffff0000, v24
	v_lshlrev_b32_e32 v24, 16, v25
	v_and_b32_e32 v25, 0xffff0000, v25
	v_lshlrev_b64 v[8:9], 5, v[8:9]
	v_sub_f32_e32 v25, v25, v17
	v_sub_f32_e32 v24, v24, v16
	v_lshl_add_u64 v[8:9], s[0:1], 0, v[8:9]
	v_pk_fma_f32 v[16:17], v[36:37], v[24:25], v[16:17]
	global_load_dword v24, v[8:9], off
	v_add_co_u32_e32 v8, vcc, s21, v14
	v_sub_f32_e32 v43, v5, v41
	s_nop 0
	v_addc_co_u32_e32 v9, vcc, 0, v15, vcc
	global_load_dwordx2 v[36:37], v[8:9], off offset:3072
	v_sub_f32_e32 v42, v3, v40
	v_pk_fma_f32 v[34:35], v[34:35], v[42:43], v[40:41]
	v_pk_mul_f32 v[40:41], v[12:13], v[38:39] op_sel_hi:[1,0]
	v_pk_mul_f32 v[38:39], v[10:11], v[38:39] op_sel_hi:[1,0]
	ds_read_b128 v[8:11], v26 offset:42240
	ds_read_b128 v[12:15], v26 offset:42496
	v_add_u32_e32 v5, 12, v33
	s_waitcnt lgkmcnt(0)
	v_pk_fma_f32 v[8:9], v[38:39], v[8:9], v[12:13]
	v_pk_fma_f32 v[10:11], v[40:41], v[10:11], v[14:15]
	s_waitcnt vmcnt(0)
	v_pk_fma_f32 v[8:9], v[24:25], v[34:35], v[8:9] op_sel_hi:[0,1,1]
	v_pk_fma_f32 v[10:11], v[24:25], v[16:17], v[10:11] op_sel_hi:[0,1,1]
	v_lshlrev_b32_e32 v12, 16, v36
	v_mul_f32_e32 v3, 0xbfb8aa3b, v12
	v_exp_f32_e32 v3, v3
	v_and_b32_e32 v13, 0xffff0000, v36
	v_add_f32_e32 v3, 1.0, v3
	v_rcp_f32_e32 v14, v3
	v_mul_f32_e32 v3, 0xbfb8aa3b, v13
	v_exp_f32_e32 v3, v3
	s_nop 0
	v_add_f32_e32 v3, 1.0, v3
	v_rcp_f32_e32 v15, v3
	s_nop 0
	v_pk_mul_f32 v[12:13], v[14:15], v[12:13]
	s_nop 0
	v_pk_mul_f32 v[8:9], v[12:13], v[8:9]
	v_lshlrev_b32_e32 v12, 16, v37
	v_mul_f32_e32 v3, 0xbfb8aa3b, v12
	v_exp_f32_e32 v3, v3
	v_and_b32_e32 v13, 0xffff0000, v37
	v_cvt_pk_bf16_f32 v8, v8, v9
	v_add_f32_e32 v3, 1.0, v3
	v_rcp_f32_e32 v14, v3
	v_mul_f32_e32 v3, 0xbfb8aa3b, v13
	v_exp_f32_e32 v3, v3
	s_nop 0
	v_add_f32_e32 v3, 1.0, v3
	v_rcp_f32_e32 v15, v3
	s_nop 0
	v_pk_mul_f32 v[12:13], v[14:15], v[12:13]
	s_nop 0
	v_pk_mul_f32 v[10:11], v[12:13], v[10:11]
	s_nop 0
	v_cvt_pk_bf16_f32 v9, v10, v11
	global_store_dwordx2 v[6:7], v[8:9], off offset:1024
	v_add_u32_e32 v6, 12, v2
	v_ashrrev_i32_e32 v7, 31, v6
	v_lshlrev_b64 v[2:3], 11, v[6:7]
	v_lshl_add_u64 v[2:3], v[22:23], 0, v[2:3]
	global_load_dwordx2 v[12:13], v[2:3], off offset:1024
	ds_read_b128 v[8:11], v32 offset:3072
	s_waitcnt vmcnt(0) lgkmcnt(0)
	v_lshlrev_b32_e32 v14, 16, v12
	v_and_b32_e32 v15, 0xffff0000, v12
	v_lshlrev_b32_e32 v12, 16, v13
	v_and_b32_e32 v13, 0xffff0000, v13
	v_pk_add_f32 v[8:9], v[8:9], v[14:15]
	v_pk_add_f32 v[10:11], v[10:11], v[12:13]
	v_mov_b32_e32 v12, v8
	v_mov_b32_e32 v13, v10
	v_mov_b32_e32 v14, v9
	v_mov_b32_e32 v15, v11
	v_pk_add_f32 v[12:13], v[12:13], v[14:15]
	s_nop 0
	v_add_f32_e32 v12, v12, v13
	s_nop 1
	v_add_f32_dpp v12, v12, v12 quad_perm:[1,0,3,2] row_mask:0xf bank_mask:0xf bound_ctrl:1
	s_nop 1
	v_add_f32_dpp v12, v12, v12 quad_perm:[2,3,0,1] row_mask:0xf bank_mask:0xf bound_ctrl:1
	s_nop 1
	v_add_f32_dpp v12, v12, v12 row_half_mirror row_mask:0xf bank_mask:0xf bound_ctrl:1
	s_nop 1
	v_add_f32_dpp v12, v12, v12 row_mirror row_mask:0xf bank_mask:0xf bound_ctrl:1
	v_fmamk_f32 v11, v12, 0xbc800000, v11
	v_fmamk_f32 v9, v12, 0xbc800000, v9
	v_fmac_f32_e32 v10, 0xbc800000, v12
	v_fmac_f32_e32 v8, 0xbc800000, v12
	v_mul_f32_e32 v12, v9, v9
	v_mul_f32_e32 v13, v11, v11
	v_fmac_f32_e32 v12, v8, v8
	v_fmac_f32_e32 v13, v10, v10
	v_add_f32_e32 v12, v12, v13
	s_nop 1
	v_add_f32_dpp v12, v12, v12 quad_perm:[1,0,3,2] row_mask:0xf bank_mask:0xf bound_ctrl:1
	s_nop 1
	v_add_f32_dpp v12, v12, v12 quad_perm:[2,3,0,1] row_mask:0xf bank_mask:0xf bound_ctrl:1
	s_nop 1
	v_add_f32_dpp v24, v12, v12 row_half_mirror row_mask:0xf bank_mask:0xf bound_ctrl:1
	v_mov_b64_e32 v[12:13], s[68:69]
	v_mad_i64_i32 v[12:13], s[2:3], v6, s76, v[12:13]
	v_lshl_add_u64 v[16:17], v[12:13], 0, v[0:1]
	v_add_co_u32_e32 v14, vcc, 0x1000, v16
	v_mov_b32_dpp v25, v24 row_mirror row_mask:0xf bank_mask:0xf bound_ctrl:1
	s_nop 0
	v_addc_co_u32_e32 v15, vcc, 0, v17, vcc
	global_load_dwordx2 v[14:15], v[14:15], off offset:2048
	v_cmp_lt_i32_e32 vcc, 0, v5
	v_mov_b32_e32 v5, 0
	s_and_saveexec_b64 s[2:3], vcc
	s_cbranch_execz .LBB0_343
	v_lshl_add_u64 v[4:5], v[16:17], 0, s[60:61]
	v_add_co_u32_e32 v4, vcc, 0xffffdf80, v4
	s_nop 1
	v_addc_co_u32_e32 v5, vcc, -1, v5, vcc
	global_load_dwordx2 v[4:5], v[4:5], off
	s_branch .LBB0_343

; __device__ __forceinline__ unsigned cvt_pk_bf16(float lo, float hi) { unsigned r; asm volatile("v_cvt_pk_bf16_f32 %0, %1, %2" : "=v"(r) : "v"(lo), "v"(hi)); return r; }
;     __device__ __forceinline__ void operator()(const f32x4 (&acc)[2][2][4][2], const Unit& u, int wr, int wc, int fr, int fq) const {
;         const int row0 = u.pm * BM + wr * 64 + fr;
;         float rsv[2][4];
; #pragma unroll
;         for (int ai = 0; ai < 2; ++ai) {
; #pragma unroll
;             for (int m = 0; m < 4; ++m) {
;                 const int row = row0 + ai * HALF + m * 16;
;                 const f32x4 h0 = *((const f32x4*)(hss + (size_t)row * 16) + fq);
;                 float ss = (h0[0] + h0[1]) + (h0[2] + h0[3]);
;                 ss += __shfl_xor(ss, 16); ss += __shfl_xor(ss, 32);
;                 rsv[ai][m] = 1.0f / sqrtf(ss * (1.0f / 1024.0f) + 1e-6f);
;             }
;             asm volatile("" ::: "memory");
;         }
; #pragma unroll
;         for (int ai = 0; ai < 2; ++ai)
; #pragma unroll
;             for (int m = 0; m < 4; ++m) {
;                 const int row = row0 + ai * HALF + m * 16;
;                 const float rs = rsv[ai][m];
;                 if (u.pn < ntile_main) {
;                     bf16_t* rowp = P + (size_t)row * 4160 + u.pn * BM + wc * 32 + 8 * fq;
; #pragma unroll
;                     for (int bj = 0; bj < 2; ++bj) {
;                         const f32x4 v0 = acc[ai][bj][m][0] * rs, v1 = acc[ai][bj][m][1] * rs;
;                         u32x4 w; w.x = cvt_pk_bf16(v0[0], v0[1]); w.y = cvt_pk_bf16(v0[2], v0[3]); w.z = cvt_pk_bf16(v1[0], v1[1]); w.w = cvt_pk_bf16(v1[2], v1[3]);
;                         *(u32x4*)(rowp + bj * HALF) = w;
;                     }
;                 } else {
;                     const int c0 = wc * 32 + 8 * fq;
;                     if (c0 < 72) {
;                         *(f32x4*)(misc + (size_t)row * 80 + c0) = acc[ai][0][m][0] * rs;
;                         *(f32x4*)(misc + (size_t)row * 80 + c0 + 4) = acc[ai][0][m][1] * rs;
;                     }
.LBB0_381:
	v_and_b32_e32 v148, 64, v216
	v_xor_b32_e32 v0, 16, v216
	v_add_u32_e32 v148, 64, v148
	v_cmp_lt_i32_e32 vcc, v0, v148
	v_lshl_add_u32 v160, s46, 8, v139
	v_ashrrev_i32_e32 v161, 31, v160
	v_cndmask_b32_e32 v0, v216, v0, vcc
	v_lshlrev_b32_e32 v173, 2, v0
	v_xor_b32_e32 v0, 32, v216
	v_cmp_lt_i32_e32 vcc, v0, v148
	v_lshlrev_b64 v[148:149], 6, v[160:161]
	v_lshl_add_u64 v[148:149], v[142:143], 0, v[148:149]
	global_load_dwordx4 v[148:151], v[148:149], off
	v_cndmask_b32_e32 v0, v216, v0, vcc
	v_lshlrev_b32_e32 v0, 2, v0
	v_or_b32_e32 v164, 16, v160
	v_ashrrev_i32_e32 v165, 31, v164
	v_or_b32_e32 v158, 32, v160
	v_ashrrev_i32_e32 v159, 31, v158
	v_or_b32_e32 v156, 48, v160
	v_ashrrev_i32_e32 v157, 31, v156
	v_add_u32_e32 v154, 0x80, v160
	v_ashrrev_i32_e32 v155, 31, v154
	s_cmp_gt_i32 s45, 15
	s_cselect_b64 s[8:9], -1, 0
	s_waitcnt vmcnt(0) lgkmcnt(0)
	v_add_f32_e32 v148, v148, v149
	v_add_f32_e32 v149, v150, v151
	v_add_f32_e32 v148, v148, v149
	ds_bpermute_b32 v149, v173, v148
	s_waitcnt lgkmcnt(0)
	v_add_f32_e32 v148, v148, v149
	ds_bpermute_b32 v149, v0, v148
	s_waitcnt lgkmcnt(0)
	v_add_f32_e32 v148, v148, v149
	v_fmamk_f32 v148, v148, 0x3a800000, v211
	v_cmp_gt_f32_e32 vcc, s55, v148
	v_mul_f32_e32 v149, 0x4f800000, v148
	s_nop 0
	v_cndmask_b32_e32 v148, v148, v149, vcc
	v_sqrt_f32_e32 v149, v148
	s_nop 0
	v_add_u32_e32 v150, -1, v149
	v_fma_f32 v151, -v150, v149, v148
	v_cmp_ge_f32_e64 s[0:1], 0, v151
	v_add_u32_e32 v151, 1, v149
	s_nop 0
	v_cndmask_b32_e64 v150, v149, v150, s[0:1]
	v_fma_f32 v149, -v151, v149, v148
	v_cmp_lt_f32_e64 s[0:1], 0, v149
	s_nop 1
	v_cndmask_b32_e64 v149, v150, v151, s[0:1]
	v_mul_f32_e32 v150, 0x37800000, v149
	v_cndmask_b32_e32 v149, v149, v150, vcc
	v_cmp_class_f32_e32 vcc, v148, v212
	s_nop 1
	v_cndmask_b32_e32 v148, v149, v148, vcc
	v_div_scale_f32 v149, s[0:1], v148, v148, 1.0
	v_rcp_f32_e32 v150, v149
	s_mov_b64 s[0:1], -1
	v_fma_f32 v151, -v149, v150, 1.0
	v_fmac_f32_e32 v150, v151, v150
	v_div_scale_f32 v151, vcc, 1.0, v148, 1.0
	v_mul_f32_e32 v152, v151, v150
	v_fma_f32 v153, -v149, v152, v151
	v_fmac_f32_e32 v152, v153, v150
	v_fma_f32 v149, -v149, v152, v151
	v_div_fmas_f32 v149, v149, v150, v152
	v_div_fixup_f32 v162, v149, v148, 1.0
	v_lshlrev_b64 v[148:149], 6, v[164:165]
	v_lshl_add_u64 v[148:149], v[142:143], 0, v[148:149]
	global_load_dwordx4 v[148:151], v[148:149], off
	v_add_u32_e32 v152, 0x90, v160
	v_ashrrev_i32_e32 v153, 31, v152
	s_and_b64 vcc, exec, s[8:9]
	s_waitcnt vmcnt(0) lgkmcnt(0)
	v_add_f32_e32 v148, v148, v149
	v_add_f32_e32 v149, v150, v151
	v_add_f32_e32 v148, v148, v149
	ds_bpermute_b32 v149, v173, v148
	s_waitcnt lgkmcnt(0)
	v_add_f32_e32 v171, v148, v149
	v_lshlrev_b64 v[148:149], 6, v[158:159]
	v_lshl_add_u64 v[148:149], v[142:143], 0, v[148:149]
	global_load_dwordx4 v[148:151], v[148:149], off
	ds_bpermute_b32 v172, v0, v171
	s_waitcnt vmcnt(0) lgkmcnt(0)
	v_add_f32_e32 v148, v148, v149
	v_add_f32_e32 v149, v150, v151
	v_add_f32_e32 v148, v148, v149
	ds_bpermute_b32 v149, v173, v148
	s_waitcnt lgkmcnt(0)
	v_add_f32_e32 v169, v148, v149
	v_lshlrev_b64 v[148:149], 6, v[156:157]
	v_lshl_add_u64 v[148:149], v[142:143], 0, v[148:149]
	global_load_dwordx4 v[148:151], v[148:149], off
	ds_bpermute_b32 v170, v0, v169
	s_waitcnt vmcnt(0) lgkmcnt(0)
	v_add_f32_e32 v148, v148, v149
	v_add_f32_e32 v149, v150, v151
	v_add_f32_e32 v148, v148, v149
	ds_bpermute_b32 v149, v173, v148
	s_waitcnt lgkmcnt(0)
	v_add_f32_e32 v167, v148, v149
	v_lshlrev_b64 v[148:149], 6, v[154:155]
	v_lshl_add_u64 v[148:149], v[142:143], 0, v[148:149]
	global_load_dwordx4 v[148:151], v[148:149], off
	ds_bpermute_b32 v168, v0, v167
	s_waitcnt vmcnt(0) lgkmcnt(0)
	v_add_f32_e32 v148, v148, v149
	v_add_f32_e32 v149, v150, v151
	v_add_f32_e32 v148, v148, v149
	ds_bpermute_b32 v149, v173, v148
	s_waitcnt lgkmcnt(0)
	v_add_f32_e32 v161, v148, v149
	v_lshlrev_b64 v[148:149], 6, v[152:153]
	v_lshl_add_u64 v[148:149], v[142:143], 0, v[148:149]
	global_load_dwordx4 v[148:151], v[148:149], off
	ds_bpermute_b32 v165, v0, v161
	s_waitcnt vmcnt(0) lgkmcnt(0)
	v_add_f32_e32 v148, v148, v149
	v_add_f32_e32 v149, v150, v151
	v_add_f32_e32 v148, v148, v149
	ds_bpermute_b32 v149, v173, v148
	v_add_u32_e32 v150, 0xa0, v160
	v_ashrrev_i32_e32 v151, 31, v150
	s_waitcnt lgkmcnt(0)
	v_add_f32_e32 v155, v148, v149
	v_lshlrev_b64 v[148:149], 6, v[150:151]
	v_lshl_add_u64 v[148:149], v[142:143], 0, v[148:149]
	global_load_dwordx4 v[174:177], v[148:149], off
	ds_bpermute_b32 v157, v0, v155
	s_waitcnt vmcnt(0) lgkmcnt(0)
	v_add_f32_e32 v148, v174, v175
	v_add_f32_e32 v149, v176, v177
	v_add_f32_e32 v148, v148, v149
	ds_bpermute_b32 v149, v173, v148
	s_waitcnt lgkmcnt(0)
	v_add_f32_e32 v151, v148, v149
	v_add_u32_e32 v148, 0xb0, v160
	v_ashrrev_i32_e32 v149, 31, v148
	v_lshlrev_b64 v[174:175], 6, v[148:149]
	v_lshl_add_u64 v[174:175], v[142:143], 0, v[174:175]
	global_load_dwordx4 v[174:177], v[174:175], off
	ds_bpermute_b32 v153, v0, v151
	s_waitcnt vmcnt(0) lgkmcnt(0)
	v_add_f32_e32 v149, v174, v175
	v_add_f32_e32 v159, v176, v177
	v_add_f32_e32 v149, v149, v159
	ds_bpermute_b32 v159, v173, v149
	s_waitcnt lgkmcnt(0)
	v_add_f32_e32 v149, v149, v159
	ds_bpermute_b32 v159, v0, v149
	s_cbranch_vccz .LBB0_385
	s_and_saveexec_b64 s[0:1], s[6:7]
	s_cbranch_execz .LBB0_384
	s_movk_i32 s19, 0x140
	v_pk_mul_f32 v[176:177], v[128:129], v[162:163] op_sel_hi:[1,0]
	v_pk_mul_f32 v[174:175], v[126:127], v[162:163] op_sel_hi:[1,0]
	v_mad_i64_i32 v[178:179], s[28:29], v160, s19, v[140:141]
	global_store_dwordx4 v[178:179], v[174:177], off
	s_nop 1
	v_pk_mul_f32 v[176:177], v[124:125], v[162:163] op_sel_hi:[1,0]
	v_pk_mul_f32 v[174:175], v[122:123], v[162:163] op_sel_hi:[1,0]
	global_store_dwordx4 v[178:179], v[174:177], off offset:16

; __device__ __forceinline__ unsigned cvt_pk_bf16(float lo, float hi) { unsigned r; asm volatile("v_cvt_pk_bf16_f32 %0, %1, %2" : "=v"(r) : "v"(lo), "v"(hi)); return r; }
;     __device__ __forceinline__ void operator()(const f32x4 (&acc)[2][2][4][2], const Unit& u, int wr, int wc, int fr, int fq) const {
;     ...
;                 const int row = row0 + ai * HALF + m * 16;
;                 const f32x4 h0 = *((const f32x4*)(hss + (size_t)row * 16) + fq);
;                 float ss = (h0[0] + h0[1]) + (h0[2] + h0[3]);
;                 ss += __shfl_xor(ss, 16); ss += __shfl_xor(ss, 32);
;                 rsv[ai][m] = 1.0f / sqrtf(ss * (1.0f / 1024.0f) + 1e-6f);
;             }
;             asm volatile("" ::: "memory");
;         }
; #pragma unroll
;         for (int ai = 0; ai < 2; ++ai)
; #pragma unroll
;             for (int m = 0; m < 4; ++m) {
;                 const int row = row0 + ai * HALF + m * 16;
;                 const float rs = rsv[ai][m];
;                 if (u.pn < ntile_main) {
;                     bf16_t* rowp = P + (size_t)row * 4160 + u.pn * BM + wc * 32 + 8 * fq;
; #pragma unroll
;                     for (int bj = 0; bj < 2; ++bj) {
;                         const f32x4 v0 = acc[ai][bj][m][0] * rs, v1 = acc[ai][bj][m][1] * rs;
;                         u32x4 w; w.x = cvt_pk_bf16(v0[0], v0[1]); w.y = cvt_pk_bf16(v0[2], v0[3]); w.z = cvt_pk_bf16(v1[0], v1[1]); w.w = cvt_pk_bf16(v1[2], v1[3]);
;                         *(u32x4*)(rowp + bj * HALF) = w;
;                     }
;                 } else {
;                     const int c0 = wc * 32 + 8 * fq;
;                     if (c0 < 72) {
;                         *(f32x4*)(misc + (size_t)row * 80 + c0) = acc[ai][0][m][0] * rs;
;                         *(f32x4*)(misc + (size_t)row * 80 + c0 + 4) = acc[ai][0][m][1] * rs;
;                     }
.LBB0_385:
	s_andn2_b64 vcc, exec, s[0:1]
	v_lshlrev_b32_e32 v0, 1, v138
	s_cbranch_vccnz .LBB0_387
	v_mov_b64_e32 v[174:175], s[14:15]
	v_mad_i64_i32 v[174:175], s[0:1], v160, s76, v[174:175]
	s_lshl_b32 s0, s45, 8
	s_ashr_i32 s1, s0, 31
	v_lshl_add_u64 v[174:175], s[0:1], 1, v[174:175]
	s_lshl_b32 s92, s40, 1
	v_lshl_add_u64 v[174:175], v[174:175], 0, s[92:93]
	v_lshl_add_u64 v[174:175], v[174:175], 0, v[0:1]
	v_pk_mul_f32 v[128:129], v[128:129], v[162:163] op_sel_hi:[1,0]
	v_pk_mul_f32 v[126:127], v[126:127], v[162:163] op_sel_hi:[1,0]
	v_pk_mul_f32 v[176:177], v[124:125], v[162:163] op_sel_hi:[1,0]
	v_pk_mul_f32 v[124:125], v[122:123], v[162:163] op_sel_hi:[1,0]
	v_cvt_pk_bf16_f32 v122, v126, v127
	v_cvt_pk_bf16_f32 v123, v128, v129
	v_pk_mul_f32 v[120:121], v[120:121], v[162:163] op_sel_hi:[1,0]
	v_cvt_pk_bf16_f32 v124, v124, v125
	v_cvt_pk_bf16_f32 v125, v176, v177
	global_store_dwordx4 v[174:175], v[122:125], off
	v_pk_mul_f32 v[118:119], v[118:119], v[162:163] op_sel_hi:[1,0]
	s_nop 0
	v_pk_mul_f32 v[122:123], v[116:117], v[162:163] op_sel_hi:[1,0]
	v_pk_mul_f32 v[116:117], v[114:115], v[162:163] op_sel_hi:[1,0]
	v_cvt_pk_bf16_f32 v114, v118, v119
	v_cvt_pk_bf16_f32 v115, v120, v121
	s_nop 0
	v_cvt_pk_bf16_f32 v116, v116, v117
	v_cvt_pk_bf16_f32 v117, v122, v123
	global_store_dwordx4 v[174:175], v[114:117], off offset:256
.LBB0_387:
	s_nop 1
	v_add_f32_e32 v114, v171, v172
	v_fmamk_f32 v114, v114, 0x3a800000, v211
	v_mul_f32_e32 v115, 0x4f800000, v114
	v_cmp_gt_f32_e32 vcc, s55, v114
	s_nop 1
	v_cndmask_b32_e32 v114, v114, v115, vcc
	v_sqrt_f32_e32 v115, v114
	s_nop 0
	v_add_u32_e32 v116, -1, v115
	v_fma_f32 v118, -v116, v115, v114
	v_add_u32_e32 v117, 1, v115
	v_cmp_ge_f32_e64 s[0:1], 0, v118
	s_nop 1
	v_cndmask_b32_e64 v116, v115, v116, s[0:1]
	v_fma_f32 v115, -v117, v115, v114
	v_cmp_lt_f32_e64 s[0:1], 0, v115
	s_nop 1
	v_cndmask_b32_e64 v115, v116, v117, s[0:1]
	v_mul_f32_e32 v116, 0x37800000, v115
	v_cndmask_b32_e32 v115, v115, v116, vcc
	v_cmp_class_f32_e32 vcc, v114, v212
	s_nop 1
	v_cndmask_b32_e32 v114, v115, v114, vcc
	v_div_scale_f32 v115, s[0:1], v114, v114, 1.0
	v_rcp_f32_e32 v116, v115
	s_nop 0
	v_fma_f32 v117, -v115, v116, 1.0
	v_fmac_f32_e32 v116, v117, v116
	v_div_scale_f32 v117, vcc, 1.0, v114, 1.0
	v_mul_f32_e32 v118, v117, v116
	v_fma_f32 v119, -v115, v118, v117
	v_fmac_f32_e32 v118, v119, v116
	v_fma_f32 v115, -v115, v118, v117
	v_div_fmas_f32 v115, v115, v116, v118
	v_div_fixup_f32 v114, v115, v114, 1.0
	v_cndmask_b32_e64 v115, 0, 1, s[8:9]
	v_cmp_ne_u32_e64 s[0:1], 1, v115
	s_andn2_b64 vcc, exec, s[8:9]
	s_mov_b64 s[8:9], -1
	s_cbranch_vccnz .LBB0_391
	s_and_saveexec_b64 s[8:9], s[6:7]
	s_cbranch_execz .LBB0_390
	s_movk_i32 s19, 0x140
	v_pk_mul_f32 v[118:119], v[112:113], v[114:115] op_sel_hi:[1,0]
	v_pk_mul_f32 v[116:117], v[110:111], v[114:115] op_sel_hi:[1,0]
	v_mad_i64_i32 v[120:121], s[28:29], v164, s19, v[140:141]
	global_store_dwordx4 v[120:121], v[116:119], off
	s_nop 1
	v_pk_mul_f32 v[118:119], v[108:109], v[114:115] op_sel_hi:[1,0]
	v_pk_mul_f32 v[116:117], v[106:107], v[114:115] op_sel_hi:[1,0]
	global_store_dwordx4 v[120:121], v[116:119], off offset:16

; __device__ __forceinline__ unsigned cvt_pk_bf16(float lo, float hi) { unsigned r; asm volatile("v_cvt_pk_bf16_f32 %0, %1, %2" : "=v"(r) : "v"(lo), "v"(hi)); return r; }
;     __device__ __forceinline__ void operator()(const f32x4 (&acc)[2][2][4][2], const Unit& u, int wr, int wc, int fr, int fq) const {
;     ...
;                 const int row = row0 + ai * HALF + m * 16;
;                 const f32x4 h0 = *((const f32x4*)(hss + (size_t)row * 16) + fq);
;                 float ss = (h0[0] + h0[1]) + (h0[2] + h0[3]);
;                 ss += __shfl_xor(ss, 16); ss += __shfl_xor(ss, 32);
;                 rsv[ai][m] = 1.0f / sqrtf(ss * (1.0f / 1024.0f) + 1e-6f);
;             }
;             asm volatile("" ::: "memory");
;         }
; #pragma unroll
;         for (int ai = 0; ai < 2; ++ai)
; #pragma unroll
;             for (int m = 0; m < 4; ++m) {
;                 const int row = row0 + ai * HALF + m * 16;
;                 const float rs = rsv[ai][m];
;                 if (u.pn < ntile_main) {
;                     bf16_t* rowp = P + (size_t)row * 4160 + u.pn * BM + wc * 32 + 8 * fq;
; #pragma unroll
;                     for (int bj = 0; bj < 2; ++bj) {
;                         const f32x4 v0 = acc[ai][bj][m][0] * rs, v1 = acc[ai][bj][m][1] * rs;
;                         u32x4 w; w.x = cvt_pk_bf16(v0[0], v0[1]); w.y = cvt_pk_bf16(v0[2], v0[3]); w.z = cvt_pk_bf16(v1[0], v1[1]); w.w = cvt_pk_bf16(v1[2], v1[3]);
;                         *(u32x4*)(rowp + bj * HALF) = w;
;                     }
;                 } else {
;                     const int c0 = wc * 32 + 8 * fq;
;                     if (c0 < 72) {
;                         *(f32x4*)(misc + (size_t)row * 80 + c0) = acc[ai][0][m][0] * rs;
;                         *(f32x4*)(misc + (size_t)row * 80 + c0 + 4) = acc[ai][0][m][1] * rs;
;                     }
.LBB0_391:
	s_andn2_b64 vcc, exec, s[8:9]
	s_cbranch_vccnz .LBB0_393
	v_mov_b64_e32 v[116:117], s[14:15]
	v_mad_i64_i32 v[116:117], s[8:9], v164, s76, v[116:117]
	s_lshl_b32 s8, s45, 8
	s_ashr_i32 s9, s8, 31
	v_lshl_add_u64 v[116:117], s[8:9], 1, v[116:117]
	s_lshl_b32 s92, s40, 1
	v_lshl_add_u64 v[116:117], v[116:117], 0, s[92:93]
	v_lshl_add_u64 v[116:117], v[116:117], 0, v[0:1]
	v_pk_mul_f32 v[112:113], v[112:113], v[114:115] op_sel_hi:[1,0]
	v_pk_mul_f32 v[110:111], v[110:111], v[114:115] op_sel_hi:[1,0]
	v_pk_mul_f32 v[118:119], v[108:109], v[114:115] op_sel_hi:[1,0]
	v_pk_mul_f32 v[108:109], v[106:107], v[114:115] op_sel_hi:[1,0]
	v_cvt_pk_bf16_f32 v106, v110, v111
	v_cvt_pk_bf16_f32 v107, v112, v113
	v_pk_mul_f32 v[104:105], v[104:105], v[114:115] op_sel_hi:[1,0]
	v_cvt_pk_bf16_f32 v108, v108, v109
	v_cvt_pk_bf16_f32 v109, v118, v119
	global_store_dwordx4 v[116:117], v[106:109], off
	v_pk_mul_f32 v[102:103], v[102:103], v[114:115] op_sel_hi:[1,0]
	s_nop 0
	v_pk_mul_f32 v[106:107], v[100:101], v[114:115] op_sel_hi:[1,0]
	v_pk_mul_f32 v[100:101], v[98:99], v[114:115] op_sel_hi:[1,0]
	v_cvt_pk_bf16_f32 v98, v102, v103
	v_cvt_pk_bf16_f32 v99, v104, v105
	s_nop 0
	v_cvt_pk_bf16_f32 v100, v100, v101
	v_cvt_pk_bf16_f32 v101, v106, v107
	global_store_dwordx4 v[116:117], v[98:101], off offset:256
.LBB0_393:
	s_nop 1
	v_add_f32_e32 v98, v169, v170
	v_fmamk_f32 v98, v98, 0x3a800000, v211
	v_mul_f32_e32 v99, 0x4f800000, v98
	v_cmp_gt_f32_e32 vcc, s55, v98
	s_nop 1
	v_cndmask_b32_e32 v98, v98, v99, vcc
	v_sqrt_f32_e32 v99, v98
	s_nop 0
	v_add_u32_e32 v100, -1, v99
	v_fma_f32 v102, -v100, v99, v98
	v_add_u32_e32 v101, 1, v99
	v_cmp_ge_f32_e64 s[8:9], 0, v102
	s_nop 1
	v_cndmask_b32_e64 v100, v99, v100, s[8:9]
	v_fma_f32 v99, -v101, v99, v98
	v_cmp_lt_f32_e64 s[8:9], 0, v99
	s_nop 1
	v_cndmask_b32_e64 v99, v100, v101, s[8:9]
	v_mul_f32_e32 v100, 0x37800000, v99
	v_cndmask_b32_e32 v99, v99, v100, vcc
	v_cmp_class_f32_e32 vcc, v98, v212
	s_nop 1
	v_cndmask_b32_e32 v98, v99, v98, vcc
	v_div_scale_f32 v99, s[8:9], v98, v98, 1.0
	v_rcp_f32_e32 v100, v99
	s_mov_b64 s[8:9], -1
	v_fma_f32 v101, -v99, v100, 1.0
	v_fmac_f32_e32 v100, v101, v100
	v_div_scale_f32 v101, vcc, 1.0, v98, 1.0
	v_mul_f32_e32 v102, v101, v100
	v_fma_f32 v103, -v99, v102, v101
	v_fmac_f32_e32 v102, v103, v100
	v_fma_f32 v99, -v99, v102, v101
	v_div_fmas_f32 v99, v99, v100, v102
	v_div_fixup_f32 v98, v99, v98, 1.0
	s_and_b64 vcc, exec, s[0:1]
	s_cbranch_vccnz .LBB0_397
	s_and_saveexec_b64 s[8:9], s[6:7]
	s_cbranch_execz .LBB0_396
	s_movk_i32 s19, 0x140
	v_pk_mul_f32 v[102:103], v[96:97], v[98:99] op_sel_hi:[1,0]
	v_pk_mul_f32 v[100:101], v[94:95], v[98:99] op_sel_hi:[1,0]
	v_mad_i64_i32 v[104:105], s[28:29], v158, s19, v[140:141]
	global_store_dwordx4 v[104:105], v[100:103], off
	s_nop 1
	v_pk_mul_f32 v[102:103], v[92:93], v[98:99] op_sel_hi:[1,0]
	v_pk_mul_f32 v[100:101], v[90:91], v[98:99] op_sel_hi:[1,0]
	global_store_dwordx4 v[104:105], v[100:103], off offset:16

; __device__ __forceinline__ unsigned cvt_pk_bf16(float lo, float hi) { unsigned r; asm volatile("v_cvt_pk_bf16_f32 %0, %1, %2" : "=v"(r) : "v"(lo), "v"(hi)); return r; }
;     __device__ __forceinline__ void operator()(const f32x4 (&acc)[2][2][4][2], const Unit& u, int wr, int wc, int fr, int fq) const {
;     ...
;                 const int row = row0 + ai * HALF + m * 16;
;                 const f32x4 h0 = *((const f32x4*)(hss + (size_t)row * 16) + fq);
;                 float ss = (h0[0] + h0[1]) + (h0[2] + h0[3]);
;                 ss += __shfl_xor(ss, 16); ss += __shfl_xor(ss, 32);
;                 rsv[ai][m] = 1.0f / sqrtf(ss * (1.0f / 1024.0f) + 1e-6f);
;             }
;             asm volatile("" ::: "memory");
;         }
; #pragma unroll
;         for (int ai = 0; ai < 2; ++ai)
; #pragma unroll
;             for (int m = 0; m < 4; ++m) {
;                 const int row = row0 + ai * HALF + m * 16;
;                 const float rs = rsv[ai][m];
;                 if (u.pn < ntile_main) {
;                     bf16_t* rowp = P + (size_t)row * 4160 + u.pn * BM + wc * 32 + 8 * fq;
; #pragma unroll
;                     for (int bj = 0; bj < 2; ++bj) {
;                         const f32x4 v0 = acc[ai][bj][m][0] * rs, v1 = acc[ai][bj][m][1] * rs;
;                         u32x4 w; w.x = cvt_pk_bf16(v0[0], v0[1]); w.y = cvt_pk_bf16(v0[2], v0[3]); w.z = cvt_pk_bf16(v1[0], v1[1]); w.w = cvt_pk_bf16(v1[2], v1[3]);
;                         *(u32x4*)(rowp + bj * HALF) = w;
;                     }
;                 } else {
;                     const int c0 = wc * 32 + 8 * fq;
;                     if (c0 < 72) {
;                         *(f32x4*)(misc + (size_t)row * 80 + c0) = acc[ai][0][m][0] * rs;
;                         *(f32x4*)(misc + (size_t)row * 80 + c0 + 4) = acc[ai][0][m][1] * rs;
;                     }
.LBB0_397:
	s_andn2_b64 vcc, exec, s[8:9]
	s_cbranch_vccnz .LBB0_399
	v_mov_b64_e32 v[100:101], s[14:15]
	v_mad_i64_i32 v[100:101], s[8:9], v158, s76, v[100:101]
	s_lshl_b32 s8, s45, 8
	s_ashr_i32 s9, s8, 31
	v_lshl_add_u64 v[100:101], s[8:9], 1, v[100:101]
	s_lshl_b32 s92, s40, 1
	v_lshl_add_u64 v[100:101], v[100:101], 0, s[92:93]
	v_lshl_add_u64 v[100:101], v[100:101], 0, v[0:1]
	v_pk_mul_f32 v[96:97], v[96:97], v[98:99] op_sel_hi:[1,0]
	v_pk_mul_f32 v[94:95], v[94:95], v[98:99] op_sel_hi:[1,0]
	v_pk_mul_f32 v[102:103], v[92:93], v[98:99] op_sel_hi:[1,0]
	v_pk_mul_f32 v[92:93], v[90:91], v[98:99] op_sel_hi:[1,0]
	v_cvt_pk_bf16_f32 v90, v94, v95
	v_cvt_pk_bf16_f32 v91, v96, v97
	v_pk_mul_f32 v[88:89], v[88:89], v[98:99] op_sel_hi:[1,0]
	v_cvt_pk_bf16_f32 v92, v92, v93
	v_cvt_pk_bf16_f32 v93, v102, v103
	global_store_dwordx4 v[100:101], v[90:93], off
	v_pk_mul_f32 v[86:87], v[86:87], v[98:99] op_sel_hi:[1,0]
	s_nop 0
	v_pk_mul_f32 v[90:91], v[84:85], v[98:99] op_sel_hi:[1,0]
	v_pk_mul_f32 v[84:85], v[82:83], v[98:99] op_sel_hi:[1,0]
	v_cvt_pk_bf16_f32 v82, v86, v87
	v_cvt_pk_bf16_f32 v83, v88, v89
	s_nop 0
	v_cvt_pk_bf16_f32 v84, v84, v85
	v_cvt_pk_bf16_f32 v85, v90, v91
	global_store_dwordx4 v[100:101], v[82:85], off offset:256
.LBB0_399:
	s_nop 1
	v_add_f32_e32 v82, v167, v168
	v_fmamk_f32 v82, v82, 0x3a800000, v211
	v_mul_f32_e32 v83, 0x4f800000, v82
	v_cmp_gt_f32_e32 vcc, s55, v82
	s_nop 1
	v_cndmask_b32_e32 v82, v82, v83, vcc
	v_sqrt_f32_e32 v83, v82
	s_nop 0
	v_add_u32_e32 v84, -1, v83
	v_fma_f32 v86, -v84, v83, v82
	v_add_u32_e32 v85, 1, v83
	v_cmp_ge_f32_e64 s[8:9], 0, v86
	s_nop 1
	v_cndmask_b32_e64 v84, v83, v84, s[8:9]
	v_fma_f32 v83, -v85, v83, v82
	v_cmp_lt_f32_e64 s[8:9], 0, v83
	s_nop 1
	v_cndmask_b32_e64 v83, v84, v85, s[8:9]
	v_mul_f32_e32 v84, 0x37800000, v83
	v_cndmask_b32_e32 v83, v83, v84, vcc
	v_cmp_class_f32_e32 vcc, v82, v212
	s_nop 1
	v_cndmask_b32_e32 v82, v83, v82, vcc
	v_div_scale_f32 v83, s[8:9], v82, v82, 1.0
	v_rcp_f32_e32 v84, v83
	s_mov_b64 s[8:9], -1
	v_fma_f32 v85, -v83, v84, 1.0
	v_fmac_f32_e32 v84, v85, v84
	v_div_scale_f32 v85, vcc, 1.0, v82, 1.0
	v_mul_f32_e32 v86, v85, v84
	v_fma_f32 v87, -v83, v86, v85
	v_fmac_f32_e32 v86, v87, v84
	v_fma_f32 v83, -v83, v86, v85
	v_div_fmas_f32 v83, v83, v84, v86
	v_div_fixup_f32 v82, v83, v82, 1.0
	s_and_b64 vcc, exec, s[0:1]
	s_cbranch_vccnz .LBB0_403
	s_and_saveexec_b64 s[8:9], s[6:7]
	s_cbranch_execz .LBB0_402
	s_movk_i32 s19, 0x140
	v_pk_mul_f32 v[86:87], v[80:81], v[82:83] op_sel_hi:[1,0]
	v_pk_mul_f32 v[84:85], v[78:79], v[82:83] op_sel_hi:[1,0]
	v_mad_i64_i32 v[88:89], s[28:29], v156, s19, v[140:141]
	global_store_dwordx4 v[88:89], v[84:87], off
	s_nop 1
	v_pk_mul_f32 v[86:87], v[76:77], v[82:83] op_sel_hi:[1,0]
	v_pk_mul_f32 v[84:85], v[74:75], v[82:83] op_sel_hi:[1,0]
	global_store_dwordx4 v[88:89], v[84:87], off offset:16

; __device__ __forceinline__ unsigned cvt_pk_bf16(float lo, float hi) { unsigned r; asm volatile("v_cvt_pk_bf16_f32 %0, %1, %2" : "=v"(r) : "v"(lo), "v"(hi)); return r; }
;     __device__ __forceinline__ void operator()(const f32x4 (&acc)[2][2][4][2], const Unit& u, int wr, int wc, int fr, int fq) const {
;     ...
;                 const int row = row0 + ai * HALF + m * 16;
;                 const f32x4 h0 = *((const f32x4*)(hss + (size_t)row * 16) + fq);
;                 float ss = (h0[0] + h0[1]) + (h0[2] + h0[3]);
;                 ss += __shfl_xor(ss, 16); ss += __shfl_xor(ss, 32);
;                 rsv[ai][m] = 1.0f / sqrtf(ss * (1.0f / 1024.0f) + 1e-6f);
;             }
;             asm volatile("" ::: "memory");
;         }
; #pragma unroll
;         for (int ai = 0; ai < 2; ++ai)
; #pragma unroll
;             for (int m = 0; m < 4; ++m) {
;                 const int row = row0 + ai * HALF + m * 16;
;                 const float rs = rsv[ai][m];
;                 if (u.pn < ntile_main) {
;                     bf16_t* rowp = P + (size_t)row * 4160 + u.pn * BM + wc * 32 + 8 * fq;
; #pragma unroll
;                     for (int bj = 0; bj < 2; ++bj) {
;                         const f32x4 v0 = acc[ai][bj][m][0] * rs, v1 = acc[ai][bj][m][1] * rs;
;                         u32x4 w; w.x = cvt_pk_bf16(v0[0], v0[1]); w.y = cvt_pk_bf16(v0[2], v0[3]); w.z = cvt_pk_bf16(v1[0], v1[1]); w.w = cvt_pk_bf16(v1[2], v1[3]);
;                         *(u32x4*)(rowp + bj * HALF) = w;
;                     }
;                 } else {
;                     const int c0 = wc * 32 + 8 * fq;
;                     if (c0 < 72) {
;                         *(f32x4*)(misc + (size_t)row * 80 + c0) = acc[ai][0][m][0] * rs;
;                         *(f32x4*)(misc + (size_t)row * 80 + c0 + 4) = acc[ai][0][m][1] * rs;
;                     }
.LBB0_403:
	s_andn2_b64 vcc, exec, s[8:9]
	s_cbranch_vccnz .LBB0_405
	v_mov_b64_e32 v[84:85], s[14:15]
	v_mad_i64_i32 v[84:85], s[8:9], v156, s76, v[84:85]
	s_lshl_b32 s8, s45, 8
	s_ashr_i32 s9, s8, 31
	v_lshl_add_u64 v[84:85], s[8:9], 1, v[84:85]
	s_lshl_b32 s92, s40, 1
	v_lshl_add_u64 v[84:85], v[84:85], 0, s[92:93]
	v_lshl_add_u64 v[84:85], v[84:85], 0, v[0:1]
	v_pk_mul_f32 v[80:81], v[80:81], v[82:83] op_sel_hi:[1,0]
	v_pk_mul_f32 v[78:79], v[78:79], v[82:83] op_sel_hi:[1,0]
	v_pk_mul_f32 v[86:87], v[76:77], v[82:83] op_sel_hi:[1,0]
	v_pk_mul_f32 v[76:77], v[74:75], v[82:83] op_sel_hi:[1,0]
	v_cvt_pk_bf16_f32 v74, v78, v79
	v_cvt_pk_bf16_f32 v75, v80, v81
	v_pk_mul_f32 v[72:73], v[72:73], v[82:83] op_sel_hi:[1,0]
	v_cvt_pk_bf16_f32 v76, v76, v77
	v_cvt_pk_bf16_f32 v77, v86, v87
	global_store_dwordx4 v[84:85], v[74:77], off
	v_pk_mul_f32 v[70:71], v[70:71], v[82:83] op_sel_hi:[1,0]
	s_nop 0
	v_pk_mul_f32 v[74:75], v[68:69], v[82:83] op_sel_hi:[1,0]
	v_pk_mul_f32 v[68:69], v[66:67], v[82:83] op_sel_hi:[1,0]
	v_cvt_pk_bf16_f32 v66, v70, v71
	v_cvt_pk_bf16_f32 v67, v72, v73
	s_nop 0
	v_cvt_pk_bf16_f32 v68, v68, v69
	v_cvt_pk_bf16_f32 v69, v74, v75
	global_store_dwordx4 v[84:85], v[66:69], off offset:256
.LBB0_405:
	s_nop 1
	v_add_f32_e32 v66, v161, v165
	v_fmamk_f32 v66, v66, 0x3a800000, v211
	v_mul_f32_e32 v67, 0x4f800000, v66
	v_cmp_gt_f32_e32 vcc, s55, v66
	s_nop 1
	v_cndmask_b32_e32 v66, v66, v67, vcc
	v_sqrt_f32_e32 v67, v66
	s_nop 0
	v_add_u32_e32 v68, -1, v67
	v_fma_f32 v70, -v68, v67, v66
	v_add_u32_e32 v69, 1, v67
	v_cmp_ge_f32_e64 s[8:9], 0, v70
	s_nop 1
	v_cndmask_b32_e64 v68, v67, v68, s[8:9]
	v_fma_f32 v67, -v69, v67, v66
	v_cmp_lt_f32_e64 s[8:9], 0, v67
	s_nop 1
	v_cndmask_b32_e64 v67, v68, v69, s[8:9]
	v_mul_f32_e32 v68, 0x37800000, v67
	v_cndmask_b32_e32 v67, v67, v68, vcc
	v_cmp_class_f32_e32 vcc, v66, v212
	s_nop 1
	v_cndmask_b32_e32 v66, v67, v66, vcc
	v_div_scale_f32 v67, s[8:9], v66, v66, 1.0
	v_rcp_f32_e32 v68, v67
	s_mov_b64 s[8:9], -1
	v_fma_f32 v69, -v67, v68, 1.0
	v_fmac_f32_e32 v68, v69, v68
	v_div_scale_f32 v69, vcc, 1.0, v66, 1.0
	v_mul_f32_e32 v70, v69, v68
	v_fma_f32 v71, -v67, v70, v69
	v_fmac_f32_e32 v70, v71, v68
	v_fma_f32 v67, -v67, v70, v69
	v_div_fmas_f32 v67, v67, v68, v70
	v_div_fixup_f32 v66, v67, v66, 1.0
	s_and_b64 vcc, exec, s[0:1]
	s_cbranch_vccnz .LBB0_409
	s_and_saveexec_b64 s[8:9], s[6:7]
	s_cbranch_execz .LBB0_408
	s_movk_i32 s19, 0x140
	v_pk_mul_f32 v[70:71], v[64:65], v[66:67] op_sel_hi:[1,0]
	v_pk_mul_f32 v[68:69], v[62:63], v[66:67] op_sel_hi:[1,0]
	v_mad_i64_i32 v[72:73], s[28:29], v154, s19, v[140:141]
	global_store_dwordx4 v[72:73], v[68:71], off
	s_nop 1
	v_pk_mul_f32 v[70:71], v[60:61], v[66:67] op_sel_hi:[1,0]
	v_pk_mul_f32 v[68:69], v[58:59], v[66:67] op_sel_hi:[1,0]
	global_store_dwordx4 v[72:73], v[68:71], off offset:16

; __device__ __forceinline__ unsigned cvt_pk_bf16(float lo, float hi) { unsigned r; asm volatile("v_cvt_pk_bf16_f32 %0, %1, %2" : "=v"(r) : "v"(lo), "v"(hi)); return r; }
;     __device__ __forceinline__ void operator()(const f32x4 (&acc)[2][2][4][2], const Unit& u, int wr, int wc, int fr, int fq) const {
;     ...
;                 const int row = row0 + ai * HALF + m * 16;
;                 const f32x4 h0 = *((const f32x4*)(hss + (size_t)row * 16) + fq);
;                 float ss = (h0[0] + h0[1]) + (h0[2] + h0[3]);
;                 ss += __shfl_xor(ss, 16); ss += __shfl_xor(ss, 32);
;                 rsv[ai][m] = 1.0f / sqrtf(ss * (1.0f / 1024.0f) + 1e-6f);
;             }
;             asm volatile("" ::: "memory");
;         }
; #pragma unroll
;         for (int ai = 0; ai < 2; ++ai)
; #pragma unroll
;             for (int m = 0; m < 4; ++m) {
;                 const int row = row0 + ai * HALF + m * 16;
;                 const float rs = rsv[ai][m];
;                 if (u.pn < ntile_main) {
;                     bf16_t* rowp = P + (size_t)row * 4160 + u.pn * BM + wc * 32 + 8 * fq;
; #pragma unroll
;                     for (int bj = 0; bj < 2; ++bj) {
;                         const f32x4 v0 = acc[ai][bj][m][0] * rs, v1 = acc[ai][bj][m][1] * rs;
;                         u32x4 w; w.x = cvt_pk_bf16(v0[0], v0[1]); w.y = cvt_pk_bf16(v0[2], v0[3]); w.z = cvt_pk_bf16(v1[0], v1[1]); w.w = cvt_pk_bf16(v1[2], v1[3]);
;                         *(u32x4*)(rowp + bj * HALF) = w;
;                     }
;                 } else {
;                     const int c0 = wc * 32 + 8 * fq;
;                     if (c0 < 72) {
;                         *(f32x4*)(misc + (size_t)row * 80 + c0) = acc[ai][0][m][0] * rs;
;                         *(f32x4*)(misc + (size_t)row * 80 + c0 + 4) = acc[ai][0][m][1] * rs;
;                     }
.LBB0_409:
	s_andn2_b64 vcc, exec, s[8:9]
	s_cbranch_vccnz .LBB0_411
	v_mov_b64_e32 v[68:69], s[14:15]
	v_mad_i64_i32 v[68:69], s[8:9], v154, s76, v[68:69]
	s_lshl_b32 s8, s45, 8
	s_ashr_i32 s9, s8, 31
	v_lshl_add_u64 v[68:69], s[8:9], 1, v[68:69]
	s_lshl_b32 s92, s40, 1
	v_lshl_add_u64 v[68:69], v[68:69], 0, s[92:93]
	v_lshl_add_u64 v[68:69], v[68:69], 0, v[0:1]
	v_pk_mul_f32 v[64:65], v[64:65], v[66:67] op_sel_hi:[1,0]
	v_pk_mul_f32 v[62:63], v[62:63], v[66:67] op_sel_hi:[1,0]
	v_pk_mul_f32 v[70:71], v[60:61], v[66:67] op_sel_hi:[1,0]
	v_pk_mul_f32 v[60:61], v[58:59], v[66:67] op_sel_hi:[1,0]
	v_cvt_pk_bf16_f32 v58, v62, v63
	v_cvt_pk_bf16_f32 v59, v64, v65
	v_pk_mul_f32 v[56:57], v[56:57], v[66:67] op_sel_hi:[1,0]
	v_cvt_pk_bf16_f32 v60, v60, v61
	v_cvt_pk_bf16_f32 v61, v70, v71
	global_store_dwordx4 v[68:69], v[58:61], off
	v_pk_mul_f32 v[54:55], v[54:55], v[66:67] op_sel_hi:[1,0]
	s_nop 0
	v_pk_mul_f32 v[58:59], v[52:53], v[66:67] op_sel_hi:[1,0]
	v_pk_mul_f32 v[52:53], v[50:51], v[66:67] op_sel_hi:[1,0]
	v_cvt_pk_bf16_f32 v50, v54, v55
	v_cvt_pk_bf16_f32 v51, v56, v57
	s_nop 0
	v_cvt_pk_bf16_f32 v52, v52, v53
	v_cvt_pk_bf16_f32 v53, v58, v59
	global_store_dwordx4 v[68:69], v[50:53], off offset:256
.LBB0_411:
	s_nop 1
	v_add_f32_e32 v50, v155, v157
	v_fmamk_f32 v50, v50, 0x3a800000, v211
	v_mul_f32_e32 v51, 0x4f800000, v50
	v_cmp_gt_f32_e32 vcc, s55, v50
	s_nop 1
	v_cndmask_b32_e32 v50, v50, v51, vcc
	v_sqrt_f32_e32 v51, v50
	s_nop 0
	v_add_u32_e32 v52, -1, v51
	v_fma_f32 v54, -v52, v51, v50
	v_add_u32_e32 v53, 1, v51
	v_cmp_ge_f32_e64 s[8:9], 0, v54
	s_nop 1
	v_cndmask_b32_e64 v52, v51, v52, s[8:9]
	v_fma_f32 v51, -v53, v51, v50
	v_cmp_lt_f32_e64 s[8:9], 0, v51
	s_nop 1
	v_cndmask_b32_e64 v51, v52, v53, s[8:9]
	v_mul_f32_e32 v52, 0x37800000, v51
	v_cndmask_b32_e32 v51, v51, v52, vcc
	v_cmp_class_f32_e32 vcc, v50, v212
	s_nop 1
	v_cndmask_b32_e32 v50, v51, v50, vcc
	v_div_scale_f32 v51, s[8:9], v50, v50, 1.0
	v_rcp_f32_e32 v52, v51
	s_mov_b64 s[8:9], -1
	v_fma_f32 v53, -v51, v52, 1.0
	v_fmac_f32_e32 v52, v53, v52
	v_div_scale_f32 v53, vcc, 1.0, v50, 1.0
	v_mul_f32_e32 v54, v53, v52
	v_fma_f32 v55, -v51, v54, v53
	v_fmac_f32_e32 v54, v55, v52
	v_fma_f32 v51, -v51, v54, v53
	v_div_fmas_f32 v51, v51, v52, v54
	v_div_fixup_f32 v50, v51, v50, 1.0
	s_and_b64 vcc, exec, s[0:1]
	s_cbranch_vccnz .LBB0_415
	s_and_saveexec_b64 s[8:9], s[6:7]
	s_cbranch_execz .LBB0_414
	s_movk_i32 s19, 0x140
	v_pk_mul_f32 v[54:55], v[48:49], v[50:51] op_sel_hi:[1,0]
	v_pk_mul_f32 v[52:53], v[46:47], v[50:51] op_sel_hi:[1,0]
	v_mad_i64_i32 v[56:57], s[28:29], v152, s19, v[140:141]
	global_store_dwordx4 v[56:57], v[52:55], off
	s_nop 1
	v_pk_mul_f32 v[54:55], v[44:45], v[50:51] op_sel_hi:[1,0]
	v_pk_mul_f32 v[52:53], v[42:43], v[50:51] op_sel_hi:[1,0]
	global_store_dwordx4 v[56:57], v[52:55], off offset:16

; __device__ __forceinline__ unsigned cvt_pk_bf16(float lo, float hi) { unsigned r; asm volatile("v_cvt_pk_bf16_f32 %0, %1, %2" : "=v"(r) : "v"(lo), "v"(hi)); return r; }
;     __device__ __forceinline__ void operator()(const f32x4 (&acc)[2][2][4][2], const Unit& u, int wr, int wc, int fr, int fq) const {
;     ...
;                 const int row = row0 + ai * HALF + m * 16;
;                 const f32x4 h0 = *((const f32x4*)(hss + (size_t)row * 16) + fq);
;                 float ss = (h0[0] + h0[1]) + (h0[2] + h0[3]);
;                 ss += __shfl_xor(ss, 16); ss += __shfl_xor(ss, 32);
;                 rsv[ai][m] = 1.0f / sqrtf(ss * (1.0f / 1024.0f) + 1e-6f);
;             }
;             asm volatile("" ::: "memory");
;         }
; #pragma unroll
;         for (int ai = 0; ai < 2; ++ai)
; #pragma unroll
;             for (int m = 0; m < 4; ++m) {
;                 const int row = row0 + ai * HALF + m * 16;
;                 const float rs = rsv[ai][m];
;                 if (u.pn < ntile_main) {
;                     bf16_t* rowp = P + (size_t)row * 4160 + u.pn * BM + wc * 32 + 8 * fq;
; #pragma unroll
;                     for (int bj = 0; bj < 2; ++bj) {
;                         const f32x4 v0 = acc[ai][bj][m][0] * rs, v1 = acc[ai][bj][m][1] * rs;
;                         u32x4 w; w.x = cvt_pk_bf16(v0[0], v0[1]); w.y = cvt_pk_bf16(v0[2], v0[3]); w.z = cvt_pk_bf16(v1[0], v1[1]); w.w = cvt_pk_bf16(v1[2], v1[3]);
;                         *(u32x4*)(rowp + bj * HALF) = w;
;                     }
;                 } else {
;                     const int c0 = wc * 32 + 8 * fq;
;                     if (c0 < 72) {
;                         *(f32x4*)(misc + (size_t)row * 80 + c0) = acc[ai][0][m][0] * rs;
;                         *(f32x4*)(misc + (size_t)row * 80 + c0 + 4) = acc[ai][0][m][1] * rs;
;                     }
.LBB0_415:
	s_andn2_b64 vcc, exec, s[8:9]
	s_cbranch_vccnz .LBB0_417
	v_mov_b64_e32 v[52:53], s[14:15]
	v_mad_i64_i32 v[52:53], s[8:9], v152, s76, v[52:53]
	s_lshl_b32 s8, s45, 8
	s_ashr_i32 s9, s8, 31
	v_lshl_add_u64 v[52:53], s[8:9], 1, v[52:53]
	s_lshl_b32 s92, s40, 1
	v_lshl_add_u64 v[52:53], v[52:53], 0, s[92:93]
	v_lshl_add_u64 v[52:53], v[52:53], 0, v[0:1]
	v_pk_mul_f32 v[48:49], v[48:49], v[50:51] op_sel_hi:[1,0]
	v_pk_mul_f32 v[46:47], v[46:47], v[50:51] op_sel_hi:[1,0]
	v_pk_mul_f32 v[54:55], v[44:45], v[50:51] op_sel_hi:[1,0]
	v_pk_mul_f32 v[44:45], v[42:43], v[50:51] op_sel_hi:[1,0]
	v_cvt_pk_bf16_f32 v42, v46, v47
	v_cvt_pk_bf16_f32 v43, v48, v49
	v_pk_mul_f32 v[40:41], v[40:41], v[50:51] op_sel_hi:[1,0]
	v_cvt_pk_bf16_f32 v44, v44, v45
	v_cvt_pk_bf16_f32 v45, v54, v55
	global_store_dwordx4 v[52:53], v[42:45], off
	v_pk_mul_f32 v[38:39], v[38:39], v[50:51] op_sel_hi:[1,0]
	s_nop 0
	v_pk_mul_f32 v[42:43], v[36:37], v[50:51] op_sel_hi:[1,0]
	v_pk_mul_f32 v[36:37], v[34:35], v[50:51] op_sel_hi:[1,0]
	v_cvt_pk_bf16_f32 v34, v38, v39
	v_cvt_pk_bf16_f32 v35, v40, v41
	s_nop 0
	v_cvt_pk_bf16_f32 v36, v36, v37
	v_cvt_pk_bf16_f32 v37, v42, v43
	global_store_dwordx4 v[52:53], v[34:37], off offset:256
.LBB0_417:
	s_nop 1
	v_add_f32_e32 v34, v151, v153
	v_fmamk_f32 v34, v34, 0x3a800000, v211
	v_mul_f32_e32 v35, 0x4f800000, v34
	v_cmp_gt_f32_e32 vcc, s55, v34
	s_nop 1
	v_cndmask_b32_e32 v34, v34, v35, vcc
	v_sqrt_f32_e32 v35, v34
	s_nop 0
	v_add_u32_e32 v36, -1, v35
	v_fma_f32 v38, -v36, v35, v34
	v_add_u32_e32 v37, 1, v35
	v_cmp_ge_f32_e64 s[8:9], 0, v38
	s_nop 1
	v_cndmask_b32_e64 v36, v35, v36, s[8:9]
	v_fma_f32 v35, -v37, v35, v34
	v_cmp_lt_f32_e64 s[8:9], 0, v35
	s_nop 1
	v_cndmask_b32_e64 v35, v36, v37, s[8:9]
	v_mul_f32_e32 v36, 0x37800000, v35
	v_cndmask_b32_e32 v35, v35, v36, vcc
	v_cmp_class_f32_e32 vcc, v34, v212
	s_nop 1
	v_cndmask_b32_e32 v34, v35, v34, vcc
	v_div_scale_f32 v35, s[8:9], v34, v34, 1.0
	v_rcp_f32_e32 v36, v35
	s_mov_b64 s[8:9], -1
	v_fma_f32 v37, -v35, v36, 1.0
	v_fmac_f32_e32 v36, v37, v36
	v_div_scale_f32 v37, vcc, 1.0, v34, 1.0
	v_mul_f32_e32 v38, v37, v36
	v_fma_f32 v39, -v35, v38, v37
	v_fmac_f32_e32 v38, v39, v36
	v_fma_f32 v35, -v35, v38, v37
	v_div_fmas_f32 v35, v35, v36, v38
	v_div_fixup_f32 v34, v35, v34, 1.0
	s_and_b64 vcc, exec, s[0:1]
	s_cbranch_vccnz .LBB0_421
	s_and_saveexec_b64 s[8:9], s[6:7]
	s_cbranch_execz .LBB0_420
	s_movk_i32 s19, 0x140
	v_pk_mul_f32 v[38:39], v[32:33], v[34:35] op_sel_hi:[1,0]
	v_pk_mul_f32 v[36:37], v[30:31], v[34:35] op_sel_hi:[1,0]
	v_mad_i64_i32 v[40:41], s[28:29], v150, s19, v[140:141]
	global_store_dwordx4 v[40:41], v[36:39], off
	s_nop 1
	v_pk_mul_f32 v[38:39], v[28:29], v[34:35] op_sel_hi:[1,0]
	v_pk_mul_f32 v[36:37], v[26:27], v[34:35] op_sel_hi:[1,0]
	global_store_dwordx4 v[40:41], v[36:39], off offset:16

; __device__ __forceinline__ unsigned cvt_pk_bf16(float lo, float hi) { unsigned r; asm volatile("v_cvt_pk_bf16_f32 %0, %1, %2" : "=v"(r) : "v"(lo), "v"(hi)); return r; }
;     __device__ __forceinline__ void operator()(const f32x4 (&acc)[2][2][4][2], const Unit& u, int wr, int wc, int fr, int fq) const {
;     ...
;                 if (u.pn < ntile_main) {
;                     bf16_t* rowp = P + (size_t)row * 4160 + u.pn * BM + wc * 32 + 8 * fq;
; #pragma unroll
;                     for (int bj = 0; bj < 2; ++bj) {
;                         const f32x4 v0 = acc[ai][bj][m][0] * rs, v1 = acc[ai][bj][m][1] * rs;
;                         u32x4 w; w.x = cvt_pk_bf16(v0[0], v0[1]); w.y = cvt_pk_bf16(v0[2], v0[3]); w.z = cvt_pk_bf16(v1[0], v1[1]); w.w = cvt_pk_bf16(v1[2], v1[3]);
;                         *(u32x4*)(rowp + bj * HALF) = w;
;                     }
.LBB0_421:
	s_andn2_b64 vcc, exec, s[8:9]
	s_cbranch_vccnz .LBB0_423
	v_mov_b64_e32 v[36:37], s[14:15]
	v_mad_i64_i32 v[36:37], s[8:9], v150, s76, v[36:37]
	s_lshl_b32 s8, s45, 8
	s_ashr_i32 s9, s8, 31
	v_lshl_add_u64 v[36:37], s[8:9], 1, v[36:37]
	s_lshl_b32 s92, s40, 1
	v_lshl_add_u64 v[36:37], v[36:37], 0, s[92:93]
	v_lshl_add_u64 v[36:37], v[36:37], 0, v[0:1]
	v_pk_mul_f32 v[32:33], v[32:33], v[34:35] op_sel_hi:[1,0]
	v_pk_mul_f32 v[30:31], v[30:31], v[34:35] op_sel_hi:[1,0]
	v_pk_mul_f32 v[38:39], v[28:29], v[34:35] op_sel_hi:[1,0]
	v_pk_mul_f32 v[28:29], v[26:27], v[34:35] op_sel_hi:[1,0]
	v_cvt_pk_bf16_f32 v26, v30, v31
	v_cvt_pk_bf16_f32 v27, v32, v33
	v_pk_mul_f32 v[24:25], v[24:25], v[34:35] op_sel_hi:[1,0]
	v_cvt_pk_bf16_f32 v28, v28, v29
	v_cvt_pk_bf16_f32 v29, v38, v39
	global_store_dwordx4 v[36:37], v[26:29], off
	v_pk_mul_f32 v[22:23], v[22:23], v[34:35] op_sel_hi:[1,0]
	s_nop 0
	v_pk_mul_f32 v[26:27], v[20:21], v[34:35] op_sel_hi:[1,0]
	v_pk_mul_f32 v[20:21], v[18:19], v[34:35] op_sel_hi:[1,0]
	v_cvt_pk_bf16_f32 v18, v22, v23
	v_cvt_pk_bf16_f32 v19, v24, v25
	s_nop 0
	v_cvt_pk_bf16_f32 v20, v20, v21
	v_cvt_pk_bf16_f32 v21, v26, v27
	global_store_dwordx4 v[36:37], v[18:21], off offset:256

; __device__ __forceinline__ unsigned cvt_pk_bf16(float lo, float hi) { unsigned r; asm volatile("v_cvt_pk_bf16_f32 %0, %1, %2" : "=v"(r) : "v"(lo), "v"(hi)); return r; }
;     __device__ __forceinline__ void operator()(const f32x4 (&acc)[2][2][4][2], const Unit& u, int wr, int wc, int fr, int fq) const {
;     ...
;                 if (u.pn < ntile_main) {
;                     bf16_t* rowp = P + (size_t)row * 4160 + u.pn * BM + wc * 32 + 8 * fq;
; #pragma unroll
;                     for (int bj = 0; bj < 2; ++bj) {
;                         const f32x4 v0 = acc[ai][bj][m][0] * rs, v1 = acc[ai][bj][m][1] * rs;
;                         u32x4 w; w.x = cvt_pk_bf16(v0[0], v0[1]); w.y = cvt_pk_bf16(v0[2], v0[3]); w.z = cvt_pk_bf16(v1[0], v1[1]); w.w = cvt_pk_bf16(v1[2], v1[3]);
;                         *(u32x4*)(rowp + bj * HALF) = w;
;                     }
.LBB0_427:
	s_andn2_b64 vcc, exec, s[0:1]
	s_cbranch_vccnz .LBB0_429
	v_mov_b64_e32 v[20:21], s[14:15]
	v_mad_i64_i32 v[20:21], s[0:1], v148, s76, v[20:21]
	s_lshl_b32 s0, s45, 8
	s_ashr_i32 s1, s0, 31
	v_lshl_add_u64 v[20:21], s[0:1], 1, v[20:21]
	s_lshl_b32 s92, s40, 1
	v_lshl_add_u64 v[20:21], v[20:21], 0, s[92:93]
	v_lshl_add_u64 v[20:21], v[20:21], 0, v[0:1]
	v_pk_mul_f32 v[16:17], v[16:17], v[18:19] op_sel_hi:[1,0]
	v_pk_mul_f32 v[14:15], v[14:15], v[18:19] op_sel_hi:[1,0]
	v_pk_mul_f32 v[22:23], v[12:13], v[18:19] op_sel_hi:[1,0]
	v_pk_mul_f32 v[12:13], v[10:11], v[18:19] op_sel_hi:[1,0]
	v_cvt_pk_bf16_f32 v10, v14, v15
	v_cvt_pk_bf16_f32 v11, v16, v17
	v_pk_mul_f32 v[8:9], v[8:9], v[18:19] op_sel_hi:[1,0]
	v_cvt_pk_bf16_f32 v12, v12, v13
	v_cvt_pk_bf16_f32 v13, v22, v23
	global_store_dwordx4 v[20:21], v[10:13], off
	v_pk_mul_f32 v[6:7], v[6:7], v[18:19] op_sel_hi:[1,0]
	s_nop 0
	v_pk_mul_f32 v[10:11], v[4:5], v[18:19] op_sel_hi:[1,0]
	v_pk_mul_f32 v[4:5], v[2:3], v[18:19] op_sel_hi:[1,0]
	v_cvt_pk_bf16_f32 v2, v6, v7
	v_cvt_pk_bf16_f32 v3, v8, v9
	s_nop 0
	v_cvt_pk_bf16_f32 v4, v4, v5
	v_cvt_pk_bf16_f32 v5, v10, v11
	global_store_dwordx4 v[20:21], v[2:5], off offset:256

;     __device__ __forceinline__ void operator()(const f32x4 (&acc)[2][2][4][2], const Unit& u, int wr, int wc, int fr, int fq) const {
;     ...
;                 const int row = u.pm * BM + ai * HALF + wr * 64 + m * 16 + fr;
;                 const size_t off = (size_t)row * 1024 + col0;
;                 float ss = 0.f;
; #pragma unroll
;                 for (int bj = 0; bj < 2; ++bj)
; #pragma unroll
;                     for (int n = 0; n < 2; ++n) {
;                         const f32x4 o = *(const f32x4*)(res + off + bj * HALF + n * 16) + acc[ai][bj][m][n];
;                         *(f32x4*)(out + off + bj * HALF + n * 16) = o;
.LBB0_449:
	v_lshl_add_u32 v138, s41, 8, v140
	v_lshl_or_b32 v136, s40, 8, v142
	v_ashrrev_i32_e32 v139, 31, v138
	v_ashrrev_i32_e32 v137, 31, v136
	v_lshlrev_b64 v[144:145], 10, v[138:139]
	v_lshl_add_u64 v[144:145], v[144:145], 0, v[136:137]
	v_lshlrev_b64 v[148:149], 2, v[144:145]
	v_lshl_add_u64 v[150:151], s[4:5], 0, v[148:149]
	global_load_dwordx4 v[144:147], v[150:151], off
	v_lshl_add_u64 v[148:149], s[10:11], 0, v[148:149]
	s_andn2_b64 vcc, exec, s[0:1]
	s_mov_b64 s[0:1], -1
	s_waitcnt vmcnt(0) lgkmcnt(0)
	v_pk_add_f32 v[128:129], v[128:129], v[146:147]
	v_pk_add_f32 v[126:127], v[126:127], v[144:145]
	global_store_dwordx4 v[148:149], v[126:129], off
	global_load_dwordx4 v[126:129], v[150:151], off offset:64
	s_waitcnt vmcnt(0) lgkmcnt(0)
	v_pk_add_f32 v[124:125], v[124:125], v[128:129]
	v_pk_add_f32 v[122:123], v[122:123], v[126:127]
	global_store_dwordx4 v[148:149], v[122:125], off offset:64
	global_load_dwordx4 v[122:125], v[150:151], off offset:512
	s_waitcnt vmcnt(0) lgkmcnt(0)
	v_pk_add_f32 v[120:121], v[120:121], v[124:125]
	v_pk_add_f32 v[118:119], v[118:119], v[122:123]
	global_store_dwordx4 v[148:149], v[118:121], off offset:512
	global_load_dwordx4 v[118:121], v[150:151], off offset:576
	v_or_b32_e32 v122, 16, v138
	v_ashrrev_i32_e32 v123, 31, v122
	v_lshlrev_b64 v[122:123], 10, v[122:123]
	v_lshl_add_u64 v[122:123], v[122:123], 0, v[136:137]
	v_lshlrev_b64 v[122:123], 2, v[122:123]
	v_lshl_add_u64 v[124:125], s[4:5], 0, v[122:123]
	s_waitcnt vmcnt(0) lgkmcnt(0)
	v_pk_add_f32 v[108:109], v[108:109], v[120:121]
	v_pk_add_f32 v[106:107], v[106:107], v[118:119]
	global_store_dwordx4 v[148:149], v[106:109], off offset:576
	global_load_dwordx4 v[106:109], v[124:125], off
	v_lshl_add_u64 v[118:119], s[10:11], 0, v[122:123]
	s_waitcnt vmcnt(0) lgkmcnt(0)
	v_pk_add_f32 v[108:109], v[116:117], v[108:109]
	v_pk_add_f32 v[106:107], v[114:115], v[106:107]
	global_store_dwordx4 v[118:119], v[106:109], off
	global_load_dwordx4 v[106:109], v[124:125], off offset:64
	s_waitcnt vmcnt(0) lgkmcnt(0)
	v_pk_add_f32 v[108:109], v[112:113], v[108:109]
	v_pk_add_f32 v[106:107], v[110:111], v[106:107]
	global_store_dwordx4 v[118:119], v[106:109], off offset:64
	global_load_dwordx4 v[106:109], v[124:125], off offset:512
	s_waitcnt vmcnt(0) lgkmcnt(0)
	v_pk_add_f32 v[104:105], v[104:105], v[108:109]
	v_pk_add_f32 v[102:103], v[102:103], v[106:107]
	global_store_dwordx4 v[118:119], v[102:105], off offset:512
	global_load_dwordx4 v[102:105], v[124:125], off offset:576
	v_or_b32_e32 v106, 32, v138
	v_ashrrev_i32_e32 v107, 31, v106
	v_lshlrev_b64 v[106:107], 10, v[106:107]
	v_lshl_add_u64 v[106:107], v[106:107], 0, v[136:137]
	v_lshlrev_b64 v[106:107], 2, v[106:107]
	v_lshl_add_u64 v[108:109], s[4:5], 0, v[106:107]
	s_waitcnt vmcnt(0) lgkmcnt(0)
	v_pk_add_f32 v[92:93], v[92:93], v[104:105]
	v_pk_add_f32 v[90:91], v[90:91], v[102:103]
	global_store_dwordx4 v[118:119], v[90:93], off offset:576
	global_load_dwordx4 v[90:93], v[108:109], off
	v_lshl_add_u64 v[102:103], s[10:11], 0, v[106:107]
	s_waitcnt vmcnt(0) lgkmcnt(0)
	v_pk_add_f32 v[92:93], v[100:101], v[92:93]
	v_pk_add_f32 v[90:91], v[98:99], v[90:91]
	global_store_dwordx4 v[102:103], v[90:93], off
	global_load_dwordx4 v[90:93], v[108:109], off offset:64
	s_waitcnt vmcnt(0) lgkmcnt(0)
	v_pk_add_f32 v[92:93], v[96:97], v[92:93]
	v_pk_add_f32 v[90:91], v[94:95], v[90:91]
	global_store_dwordx4 v[102:103], v[90:93], off offset:64
	global_load_dwordx4 v[90:93], v[108:109], off offset:512
	s_waitcnt vmcnt(0) lgkmcnt(0)
	v_pk_add_f32 v[88:89], v[88:89], v[92:93]
	v_pk_add_f32 v[86:87], v[86:87], v[90:91]
	global_store_dwordx4 v[102:103], v[86:89], off offset:512
	global_load_dwordx4 v[86:89], v[108:109], off offset:576
	v_or_b32_e32 v90, 48, v138
	v_ashrrev_i32_e32 v91, 31, v90
	v_lshlrev_b64 v[90:91], 10, v[90:91]
	v_lshl_add_u64 v[90:91], v[90:91], 0, v[136:137]
	v_lshlrev_b64 v[90:91], 2, v[90:91]
	v_lshl_add_u64 v[92:93], s[4:5], 0, v[90:91]
	s_waitcnt vmcnt(0) lgkmcnt(0)
	v_pk_add_f32 v[76:77], v[76:77], v[88:89]
	v_pk_add_f32 v[74:75], v[74:75], v[86:87]
	global_store_dwordx4 v[102:103], v[74:77], off offset:576
	global_load_dwordx4 v[74:77], v[92:93], off
	v_lshl_add_u64 v[86:87], s[10:11], 0, v[90:91]
	s_waitcnt vmcnt(0) lgkmcnt(0)
	v_pk_add_f32 v[76:77], v[84:85], v[76:77]
	v_pk_add_f32 v[74:75], v[82:83], v[74:75]
	global_store_dwordx4 v[86:87], v[74:77], off
	global_load_dwordx4 v[74:77], v[92:93], off offset:64
	s_waitcnt vmcnt(0) lgkmcnt(0)
	v_pk_add_f32 v[76:77], v[80:81], v[76:77]
	v_pk_add_f32 v[74:75], v[78:79], v[74:75]
	global_store_dwordx4 v[86:87], v[74:77], off offset:64
	global_load_dwordx4 v[74:77], v[92:93], off offset:512
	s_waitcnt vmcnt(0) lgkmcnt(0)
	v_pk_add_f32 v[72:73], v[72:73], v[76:77]
	v_pk_add_f32 v[70:71], v[70:71], v[74:75]
	global_store_dwordx4 v[86:87], v[70:73], off offset:512
	global_load_dwordx4 v[70:73], v[92:93], off offset:576
	v_add_u32_e32 v74, 0x80, v138
	v_ashrrev_i32_e32 v75, 31, v74
	v_lshlrev_b64 v[74:75], 10, v[74:75]
	v_lshl_add_u64 v[74:75], v[74:75], 0, v[136:137]
	v_lshlrev_b64 v[74:75], 2, v[74:75]
	v_lshl_add_u64 v[76:77], s[4:5], 0, v[74:75]
	s_waitcnt vmcnt(0) lgkmcnt(0)
; #define PG8_BAR __builtin_amdgcn_s_barrier()
;     __device__ __forceinline__ void operator()(const f32x4 (&acc)[2][2][4][2], const Unit& u, int wr, int wc, int fr, int fq) const {
;     ...
;                 const int row = u.pm * BM + ai * HALF + wr * 64 + m * 16 + fr;
;                 const size_t off = (size_t)row * 1024 + col0;
;                 float ss = 0.f;
; #pragma unroll
;                 for (int bj = 0; bj < 2; ++bj)
; #pragma unroll
;                     for (int n = 0; n < 2; ++n) {
;                         const f32x4 o = *(const f32x4*)(res + off + bj * HALF + n * 16) + acc[ai][bj][m][n];
;                         *(f32x4*)(out + off + bj * HALF + n * 16) = o;
; template <class Epi, class Sched, bool ALIGN_EPI = false, bool SP2 = false>
; __device__ __forceinline__ void gemm_phase(PG8_LAS unsigned char* lds, const Gemm g, const Sched& S, const Epi& E) {
;     ...
;         if (!has_next) break;
; #pragma unroll
;         for (int a = 0; a < 2; ++a)
; #pragma unroll
;             for (int b = 0; b < 2; ++b)
; #pragma unroll
;                 for (int m = 0; m < 4; ++m)
; #pragma unroll
;                     for (int n = 0; n < 2; ++n) acc[a][b][m][n] = (f32x4){0.f, 0.f, 0.f, 0.f};
;         cur = nxt; cA = nA; cB = nB; ++ui;
;         if constexpr (ALIGN_EPI) { if (wr == 1) PG8_BAR; }
	v_pk_add_f32 v[68:69], v[68:69], v[72:73]
	v_pk_add_f32 v[66:67], v[66:67], v[70:71]
	global_store_dwordx4 v[86:87], v[66:69], off offset:576
	global_load_dwordx4 v[66:69], v[76:77], off
	v_lshl_add_u64 v[70:71], s[10:11], 0, v[74:75]
	s_waitcnt vmcnt(0) lgkmcnt(0)
	v_pk_add_f32 v[64:65], v[64:65], v[68:69]
	v_pk_add_f32 v[62:63], v[62:63], v[66:67]
	global_store_dwordx4 v[70:71], v[62:65], off
	global_load_dwordx4 v[62:65], v[76:77], off offset:64
	s_waitcnt vmcnt(0) lgkmcnt(0)
	v_pk_add_f32 v[60:61], v[60:61], v[64:65]
	v_pk_add_f32 v[58:59], v[58:59], v[62:63]
	global_store_dwordx4 v[70:71], v[58:61], off offset:64
	global_load_dwordx4 v[58:61], v[76:77], off offset:512
	s_waitcnt vmcnt(0) lgkmcnt(0)
	v_pk_add_f32 v[56:57], v[56:57], v[60:61]
	v_pk_add_f32 v[54:55], v[54:55], v[58:59]
	global_store_dwordx4 v[70:71], v[54:57], off offset:512
	global_load_dwordx4 v[54:57], v[76:77], off offset:576
	v_add_u32_e32 v58, 0x90, v138
	v_ashrrev_i32_e32 v59, 31, v58
	v_lshlrev_b64 v[58:59], 10, v[58:59]
	v_lshl_add_u64 v[58:59], v[58:59], 0, v[136:137]
	v_lshlrev_b64 v[58:59], 2, v[58:59]
	v_lshl_add_u64 v[60:61], s[4:5], 0, v[58:59]
	s_waitcnt vmcnt(0) lgkmcnt(0)
	v_pk_add_f32 v[44:45], v[44:45], v[56:57]
	v_pk_add_f32 v[42:43], v[42:43], v[54:55]
	global_store_dwordx4 v[70:71], v[42:45], off offset:576
	global_load_dwordx4 v[42:45], v[60:61], off
	v_lshl_add_u64 v[54:55], s[10:11], 0, v[58:59]
	s_waitcnt vmcnt(0) lgkmcnt(0)
	v_pk_add_f32 v[44:45], v[52:53], v[44:45]
	v_pk_add_f32 v[42:43], v[50:51], v[42:43]
	global_store_dwordx4 v[54:55], v[42:45], off
	global_load_dwordx4 v[42:45], v[60:61], off offset:64
	s_waitcnt vmcnt(0) lgkmcnt(0)
	v_pk_add_f32 v[44:45], v[48:49], v[44:45]
	v_pk_add_f32 v[42:43], v[46:47], v[42:43]
	global_store_dwordx4 v[54:55], v[42:45], off offset:64
	global_load_dwordx4 v[42:45], v[60:61], off offset:512
	s_waitcnt vmcnt(0) lgkmcnt(0)
	v_pk_add_f32 v[40:41], v[40:41], v[44:45]
	v_pk_add_f32 v[38:39], v[38:39], v[42:43]
	global_store_dwordx4 v[54:55], v[38:41], off offset:512
	global_load_dwordx4 v[38:41], v[60:61], off offset:576
	v_add_u32_e32 v42, 0xa0, v138
	v_ashrrev_i32_e32 v43, 31, v42
	v_lshlrev_b64 v[42:43], 10, v[42:43]
	v_lshl_add_u64 v[42:43], v[42:43], 0, v[136:137]
	v_lshlrev_b64 v[42:43], 2, v[42:43]
	v_lshl_add_u64 v[44:45], s[4:5], 0, v[42:43]
	s_waitcnt vmcnt(0) lgkmcnt(0)
	v_pk_add_f32 v[28:29], v[28:29], v[40:41]
	v_pk_add_f32 v[26:27], v[26:27], v[38:39]
	global_store_dwordx4 v[54:55], v[26:29], off offset:576
	global_load_dwordx4 v[26:29], v[44:45], off
	v_lshl_add_u64 v[38:39], s[10:11], 0, v[42:43]
	s_waitcnt vmcnt(0) lgkmcnt(0)
	v_pk_add_f32 v[28:29], v[36:37], v[28:29]
	v_pk_add_f32 v[26:27], v[34:35], v[26:27]
	global_store_dwordx4 v[38:39], v[26:29], off
	global_load_dwordx4 v[26:29], v[44:45], off offset:64
	s_waitcnt vmcnt(0) lgkmcnt(0)
	v_pk_add_f32 v[28:29], v[32:33], v[28:29]
	v_pk_add_f32 v[26:27], v[30:31], v[26:27]
	global_store_dwordx4 v[38:39], v[26:29], off offset:64
	global_load_dwordx4 v[26:29], v[44:45], off offset:512
	s_waitcnt vmcnt(0) lgkmcnt(0)
	v_pk_add_f32 v[24:25], v[24:25], v[28:29]
	v_pk_add_f32 v[22:23], v[22:23], v[26:27]
	global_store_dwordx4 v[38:39], v[22:25], off offset:512
	global_load_dwordx4 v[22:25], v[44:45], off offset:576
	v_add_u32_e32 v26, 0xb0, v138
	v_ashrrev_i32_e32 v27, 31, v26
	v_lshlrev_b64 v[26:27], 10, v[26:27]
	v_lshl_add_u64 v[26:27], v[26:27], 0, v[136:137]
	v_lshlrev_b64 v[26:27], 2, v[26:27]
	v_lshl_add_u64 v[28:29], s[4:5], 0, v[26:27]
	s_waitcnt vmcnt(0) lgkmcnt(0)
	v_pk_add_f32 v[12:13], v[12:13], v[24:25]
	v_pk_add_f32 v[10:11], v[10:11], v[22:23]
	global_store_dwordx4 v[38:39], v[10:13], off offset:576
	global_load_dwordx4 v[10:13], v[28:29], off
	v_lshl_add_u64 v[22:23], s[10:11], 0, v[26:27]
	s_waitcnt vmcnt(0) lgkmcnt(0)
	v_pk_add_f32 v[12:13], v[20:21], v[12:13]
	v_pk_add_f32 v[10:11], v[18:19], v[10:11]
	global_store_dwordx4 v[22:23], v[10:13], off
	global_load_dwordx4 v[10:13], v[28:29], off offset:64
	s_waitcnt vmcnt(0) lgkmcnt(0)
	v_pk_add_f32 v[12:13], v[16:17], v[12:13]
	v_pk_add_f32 v[10:11], v[14:15], v[10:11]
	global_store_dwordx4 v[22:23], v[10:13], off offset:64
	global_load_dwordx4 v[10:13], v[28:29], off offset:512
	s_waitcnt vmcnt(0) lgkmcnt(0)
	v_pk_add_f32 v[8:9], v[8:9], v[12:13]
	v_pk_add_f32 v[6:7], v[6:7], v[10:11]
	global_store_dwordx4 v[22:23], v[6:9], off offset:512
	global_load_dwordx4 v[6:9], v[28:29], off offset:576
	s_waitcnt vmcnt(0) lgkmcnt(0)
	v_pk_add_f32 v[4:5], v[4:5], v[8:9]
	v_pk_add_f32 v[2:3], v[2:3], v[6:7]
	global_store_dwordx4 v[22:23], v[2:5], off offset:576
	s_cbranch_vccnz .LBB0_438
	s_andn2_b64 vcc, exec, s[2:3]
	s_cbranch_vccnz .LBB0_437
	s_barrier
	s_branch .LBB0_437

; __device__ __forceinline__ float bflo(unsigned u) { return __uint_as_float(u << 16); }
; __device__ __forceinline__ float bfhi(unsigned u) { return __uint_as_float(u & 0xffff0000u); }
; __device__ __forceinline__ float silu(float g) { return g * __builtin_amdgcn_rcpf(1.0f + __expf(-g)); }
; template <int MODE>
; __device__ __forceinline__ void attn_item(const AttnP& p, int b, int h, int qb, LAS unsigned char* lds) {
;     ...
;     float inv0 = 1.f, inv1 = 0.f;
;     if (MODE != 1) { float l0 = lsum[0]; l0 += __shfl_xor(l0, 32); inv0 = 1.0f / l0; }
;     if (MODE == 0) { float l1 = lsum[NC - 1]; l1 += __shfl_xor(l1, 32); inv1 = p.lam / l1; }
;     float ss = 0.f;
; #pragma unroll
;     for (int d = 0; d < DV / 32; ++d)
; #pragma unroll
;         for (int i = 0; i < 16; ++i) {
;             float o = O[0][d][i] * inv0;
;             if (MODE == 0) o -= O[NC - 1][d][i] * inv1;
;             O[0][d][i] = o; ss += o * o;
;         }
;     ss += __shfl_xor(ss, 32);
;     float rn = 1.0f / sqrtf(ss * (1.0f / DV) + 1e-6f);
;     if (MODE == 0) rn *= p.oml;
;     int qrow_e = qrow; asm volatile("" : "+v"(qrow_e));
;     const size_t trow = (size_t)(tok0 + qrow_e);
; #pragma unroll
;     for (int d = 0; d < DV / 32; ++d)
; #pragma unroll
;         for (int g = 0; g < 4; ++g) {
;             const int dd = d * 32 + 8 * g + 4 * hh;
;             const u32x2 gr = *(const u32x2*)(P + trow * PP + gcol + dd);
;             const f32x4 og = *(const f32x4*)(p.out_gain + gaincol + dd);
;             const float o0 = O[0][d][4 * g] * rn * og[0] * silu(bflo(gr.x)), o1 = O[0][d][4 * g + 1] * rn * og[1] * silu(bfhi(gr.x));
;             const float o2 = O[0][d][4 * g + 2] * rn * og[2] * silu(bflo(gr.y)), o3 = O[0][d][4 * g + 3] * rn * og[3] * silu(bfhi(gr.y));
.LBB0_467:
	ds_bpermute_b32 v0, v226, v209
	s_mov_b32 s1, s93
	s_waitcnt lgkmcnt(0)
	v_add_f32_e32 v0, v209, v0
	v_div_scale_f32 v130, s[2:3], v0, v0, 1.0
	v_rcp_f32_e32 v131, v130
	s_nop 0
	v_fma_f32 v132, -v130, v131, 1.0
	v_fmac_f32_e32 v131, v132, v131
	v_div_scale_f32 v132, vcc, 1.0, v0, 1.0
	v_mul_f32_e32 v133, v132, v131
	v_fma_f32 v134, -v130, v133, v132
	v_fmac_f32_e32 v133, v134, v131
	v_fma_f32 v130, -v130, v133, v132
	v_div_fmas_f32 v130, v130, v131, v133
	v_div_fixup_f32 v138, v130, v0, 1.0
	ds_bpermute_b32 v0, v226, v208
	s_waitcnt lgkmcnt(0)
	v_add_f32_e32 v0, v208, v0
	v_div_scale_f32 v130, s[2:3], v0, v0, s56
	v_rcp_f32_e32 v131, v130
	s_nop 0
	v_fma_f32 v132, -v130, v131, 1.0
	v_fmac_f32_e32 v131, v132, v131
	v_div_scale_f32 v132, vcc, s56, v0, s56
	v_mul_f32_e32 v133, v132, v131
	v_fma_f32 v134, -v130, v133, v132
	v_fmac_f32_e32 v133, v134, v131
	v_fma_f32 v130, -v130, v133, v132
	v_div_fmas_f32 v130, v130, v131, v133
	v_div_fixup_f32 v140, v130, v0, s56
	v_pk_mul_f32 v[12:13], v[12:13], v[140:141] op_sel_hi:[1,0]
	v_lshlrev_b32_e32 v0, 1, v230
	v_pk_fma_f32 v[130:131], v[44:45], v[138:139], v[12:13] op_sel_hi:[1,0,1] neg_lo:[0,0,1] neg_hi:[0,0,1]
	v_pk_mul_f32 v[12:13], v[14:15], v[140:141] op_sel_hi:[1,0]
	v_mov_b64_e32 v[14:15], s[46:47]
	v_pk_fma_f32 v[44:45], v[46:47], v[138:139], v[12:13] op_sel_hi:[1,0,1] neg_lo:[0,0,1] neg_hi:[0,0,1]
	v_pk_mul_f32 v[12:13], v[16:17], v[140:141] op_sel_hi:[1,0]
	v_pk_mul_f32 v[98:99], v[98:99], v[140:141] op_sel_hi:[1,0]
	v_pk_fma_f32 v[16:17], v[48:49], v[138:139], v[12:13] op_sel_hi:[1,0,1] neg_lo:[0,0,1] neg_hi:[0,0,1]
	v_add_u32_e32 v12, s8, v228
	v_mad_i64_i32 v[14:15], s[2:3], v12, s76, v[14:15]
	v_lshl_add_u64 v[14:15], v[14:15], 0, s[0:1]
	v_lshl_add_u64 v[48:49], v[14:15], 0, v[0:1]
	global_load_dwordx2 v[146:147], v[48:49], off offset:3072
	global_load_dwordx2 v[150:151], v[48:49], off offset:3088
	global_load_dwordx2 v[154:155], v[48:49], off offset:3104
	global_load_dwordx2 v[156:157], v[48:49], off offset:3184
	v_lshlrev_b32_e32 v139, 2, v230
	v_pk_mul_f32 v[100:101], v[100:101], v[140:141] op_sel_hi:[1,0]
	v_pk_fma_f32 v[98:99], v[114:115], v[138:139], v[98:99] op_sel_hi:[1,0,1] neg_lo:[0,0,1] neg_hi:[0,0,1]
	v_pk_fma_f32 v[100:101], v[116:117], v[138:139], v[100:101] op_sel_hi:[1,0,1] neg_lo:[0,0,1] neg_hi:[0,0,1]
	v_ashrrev_i32_e32 v13, 31, v12
	v_lshlrev_b64 v[46:47], 11, v[12:13]
	v_lshl_add_u64 v[46:47], s[44:45], 0, v[46:47]
	v_lshl_add_u64 v[46:47], v[46:47], 0, s[0:1]
	v_lshl_add_u64 v[46:47], v[46:47], 0, v[0:1]
	v_pk_mul_f32 v[144:145], v[98:99], v[98:99]
	v_pk_mul_f32 v[142:143], v[100:101], v[100:101]
	s_lshl_b32 s2, s9, 2
	s_add_u32 s4, s54, s2
	s_addc_u32 s5, s55, 0
	global_load_dwordx4 v[12:15], v139, s[4:5]
	v_pk_mul_f32 v[132:133], v[130:131], v[130:131]
	v_pk_mul_f32 v[134:135], v[44:45], v[44:45]
	v_pk_mul_f32 v[136:137], v[16:17], v[16:17]
	s_waitcnt vmcnt(0) lgkmcnt(0)
	v_lshlrev_b32_e32 v114, 16, v146
	v_and_b32_e32 v115, 0xffff0000, v146
	v_mul_f32_e32 v116, 0xbfb8aa3b, v114
	v_mul_f32_e32 v117, 0xbfb8aa3b, v115
	v_exp_f32_e32 v116, v116
	v_exp_f32_e32 v117, v117
	v_add_f32_e32 v116, 1.0, v116
	v_add_f32_e32 v117, 1.0, v117
	v_rcp_f32_e32 v116, v116
	v_rcp_f32_e32 v117, v117
	s_nop 0
	v_pk_mul_f32 v[114:115], v[116:117], v[114:115]
	v_lshlrev_b32_e32 v116, 16, v147
	v_mul_f32_e32 v141, 0xbfb8aa3b, v116
	v_exp_f32_e32 v141, v141
	v_and_b32_e32 v117, 0xffff0000, v147
	v_add_f32_e32 v141, 1.0, v141
	v_rcp_f32_e32 v146, v141
	v_mul_f32_e32 v141, 0xbfb8aa3b, v117
	v_exp_f32_e32 v141, v141
	s_nop 0
	v_add_f32_e32 v141, 1.0, v141
	v_pk_mul_f32 v[102:103], v[102:103], v[140:141] op_sel_hi:[1,0]
	v_pk_mul_f32 v[104:105], v[104:105], v[140:141] op_sel_hi:[1,0]
	v_pk_fma_f32 v[102:103], v[118:119], v[138:139], v[102:103] op_sel_hi:[1,0,1] neg_lo:[0,0,1] neg_hi:[0,0,1]
	v_lshlrev_b32_e32 v118, 16, v150
	v_mul_f32_e32 v0, 0xbfb8aa3b, v118
	v_exp_f32_e32 v0, v0
	v_and_b32_e32 v119, 0xffff0000, v150
	v_pk_fma_f32 v[104:105], v[120:121], v[138:139], v[104:105] op_sel_hi:[1,0,1] neg_lo:[0,0,1] neg_hi:[0,0,1]
	v_pk_mul_f32 v[106:107], v[106:107], v[140:141] op_sel_hi:[1,0]
	v_add_f32_e32 v0, 1.0, v0
	v_rcp_f32_e32 v120, v0
	v_mul_f32_e32 v0, 0xbfb8aa3b, v119
	v_exp_f32_e32 v0, v0
	v_pk_fma_f32 v[106:107], v[122:123], v[138:139], v[106:107] op_sel_hi:[1,0,1] neg_lo:[0,0,1] neg_hi:[0,0,1]
	v_lshlrev_b32_e32 v122, 16, v154
	v_pk_mul_f32 v[108:109], v[108:109], v[140:141] op_sel_hi:[1,0]
	v_add_f32_e32 v0, 1.0, v0
	v_rcp_f32_e32 v121, v0
	v_and_b32_e32 v123, 0xffff0000, v154
	v_pk_fma_f32 v[108:109], v[124:125], v[138:139], v[108:109] op_sel_hi:[1,0,1] neg_lo:[0,0,1] neg_hi:[0,0,1]
	v_pk_mul_f32 v[110:111], v[110:111], v[140:141] op_sel_hi:[1,0]
	v_pk_mul_f32 v[118:119], v[120:121], v[118:119]
	v_lshlrev_b32_e32 v120, 16, v151
	v_mul_f32_e32 v0, 0xbfb8aa3b, v120
	v_exp_f32_e32 v0, v0
	v_and_b32_e32 v121, 0xffff0000, v151
	v_pk_fma_f32 v[110:111], v[126:127], v[138:139], v[110:111] op_sel_hi:[1,0,1] neg_lo:[0,0,1] neg_hi:[0,0,1]
	v_pk_mul_f32 v[112:113], v[112:113], v[140:141] op_sel_hi:[1,0]
	v_add_f32_e32 v0, 1.0, v0
	v_rcp_f32_e32 v150, v0
	v_mul_f32_e32 v0, 0xbfb8aa3b, v121
	v_exp_f32_e32 v0, v0
	v_pk_fma_f32 v[112:113], v[128:129], v[138:139], v[112:113] op_sel_hi:[1,0,1] neg_lo:[0,0,1] neg_hi:[0,0,1]
	v_pk_mul_f32 v[66:67], v[66:67], v[140:141] op_sel_hi:[1,0]
	v_pk_mul_f32 v[68:69], v[68:69], v[140:141] op_sel_hi:[1,0]
	v_add_f32_e32 v0, 1.0, v0
	v_rcp_f32_e32 v151, v0
	v_mul_f32_e32 v0, 0xbfb8aa3b, v122
	v_exp_f32_e32 v0, v0
	v_pk_fma_f32 v[66:67], v[82:83], v[138:139], v[66:67] op_sel_hi:[1,0,1] neg_lo:[0,0,1] neg_hi:[0,0,1]
; __device__ __forceinline__ float bflo(unsigned u) { return __uint_as_float(u << 16); }
; __device__ __forceinline__ float bfhi(unsigned u) { return __uint_as_float(u & 0xffff0000u); }
; __device__ __forceinline__ float silu(float g) { return g * __builtin_amdgcn_rcpf(1.0f + __expf(-g)); }
; template <int MODE>
; __device__ __forceinline__ void attn_item(const AttnP& p, int b, int h, int qb, LAS unsigned char* lds) {
;     ...
;             float o = O[0][d][i] * inv0;
;             if (MODE == 0) o -= O[NC - 1][d][i] * inv1;
;             O[0][d][i] = o; ss += o * o;
;         }
;     ss += __shfl_xor(ss, 32);
;     float rn = 1.0f / sqrtf(ss * (1.0f / DV) + 1e-6f);
;     if (MODE == 0) rn *= p.oml;
;     int qrow_e = qrow; asm volatile("" : "+v"(qrow_e));
;     const size_t trow = (size_t)(tok0 + qrow_e);
; #pragma unroll
;     for (int d = 0; d < DV / 32; ++d)
; #pragma unroll
;         for (int g = 0; g < 4; ++g) {
;             const int dd = d * 32 + 8 * g + 4 * hh;
;             const u32x2 gr = *(const u32x2*)(P + trow * PP + gcol + dd);
;             const f32x4 og = *(const f32x4*)(p.out_gain + gaincol + dd);
;             const float o0 = O[0][d][4 * g] * rn * og[0] * silu(bflo(gr.x)), o1 = O[0][d][4 * g + 1] * rn * og[1] * silu(bfhi(gr.x));
;             const float o2 = O[0][d][4 * g + 2] * rn * og[2] * silu(bflo(gr.y)), o3 = O[0][d][4 * g + 3] * rn * og[3] * silu(bfhi(gr.y));
	v_pk_fma_f32 v[68:69], v[84:85], v[138:139], v[68:69] op_sel_hi:[1,0,1] neg_lo:[0,0,1] neg_hi:[0,0,1]
	v_pk_mul_f32 v[70:71], v[70:71], v[140:141] op_sel_hi:[1,0]
	v_add_f32_e32 v0, 1.0, v0
	v_rcp_f32_e32 v124, v0
	v_mul_f32_e32 v0, 0xbfb8aa3b, v123
	v_exp_f32_e32 v0, v0
	v_pk_fma_f32 v[70:71], v[86:87], v[138:139], v[70:71] op_sel_hi:[1,0,1] neg_lo:[0,0,1] neg_hi:[0,0,1]
	v_pk_mul_f32 v[72:73], v[72:73], v[140:141] op_sel_hi:[1,0]
	v_pk_mul_f32 v[74:75], v[74:75], v[140:141] op_sel_hi:[1,0]
	v_add_f32_e32 v0, 1.0, v0
	v_rcp_f32_e32 v125, v0
	v_pk_fma_f32 v[72:73], v[88:89], v[138:139], v[72:73] op_sel_hi:[1,0,1] neg_lo:[0,0,1] neg_hi:[0,0,1]
	v_pk_fma_f32 v[74:75], v[90:91], v[138:139], v[74:75] op_sel_hi:[1,0,1] neg_lo:[0,0,1] neg_hi:[0,0,1]
	v_pk_mul_f32 v[76:77], v[76:77], v[140:141] op_sel_hi:[1,0]
	v_pk_mul_f32 v[122:123], v[124:125], v[122:123]
	v_lshlrev_b32_e32 v124, 16, v155
	v_mul_f32_e32 v0, 0xbfb8aa3b, v124
	v_exp_f32_e32 v0, v0
	v_and_b32_e32 v125, 0xffff0000, v155
	v_pk_fma_f32 v[76:77], v[92:93], v[138:139], v[76:77] op_sel_hi:[1,0,1] neg_lo:[0,0,1] neg_hi:[0,0,1]
	v_pk_mul_f32 v[78:79], v[78:79], v[140:141] op_sel_hi:[1,0]
	v_add_f32_e32 v0, 1.0, v0
	v_rcp_f32_e32 v154, v0
	v_mul_f32_e32 v0, 0xbfb8aa3b, v125
	v_exp_f32_e32 v0, v0
	v_pk_fma_f32 v[94:95], v[94:95], v[138:139], v[78:79] op_sel_hi:[1,0,1] neg_lo:[0,0,1] neg_hi:[0,0,1]
	v_lshlrev_b32_e32 v78, 16, v156
	v_pk_mul_f32 v[80:81], v[80:81], v[140:141] op_sel_hi:[1,0]
	v_add_f32_e32 v0, 1.0, v0
	v_rcp_f32_e32 v155, v0
	v_and_b32_e32 v79, 0xffff0000, v156
	v_pk_fma_f32 v[96:97], v[96:97], v[138:139], v[80:81] op_sel_hi:[1,0,1] neg_lo:[0,0,1] neg_hi:[0,0,1]
	v_rcp_f32_e32 v147, v141
	v_pk_mul_f32 v[124:125], v[154:155], v[124:125]
	global_load_dwordx2 v[154:155], v[48:49], off offset:3120
	v_pk_mul_f32 v[148:149], v[102:103], v[102:103]
	v_pk_mul_f32 v[116:117], v[146:147], v[116:117]
	v_pk_mul_f32 v[146:147], v[104:105], v[104:105]
	v_pk_mul_f32 v[152:153], v[106:107], v[106:107]
	v_pk_mul_f32 v[120:121], v[150:151], v[120:121]
	v_pk_mul_f32 v[150:151], v[108:109], v[108:109]
	v_pk_mul_f32 v[160:161], v[110:111], v[110:111]
	v_pk_mul_f32 v[158:159], v[112:113], v[112:113]
	v_pk_mul_f32 v[164:165], v[66:67], v[66:67]
	v_pk_mul_f32 v[162:163], v[68:69], v[68:69]
	v_pk_mul_f32 v[168:169], v[70:71], v[70:71]
	v_pk_mul_f32 v[166:167], v[72:73], v[72:73]
	v_pk_mul_f32 v[172:173], v[74:75], v[74:75]
	v_pk_mul_f32 v[170:171], v[76:77], v[76:77]
	v_pk_mul_f32 v[176:177], v[94:95], v[94:95]
	v_pk_mul_f32 v[174:175], v[96:97], v[96:97]
	v_pk_mul_f32 v[18:19], v[18:19], v[140:141] op_sel_hi:[1,0]
	v_pk_mul_f32 v[20:21], v[20:21], v[140:141] op_sel_hi:[1,0]
	v_pk_mul_f32 v[2:3], v[2:3], v[140:141] op_sel_hi:[1,0]
	v_pk_mul_f32 v[4:5], v[4:5], v[140:141] op_sel_hi:[1,0]
	s_waitcnt vmcnt(0) lgkmcnt(0)
	v_lshlrev_b32_e32 v126, 16, v154
	v_mul_f32_e32 v0, 0xbfb8aa3b, v126
	v_exp_f32_e32 v0, v0
	v_and_b32_e32 v127, 0xffff0000, v154
	v_add_f32_e32 v0, 1.0, v0
	v_rcp_f32_e32 v128, v0
	v_mul_f32_e32 v0, 0xbfb8aa3b, v127
	v_exp_f32_e32 v0, v0
	s_nop 0
	v_add_f32_e32 v0, 1.0, v0
	v_rcp_f32_e32 v129, v0
	s_nop 0
	v_pk_mul_f32 v[128:129], v[128:129], v[126:127]
	v_lshlrev_b32_e32 v126, 16, v155
	v_mul_f32_e32 v0, 0xbfb8aa3b, v126
	v_exp_f32_e32 v0, v0
	v_and_b32_e32 v127, 0xffff0000, v155
	v_add_f32_e32 v0, 1.0, v0
	v_rcp_f32_e32 v154, v0
	v_mul_f32_e32 v0, 0xbfb8aa3b, v127
	v_exp_f32_e32 v0, v0
	s_nop 0
	v_add_f32_e32 v0, 1.0, v0
	v_rcp_f32_e32 v155, v0
	s_nop 0
	v_pk_mul_f32 v[126:127], v[154:155], v[126:127]
	global_load_dwordx2 v[154:155], v[48:49], off offset:3136
	s_waitcnt vmcnt(0) lgkmcnt(0)
	v_lshlrev_b32_e32 v82, 16, v154
	v_mul_f32_e32 v0, 0xbfb8aa3b, v82
	v_exp_f32_e32 v0, v0
	v_and_b32_e32 v83, 0xffff0000, v154
	v_add_f32_e32 v0, 1.0, v0
	v_rcp_f32_e32 v84, v0
	v_mul_f32_e32 v0, 0xbfb8aa3b, v83
	v_exp_f32_e32 v0, v0
	s_nop 0
	v_add_f32_e32 v0, 1.0, v0
	v_rcp_f32_e32 v85, v0
	s_nop 0
	v_pk_mul_f32 v[84:85], v[84:85], v[82:83]
	v_lshlrev_b32_e32 v82, 16, v155
	v_mul_f32_e32 v0, 0xbfb8aa3b, v82
	v_exp_f32_e32 v0, v0
	v_and_b32_e32 v83, 0xffff0000, v155
	v_add_f32_e32 v0, 1.0, v0
	v_rcp_f32_e32 v154, v0
	v_mul_f32_e32 v0, 0xbfb8aa3b, v83
	v_exp_f32_e32 v0, v0
	s_nop 0
	v_add_f32_e32 v0, 1.0, v0
	v_rcp_f32_e32 v155, v0
	s_nop 0
	v_pk_mul_f32 v[82:83], v[154:155], v[82:83]
	global_load_dwordx2 v[154:155], v[48:49], off offset:3152
	s_waitcnt vmcnt(0) lgkmcnt(0)
	v_lshlrev_b32_e32 v86, 16, v154
	v_mul_f32_e32 v0, 0xbfb8aa3b, v86
	v_exp_f32_e32 v0, v0
	v_and_b32_e32 v87, 0xffff0000, v154
	v_add_f32_e32 v0, 1.0, v0
	v_rcp_f32_e32 v88, v0
	v_mul_f32_e32 v0, 0xbfb8aa3b, v87
	v_exp_f32_e32 v0, v0
	s_nop 0
	v_add_f32_e32 v0, 1.0, v0
	v_rcp_f32_e32 v89, v0
	s_nop 0
	v_pk_mul_f32 v[88:89], v[88:89], v[86:87]
	v_lshlrev_b32_e32 v86, 16, v155
	v_mul_f32_e32 v0, 0xbfb8aa3b, v86
	v_exp_f32_e32 v0, v0
	v_and_b32_e32 v87, 0xffff0000, v155
	v_add_f32_e32 v0, 1.0, v0
	v_rcp_f32_e32 v154, v0
	v_mul_f32_e32 v0, 0xbfb8aa3b, v87
	v_exp_f32_e32 v0, v0
	s_nop 0
	v_add_f32_e32 v0, 1.0, v0
	v_rcp_f32_e32 v155, v0
	s_nop 0
	v_pk_mul_f32 v[86:87], v[154:155], v[86:87]
	global_load_dwordx2 v[154:155], v[48:49], off offset:3168
	s_waitcnt vmcnt(0) lgkmcnt(0)
; __device__ __forceinline__ float bflo(unsigned u) { return __uint_as_float(u << 16); }
; __device__ __forceinline__ float bfhi(unsigned u) { return __uint_as_float(u & 0xffff0000u); }
; __device__ __forceinline__ float silu(float g) { return g * __builtin_amdgcn_rcpf(1.0f + __expf(-g)); }
; template <int MODE>
; __device__ __forceinline__ void attn_item(const AttnP& p, int b, int h, int qb, LAS unsigned char* lds) {
;     ...
;             float o = O[0][d][i] * inv0;
;             if (MODE == 0) o -= O[NC - 1][d][i] * inv1;
;             O[0][d][i] = o; ss += o * o;
;         }
;     ss += __shfl_xor(ss, 32);
;     float rn = 1.0f / sqrtf(ss * (1.0f / DV) + 1e-6f);
;     if (MODE == 0) rn *= p.oml;
;     int qrow_e = qrow; asm volatile("" : "+v"(qrow_e));
;     const size_t trow = (size_t)(tok0 + qrow_e);
; #pragma unroll
;     for (int d = 0; d < DV / 32; ++d)
; #pragma unroll
;         for (int g = 0; g < 4; ++g) {
;             const int dd = d * 32 + 8 * g + 4 * hh;
;             const u32x2 gr = *(const u32x2*)(P + trow * PP + gcol + dd);
;             const f32x4 og = *(const f32x4*)(p.out_gain + gaincol + dd);
;             const float o0 = O[0][d][4 * g] * rn * og[0] * silu(bflo(gr.x)), o1 = O[0][d][4 * g + 1] * rn * og[1] * silu(bfhi(gr.x));
;             const float o2 = O[0][d][4 * g + 2] * rn * og[2] * silu(bflo(gr.y)), o3 = O[0][d][4 * g + 3] * rn * og[3] * silu(bfhi(gr.y));
	v_lshlrev_b32_e32 v90, 16, v154
	v_mul_f32_e32 v0, 0xbfb8aa3b, v90
	v_exp_f32_e32 v0, v0
	v_and_b32_e32 v91, 0xffff0000, v154
	v_add_f32_e32 v0, 1.0, v0
	v_rcp_f32_e32 v92, v0
	v_mul_f32_e32 v0, 0xbfb8aa3b, v91
	v_exp_f32_e32 v0, v0
	s_nop 0
	v_add_f32_e32 v0, 1.0, v0
	v_rcp_f32_e32 v93, v0
	s_nop 0
	v_pk_mul_f32 v[92:93], v[92:93], v[90:91]
	v_lshlrev_b32_e32 v90, 16, v155
	v_mul_f32_e32 v0, 0xbfb8aa3b, v90
	v_exp_f32_e32 v0, v0
	v_and_b32_e32 v91, 0xffff0000, v155
	v_add_f32_e32 v0, 1.0, v0
	v_rcp_f32_e32 v154, v0
	v_mul_f32_e32 v0, 0xbfb8aa3b, v91
	v_exp_f32_e32 v0, v0
	s_nop 0
	v_add_f32_e32 v0, 1.0, v0
	v_rcp_f32_e32 v155, v0
	v_mul_f32_e32 v0, 0xbfb8aa3b, v78
	v_exp_f32_e32 v0, v0
	v_pk_mul_f32 v[90:91], v[154:155], v[90:91]
	v_add_f32_e32 v0, 1.0, v0
	v_rcp_f32_e32 v80, v0
	v_mul_f32_e32 v0, 0xbfb8aa3b, v79
	v_exp_f32_e32 v0, v0
	s_nop 0
	v_add_f32_e32 v0, 1.0, v0
	v_rcp_f32_e32 v81, v0
	s_nop 0
	v_pk_mul_f32 v[154:155], v[80:81], v[78:79]
	v_lshlrev_b32_e32 v78, 16, v157
	v_mul_f32_e32 v0, 0xbfb8aa3b, v78
	v_exp_f32_e32 v0, v0
	v_and_b32_e32 v79, 0xffff0000, v157
	v_add_f32_e32 v0, 1.0, v0
	v_rcp_f32_e32 v80, v0
	v_mul_f32_e32 v0, 0xbfb8aa3b, v79
	v_exp_f32_e32 v0, v0
	s_nop 0
	v_add_f32_e32 v0, 1.0, v0
	v_rcp_f32_e32 v81, v0
	v_add_f32_e32 v0, v144, v145
	v_add_f32_e32 v0, v142, v0
	v_add_f32_e32 v0, v143, v0
	v_add_f32_e32 v0, v148, v0
	v_add_f32_e32 v0, v149, v0
	v_add_f32_e32 v0, v146, v0
	v_add_f32_e32 v0, v147, v0
	v_add_f32_e32 v0, v152, v0
	v_add_f32_e32 v0, v153, v0
	v_add_f32_e32 v0, v150, v0
	v_add_f32_e32 v0, v151, v0
	v_add_f32_e32 v0, v160, v0
	v_add_f32_e32 v0, v161, v0
	v_add_f32_e32 v0, v158, v0
	v_add_f32_e32 v0, v159, v0
	v_add_f32_e32 v0, v164, v0
	v_add_f32_e32 v0, v165, v0
	v_add_f32_e32 v0, v162, v0
	v_add_f32_e32 v0, v163, v0
	v_add_f32_e32 v0, v168, v0
	v_add_f32_e32 v0, v169, v0
	v_add_f32_e32 v0, v166, v0
	v_add_f32_e32 v0, v167, v0
	v_add_f32_e32 v0, v172, v0
	v_add_f32_e32 v0, v173, v0
	v_add_f32_e32 v0, v170, v0
	v_add_f32_e32 v0, v171, v0
	v_add_f32_e32 v0, v176, v0
	v_add_f32_e32 v0, v177, v0
	v_pk_mul_f32 v[156:157], v[80:81], v[78:79]
	v_pk_fma_f32 v[80:81], v[50:51], v[138:139], v[18:19] op_sel_hi:[1,0,1] neg_lo:[0,0,1] neg_hi:[0,0,1]
	v_add_f32_e32 v0, v174, v0
	v_pk_mul_f32 v[180:181], v[80:81], v[80:81]
	v_add_f32_e32 v0, v175, v0
	v_pk_fma_f32 v[78:79], v[52:53], v[138:139], v[20:21] op_sel_hi:[1,0,1] neg_lo:[0,0,1] neg_hi:[0,0,1]
	v_pk_mul_f32 v[18:19], v[24:25], v[140:141] op_sel_hi:[1,0]
	v_add_f32_e32 v0, v180, v0
	v_pk_mul_f32 v[178:179], v[78:79], v[78:79]
	v_pk_fma_f32 v[50:51], v[56:57], v[138:139], v[18:19] op_sel_hi:[1,0,1] neg_lo:[0,0,1] neg_hi:[0,0,1]
	v_pk_mul_f32 v[18:19], v[22:23], v[140:141] op_sel_hi:[1,0]
	v_add_f32_e32 v0, v181, v0
	v_pk_fma_f32 v[52:53], v[54:55], v[138:139], v[18:19] op_sel_hi:[1,0,1] neg_lo:[0,0,1] neg_hi:[0,0,1]
	v_add_f32_e32 v0, v178, v0
	v_pk_mul_f32 v[54:55], v[52:53], v[52:53]
	v_add_f32_e32 v0, v179, v0
	v_pk_mul_f32 v[18:19], v[28:29], v[140:141] op_sel_hi:[1,0]
	v_add_f32_e32 v0, v54, v0
	v_pk_mul_f32 v[56:57], v[50:51], v[50:51]
	v_pk_fma_f32 v[28:29], v[60:61], v[138:139], v[18:19] op_sel_hi:[1,0,1] neg_lo:[0,0,1] neg_hi:[0,0,1]
	v_pk_mul_f32 v[18:19], v[26:27], v[140:141] op_sel_hi:[1,0]
	v_add_f32_e32 v0, v55, v0
	v_pk_fma_f32 v[26:27], v[58:59], v[138:139], v[18:19] op_sel_hi:[1,0,1] neg_lo:[0,0,1] neg_hi:[0,0,1]
	v_add_f32_e32 v0, v56, v0
	v_pk_mul_f32 v[58:59], v[26:27], v[26:27]
	v_add_f32_e32 v0, v57, v0
	v_pk_mul_f32 v[18:19], v[32:33], v[140:141] op_sel_hi:[1,0]
	v_add_f32_e32 v0, v58, v0
	v_pk_mul_f32 v[60:61], v[28:29], v[28:29]
	v_pk_fma_f32 v[22:23], v[64:65], v[138:139], v[18:19] op_sel_hi:[1,0,1] neg_lo:[0,0,1] neg_hi:[0,0,1]
	v_pk_mul_f32 v[18:19], v[30:31], v[140:141] op_sel_hi:[1,0]
	v_add_f32_e32 v0, v59, v0
	v_pk_fma_f32 v[24:25], v[62:63], v[138:139], v[18:19] op_sel_hi:[1,0,1] neg_lo:[0,0,1] neg_hi:[0,0,1]
	v_add_f32_e32 v0, v60, v0
	v_pk_mul_f32 v[30:31], v[24:25], v[24:25]
	v_add_f32_e32 v0, v61, v0
	v_add_f32_e32 v0, v30, v0
	v_pk_mul_f32 v[32:33], v[22:23], v[22:23]
	v_add_f32_e32 v0, v31, v0
	v_pk_fma_f32 v[20:21], v[34:35], v[138:139], v[2:3] op_sel_hi:[1,0,1] neg_lo:[0,0,1] neg_hi:[0,0,1]
	v_add_f32_e32 v0, v32, v0
	v_pk_mul_f32 v[34:35], v[20:21], v[20:21]
	v_add_f32_e32 v0, v33, v0
	v_pk_fma_f32 v[18:19], v[36:37], v[138:139], v[4:5] op_sel_hi:[1,0,1] neg_lo:[0,0,1] neg_hi:[0,0,1]
	v_pk_mul_f32 v[2:3], v[8:9], v[140:141] op_sel_hi:[1,0]
	v_add_f32_e32 v0, v34, v0
	v_pk_mul_f32 v[36:37], v[18:19], v[18:19]
	v_pk_fma_f32 v[4:5], v[40:41], v[138:139], v[2:3] op_sel_hi:[1,0,1] neg_lo:[0,0,1] neg_hi:[0,0,1]
	v_pk_mul_f32 v[2:3], v[6:7], v[140:141] op_sel_hi:[1,0]
	v_add_f32_e32 v0, v35, v0
	v_pk_fma_f32 v[6:7], v[38:39], v[138:139], v[2:3] op_sel_hi:[1,0,1] neg_lo:[0,0,1] neg_hi:[0,0,1]
	v_add_f32_e32 v0, v36, v0
	v_pk_mul_f32 v[38:39], v[6:7], v[6:7]
	v_add_f32_e32 v0, v37, v0
	v_add_f32_e32 v0, v38, v0
	v_pk_mul_f32 v[8:9], v[4:5], v[4:5]
	v_pk_mul_f32 v[2:3], v[10:11], v[140:141] op_sel_hi:[1,0]
	v_add_f32_e32 v0, v39, v0
	v_pk_fma_f32 v[2:3], v[42:43], v[138:139], v[2:3] op_sel_hi:[1,0,1] neg_lo:[0,0,1] neg_hi:[0,0,1]
	v_add_f32_e32 v0, v8, v0
	v_pk_mul_f32 v[10:11], v[2:3], v[2:3]
	v_add_f32_e32 v0, v9, v0
	v_add_f32_e32 v0, v10, v0
	v_add_f32_e32 v0, v11, v0
	v_add_f32_e32 v0, v132, v0
	v_add_f32_e32 v0, v133, v0
	v_add_f32_e32 v0, v134, v0
	v_add_f32_e32 v0, v135, v0
	v_add_f32_e32 v0, v136, v0
	v_add_f32_e32 v0, v137, v0
	ds_bpermute_b32 v8, v226, v0
	s_waitcnt lgkmcnt(0)
; __device__ __forceinline__ unsigned pk2(float lo, float hi) { f32x2 v = {lo, hi}; bf16x2_t b = __builtin_convertvector(v, bf16x2_t); return __builtin_bit_cast(unsigned, b); }
; __device__ __forceinline__ float bflo(unsigned u) { return __uint_as_float(u << 16); }
; __device__ __forceinline__ float bfhi(unsigned u) { return __uint_as_float(u & 0xffff0000u); }
; __device__ __forceinline__ float silu(float g) { return g * __builtin_amdgcn_rcpf(1.0f + __expf(-g)); }
; template <int MODE>
; __device__ __forceinline__ void attn_item(const AttnP& p, int b, int h, int qb, LAS unsigned char* lds) {
;     ...
;     ss += __shfl_xor(ss, 32);
;     float rn = 1.0f / sqrtf(ss * (1.0f / DV) + 1e-6f);
;     if (MODE == 0) rn *= p.oml;
;     int qrow_e = qrow; asm volatile("" : "+v"(qrow_e));
;     const size_t trow = (size_t)(tok0 + qrow_e);
; #pragma unroll
;     for (int d = 0; d < DV / 32; ++d)
; #pragma unroll
;         for (int g = 0; g < 4; ++g) {
;             const int dd = d * 32 + 8 * g + 4 * hh;
;             const u32x2 gr = *(const u32x2*)(P + trow * PP + gcol + dd);
;             const f32x4 og = *(const f32x4*)(p.out_gain + gaincol + dd);
;             const float o0 = O[0][d][4 * g] * rn * og[0] * silu(bflo(gr.x)), o1 = O[0][d][4 * g + 1] * rn * og[1] * silu(bfhi(gr.x));
;             const float o2 = O[0][d][4 * g + 2] * rn * og[2] * silu(bflo(gr.y)), o3 = O[0][d][4 * g + 3] * rn * og[3] * silu(bfhi(gr.y));
;             u32x2 wv; wv.x = pk2(o0, o1); wv.y = pk2(o2, o3);
;             *(u32x2*)(p.mixed + trow * 1024 + mixcol + dd) = wv;
	v_add_f32_e32 v0, v0, v8
	v_fmamk_f32 v0, v0, 0x3c000000, v211
	v_cmp_gt_f32_e32 vcc, s74, v0
	v_mul_f32_e32 v8, 0x4f800000, v0
	s_nop 0
	v_cndmask_b32_e32 v0, v0, v8, vcc
	v_sqrt_f32_e32 v8, v0
	s_nop 0
	v_add_u32_e32 v9, -1, v8
	v_fma_f32 v10, -v9, v8, v0
	v_cmp_ge_f32_e64 s[0:1], 0, v10
	v_add_u32_e32 v10, 1, v8
	s_nop 0
	v_cndmask_b32_e64 v9, v8, v9, s[0:1]
	v_fma_f32 v8, -v10, v8, v0
	v_cmp_lt_f32_e64 s[0:1], 0, v8
	s_nop 1
	v_cndmask_b32_e64 v8, v9, v10, s[0:1]
	v_mul_f32_e32 v9, 0x37800000, v8
	v_cndmask_b32_e32 v8, v8, v9, vcc
	v_cmp_class_f32_e32 vcc, v0, v212
	s_nop 1
	v_cndmask_b32_e32 v0, v8, v0, vcc
	v_div_scale_f32 v8, s[0:1], v0, v0, 1.0
	v_rcp_f32_e32 v9, v8
	s_nop 0
	v_fma_f32 v10, -v8, v9, 1.0
	v_fmac_f32_e32 v9, v10, v9
	v_div_scale_f32 v10, vcc, 1.0, v0, 1.0
	v_mul_f32_e32 v11, v10, v9
	v_fma_f32 v30, -v8, v11, v10
	v_fmac_f32_e32 v11, v30, v9
	v_fma_f32 v8, -v8, v11, v10
	v_div_fmas_f32 v8, v8, v9, v11
	v_div_fixup_f32 v0, v8, v0, 1.0
	v_mul_f32_e32 v0, v227, v0
	v_pk_mul_f32 v[8:9], v[98:99], v[0:1] op_sel_hi:[1,0]
	v_pk_mul_f32 v[10:11], v[100:101], v[0:1] op_sel_hi:[1,0]
	v_pk_mul_f32 v[8:9], v[12:13], v[8:9]
	v_pk_mul_f32 v[10:11], v[14:15], v[10:11]
	v_pk_mul_f32 v[8:9], v[114:115], v[8:9]
	v_pk_mul_f32 v[10:11], v[116:117], v[10:11]
	v_cvt_pk_bf16_f32 v8, v8, v9
	v_cvt_pk_bf16_f32 v9, v10, v11
	global_store_dwordx2 v[46:47], v[8:9], off
	global_load_dwordx4 v[8:11], v139, s[4:5] offset:32
	v_pk_mul_f32 v[12:13], v[102:103], v[0:1] op_sel_hi:[1,0]
	v_pk_mul_f32 v[32:33], v[80:81], v[0:1] op_sel_hi:[1,0]
	v_pk_mul_f32 v[26:27], v[26:27], v[0:1] op_sel_hi:[1,0]
	v_pk_mul_f32 v[24:25], v[24:25], v[0:1] op_sel_hi:[1,0]
	v_pk_mul_f32 v[22:23], v[22:23], v[0:1] op_sel_hi:[1,0]
	v_pk_mul_f32 v[20:21], v[20:21], v[0:1] op_sel_hi:[1,0]
	v_pk_mul_f32 v[18:19], v[18:19], v[0:1] op_sel_hi:[1,0]
	v_pk_mul_f32 v[6:7], v[6:7], v[0:1] op_sel_hi:[1,0]
	v_pk_mul_f32 v[4:5], v[4:5], v[0:1] op_sel_hi:[1,0]
	v_pk_mul_f32 v[2:3], v[2:3], v[0:1] op_sel_hi:[1,0]
	s_waitcnt vmcnt(0)
	v_pk_mul_f32 v[8:9], v[8:9], v[12:13]
	v_pk_mul_f32 v[12:13], v[104:105], v[0:1] op_sel_hi:[1,0]
	v_pk_mul_f32 v[8:9], v[118:119], v[8:9]
	v_pk_mul_f32 v[10:11], v[10:11], v[12:13]
	v_cvt_pk_bf16_f32 v8, v8, v9
	v_pk_mul_f32 v[10:11], v[120:121], v[10:11]
	v_pk_mul_f32 v[12:13], v[106:107], v[0:1] op_sel_hi:[1,0]
	v_cvt_pk_bf16_f32 v9, v10, v11
	global_store_dwordx2 v[46:47], v[8:9], off offset:16
	global_load_dwordx4 v[8:11], v139, s[4:5] offset:64
	s_waitcnt vmcnt(0)
	v_pk_mul_f32 v[8:9], v[8:9], v[12:13]
	v_pk_mul_f32 v[12:13], v[108:109], v[0:1] op_sel_hi:[1,0]
	v_pk_mul_f32 v[8:9], v[122:123], v[8:9]
	v_pk_mul_f32 v[10:11], v[10:11], v[12:13]
	v_cvt_pk_bf16_f32 v8, v8, v9
	v_pk_mul_f32 v[10:11], v[124:125], v[10:11]
	v_pk_mul_f32 v[12:13], v[110:111], v[0:1] op_sel_hi:[1,0]
	v_cvt_pk_bf16_f32 v9, v10, v11
	global_store_dwordx2 v[46:47], v[8:9], off offset:32
	global_load_dwordx4 v[8:11], v139, s[4:5] offset:96
	s_waitcnt vmcnt(0)
	v_pk_mul_f32 v[8:9], v[8:9], v[12:13]
	v_pk_mul_f32 v[12:13], v[112:113], v[0:1] op_sel_hi:[1,0]
	v_pk_mul_f32 v[8:9], v[128:129], v[8:9]
	v_pk_mul_f32 v[10:11], v[10:11], v[12:13]
	v_cvt_pk_bf16_f32 v8, v8, v9
	v_pk_mul_f32 v[10:11], v[126:127], v[10:11]
	v_pk_mul_f32 v[12:13], v[66:67], v[0:1] op_sel_hi:[1,0]
	v_cvt_pk_bf16_f32 v9, v10, v11
	global_store_dwordx2 v[46:47], v[8:9], off offset:48
	global_load_dwordx4 v[8:11], v139, s[4:5] offset:128
	s_waitcnt vmcnt(0)
	v_pk_mul_f32 v[8:9], v[8:9], v[12:13]
	v_pk_mul_f32 v[12:13], v[68:69], v[0:1] op_sel_hi:[1,0]
	v_pk_mul_f32 v[8:9], v[84:85], v[8:9]
	v_pk_mul_f32 v[10:11], v[10:11], v[12:13]
	v_cvt_pk_bf16_f32 v8, v8, v9
	v_pk_mul_f32 v[10:11], v[82:83], v[10:11]
	v_pk_mul_f32 v[12:13], v[70:71], v[0:1] op_sel_hi:[1,0]
	v_cvt_pk_bf16_f32 v9, v10, v11
	global_store_dwordx2 v[46:47], v[8:9], off offset:64
	global_load_dwordx4 v[8:11], v139, s[4:5] offset:160
	s_waitcnt vmcnt(0)
	v_pk_mul_f32 v[8:9], v[8:9], v[12:13]
	v_pk_mul_f32 v[12:13], v[72:73], v[0:1] op_sel_hi:[1,0]
	v_pk_mul_f32 v[8:9], v[88:89], v[8:9]
	v_pk_mul_f32 v[10:11], v[10:11], v[12:13]
	v_cvt_pk_bf16_f32 v8, v8, v9
	v_pk_mul_f32 v[10:11], v[86:87], v[10:11]
	v_pk_mul_f32 v[12:13], v[74:75], v[0:1] op_sel_hi:[1,0]
	v_cvt_pk_bf16_f32 v9, v10, v11
	global_store_dwordx2 v[46:47], v[8:9], off offset:80
	global_load_dwordx4 v[8:11], v139, s[4:5] offset:192
	s_waitcnt vmcnt(0)
	v_pk_mul_f32 v[8:9], v[8:9], v[12:13]
	v_pk_mul_f32 v[12:13], v[76:77], v[0:1] op_sel_hi:[1,0]
	v_pk_mul_f32 v[8:9], v[92:93], v[8:9]
	v_pk_mul_f32 v[10:11], v[10:11], v[12:13]
	v_cvt_pk_bf16_f32 v8, v8, v9
	v_pk_mul_f32 v[10:11], v[90:91], v[10:11]
	v_pk_mul_f32 v[12:13], v[94:95], v[0:1] op_sel_hi:[1,0]
	v_cvt_pk_bf16_f32 v9, v10, v11
	global_store_dwordx2 v[46:47], v[8:9], off offset:96
	global_load_dwordx4 v[8:11], v139, s[4:5] offset:224
	s_waitcnt vmcnt(0)
	v_pk_mul_f32 v[8:9], v[8:9], v[12:13]
	v_pk_mul_f32 v[12:13], v[96:97], v[0:1] op_sel_hi:[1,0]
	v_pk_mul_f32 v[8:9], v[154:155], v[8:9]
	v_pk_mul_f32 v[10:11], v[10:11], v[12:13]
	v_cvt_pk_bf16_f32 v8, v8, v9
	v_pk_mul_f32 v[10:11], v[156:157], v[10:11]
	s_nop 0
	v_cvt_pk_bf16_f32 v9, v10, v11
	global_store_dwordx2 v[46:47], v[8:9], off offset:112
	global_load_dwordx2 v[12:13], v[48:49], off offset:3200
	s_nop 0
	global_load_dwordx4 v[8:11], v139, s[4:5] offset:256
	s_waitcnt vmcnt(0) lgkmcnt(0)
; __device__ __forceinline__ unsigned pk2(float lo, float hi) { f32x2 v = {lo, hi}; bf16x2_t b = __builtin_convertvector(v, bf16x2_t); return __builtin_bit_cast(unsigned, b); }
; __device__ __forceinline__ float bflo(unsigned u) { return __uint_as_float(u << 16); }
; __device__ __forceinline__ float bfhi(unsigned u) { return __uint_as_float(u & 0xffff0000u); }
; __device__ __forceinline__ float silu(float g) { return g * __builtin_amdgcn_rcpf(1.0f + __expf(-g)); }
; template <int MODE>
; __device__ __forceinline__ void attn_item(const AttnP& p, int b, int h, int qb, LAS unsigned char* lds) {
;     ...
;     for (int d = 0; d < DV / 32; ++d)
; #pragma unroll
;         for (int g = 0; g < 4; ++g) {
;             const int dd = d * 32 + 8 * g + 4 * hh;
;             const u32x2 gr = *(const u32x2*)(P + trow * PP + gcol + dd);
;             const f32x4 og = *(const f32x4*)(p.out_gain + gaincol + dd);
;             const float o0 = O[0][d][4 * g] * rn * og[0] * silu(bflo(gr.x)), o1 = O[0][d][4 * g + 1] * rn * og[1] * silu(bfhi(gr.x));
;             const float o2 = O[0][d][4 * g + 2] * rn * og[2] * silu(bflo(gr.y)), o3 = O[0][d][4 * g + 3] * rn * og[3] * silu(bfhi(gr.y));
;             u32x2 wv; wv.x = pk2(o0, o1); wv.y = pk2(o2, o3);
;             *(u32x2*)(p.mixed + trow * 1024 + mixcol + dd) = wv;
	v_lshlrev_b32_e32 v14, 16, v12
	v_and_b32_e32 v15, 0xffff0000, v12
	v_mul_f32_e32 v12, 0xbfb8aa3b, v14
	v_exp_f32_e32 v12, v12
	v_pk_mul_f32 v[8:9], v[8:9], v[32:33]
	v_pk_mul_f32 v[32:33], v[52:53], v[0:1] op_sel_hi:[1,0]
	v_add_f32_e32 v12, 1.0, v12
	v_rcp_f32_e32 v30, v12
	v_mul_f32_e32 v12, 0xbfb8aa3b, v15
	v_exp_f32_e32 v12, v12
	s_nop 0
	v_add_f32_e32 v12, 1.0, v12
	v_rcp_f32_e32 v31, v12
	v_lshlrev_b32_e32 v12, 16, v13
	v_and_b32_e32 v13, 0xffff0000, v13
	v_pk_mul_f32 v[14:15], v[30:31], v[14:15]
	s_nop 0
	v_pk_mul_f32 v[8:9], v[14:15], v[8:9]
	v_mul_f32_e32 v14, 0xbfb8aa3b, v12
	v_mul_f32_e32 v15, 0xbfb8aa3b, v13
	v_exp_f32_e32 v14, v14
	v_exp_f32_e32 v15, v15
	v_pk_mul_f32 v[30:31], v[78:79], v[0:1] op_sel_hi:[1,0]
	v_cvt_pk_bf16_f32 v8, v8, v9
	v_add_f32_e32 v14, 1.0, v14
	v_add_f32_e32 v15, 1.0, v15
	v_rcp_f32_e32 v14, v14
	v_rcp_f32_e32 v15, v15
	v_pk_mul_f32 v[10:11], v[10:11], v[30:31]
	v_pk_mul_f32 v[12:13], v[14:15], v[12:13]
	s_nop 0
	v_pk_mul_f32 v[10:11], v[12:13], v[10:11]
	s_nop 0
	v_cvt_pk_bf16_f32 v9, v10, v11
	global_store_dwordx2 v[46:47], v[8:9], off offset:128
	global_load_dwordx2 v[12:13], v[48:49], off offset:3216
	s_nop 0
	global_load_dwordx4 v[8:11], v139, s[4:5] offset:288
	s_waitcnt vmcnt(0) lgkmcnt(0)
	v_lshlrev_b32_e32 v14, 16, v12
	v_and_b32_e32 v15, 0xffff0000, v12
	v_mul_f32_e32 v12, 0xbfb8aa3b, v14
	v_exp_f32_e32 v12, v12
	v_pk_mul_f32 v[8:9], v[8:9], v[32:33]
	v_add_f32_e32 v12, 1.0, v12
	v_rcp_f32_e32 v30, v12
	v_mul_f32_e32 v12, 0xbfb8aa3b, v15
	v_exp_f32_e32 v12, v12
	s_nop 0
	v_add_f32_e32 v12, 1.0, v12
	v_rcp_f32_e32 v31, v12
	v_lshlrev_b32_e32 v12, 16, v13
	v_and_b32_e32 v13, 0xffff0000, v13
	v_pk_mul_f32 v[14:15], v[30:31], v[14:15]
	s_nop 0
	v_pk_mul_f32 v[8:9], v[14:15], v[8:9]
	v_mul_f32_e32 v14, 0xbfb8aa3b, v12
	v_mul_f32_e32 v15, 0xbfb8aa3b, v13
	v_exp_f32_e32 v14, v14
	v_exp_f32_e32 v15, v15
	v_pk_mul_f32 v[30:31], v[50:51], v[0:1] op_sel_hi:[1,0]
	v_cvt_pk_bf16_f32 v8, v8, v9
	v_add_f32_e32 v14, 1.0, v14
	v_add_f32_e32 v15, 1.0, v15
	v_rcp_f32_e32 v14, v14
	v_rcp_f32_e32 v15, v15
	v_pk_mul_f32 v[10:11], v[10:11], v[30:31]
	v_pk_mul_f32 v[12:13], v[14:15], v[12:13]
	s_nop 0
	v_pk_mul_f32 v[10:11], v[12:13], v[10:11]
	s_nop 0
	v_cvt_pk_bf16_f32 v9, v10, v11
	global_store_dwordx2 v[46:47], v[8:9], off offset:144
	global_load_dwordx2 v[12:13], v[48:49], off offset:3232
	s_nop 0
	global_load_dwordx4 v[8:11], v139, s[4:5] offset:320
	s_waitcnt vmcnt(0) lgkmcnt(0)
	v_lshlrev_b32_e32 v14, 16, v12
	v_and_b32_e32 v15, 0xffff0000, v12
	v_mul_f32_e32 v12, 0xbfb8aa3b, v14
	v_exp_f32_e32 v12, v12
	v_pk_mul_f32 v[8:9], v[8:9], v[26:27]
	v_pk_mul_f32 v[26:27], v[28:29], v[0:1] op_sel_hi:[1,0]
	v_add_f32_e32 v12, 1.0, v12
	v_rcp_f32_e32 v30, v12
	v_mul_f32_e32 v12, 0xbfb8aa3b, v15
	v_exp_f32_e32 v12, v12
	v_pk_mul_f32 v[10:11], v[10:11], v[26:27]
	v_add_f32_e32 v12, 1.0, v12
	v_rcp_f32_e32 v31, v12
	v_lshlrev_b32_e32 v12, 16, v13
	v_and_b32_e32 v13, 0xffff0000, v13
	v_pk_mul_f32 v[14:15], v[30:31], v[14:15]
	s_nop 0
	v_pk_mul_f32 v[8:9], v[14:15], v[8:9]
	v_mul_f32_e32 v14, 0xbfb8aa3b, v12
	v_mul_f32_e32 v15, 0xbfb8aa3b, v13
	v_exp_f32_e32 v14, v14
	v_exp_f32_e32 v15, v15
	v_cvt_pk_bf16_f32 v8, v8, v9
	v_add_f32_e32 v14, 1.0, v14
	v_add_f32_e32 v15, 1.0, v15
	v_rcp_f32_e32 v14, v14
	v_rcp_f32_e32 v15, v15
	s_nop 0
	v_pk_mul_f32 v[12:13], v[14:15], v[12:13]
	s_nop 0
	v_pk_mul_f32 v[10:11], v[12:13], v[10:11]
	s_nop 0
	v_cvt_pk_bf16_f32 v9, v10, v11
	global_store_dwordx2 v[46:47], v[8:9], off offset:160
	global_load_dwordx2 v[8:9], v[48:49], off offset:3248
	s_nop 0
	global_load_dwordx4 v[10:13], v139, s[4:5] offset:352
	s_waitcnt vmcnt(0) lgkmcnt(0)
	v_lshlrev_b32_e32 v14, 16, v8
	v_and_b32_e32 v15, 0xffff0000, v8
	v_mul_f32_e32 v8, 0xbfb8aa3b, v14
	v_exp_f32_e32 v8, v8
	v_pk_mul_f32 v[10:11], v[10:11], v[24:25]
	v_pk_mul_f32 v[12:13], v[12:13], v[22:23]
	v_add_f32_e32 v8, 1.0, v8
	v_rcp_f32_e32 v26, v8
	v_mul_f32_e32 v8, 0xbfb8aa3b, v15
	v_exp_f32_e32 v8, v8
	s_nop 0
	v_add_f32_e32 v8, 1.0, v8
	v_rcp_f32_e32 v27, v8
	v_lshlrev_b32_e32 v8, 16, v9
	v_and_b32_e32 v9, 0xffff0000, v9
	v_pk_mul_f32 v[14:15], v[26:27], v[14:15]
	s_nop 0
	v_pk_mul_f32 v[10:11], v[14:15], v[10:11]
	v_mul_f32_e32 v14, 0xbfb8aa3b, v8
	v_mul_f32_e32 v15, 0xbfb8aa3b, v9
	v_exp_f32_e32 v14, v14
	v_exp_f32_e32 v15, v15
	v_cvt_pk_bf16_f32 v10, v10, v11
	v_add_f32_e32 v14, 1.0, v14
	v_add_f32_e32 v15, 1.0, v15
	v_rcp_f32_e32 v14, v14
	v_rcp_f32_e32 v15, v15
	s_nop 0
	v_pk_mul_f32 v[8:9], v[14:15], v[8:9]
	s_nop 0
	v_pk_mul_f32 v[8:9], v[8:9], v[12:13]
	s_nop 0
	v_cvt_pk_bf16_f32 v11, v8, v9
	global_store_dwordx2 v[46:47], v[10:11], off offset:176
	global_load_dwordx2 v[12:13], v[48:49], off offset:3264
	s_nop 0
	global_load_dwordx4 v[8:11], v139, s[4:5] offset:384
	s_waitcnt vmcnt(0) lgkmcnt(0)
; __device__ __forceinline__ unsigned pk2(float lo, float hi) { f32x2 v = {lo, hi}; bf16x2_t b = __builtin_convertvector(v, bf16x2_t); return __builtin_bit_cast(unsigned, b); }
; __device__ __forceinline__ float bflo(unsigned u) { return __uint_as_float(u << 16); }
; __device__ __forceinline__ float bfhi(unsigned u) { return __uint_as_float(u & 0xffff0000u); }
; __device__ __forceinline__ float silu(float g) { return g * __builtin_amdgcn_rcpf(1.0f + __expf(-g)); }
; template <int MODE>
; __device__ __forceinline__ void attn_item(const AttnP& p, int b, int h, int qb, LAS unsigned char* lds) {
;     ...
;     for (int d = 0; d < DV / 32; ++d)
; #pragma unroll
;         for (int g = 0; g < 4; ++g) {
;             const int dd = d * 32 + 8 * g + 4 * hh;
;             const u32x2 gr = *(const u32x2*)(P + trow * PP + gcol + dd);
;             const f32x4 og = *(const f32x4*)(p.out_gain + gaincol + dd);
;             const float o0 = O[0][d][4 * g] * rn * og[0] * silu(bflo(gr.x)), o1 = O[0][d][4 * g + 1] * rn * og[1] * silu(bfhi(gr.x));
;             const float o2 = O[0][d][4 * g + 2] * rn * og[2] * silu(bflo(gr.y)), o3 = O[0][d][4 * g + 3] * rn * og[3] * silu(bfhi(gr.y));
;             u32x2 wv; wv.x = pk2(o0, o1); wv.y = pk2(o2, o3);
;             *(u32x2*)(p.mixed + trow * 1024 + mixcol + dd) = wv;
	v_lshlrev_b32_e32 v14, 16, v12
	v_and_b32_e32 v15, 0xffff0000, v12
	v_mul_f32_e32 v12, 0xbfb8aa3b, v14
	v_exp_f32_e32 v12, v12
	v_pk_mul_f32 v[8:9], v[8:9], v[20:21]
	v_pk_mul_f32 v[10:11], v[10:11], v[18:19]
	v_add_f32_e32 v12, 1.0, v12
	v_rcp_f32_e32 v22, v12
	v_mul_f32_e32 v12, 0xbfb8aa3b, v15
	v_exp_f32_e32 v12, v12
	s_nop 0
	v_add_f32_e32 v12, 1.0, v12
	v_rcp_f32_e32 v23, v12
	v_lshlrev_b32_e32 v12, 16, v13
	v_and_b32_e32 v13, 0xffff0000, v13
	v_pk_mul_f32 v[14:15], v[22:23], v[14:15]
	s_nop 0
	v_pk_mul_f32 v[8:9], v[14:15], v[8:9]
	v_mul_f32_e32 v14, 0xbfb8aa3b, v12
	v_mul_f32_e32 v15, 0xbfb8aa3b, v13
	v_exp_f32_e32 v14, v14
	v_exp_f32_e32 v15, v15
	v_cvt_pk_bf16_f32 v8, v8, v9
	v_add_f32_e32 v14, 1.0, v14
	v_add_f32_e32 v15, 1.0, v15
	v_rcp_f32_e32 v14, v14
	v_rcp_f32_e32 v15, v15
	s_nop 0
	v_pk_mul_f32 v[12:13], v[14:15], v[12:13]
	s_nop 0
	v_pk_mul_f32 v[10:11], v[12:13], v[10:11]
	s_nop 0
	v_cvt_pk_bf16_f32 v9, v10, v11
	global_store_dwordx2 v[46:47], v[8:9], off offset:192
	global_load_dwordx2 v[12:13], v[48:49], off offset:3280
	s_nop 0
	global_load_dwordx4 v[8:11], v139, s[4:5] offset:416
	s_waitcnt vmcnt(0) lgkmcnt(0)
	v_lshlrev_b32_e32 v14, 16, v12
	v_and_b32_e32 v15, 0xffff0000, v12
	v_mul_f32_e32 v12, 0xbfb8aa3b, v14
	v_pk_mul_f32 v[6:7], v[8:9], v[6:7]
	v_mul_f32_e32 v8, 0xbfb8aa3b, v15
	v_exp_f32_e32 v12, v12
	v_exp_f32_e32 v8, v8
	v_pk_mul_f32 v[4:5], v[10:11], v[4:5]
	v_add_f32_e32 v12, 1.0, v12
	v_add_f32_e32 v8, 1.0, v8
	v_rcp_f32_e32 v18, v12
	v_rcp_f32_e32 v19, v8
	s_nop 0
	v_pk_mul_f32 v[8:9], v[18:19], v[14:15]
	s_nop 0
	v_pk_mul_f32 v[6:7], v[8:9], v[6:7]
	v_lshlrev_b32_e32 v8, 16, v13
	v_and_b32_e32 v9, 0xffff0000, v13
	v_mul_f32_e32 v12, 0xbfb8aa3b, v8
	v_mul_f32_e32 v10, 0xbfb8aa3b, v9
	v_exp_f32_e32 v12, v12
	v_exp_f32_e32 v10, v10
	v_cvt_pk_bf16_f32 v6, v6, v7
	v_add_f32_e32 v12, 1.0, v12
	v_add_f32_e32 v10, 1.0, v10
	v_rcp_f32_e32 v12, v12
	v_rcp_f32_e32 v13, v10
	s_nop 0
	v_pk_mul_f32 v[8:9], v[12:13], v[8:9]
	s_nop 0
	v_pk_mul_f32 v[4:5], v[8:9], v[4:5]
	s_nop 0
	v_cvt_pk_bf16_f32 v7, v4, v5
	global_store_dwordx2 v[46:47], v[6:7], off offset:208
	global_load_dwordx2 v[8:9], v[48:49], off offset:3296
	s_nop 0
	global_load_dwordx4 v[4:7], v139, s[4:5] offset:448
	s_waitcnt vmcnt(0) lgkmcnt(0)
	v_lshlrev_b32_e32 v10, 16, v8
	v_and_b32_e32 v11, 0xffff0000, v8
	v_mul_f32_e32 v8, 0xbfb8aa3b, v10
	v_pk_mul_f32 v[2:3], v[4:5], v[2:3]
	v_mul_f32_e32 v4, 0xbfb8aa3b, v11
	v_exp_f32_e32 v8, v8
	v_exp_f32_e32 v4, v4
	v_add_f32_e32 v8, 1.0, v8
	v_add_f32_e32 v4, 1.0, v4
	v_rcp_f32_e32 v12, v8
	v_rcp_f32_e32 v13, v4
	s_nop 0
	v_pk_mul_f32 v[4:5], v[12:13], v[10:11]
	s_nop 0
	v_pk_mul_f32 v[2:3], v[4:5], v[2:3]
	v_lshlrev_b32_e32 v4, 16, v9
	v_and_b32_e32 v5, 0xffff0000, v9
	v_mul_f32_e32 v8, 0xbfb8aa3b, v4
	v_mul_f32_e32 v9, 0xbfb8aa3b, v5
	v_exp_f32_e32 v8, v8
	v_exp_f32_e32 v9, v9
	v_pk_mul_f32 v[10:11], v[130:131], v[0:1] op_sel_hi:[1,0]
	v_cvt_pk_bf16_f32 v2, v2, v3
	v_add_f32_e32 v8, 1.0, v8
	v_add_f32_e32 v9, 1.0, v9
	v_rcp_f32_e32 v8, v8
	v_rcp_f32_e32 v9, v9
	v_pk_mul_f32 v[6:7], v[6:7], v[10:11]
	v_pk_mul_f32 v[12:13], v[44:45], v[0:1] op_sel_hi:[1,0]
	v_pk_mul_f32 v[4:5], v[8:9], v[4:5]
	s_nop 0
	v_pk_mul_f32 v[4:5], v[4:5], v[6:7]
	s_nop 0
	v_cvt_pk_bf16_f32 v3, v4, v5
	global_store_dwordx2 v[46:47], v[2:3], off offset:224
	global_load_dwordx2 v[2:3], v[48:49], off offset:3312
	s_nop 0
	global_load_dwordx4 v[4:7], v139, s[4:5] offset:480
	s_waitcnt vmcnt(0) lgkmcnt(0)
	v_lshlrev_b32_e32 v8, 16, v2
	v_and_b32_e32 v9, 0xffff0000, v2
	v_mul_f32_e32 v2, 0xbfb8aa3b, v8
	v_exp_f32_e32 v2, v2
	v_pk_mul_f32 v[4:5], v[4:5], v[12:13]
	v_add_f32_e32 v2, 1.0, v2
	v_rcp_f32_e32 v10, v2
	v_mul_f32_e32 v2, 0xbfb8aa3b, v9
	v_exp_f32_e32 v2, v2
	s_nop 0
	v_add_f32_e32 v2, 1.0, v2
	v_rcp_f32_e32 v11, v2
	v_lshlrev_b32_e32 v2, 16, v3
	v_and_b32_e32 v3, 0xffff0000, v3
	v_pk_mul_f32 v[8:9], v[10:11], v[8:9]
	s_nop 0
	v_pk_mul_f32 v[4:5], v[8:9], v[4:5]
	v_mul_f32_e32 v8, 0xbfb8aa3b, v2
	v_pk_mul_f32 v[10:11], v[16:17], v[0:1] op_sel_hi:[1,0]
	v_mul_f32_e32 v0, 0xbfb8aa3b, v3
	v_exp_f32_e32 v8, v8
	v_exp_f32_e32 v0, v0
	v_pk_mul_f32 v[6:7], v[6:7], v[10:11]
	v_cvt_pk_bf16_f32 v4, v4, v5
	v_add_f32_e32 v8, 1.0, v8
	v_add_f32_e32 v0, 1.0, v0
	v_rcp_f32_e32 v8, v8
	v_rcp_f32_e32 v9, v0
	s_nop 0
	v_pk_mul_f32 v[2:3], v[8:9], v[2:3]
	s_nop 0
	v_pk_mul_f32 v[2:3], v[2:3], v[6:7]
	s_nop 0
	v_cvt_pk_bf16_f32 v5, v2, v3
	global_store_dwordx2 v[46:47], v[4:5], off offset:240
	v_mov_b64_e32 v[194:195], 0x880
	v_mov_b64_e32 v[196:197], 0x87f
	v_mov_b64_e32 v[198:199], 0x800
	v_mov_b64_e32 v[200:201], 0x7ff
	v_mov_b64_e32 v[202:203], 0x200
	v_mov_b64_e32 v[204:205], 0x1ff
	v_mov_b32_e32 v213, 1
	v_mov_b32_e32 v214, 0x3a27c5ac
	v_mov_b32_e32 v215, 0x3f4ccccd
	v_mbcnt_lo_u32_b32 v216, -1, 0
	v_mbcnt_hi_u32_b32 v216, -1, v216
	v_mov_b32_e32 v217, 0x100
	v_mov_b32_e32 v218, 0x41b17218
	v_mov_b32_e32 v219, 0xff61b1e6
	v_mov_b32_e32 v220, 0x7f800000

; #define LAS __attribute__((address_space(3)))
; __device__ __forceinline__ int next_item(unsigned* ctr, LAS unsigned* slot) {
;     __syncthreads();
;     if (threadIdx.x == 0) *slot = atomicAdd(ctr, 1u);
;     __syncthreads();
;     return (int)*slot;
; }
.LBB0_470:
	s_barrier
	s_mov_b64 s[0:1], exec
	v_readlane_b32 s2, v253, 0
	v_readlane_b32 s3, v253, 1
	s_and_b64 s[2:3], s[0:1], s[2:3]
	s_mov_b64 exec, s[2:3]
	s_cbranch_execz .LBB0_472
	v_mov_b64_e32 v[2:3], s[48:49]
	global_atomic_add v0, v[2:3], v213, off offset:16 sc0
	v_readlane_b32 s2, v254, 19
	s_nop 1
	v_mov_b32_e32 v2, s2
	s_waitcnt vmcnt(0) lgkmcnt(0)
	ds_write_b32 v2, v0
; #define LAS __attribute__((address_space(3)))
; __device__ __forceinline__ unsigned pk2(float lo, float hi) { f32x2 v = {lo, hi}; bf16x2_t b = __builtin_convertvector(v, bf16x2_t); return __builtin_bit_cast(unsigned, b); }
; __device__ __forceinline__ float bflo(unsigned u) { return __uint_as_float(u << 16); }
; __device__ __forceinline__ float bfhi(unsigned u) { return __uint_as_float(u & 0xffff0000u); }
; #define ATT_LOAD(jt) do { ATT_LOADK(jt); ATT_LOADV(jt); } while (0)
; template <int MODE>
; __device__ __forceinline__ void attn_item(const AttnP& p, int b, int h, int qb, LAS unsigned char* lds) {
;     ...
;     bf16x8 Qf[NC][4];
; #pragma unroll
;     for (int c = 0; c < NC; ++c) {
;         u32x4 raw[4]; float ss = 0.f;
; #pragma unroll
;         for (int ks = 0; ks < 4; ++ks) {
;             raw[ks] = *(const u32x4*)(P + (size_t)(tok0 + qrow) * PP + qcol + c * 64 + ks * 16 + hh * 8);
; #pragma unroll
;             for (int e = 0; e < 4; ++e) { const float lo = bflo(raw[ks][e]), hi = bfhi(raw[ks][e]); ss += lo * lo + hi * hi; }
;         }
;         float sc = 0.125f * LOG2E;
;         if (MODE != 1) { ss += __shfl_xor(ss, 32); sc *= 1.0f / sqrtf(ss * (1.0f / 64.0f) + 1e-6f); }
; #pragma unroll
;         for (int ks = 0; ks < 4; ++ks) {
;             u32x4 o;
; #pragma unroll
;             for (int e = 0; e < 4; ++e) {
;                 float lo = bflo(raw[ks][e]) * sc, hi = bfhi(raw[ks][e]) * sc;
;                 if (MODE != 1) {
;                     const int d = ks * 16 + hh * 8 + 2 * e;
;                     const float* gq = p.qk_gain + ((MODE == 0) ? 0 : 128); const float* gk = gq + 64;
;                     lo *= gq[d] * gk[d]; hi *= gq[d + 1] * gk[d + 1];
;                 }
;                 o[e] = pk2(lo, hi);
;             }
;             Qf[c][ks] = __builtin_bit_cast(bf16x8, o);
;             if (QPARK) *(LAS u32x4*)(lds + QP_OFF + w * 8192 + ((c * 4 + ks) * 64 + lane) * 16) = o;
;         }
;     }
;     if (MODE == 0) { LAS float* tab = (LAS float*)(lds + TAB_OFF); if (tid < 256) tab[tid] = p.biasT[h * 256 + tid]; }
;     LAS unsigned* flags = (LAS unsigned*)(lds + FLAG_OFF);
;     if (MODE == 1 && tid < 16) flags[tid] = 0u;
;     ...
;     ATT_LOAD(jt_max);
;     ATT_STORE(0, jt_max);
.LBB0_472:
	s_or_b64 exec, exec, s[0:1]
	v_readlane_b32 s0, v254, 19
	s_waitcnt lgkmcnt(0)
	s_barrier
	v_mov_b32_e32 v0, s0
	ds_read_b32 v0, v0
	s_mov_b64 s[0:1], -1
	s_waitcnt lgkmcnt(0)
	v_cmp_lt_i32_e32 vcc, s75, v0
	v_readfirstlane_b32 s57, v0
	s_cbranch_vccnz .LBB0_469
	s_cmpk_gt_i32 s57, 0x1ff
	s_cbranch_scc0 .LBB0_491
	s_add_i32 s0, s57, 0xfffffe00
	v_mov_b32_e32 v18, v210
	s_lshr_b32 s2, s0, 6
	s_sub_i32 s4, 15, s2
	v_readfirstlane_b32 s0, v18
	s_ashr_i32 s3, s0, 6
	s_lshl_b32 s0, s57, 6
	s_and_b32 s20, s0, 0x1c0
	s_lshl_b32 s0, s57, 9
	s_and_b32 s33, s0, 0x7000
	s_lshl_b32 s0, s4, 8
	s_lshl_b32 s58, s3, 5
	v_and_b32_e32 v19, 31, v18
	s_add_i32 s58, s58, s0
	v_or_b32_e32 v86, s58, v19
	v_add_u32_e32 v0, s33, v86
	v_mov_b64_e32 v[2:3], s[46:47]
	v_bfe_u32 v20, v18, 5, 1
	v_mad_i64_i32 v[2:3], s[0:1], v0, s76, v[2:3]
	s_lshl_b32 s92, s20, 1
	v_lshl_add_u64 v[2:3], v[2:3], 0, s[92:93]
	v_lshlrev_b32_e32 v0, 4, v20
	v_lshl_add_u64 v[2:3], v[2:3], 0, v[0:1]
	s_mov_b64 s[0:1], 0x1000
	v_lshl_add_u64 v[4:5], v[2:3], 0, s[0:1]
	v_add_co_u32_e32 v2, vcc, 0x1000, v2
	s_nop 1
	v_addc_co_u32_e32 v3, vcc, 0, v3, vcc
	global_load_dwordx4 v[10:13], v[4:5], off offset:32
	global_load_dwordx4 v[6:9], v[4:5], off offset:64
	global_load_dwordx4 v[14:17], v[2:3], off
	s_nop 0
	global_load_dwordx4 v[2:5], v[4:5], off offset:96
	v_cmp_gt_i32_e32 vcc, 16, v18
	s_and_saveexec_b64 s[0:1], vcc
	v_lshl_add_u32 v21, v18, 2, 0
	ds_write_b32 v21, v1 offset:44544
	s_or_b64 exec, exec, s[0:1]
	s_lshl_b32 s0, s4, 2
	s_or_b32 s59, s0, 3
	s_lshl_b32 s0, s59, 6
	v_ashrrev_i32_e32 v21, 3, v18
	s_or_b32 s0, s0, s33
	v_add_u32_e32 v24, s0, v21
	v_mov_b64_e32 v[22:23], s[46:47]
	v_mad_i64_i32 v[22:23], s[0:1], v24, s76, v[22:23]
	v_lshlrev_b32_e32 v24, 3, v18
	v_and_b32_e32 v24, 56, v24
	v_lshlrev_b32_e32 v26, 1, v24
	v_mov_b32_e32 v27, v1
	v_lshl_add_u64 v[22:23], v[22:23], 0, v[26:27]
	s_or_b32 s0, s92, 0x1400
	s_mov_b32 s1, s93
	v_lshl_add_u64 v[28:29], v[22:23], 0, s[0:1]
	s_or_b32 s4, s92, 0x1800
	s_mov_b32 s5, s93
	v_lshl_add_u64 v[22:23], v[22:23], 0, s[4:5]
	global_load_dwordx4 v[50:53], v[28:29], off
	global_load_dwordx4 v[58:61], v[22:23], off
	s_waitcnt vmcnt(0) lgkmcnt(0)
	v_lshlrev_b32_e32 v22, 16, v14
	v_and_b32_e32 v23, 0xffff0000, v14
	s_mov_b32 s6, 0x3e38aa3b
	v_lshlrev_b32_e32 v14, 16, v15
	v_and_b32_e32 v15, 0xffff0000, v15
	v_pk_mul_f32 v[14:15], v[14:15], s[6:7] op_sel_hi:[1,0]
	v_and_b32_e32 v25, 63, v18
	v_cvt_pk_bf16_f32 v55, v14, v15
	v_lshlrev_b32_e32 v14, 16, v16
	v_and_b32_e32 v15, 0xffff0000, v16
	v_pk_mul_f32 v[14:15], v[14:15], s[6:7] op_sel_hi:[1,0]
	v_pk_mul_f32 v[22:23], v[22:23], s[6:7] op_sel_hi:[1,0]
	v_cvt_pk_bf16_f32 v56, v14, v15
	v_lshlrev_b32_e32 v14, 16, v17
	v_and_b32_e32 v15, 0xffff0000, v17
	v_pk_mul_f32 v[14:15], v[14:15], s[6:7] op_sel_hi:[1,0]
	v_lshlrev_b32_e32 v87, 2, v20
	v_cvt_pk_bf16_f32 v57, v14, v15
	v_lshlrev_b32_e32 v14, 16, v10
	v_and_b32_e32 v15, 0xffff0000, v10
	v_lshlrev_b32_e32 v10, 16, v11
	v_and_b32_e32 v11, 0xffff0000, v11
	v_pk_mul_f32 v[10:11], v[10:11], s[6:7] op_sel_hi:[1,0]
	v_pk_mul_f32 v[14:15], v[14:15], s[6:7] op_sel_hi:[1,0]
	v_cvt_pk_bf16_f32 v63, v10, v11
	v_lshlrev_b32_e32 v10, 16, v12
	v_and_b32_e32 v11, 0xffff0000, v12
	v_pk_mul_f32 v[10:11], v[10:11], s[6:7] op_sel_hi:[1,0]
	v_mov_b32_e32 v16, v1
	v_cvt_pk_bf16_f32 v64, v10, v11
	v_lshlrev_b32_e32 v10, 16, v13
	v_and_b32_e32 v11, 0xffff0000, v13
	v_pk_mul_f32 v[10:11], v[10:11], s[6:7] op_sel_hi:[1,0]
	v_mov_b32_e32 v17, v1
	v_cvt_pk_bf16_f32 v65, v10, v11
	v_lshlrev_b32_e32 v10, 16, v6
	v_and_b32_e32 v11, 0xffff0000, v6
	v_lshlrev_b32_e32 v6, 16, v7
	v_and_b32_e32 v7, 0xffff0000, v7
	v_pk_mul_f32 v[6:7], v[6:7], s[6:7] op_sel_hi:[1,0]
	v_pk_mul_f32 v[10:11], v[10:11], s[6:7] op_sel_hi:[1,0]
	v_cvt_pk_bf16_f32 v67, v6, v7
	v_lshlrev_b32_e32 v6, 16, v8
	v_and_b32_e32 v7, 0xffff0000, v8
	v_pk_mul_f32 v[6:7], v[6:7], s[6:7] op_sel_hi:[1,0]
	v_cvt_pk_bf16_f32 v54, v22, v23
	v_cvt_pk_bf16_f32 v68, v6, v7
	v_lshlrev_b32_e32 v6, 16, v9
	v_and_b32_e32 v7, 0xffff0000, v9
	v_pk_mul_f32 v[6:7], v[6:7], s[6:7] op_sel_hi:[1,0]
	v_cvt_pk_bf16_f32 v62, v14, v15
	v_cvt_pk_bf16_f32 v69, v6, v7
	v_lshlrev_b32_e32 v6, 16, v2
	v_and_b32_e32 v7, 0xffff0000, v2
	v_lshlrev_b32_e32 v2, 16, v3
	v_and_b32_e32 v3, 0xffff0000, v3
	v_pk_mul_f32 v[2:3], v[2:3], s[6:7] op_sel_hi:[1,0]
	v_pk_mul_f32 v[6:7], v[6:7], s[6:7] op_sel_hi:[1,0]
	v_cvt_pk_bf16_f32 v71, v2, v3
	v_lshlrev_b32_e32 v2, 16, v4
	v_and_b32_e32 v3, 0xffff0000, v4
	v_pk_mul_f32 v[2:3], v[2:3], s[6:7] op_sel_hi:[1,0]
	v_mul_lo_u32 v4, v21, 24
	v_cvt_pk_bf16_f32 v72, v2, v3
	v_lshlrev_b32_e32 v2, 16, v5
	v_and_b32_e32 v3, 0xffff0000, v5
	v_pk_mul_f32 v[2:3], v[2:3], s[6:7] op_sel_hi:[1,0]
	v_cvt_pk_bf16_f32 v66, v10, v11
	v_cvt_pk_bf16_f32 v73, v2, v3
	v_mad_u64_u32 v[2:3], s[6:7], v21, s72, v[24:25]
	v_lshlrev_b32_e32 v88, 1, v2
	v_add_lshl_u32 v89, v2, v4, 1
	v_add_u32_e32 v3, 0, v88
	v_add_u32_e32 v2, 0, v89
	ds_write_b128 v3, v[50:53]
	ds_write_b128 v2, v[58:61] offset:9216
	v_lshl_add_u64 v[2:3], s[46:47], 0, v[26:27]
	v_lshl_add_u64 v[74:75], v[2:3], 0, s[0:1]
	v_lshl_add_u64 v[76:77], v[2:3], 0, s[4:5]
	v_lshrrev_b32_e32 v2, 2, v18
	v_and_or_b32 v2, v2, 3, v87
	v_lshlrev_b32_e32 v4, 2, v18
	v_and_b32_e32 v3, 16, v18
	v_and_b32_e32 v4, 12, v4
	v_mul_u32_u24_e32 v2, 0x60, v2
	v_or3_b32 v2, v4, v3, v2
	v_cvt_pk_bf16_f32 v70, v6, v7
	s_lshl_b32 s3, s3, 2
	v_cmp_gt_u32_e64 s[0:1], 32, v25
	v_cmp_eq_u32_e64 s[38:39], 0, v25
	v_mul_u32_u24_e32 v90, 0x90, v19
	v_lshlrev_b32_e32 v91, 1, v2
	s_lshl_b32 s2, s2, 8
	v_add_u32_e32 v95, s33, v21
	v_mov_b32_e32 v2, v1
	v_mov_b32_e32 v3, v1
	v_mov_b32_e32 v4, v1
	v_mov_b32_e32 v5, v1
	v_mov_b32_e32 v6, v1
	v_mov_b32_e32 v7, v1
	v_mov_b32_e32 v8, v1
	v_mov_b32_e32 v9, v1
	v_mov_b32_e32 v10, v1
	v_mov_b32_e32 v11, v1
	v_mov_b32_e32 v12, v1
	v_mov_b32_e32 v13, v1
	v_mov_b32_e32 v14, v1
	v_mov_b32_e32 v15, v1
	v_mov_b64_e32 v[32:33], v[16:17]
	s_add_i32 s62, s3, 0
	s_or_b32 s63, s58, 30
	s_mov_b32 s65, 0
	v_or_b32_e32 v92, 0x1800, v91
	v_add_u32_e32 v93, 0x2400, v91
	v_add_u32_e32 v94, 0xc00, v91
	s_sub_i32 s64, 0xfff, s2
	s_mov_b64 s[2:3], 0
	v_mov_b32_e32 v79, 0
	v_mov_b64_e32 v[30:31], v[14:15]
	v_mov_b64_e32 v[28:29], v[12:13]
	v_mov_b64_e32 v[26:27], v[10:11]
	v_mov_b64_e32 v[24:25], v[8:9]
	v_mov_b64_e32 v[22:23], v[6:7]
	v_mov_b64_e32 v[20:21], v[4:5]
	v_mov_b64_e32 v[18:19], v[2:3]
	s_waitcnt lgkmcnt(0)
	s_barrier
	s_cmp_lt_u32 s65, s59
	s_cselect_b64 s[50:51], -1, 0
	s_cmp_ge_u32 s65, s59
	s_cbranch_scc1 .LBB0_478
.LBB0_477:
	v_add_u32_e32 v34, s64, v95
	v_add_u32_e32 v36, 0xffffff81, v34
	v_mad_i64_i32 v[34:35], s[4:5], v36, s76, v[74:75]
	v_mad_i64_i32 v[36:37], s[4:5], v36, s76, v[76:77]
	s_waitcnt vmcnt(0)
	global_load_dwordx4 v[50:53], v[34:35], off
	global_load_dwordx4 v[58:61], v[36:37], off

; __device__ __forceinline__ unsigned pk2(float lo, float hi) { f32x2 v = {lo, hi}; bf16x2_t b = __builtin_convertvector(v, bf16x2_t); return __builtin_bit_cast(unsigned, b); }
; __device__ __forceinline__ float bflo(unsigned u) { return __uint_as_float(u << 16); }
; __device__ __forceinline__ float bfhi(unsigned u) { return __uint_as_float(u & 0xffff0000u); }
; __device__ __forceinline__ float silu(float g) { return g * __builtin_amdgcn_rcpf(1.0f + __expf(-g)); }
; template <int MODE>
; __device__ __forceinline__ void attn_item(const AttnP& p, int b, int h, int qb, LAS unsigned char* lds) {
;     ...
;     float ss = 0.f;
; #pragma unroll
;     for (int d = 0; d < DV / 32; ++d)
; #pragma unroll
;         for (int i = 0; i < 16; ++i) {
;             float o = O[0][d][i] * inv0;
;             if (MODE == 0) o -= O[NC - 1][d][i] * inv1;
;             O[0][d][i] = o; ss += o * o;
;         }
;     ss += __shfl_xor(ss, 32);
;     float rn = 1.0f / sqrtf(ss * (1.0f / DV) + 1e-6f);
;     if (MODE == 0) rn *= p.oml;
;     int qrow_e = qrow; asm volatile("" : "+v"(qrow_e));
;     const size_t trow = (size_t)(tok0 + qrow_e);
; #pragma unroll
;     for (int d = 0; d < DV / 32; ++d)
; #pragma unroll
;         for (int g = 0; g < 4; ++g) {
;             const int dd = d * 32 + 8 * g + 4 * hh;
;             const u32x2 gr = *(const u32x2*)(P + trow * PP + gcol + dd);
;             const f32x4 og = *(const f32x4*)(p.out_gain + gaincol + dd);
;             const float o0 = O[0][d][4 * g] * rn * og[0] * silu(bflo(gr.x)), o1 = O[0][d][4 * g + 1] * rn * og[1] * silu(bfhi(gr.x));
;             const float o2 = O[0][d][4 * g + 2] * rn * og[2] * silu(bflo(gr.y)), o3 = O[0][d][4 * g + 3] * rn * og[3] * silu(bfhi(gr.y));
;             u32x2 wv; wv.x = pk2(o0, o1); wv.y = pk2(o2, o3);
;             *(u32x2*)(p.mixed + trow * 1024 + mixcol + dd) = wv;
;         }
.LBB0_490:
	v_mul_f32_e32 v0, v19, v19
	v_fmac_f32_e32 v0, v18, v18
	v_fmac_f32_e32 v0, v20, v20
	v_fmac_f32_e32 v0, v21, v21
	v_fmac_f32_e32 v0, v22, v22
	v_fmac_f32_e32 v0, v23, v23
	v_fmac_f32_e32 v0, v24, v24
	v_fmac_f32_e32 v0, v25, v25
	v_fmac_f32_e32 v0, v26, v26
	v_fmac_f32_e32 v0, v27, v27
	v_fmac_f32_e32 v0, v28, v28
	v_fmac_f32_e32 v0, v29, v29
	v_fmac_f32_e32 v0, v30, v30
	v_fmac_f32_e32 v0, v31, v31
	v_fmac_f32_e32 v0, v32, v32
	v_fmac_f32_e32 v0, v33, v33
	v_fmac_f32_e32 v0, v2, v2
	v_fmac_f32_e32 v0, v3, v3
	v_fmac_f32_e32 v0, v4, v4
	v_fmac_f32_e32 v0, v5, v5
	v_fmac_f32_e32 v0, v6, v6
	v_fmac_f32_e32 v0, v7, v7
	v_fmac_f32_e32 v0, v8, v8
	v_fmac_f32_e32 v0, v9, v9
	v_fmac_f32_e32 v0, v10, v10
	v_fmac_f32_e32 v0, v11, v11
	v_pk_mul_f32 v[38:39], v[12:13], v[12:13]
	v_pk_mul_f32 v[36:37], v[14:15], v[14:15]
	v_add_f32_e32 v0, v38, v0
	v_add_f32_e32 v0, v39, v0
	v_add_f32_e32 v0, v36, v0
	v_pk_mul_f32 v[34:35], v[16:17], v[16:17]
	v_add_f32_e32 v0, v37, v0
	v_add_f32_e32 v0, v34, v0
	v_add_f32_e32 v0, v35, v0
	ds_bpermute_b32 v34, v226, v0
	v_lshlrev_b32_e32 v39, 2, v87
	s_waitcnt lgkmcnt(0)
	v_add_f32_e32 v0, v0, v34
	v_fmamk_f32 v0, v0, 0x3c800000, v211
	v_cmp_gt_f32_e32 vcc, s74, v0
	v_mul_f32_e32 v34, 0x4f800000, v0
	s_nop 0
	v_cndmask_b32_e32 v0, v0, v34, vcc
	v_sqrt_f32_e32 v34, v0
	s_nop 0
	v_add_u32_e32 v35, -1, v34
	v_fma_f32 v36, -v35, v34, v0
	v_cmp_ge_f32_e64 s[0:1], 0, v36
	v_add_u32_e32 v36, 1, v34
	s_nop 0
	v_cndmask_b32_e64 v35, v34, v35, s[0:1]
	v_fma_f32 v34, -v36, v34, v0
	v_cmp_lt_f32_e64 s[0:1], 0, v34
	s_nop 1
	v_cndmask_b32_e64 v34, v35, v36, s[0:1]
	v_mul_f32_e32 v35, 0x37800000, v34
	v_cndmask_b32_e32 v34, v34, v35, vcc
	v_cmp_class_f32_e32 vcc, v0, v212
	s_nop 1
	v_cndmask_b32_e32 v0, v34, v0, vcc
	v_div_scale_f32 v34, s[0:1], v0, v0, 1.0
	v_rcp_f32_e32 v35, v34
	s_nop 0
	v_fma_f32 v36, -v34, v35, 1.0
	v_fmac_f32_e32 v35, v36, v35
	v_div_scale_f32 v36, vcc, 1.0, v0, 1.0
	v_mul_f32_e32 v37, v36, v35
	v_fma_f32 v38, -v34, v37, v36
	v_fmac_f32_e32 v37, v38, v35
	v_fma_f32 v34, -v34, v37, v36
	v_div_fmas_f32 v34, v34, v35, v37
	v_div_fixup_f32 v38, v34, v0, 1.0
	v_add_u32_e32 v34, s33, v86
	v_mov_b64_e32 v[36:37], s[46:47]
	v_mad_i64_i32 v[36:37], s[0:1], v34, s76, v[36:37]
	v_lshl_add_u64 v[36:37], v[36:37], 0, s[92:93]
	s_mov_b64 s[0:1], 0x1c00
	v_ashrrev_i32_e32 v35, 31, v34
	v_lshl_add_u64 v[40:41], v[36:37], 0, s[0:1]
	v_lshlrev_b32_e32 v0, 1, v87
	s_lshl_b32 s0, s20, 2
	v_lshlrev_b64 v[42:43], 11, v[34:35]
	v_lshl_add_u64 v[34:35], v[40:41], 0, v[0:1]
	s_add_u32 s0, s54, s0
	global_load_dwordx2 v[44:45], v[34:35], off
	s_addc_u32 s1, s55, 0
	global_load_dwordx4 v[34:37], v39, s[0:1] offset:2048
	v_pk_mul_f32 v[18:19], v[18:19], v[38:39] op_sel_hi:[1,0]
	v_pk_mul_f32 v[20:21], v[20:21], v[38:39] op_sel_hi:[1,0]
	v_pk_mul_f32 v[22:23], v[22:23], v[38:39] op_sel_hi:[1,0]
	v_pk_mul_f32 v[24:25], v[24:25], v[38:39] op_sel_hi:[1,0]
	v_pk_mul_f32 v[26:27], v[26:27], v[38:39] op_sel_hi:[1,0]
	v_pk_mul_f32 v[28:29], v[28:29], v[38:39] op_sel_hi:[1,0]
	v_pk_mul_f32 v[30:31], v[30:31], v[38:39] op_sel_hi:[1,0]
	v_pk_mul_f32 v[2:3], v[2:3], v[38:39] op_sel_hi:[1,0]
	v_pk_mul_f32 v[4:5], v[4:5], v[38:39] op_sel_hi:[1,0]
	v_pk_mul_f32 v[6:7], v[6:7], v[38:39] op_sel_hi:[1,0]
	v_pk_mul_f32 v[8:9], v[8:9], v[38:39] op_sel_hi:[1,0]
	v_pk_mul_f32 v[10:11], v[10:11], v[38:39] op_sel_hi:[1,0]
	s_waitcnt vmcnt(0) lgkmcnt(0)
	v_lshlrev_b32_e32 v46, 16, v44
	v_and_b32_e32 v47, 0xffff0000, v44
	v_mul_f32_e32 v44, 0xbfb8aa3b, v46
	v_pk_mul_f32 v[18:19], v[34:35], v[18:19]
	v_mul_f32_e32 v34, 0xbfb8aa3b, v47
	v_exp_f32_e32 v44, v44
	v_exp_f32_e32 v34, v34
	v_pk_mul_f32 v[20:21], v[36:37], v[20:21]
	v_add_f32_e32 v44, 1.0, v44
	v_add_f32_e32 v34, 1.0, v34
	v_rcp_f32_e32 v48, v44
	v_rcp_f32_e32 v49, v34
	s_nop 0
	v_pk_mul_f32 v[34:35], v[48:49], v[46:47]
	s_nop 0
	v_pk_mul_f32 v[18:19], v[18:19], v[34:35]
	v_lshlrev_b32_e32 v34, 16, v45
	v_and_b32_e32 v35, 0xffff0000, v45
	v_mul_f32_e32 v44, 0xbfb8aa3b, v34
	v_mul_f32_e32 v36, 0xbfb8aa3b, v35
	v_exp_f32_e32 v44, v44
	v_exp_f32_e32 v36, v36
	v_add_f32_e32 v44, 1.0, v44
	v_add_f32_e32 v36, 1.0, v36
	v_rcp_f32_e32 v44, v44
	v_rcp_f32_e32 v45, v36
	s_nop 0
	v_pk_mul_f32 v[34:35], v[44:45], v[34:35]
	s_nop 0
	v_pk_mul_f32 v[20:21], v[20:21], v[34:35]
	v_cvt_pk_bf16_f32 v34, v18, v19
	v_lshl_add_u64 v[18:19], s[44:45], 0, v[42:43]
	v_lshl_add_u64 v[18:19], v[18:19], 0, s[92:93]
	v_cvt_pk_bf16_f32 v35, v20, v21
	v_lshl_add_u64 v[18:19], v[18:19], 0, v[0:1]
	v_or_b32_e32 v20, 16, v0
	v_mov_b32_e32 v21, v1
	global_store_dwordx2 v[18:19], v[34:35], off offset:1024
	v_lshl_add_u64 v[20:21], v[40:41], 0, v[20:21]
	global_load_dwordx2 v[20:21], v[20:21], off
	s_nop 0
	global_load_dwordx4 v[34:37], v39, s[0:1] offset:2080
	s_waitcnt vmcnt(0) lgkmcnt(0)
	v_lshlrev_b32_e32 v42, 16, v20
	v_and_b32_e32 v43, 0xffff0000, v20
	v_mul_f32_e32 v20, 0xbfb8aa3b, v42
	v_exp_f32_e32 v20, v20
	v_pk_mul_f32 v[22:23], v[34:35], v[22:23]
	v_pk_mul_f32 v[24:25], v[36:37], v[24:25]
	v_add_f32_e32 v20, 1.0, v20
	v_rcp_f32_e32 v44, v20
	v_mul_f32_e32 v20, 0xbfb8aa3b, v43
	v_exp_f32_e32 v20, v20
	s_nop 0
	v_add_f32_e32 v20, 1.0, v20
	v_rcp_f32_e32 v45, v20
	v_lshlrev_b32_e32 v20, 16, v21
	v_and_b32_e32 v21, 0xffff0000, v21
	v_pk_mul_f32 v[34:35], v[44:45], v[42:43]
	s_nop 0
	v_pk_mul_f32 v[22:23], v[22:23], v[34:35]
	v_mul_f32_e32 v34, 0xbfb8aa3b, v20
	v_mul_f32_e32 v35, 0xbfb8aa3b, v21
	v_exp_f32_e32 v34, v34
	v_exp_f32_e32 v35, v35
	v_cvt_pk_bf16_f32 v22, v22, v23
	v_add_f32_e32 v34, 1.0, v34
	v_add_f32_e32 v35, 1.0, v35
	v_rcp_f32_e32 v34, v34
	v_rcp_f32_e32 v35, v35
	s_nop 0
	v_pk_mul_f32 v[20:21], v[34:35], v[20:21]
	s_nop 0
	v_pk_mul_f32 v[20:21], v[24:25], v[20:21]
	s_nop 0
	v_cvt_pk_bf16_f32 v23, v20, v21
	v_or_b32_e32 v20, 32, v0
	v_mov_b32_e32 v21, v1
	global_store_dwordx2 v[18:19], v[22:23], off offset:1040
	v_lshl_add_u64 v[20:21], v[40:41], 0, v[20:21]
	global_load_dwordx2 v[24:25], v[20:21], off
	s_nop 0
	global_load_dwordx4 v[20:23], v39, s[0:1] offset:2112
	s_waitcnt vmcnt(0) lgkmcnt(0)
; __device__ __forceinline__ unsigned pk2(float lo, float hi) { f32x2 v = {lo, hi}; bf16x2_t b = __builtin_convertvector(v, bf16x2_t); return __builtin_bit_cast(unsigned, b); }
; __device__ __forceinline__ float bflo(unsigned u) { return __uint_as_float(u << 16); }
; __device__ __forceinline__ float bfhi(unsigned u) { return __uint_as_float(u & 0xffff0000u); }
; __device__ __forceinline__ float silu(float g) { return g * __builtin_amdgcn_rcpf(1.0f + __expf(-g)); }
; template <int MODE>
; __device__ __forceinline__ void attn_item(const AttnP& p, int b, int h, int qb, LAS unsigned char* lds) {
;     ...
;     for (int d = 0; d < DV / 32; ++d)
; #pragma unroll
;         for (int g = 0; g < 4; ++g) {
;             const int dd = d * 32 + 8 * g + 4 * hh;
;             const u32x2 gr = *(const u32x2*)(P + trow * PP + gcol + dd);
;             const f32x4 og = *(const f32x4*)(p.out_gain + gaincol + dd);
;             const float o0 = O[0][d][4 * g] * rn * og[0] * silu(bflo(gr.x)), o1 = O[0][d][4 * g + 1] * rn * og[1] * silu(bfhi(gr.x));
;             const float o2 = O[0][d][4 * g + 2] * rn * og[2] * silu(bflo(gr.y)), o3 = O[0][d][4 * g + 3] * rn * og[3] * silu(bfhi(gr.y));
;             u32x2 wv; wv.x = pk2(o0, o1); wv.y = pk2(o2, o3);
;             *(u32x2*)(p.mixed + trow * 1024 + mixcol + dd) = wv;
;         }
	v_lshlrev_b32_e32 v34, 16, v24
	v_and_b32_e32 v35, 0xffff0000, v24
	v_mul_f32_e32 v24, 0xbfb8aa3b, v34
	v_exp_f32_e32 v24, v24
	v_pk_mul_f32 v[20:21], v[26:27], v[20:21]
	v_pk_mul_f32 v[22:23], v[28:29], v[22:23]
	v_add_f32_e32 v24, 1.0, v24
	v_rcp_f32_e32 v36, v24
	v_mul_f32_e32 v24, 0xbfb8aa3b, v35
	v_exp_f32_e32 v24, v24
	s_nop 0
	v_add_f32_e32 v24, 1.0, v24
	v_rcp_f32_e32 v37, v24
	v_lshlrev_b32_e32 v24, 16, v25
	v_and_b32_e32 v25, 0xffff0000, v25
	v_pk_mul_f32 v[26:27], v[36:37], v[34:35]
	s_nop 0
	v_pk_mul_f32 v[20:21], v[20:21], v[26:27]
	v_mul_f32_e32 v26, 0xbfb8aa3b, v24
	v_mul_f32_e32 v27, 0xbfb8aa3b, v25
	v_exp_f32_e32 v26, v26
	v_exp_f32_e32 v27, v27
	v_cvt_pk_bf16_f32 v20, v20, v21
	v_add_f32_e32 v26, 1.0, v26
	v_add_f32_e32 v27, 1.0, v27
	v_rcp_f32_e32 v26, v26
	v_rcp_f32_e32 v27, v27
	s_nop 0
	v_pk_mul_f32 v[24:25], v[26:27], v[24:25]
	s_nop 0
	v_pk_mul_f32 v[22:23], v[22:23], v[24:25]
	s_nop 0
	v_cvt_pk_bf16_f32 v21, v22, v23
	global_store_dwordx2 v[18:19], v[20:21], off offset:1056
	v_or_b32_e32 v20, 48, v0
	v_mov_b32_e32 v21, v1
	v_lshl_add_u64 v[20:21], v[40:41], 0, v[20:21]
	global_load_dwordx2 v[24:25], v[20:21], off
	s_nop 0
	global_load_dwordx4 v[20:23], v39, s[0:1] offset:2144
	s_waitcnt vmcnt(0) lgkmcnt(0)
	v_lshlrev_b32_e32 v26, 16, v24
	v_and_b32_e32 v27, 0xffff0000, v24
	v_mul_f32_e32 v24, 0xbfb8aa3b, v26
	v_exp_f32_e32 v24, v24
	v_pk_mul_f32 v[20:21], v[30:31], v[20:21]
	v_add_f32_e32 v24, 1.0, v24
	v_rcp_f32_e32 v28, v24
	v_mul_f32_e32 v24, 0xbfb8aa3b, v27
	v_exp_f32_e32 v24, v24
	s_nop 0
	v_add_f32_e32 v24, 1.0, v24
	v_rcp_f32_e32 v29, v24
	v_lshlrev_b32_e32 v24, 16, v25
	v_and_b32_e32 v25, 0xffff0000, v25
	v_pk_mul_f32 v[26:27], v[28:29], v[26:27]
	s_nop 0
	v_pk_mul_f32 v[20:21], v[20:21], v[26:27]
	v_mul_f32_e32 v26, 0xbfb8aa3b, v24
	v_mul_f32_e32 v27, 0xbfb8aa3b, v25
	v_exp_f32_e32 v26, v26
	v_exp_f32_e32 v27, v27
	v_pk_mul_f32 v[28:29], v[32:33], v[38:39] op_sel_hi:[1,0]
	v_cvt_pk_bf16_f32 v20, v20, v21
	v_add_f32_e32 v26, 1.0, v26
	v_add_f32_e32 v27, 1.0, v27
	v_rcp_f32_e32 v26, v26
	v_rcp_f32_e32 v27, v27
	v_pk_mul_f32 v[22:23], v[28:29], v[22:23]
	v_pk_mul_f32 v[24:25], v[26:27], v[24:25]
	s_nop 0
	v_pk_mul_f32 v[22:23], v[22:23], v[24:25]
	s_nop 0
	v_cvt_pk_bf16_f32 v21, v22, v23
	global_store_dwordx2 v[18:19], v[20:21], off offset:1072
	v_or_b32_e32 v20, 64, v0
	v_mov_b32_e32 v21, v1
	v_lshl_add_u64 v[20:21], v[40:41], 0, v[20:21]
	global_load_dwordx2 v[20:21], v[20:21], off
	s_nop 0
	global_load_dwordx4 v[22:25], v39, s[0:1] offset:2176
	s_waitcnt vmcnt(0) lgkmcnt(0)
	v_lshlrev_b32_e32 v26, 16, v20
	v_and_b32_e32 v27, 0xffff0000, v20
	v_mul_f32_e32 v20, 0xbfb8aa3b, v26
	v_exp_f32_e32 v20, v20
	v_pk_mul_f32 v[2:3], v[2:3], v[22:23]
	v_pk_mul_f32 v[4:5], v[4:5], v[24:25]
	v_add_f32_e32 v20, 1.0, v20
	v_rcp_f32_e32 v28, v20
	v_mul_f32_e32 v20, 0xbfb8aa3b, v27
	v_exp_f32_e32 v20, v20
	s_nop 0
	v_add_f32_e32 v20, 1.0, v20
	v_rcp_f32_e32 v29, v20
	v_lshlrev_b32_e32 v20, 16, v21
	v_and_b32_e32 v21, 0xffff0000, v21
	v_pk_mul_f32 v[22:23], v[28:29], v[26:27]
	s_nop 0
	v_pk_mul_f32 v[2:3], v[2:3], v[22:23]
	v_mul_f32_e32 v22, 0xbfb8aa3b, v20
	v_mul_f32_e32 v23, 0xbfb8aa3b, v21
	v_exp_f32_e32 v22, v22
	v_exp_f32_e32 v23, v23
	v_cvt_pk_bf16_f32 v2, v2, v3
	v_add_f32_e32 v22, 1.0, v22
	v_add_f32_e32 v23, 1.0, v23
	v_rcp_f32_e32 v22, v22
	v_rcp_f32_e32 v23, v23
	s_nop 0
	v_pk_mul_f32 v[20:21], v[22:23], v[20:21]
	s_nop 0
	v_pk_mul_f32 v[4:5], v[4:5], v[20:21]
	s_nop 0
	v_cvt_pk_bf16_f32 v3, v4, v5
	global_store_dwordx2 v[18:19], v[2:3], off offset:1088
	v_or_b32_e32 v2, 0x50, v0
	v_mov_b32_e32 v3, v1
	v_lshl_add_u64 v[2:3], v[40:41], 0, v[2:3]
	global_load_dwordx2 v[20:21], v[2:3], off
	s_nop 0
	global_load_dwordx4 v[2:5], v39, s[0:1] offset:2208
	s_waitcnt vmcnt(0) lgkmcnt(0)
	v_lshlrev_b32_e32 v22, 16, v20
	v_and_b32_e32 v23, 0xffff0000, v20
	v_mul_f32_e32 v20, 0xbfb8aa3b, v22
	v_pk_mul_f32 v[2:3], v[6:7], v[2:3]
	v_mul_f32_e32 v6, 0xbfb8aa3b, v23
	v_exp_f32_e32 v20, v20
	v_exp_f32_e32 v6, v6
	v_pk_mul_f32 v[4:5], v[8:9], v[4:5]
	v_add_f32_e32 v20, 1.0, v20
	v_add_f32_e32 v6, 1.0, v6
	v_rcp_f32_e32 v24, v20
	v_rcp_f32_e32 v25, v6
	s_nop 0
	v_pk_mul_f32 v[6:7], v[24:25], v[22:23]
	s_nop 0
	v_pk_mul_f32 v[2:3], v[2:3], v[6:7]
	v_lshlrev_b32_e32 v6, 16, v21
	v_and_b32_e32 v7, 0xffff0000, v21
	v_mul_f32_e32 v20, 0xbfb8aa3b, v6
	v_mul_f32_e32 v8, 0xbfb8aa3b, v7
	v_exp_f32_e32 v20, v20
	v_exp_f32_e32 v8, v8
	v_cvt_pk_bf16_f32 v2, v2, v3
	v_add_f32_e32 v20, 1.0, v20
	v_add_f32_e32 v8, 1.0, v8
	v_rcp_f32_e32 v20, v20
	v_rcp_f32_e32 v21, v8
	s_nop 0
	v_pk_mul_f32 v[6:7], v[20:21], v[6:7]
	s_nop 0
	v_pk_mul_f32 v[4:5], v[4:5], v[6:7]
	s_nop 0
	v_cvt_pk_bf16_f32 v3, v4, v5
	global_store_dwordx2 v[18:19], v[2:3], off offset:1104
	v_or_b32_e32 v2, 0x60, v0
	v_mov_b32_e32 v3, v1
	v_lshl_add_u64 v[2:3], v[40:41], 0, v[2:3]
	global_load_dwordx2 v[6:7], v[2:3], off
	s_nop 0
	global_load_dwordx4 v[2:5], v39, s[0:1] offset:2240
	v_or_b32_e32 v0, 0x70, v0
	s_waitcnt vmcnt(0) lgkmcnt(0)
	v_lshlrev_b32_e32 v8, 16, v6
	v_and_b32_e32 v9, 0xffff0000, v6
	v_mul_f32_e32 v6, 0xbfb8aa3b, v8
	v_exp_f32_e32 v6, v6
	v_pk_mul_f32 v[2:3], v[10:11], v[2:3]
	v_pk_mul_f32 v[10:11], v[12:13], v[38:39] op_sel_hi:[1,0]
	v_pk_mul_f32 v[12:13], v[14:15], v[38:39] op_sel_hi:[1,0]
	v_add_f32_e32 v6, 1.0, v6
	v_rcp_f32_e32 v20, v6
	v_mul_f32_e32 v6, 0xbfb8aa3b, v9
	v_exp_f32_e32 v6, v6
	v_pk_mul_f32 v[4:5], v[10:11], v[4:5]
	v_add_f32_e32 v6, 1.0, v6
	v_rcp_f32_e32 v21, v6
	v_lshlrev_b32_e32 v6, 16, v7
	v_and_b32_e32 v7, 0xffff0000, v7
	v_pk_mul_f32 v[8:9], v[20:21], v[8:9]
	s_nop 0
	v_pk_mul_f32 v[2:3], v[2:3], v[8:9]
	v_mul_f32_e32 v8, 0xbfb8aa3b, v6
	v_mul_f32_e32 v9, 0xbfb8aa3b, v7
	v_exp_f32_e32 v8, v8
	v_exp_f32_e32 v9, v9
	v_cvt_pk_bf16_f32 v2, v2, v3
	v_add_f32_e32 v8, 1.0, v8
	v_add_f32_e32 v9, 1.0, v9
	v_rcp_f32_e32 v8, v8
	v_rcp_f32_e32 v9, v9
	s_nop 0
	v_pk_mul_f32 v[6:7], v[8:9], v[6:7]
	s_nop 0
	v_pk_mul_f32 v[4:5], v[4:5], v[6:7]
	s_nop 0
	v_cvt_pk_bf16_f32 v3, v4, v5
	global_store_dwordx2 v[18:19], v[2:3], off offset:1120
	v_lshl_add_u64 v[2:3], v[40:41], 0, v[0:1]
	global_load_dwordx2 v[2:3], v[2:3], off
	s_nop 0
	global_load_dwordx4 v[4:7], v39, s[0:1] offset:2272
	s_mov_b64 s[0:1], 0
	s_waitcnt vmcnt(0) lgkmcnt(0)
; __device__ __forceinline__ unsigned pk2(float lo, float hi) { f32x2 v = {lo, hi}; bf16x2_t b = __builtin_convertvector(v, bf16x2_t); return __builtin_bit_cast(unsigned, b); }
; __device__ __forceinline__ float bflo(unsigned u) { return __uint_as_float(u << 16); }
; __device__ __forceinline__ float bfhi(unsigned u) { return __uint_as_float(u & 0xffff0000u); }
; __device__ __forceinline__ float silu(float g) { return g * __builtin_amdgcn_rcpf(1.0f + __expf(-g)); }
; template <int MODE>
; __device__ __forceinline__ void attn_item(const AttnP& p, int b, int h, int qb, LAS unsigned char* lds) {
;     ...
;     bf16x8 Qf[NC][4];
; #pragma unroll
;     for (int c = 0; c < NC; ++c) {
;         u32x4 raw[4]; float ss = 0.f;
; #pragma unroll
;         for (int ks = 0; ks < 4; ++ks) {
;             raw[ks] = *(const u32x4*)(P + (size_t)(tok0 + qrow) * PP + qcol + c * 64 + ks * 16 + hh * 8);
; #pragma unroll
;             for (int e = 0; e < 4; ++e) { const float lo = bflo(raw[ks][e]), hi = bfhi(raw[ks][e]); ss += lo * lo + hi * hi; }
;         }
;         float sc = 0.125f * LOG2E;
;         if (MODE != 1) { ss += __shfl_xor(ss, 32); sc *= 1.0f / sqrtf(ss * (1.0f / 64.0f) + 1e-6f); }
;     ...
;     for (int d = 0; d < DV / 32; ++d)
; #pragma unroll
;         for (int g = 0; g < 4; ++g) {
;             const int dd = d * 32 + 8 * g + 4 * hh;
;             const u32x2 gr = *(const u32x2*)(P + trow * PP + gcol + dd);
;             const f32x4 og = *(const f32x4*)(p.out_gain + gaincol + dd);
;             const float o0 = O[0][d][4 * g] * rn * og[0] * silu(bflo(gr.x)), o1 = O[0][d][4 * g + 1] * rn * og[1] * silu(bfhi(gr.x));
;             const float o2 = O[0][d][4 * g + 2] * rn * og[2] * silu(bflo(gr.y)), o3 = O[0][d][4 * g + 3] * rn * og[3] * silu(bfhi(gr.y));
;             u32x2 wv; wv.x = pk2(o0, o1); wv.y = pk2(o2, o3);
;             *(u32x2*)(p.mixed + trow * 1024 + mixcol + dd) = wv;
;         }
	v_lshlrev_b32_e32 v8, 16, v2
	v_mul_f32_e32 v0, 0xbfb8aa3b, v8
	v_exp_f32_e32 v0, v0
	v_and_b32_e32 v9, 0xffff0000, v2
	v_lshlrev_b32_e32 v2, 16, v3
	v_pk_mul_f32 v[4:5], v[12:13], v[4:5]
	v_add_f32_e32 v0, 1.0, v0
	v_rcp_f32_e32 v10, v0
	v_mul_f32_e32 v0, 0xbfb8aa3b, v9
	v_exp_f32_e32 v0, v0
	v_and_b32_e32 v3, 0xffff0000, v3
	v_add_f32_e32 v0, 1.0, v0
	v_rcp_f32_e32 v11, v0
	v_mul_f32_e32 v0, 0xbfb8aa3b, v2
	v_exp_f32_e32 v0, v0
	v_pk_mul_f32 v[8:9], v[10:11], v[8:9]
	s_nop 0
	v_pk_mul_f32 v[4:5], v[4:5], v[8:9]
	v_add_f32_e32 v0, 1.0, v0
	v_rcp_f32_e32 v8, v0
	v_mul_f32_e32 v0, 0xbfb8aa3b, v3
	v_exp_f32_e32 v0, v0
	v_pk_mul_f32 v[10:11], v[16:17], v[38:39] op_sel_hi:[1,0]
	v_cvt_pk_bf16_f32 v4, v4, v5
	v_pk_mul_f32 v[6:7], v[10:11], v[6:7]
	v_add_f32_e32 v0, 1.0, v0
	v_rcp_f32_e32 v9, v0
	s_nop 0
	v_pk_mul_f32 v[2:3], v[8:9], v[2:3]
	s_nop 0
	v_pk_mul_f32 v[2:3], v[6:7], v[2:3]
	s_nop 0
	v_cvt_pk_bf16_f32 v5, v2, v3
	global_store_dwordx2 v[18:19], v[4:5], off offset:1136
.LBB0_491:
	s_and_b64 vcc, exec, s[0:1]
	s_cbranch_vccz .LBB0_468
	v_mov_b32_e32 v50, v210
	s_ashr_i32 s2, s57, 5
	s_sub_i32 s5, 15, s2
	v_readfirstlane_b32 s0, v50
	s_ashr_i32 s7, s0, 6
	s_lshl_b32 s0, s57, 10
	s_and_b32 s8, s0, 0x7000
	s_lshl_b32 s0, s5, 8
	s_lshl_b32 s3, s7, 5
	v_and_b32_e32 v49, 31, v50
	s_add_i32 s4, s3, s0
	v_or_b32_e32 v228, s4, v49
	s_and_b32 s6, s57, 3
	v_add_u32_e32 v0, s8, v228
	v_mov_b64_e32 v[2:3], s[46:47]
	v_bfe_u32 v48, v50, 5, 1
	v_mad_i64_i32 v[2:3], s[0:1], v0, s76, v[2:3]
	s_lshl_b32 s92, s6, 8
	v_lshl_add_u64 v[2:3], v[2:3], 0, s[92:93]
	v_lshlrev_b32_e32 v206, 4, v48
	v_mov_b32_e32 v207, v1
	v_and_b32_e32 v0, 32, v50
	v_lshl_add_u64 v[32:33], v[2:3], 0, v[206:207]
	global_load_dwordx4 v[52:55], v0, s[40:41] offset:16
	global_load_dwordx4 v[34:37], v0, s[40:41]
	global_load_dwordx4 v[56:59], v0, s[40:41] offset:272
	global_load_dwordx4 v[38:41], v0, s[40:41] offset:256
	global_load_dwordx4 v[60:63], v[32:33], off offset:64
	global_load_dwordx4 v[64:67], v[32:33], off offset:96
	global_load_dwordx4 v[68:71], v[32:33], off
	global_load_dwordx4 v[72:75], v[32:33], off offset:32
	global_load_dwordx4 v[14:17], v0, s[40:41] offset:80
	global_load_dwordx4 v[22:25], v0, s[40:41] offset:64
	global_load_dwordx4 v[76:79], v0, s[40:41] offset:336
	global_load_dwordx4 v[80:83], v0, s[40:41] offset:320
	global_load_dwordx4 v[2:5], v0, s[40:41] offset:144
	global_load_dwordx4 v[10:13], v0, s[40:41] offset:128
	global_load_dwordx4 v[6:9], v0, s[40:41] offset:400
	global_load_dwordx4 v[18:21], v0, s[40:41] offset:384
	s_lshl_b32 s0, s7, 13
	v_and_b32_e32 v51, 63, v50
	s_add_i32 s0, s0, 0
	s_mov_b32 s7, 0xf800000
	s_add_i32 s0, s0, 0x13000
	s_mov_b32 s74, 0xf800000
	s_lshl_b32 s9, s6, 7
	s_waitcnt vmcnt(0)
	v_pk_mul_f32 v[14:15], v[14:15], v[76:77]
	s_waitcnt lgkmcnt(0)
	v_lshlrev_b32_e32 v45, 16, v63
	v_lshlrev_b32_e32 v44, 16, v62
	v_lshlrev_b32_e32 v84, 16, v71
	v_and_b32_e32 v85, 0xffff0000, v71
	v_lshlrev_b32_e32 v86, 16, v70
	v_and_b32_e32 v87, 0xffff0000, v70
	v_lshlrev_b32_e32 v70, 16, v69
	v_and_b32_e32 v71, 0xffff0000, v69
	v_lshlrev_b32_e32 v88, 16, v68
	v_and_b32_e32 v89, 0xffff0000, v68
	v_pk_mul_f32 v[28:29], v[36:37], v[40:41]
	v_pk_mul_f32 v[30:31], v[34:35], v[38:39]
	v_and_b32_e32 v47, 0xffff0000, v63
	v_and_b32_e32 v46, 0xffff0000, v62
	v_lshlrev_b32_e32 v39, 16, v67
	v_lshlrev_b32_e32 v38, 16, v66
	v_and_b32_e32 v37, 0xffff0000, v67
	v_and_b32_e32 v36, 0xffff0000, v66
	v_pk_mul_f32 v[62:63], v[84:85], v[84:85]
	v_pk_mul_f32 v[66:67], v[70:71], v[70:71]
	v_pk_mul_f32 v[96:97], v[88:89], v[88:89]
	v_lshlrev_b32_e32 v43, 16, v65
	v_lshlrev_b32_e32 v42, 16, v64
	v_and_b32_e32 v41, 0xffff0000, v65
	v_and_b32_e32 v40, 0xffff0000, v64
	v_pk_mul_f32 v[64:65], v[86:87], v[86:87]
	v_add_f32_e32 v62, v62, v63
	v_add_f32_e32 v63, v66, v67
	v_add_f32_e32 v66, v96, v97
	v_lshlrev_b32_e32 v92, 16, v72
	v_and_b32_e32 v93, 0xffff0000, v72
	v_add_f32_e32 v63, v66, v63
	v_add_f32_e32 v64, v64, v65
	v_lshlrev_b32_e32 v68, 16, v75
	v_and_b32_e32 v69, 0xffff0000, v75
	v_lshlrev_b32_e32 v90, 16, v74
	v_and_b32_e32 v91, 0xffff0000, v74
	v_lshlrev_b32_e32 v74, 16, v73
	v_and_b32_e32 v75, 0xffff0000, v73
	v_pk_mul_f32 v[104:105], v[92:93], v[92:93]
	v_add_f32_e32 v63, v64, v63
	v_pk_mul_f32 v[102:103], v[74:75], v[74:75]
	v_add_f32_e32 v62, v62, v63
	v_add_f32_e32 v63, v104, v105
	v_pk_mul_f32 v[100:101], v[90:91], v[90:91]
	v_add_f32_e32 v62, v63, v62
	v_add_f32_e32 v63, v102, v103
	v_lshlrev_b32_e32 v94, 16, v60
	v_pk_mul_f32 v[98:99], v[68:69], v[68:69]
	v_and_b32_e32 v95, 0xffff0000, v60
	v_add_f32_e32 v62, v63, v62
	v_add_f32_e32 v63, v100, v101
	v_lshlrev_b32_e32 v72, 16, v61
	v_and_b32_e32 v73, 0xffff0000, v61
	v_pk_mul_f32 v[60:61], v[94:95], v[94:95]
	v_add_f32_e32 v62, v63, v62
	v_add_f32_e32 v63, v98, v99
	v_pk_mul_f32 v[106:107], v[72:73], v[72:73]
	v_add_f32_e32 v62, v63, v62
	v_add_f32_e32 v60, v60, v61
	v_pk_mul_f32 v[34:35], v[46:47], v[46:47]
	v_add_f32_e32 v60, v60, v62
	v_add_f32_e32 v61, v106, v107
	v_pk_fma_f32 v[34:35], v[44:45], v[44:45], v[34:35]
	v_add_f32_e32 v60, v61, v60
	v_pk_mul_f32 v[26:27], v[52:53], v[56:57]
	v_pk_mul_f32 v[52:53], v[40:41], v[40:41]
	v_add_f32_e32 v34, v34, v60
	v_pk_fma_f32 v[52:53], v[42:43], v[42:43], v[52:53]
	v_add_f32_e32 v34, v35, v34
	v_pk_mul_f32 v[56:57], v[36:37], v[36:37]
	v_add_f32_e32 v34, v52, v34
	v_pk_fma_f32 v[56:57], v[38:39], v[38:39], v[56:57]
	v_add_f32_e32 v34, v53, v34
	v_add_f32_e32 v34, v56, v34
	v_add_f32_e32 v52, v57, v34
	ds_bpermute_b32 v53, v226, v52
	v_pk_mul_f32 v[34:35], v[54:55], v[58:59]
	v_lshlrev_b32_e32 v54, 4, v51
	v_add_u32_e32 v207, s0, v54
	v_pk_mul_f32 v[24:25], v[24:25], v[82:83]
	s_waitcnt lgkmcnt(0)
; #define LAS __attribute__((address_space(3)))
; __device__ __forceinline__ unsigned pk2(float lo, float hi) { f32x2 v = {lo, hi}; bf16x2_t b = __builtin_convertvector(v, bf16x2_t); return __builtin_bit_cast(unsigned, b); }
; __device__ __forceinline__ float bflo(unsigned u) { return __uint_as_float(u << 16); }
; __device__ __forceinline__ float bfhi(unsigned u) { return __uint_as_float(u & 0xffff0000u); }
; template <int MODE>
; __device__ __forceinline__ void attn_item(const AttnP& p, int b, int h, int qb, LAS unsigned char* lds) {
;     ...
;     for (int c = 0; c < NC; ++c) {
;         u32x4 raw[4]; float ss = 0.f;
; #pragma unroll
;         for (int ks = 0; ks < 4; ++ks) {
;             raw[ks] = *(const u32x4*)(P + (size_t)(tok0 + qrow) * PP + qcol + c * 64 + ks * 16 + hh * 8);
; #pragma unroll
;             for (int e = 0; e < 4; ++e) { const float lo = bflo(raw[ks][e]), hi = bfhi(raw[ks][e]); ss += lo * lo + hi * hi; }
;         }
;         float sc = 0.125f * LOG2E;
;         if (MODE != 1) { ss += __shfl_xor(ss, 32); sc *= 1.0f / sqrtf(ss * (1.0f / 64.0f) + 1e-6f); }
; #pragma unroll
;         for (int ks = 0; ks < 4; ++ks) {
;             u32x4 o;
; #pragma unroll
;             for (int e = 0; e < 4; ++e) {
;                 float lo = bflo(raw[ks][e]) * sc, hi = bfhi(raw[ks][e]) * sc;
;                 if (MODE != 1) {
;                     const int d = ks * 16 + hh * 8 + 2 * e;
;                     const float* gq = p.qk_gain + ((MODE == 0) ? 0 : 128); const float* gk = gq + 64;
;                     lo *= gq[d] * gk[d]; hi *= gq[d + 1] * gk[d + 1];
;                 }
;                 o[e] = pk2(lo, hi);
;             }
;             Qf[c][ks] = __builtin_bit_cast(bf16x8, o);
;             if (QPARK) *(LAS u32x4*)(lds + QP_OFF + w * 8192 + ((c * 4 + ks) * 64 + lane) * 16) = o;
;         }
;     }
	v_add_f32_e32 v52, v52, v53
	v_fmamk_f32 v52, v52, 0x3c800000, v211
	v_mul_f32_e32 v53, 0x4f800000, v52
	v_cmp_gt_f32_e32 vcc, s7, v52
	v_pk_mul_f32 v[10:11], v[10:11], v[18:19]
	v_pk_mul_f32 v[16:17], v[16:17], v[78:79]
	v_cndmask_b32_e32 v76, v52, v53, vcc
	global_load_dwordx4 v[52:55], v0, s[40:41] offset:208
	global_load_dwordx4 v[56:59], v0, s[40:41] offset:192
	global_load_dwordx4 v[60:63], v0, s[40:41] offset:464
	global_load_dwordx4 v[64:67], v0, s[40:41] offset:448
	v_sqrt_f32_e32 v77, v76
	v_pk_mul_f32 v[22:23], v[22:23], v[80:81]
	v_pk_mul_f32 v[12:13], v[12:13], v[20:21]
	v_add_u32_e32 v0, -1, v77
	v_fma_f32 v82, -v0, v77, v76
	v_cmp_ge_f32_e64 s[0:1], 0, v82
	v_add_u32_e32 v82, 1, v77
	s_nop 0
	v_cndmask_b32_e64 v0, v77, v0, s[0:1]
	v_fma_f32 v77, -v82, v77, v76
	v_cmp_lt_f32_e64 s[0:1], 0, v77
	s_nop 1
	v_cndmask_b32_e64 v0, v0, v82, s[0:1]
	v_mul_f32_e32 v77, 0x37800000, v0
	v_cndmask_b32_e32 v0, v0, v77, vcc
	v_cmp_class_f32_e32 vcc, v76, v212
	s_nop 1
	v_cndmask_b32_e32 v0, v0, v76, vcc
	v_div_scale_f32 v76, s[0:1], v0, v0, 1.0
	v_rcp_f32_e32 v77, v76
	s_nop 0
	v_fma_f32 v18, -v76, v77, 1.0
	v_fmac_f32_e32 v77, v18, v77
	v_div_scale_f32 v18, vcc, 1.0, v0, 1.0
	v_mul_f32_e32 v19, v18, v77
	v_fma_f32 v78, -v76, v19, v18
	v_fmac_f32_e32 v19, v78, v77
	v_fma_f32 v18, -v76, v19, v18
	v_div_fmas_f32 v18, v18, v77, v19
	v_div_fixup_f32 v0, v18, v0, 1.0
	v_mul_f32_e32 v0, 0x3e38aa3b, v0
	v_pk_mul_f32 v[18:19], v[0:1], v[88:89] op_sel_hi:[0,1]
	v_pk_mul_f32 v[18:19], v[30:31], v[18:19]
	s_nop 0
	v_cvt_pk_bf16_f32 v162, v18, v19
	v_pk_mul_f32 v[18:19], v[0:1], v[70:71] op_sel_hi:[0,1]
	v_pk_mul_f32 v[18:19], v[28:29], v[18:19]
	s_nop 0
	v_cvt_pk_bf16_f32 v163, v18, v19
	v_pk_mul_f32 v[18:19], v[0:1], v[86:87] op_sel_hi:[0,1]
	v_pk_mul_f32 v[18:19], v[26:27], v[18:19]
	s_nop 0
	v_cvt_pk_bf16_f32 v164, v18, v19
	v_pk_mul_f32 v[18:19], v[0:1], v[84:85] op_sel_hi:[0,1]
	v_pk_mul_f32 v[18:19], v[34:35], v[18:19]
	s_nop 0
	v_cvt_pk_bf16_f32 v165, v18, v19
	v_pk_mul_f32 v[18:19], v[0:1], v[92:93] op_sel_hi:[0,1]
	v_pk_mul_f32 v[18:19], v[22:23], v[18:19]
	ds_write_b128 v207, v[162:165]
	v_cvt_pk_bf16_f32 v166, v18, v19
	v_pk_mul_f32 v[18:19], v[0:1], v[74:75] op_sel_hi:[0,1]
	v_pk_mul_f32 v[18:19], v[18:19], v[24:25]
	s_nop 0
	v_cvt_pk_bf16_f32 v167, v18, v19
	v_pk_mul_f32 v[18:19], v[0:1], v[90:91] op_sel_hi:[0,1]
	v_pk_mul_f32 v[18:19], v[18:19], v[14:15]
	s_nop 0
	v_cvt_pk_bf16_f32 v168, v18, v19
	v_pk_mul_f32 v[18:19], v[0:1], v[68:69] op_sel_hi:[0,1]
	v_pk_mul_f32 v[18:19], v[18:19], v[16:17]
	v_pk_mul_f32 v[68:69], v[2:3], v[6:7]
	v_cvt_pk_bf16_f32 v169, v18, v19
	v_pk_mul_f32 v[18:19], v[0:1], v[94:95] op_sel_hi:[0,1]
	v_pk_mul_f32 v[18:19], v[18:19], v[10:11]
	ds_write_b128 v207, v[166:169] offset:1024
	v_cvt_pk_bf16_f32 v170, v18, v19
	v_pk_mul_f32 v[18:19], v[0:1], v[72:73] op_sel_hi:[0,1]
	v_pk_mul_f32 v[18:19], v[18:19], v[12:13]
	s_nop 0
	v_cvt_pk_bf16_f32 v171, v18, v19
	v_mov_b32_e32 v18, v44
	v_mov_b32_e32 v19, v46
	v_pk_mul_f32 v[18:19], v[0:1], v[18:19] op_sel_hi:[0,1]
	v_pk_mul_f32 v[2:3], v[18:19], v[68:69]
	v_mov_b32_e32 v46, v45
	v_cvt_pk_bf16_f32 v172, v2, v3
	v_pk_mul_f32 v[2:3], v[0:1], v[46:47] op_sel_hi:[0,1]
	v_pk_mul_f32 v[44:45], v[4:5], v[8:9]
	s_waitcnt vmcnt(0)
	v_pk_mul_f32 v[46:47], v[56:57], v[64:65]
	v_pk_mul_f32 v[2:3], v[2:3], v[44:45]
	s_nop 0
	v_cvt_pk_bf16_f32 v173, v2, v3
	v_mov_b32_e32 v2, v42
	v_mov_b32_e32 v3, v40
	v_pk_mul_f32 v[2:3], v[0:1], v[2:3] op_sel_hi:[0,1]
	v_pk_mul_f32 v[2:3], v[2:3], v[46:47]
	v_mov_b32_e32 v40, v43
	v_cvt_pk_bf16_f32 v174, v2, v3
	v_pk_mul_f32 v[2:3], v[0:1], v[40:41] op_sel_hi:[0,1]
	v_pk_mul_f32 v[40:41], v[58:59], v[66:67]
	v_pk_mul_f32 v[42:43], v[52:53], v[60:61]
	v_pk_mul_f32 v[2:3], v[2:3], v[40:41]
	v_pk_mul_f32 v[52:53], v[54:55], v[62:63]
	v_cvt_pk_bf16_f32 v175, v2, v3
	v_mov_b32_e32 v2, v38
	v_mov_b32_e32 v3, v36
	v_pk_mul_f32 v[2:3], v[0:1], v[2:3] op_sel_hi:[0,1]
	v_pk_mul_f32 v[2:3], v[2:3], v[42:43]
	v_mov_b32_e32 v36, v39
	v_cvt_pk_bf16_f32 v176, v2, v3
	v_pk_mul_f32 v[2:3], v[0:1], v[36:37] op_sel_hi:[0,1]
	v_pk_mul_f32 v[2:3], v[2:3], v[52:53]
	ds_write_b128 v207, v[170:173] offset:2048
	v_cvt_pk_bf16_f32 v177, v2, v3
	ds_write_b128 v207, v[174:177] offset:3072
	global_load_dwordx4 v[2:5], v[32:33], off offset:192
	global_load_dwordx4 v[6:9], v[32:33], off offset:224
	global_load_dwordx4 v[18:21], v[32:33], off offset:128
	global_load_dwordx4 v[36:39], v[32:33], off offset:160
	s_waitcnt vmcnt(0) lgkmcnt(0)
; #define LAS __attribute__((address_space(3)))
; __device__ __forceinline__ unsigned pk2(float lo, float hi) { f32x2 v = {lo, hi}; bf16x2_t b = __builtin_convertvector(v, bf16x2_t); return __builtin_bit_cast(unsigned, b); }
; __device__ __forceinline__ float bflo(unsigned u) { return __uint_as_float(u << 16); }
; __device__ __forceinline__ float bfhi(unsigned u) { return __uint_as_float(u & 0xffff0000u); }
; template <int MODE>
; __device__ __forceinline__ void attn_item(const AttnP& p, int b, int h, int qb, LAS unsigned char* lds) {
;     ...
;     for (int c = 0; c < NC; ++c) {
;         u32x4 raw[4]; float ss = 0.f;
; #pragma unroll
;         for (int ks = 0; ks < 4; ++ks) {
;             raw[ks] = *(const u32x4*)(P + (size_t)(tok0 + qrow) * PP + qcol + c * 64 + ks * 16 + hh * 8);
; #pragma unroll
;             for (int e = 0; e < 4; ++e) { const float lo = bflo(raw[ks][e]), hi = bfhi(raw[ks][e]); ss += lo * lo + hi * hi; }
;         }
;         float sc = 0.125f * LOG2E;
;         if (MODE != 1) { ss += __shfl_xor(ss, 32); sc *= 1.0f / sqrtf(ss * (1.0f / 64.0f) + 1e-6f); }
; #pragma unroll
;         for (int ks = 0; ks < 4; ++ks) {
;             u32x4 o;
; #pragma unroll
;             for (int e = 0; e < 4; ++e) {
;                 float lo = bflo(raw[ks][e]) * sc, hi = bfhi(raw[ks][e]) * sc;
;                 if (MODE != 1) {
;                     const int d = ks * 16 + hh * 8 + 2 * e;
;                     const float* gq = p.qk_gain + ((MODE == 0) ? 0 : 128); const float* gk = gq + 64;
;                     lo *= gq[d] * gk[d]; hi *= gq[d + 1] * gk[d + 1];
;                 }
;                 o[e] = pk2(lo, hi);
;             }
;             Qf[c][ks] = __builtin_bit_cast(bf16x8, o);
;             if (QPARK) *(LAS u32x4*)(lds + QP_OFF + w * 8192 + ((c * 4 + ks) * 64 + lane) * 16) = o;
;         }
;     }
;     if (MODE == 0) { LAS float* tab = (LAS float*)(lds + TAB_OFF); if (tid < 256) tab[tid] = p.biasT[h * 256 + tid]; }
	v_lshlrev_b32_e32 v94, 16, v2
	v_and_b32_e32 v95, 0xffff0000, v2
	v_lshlrev_b32_e32 v64, 16, v21
	v_and_b32_e32 v65, 0xffff0000, v21
	v_lshlrev_b32_e32 v72, 16, v19
	v_and_b32_e32 v73, 0xffff0000, v19
	v_lshlrev_b32_e32 v76, 16, v18
	v_and_b32_e32 v77, 0xffff0000, v18
	v_pk_mul_f32 v[66:67], v[64:65], v[64:65]
	v_lshlrev_b32_e32 v70, 16, v20
	v_and_b32_e32 v71, 0xffff0000, v20
	v_pk_mul_f32 v[74:75], v[72:73], v[72:73]
	v_pk_mul_f32 v[18:19], v[76:77], v[76:77]
	v_pk_mul_f32 v[20:21], v[70:71], v[70:71]
	v_add_f32_e32 v0, v66, v67
	v_add_f32_e32 v66, v74, v75
	v_add_f32_e32 v18, v18, v19
	v_lshlrev_b32_e32 v88, 16, v36
	v_and_b32_e32 v89, 0xffff0000, v36
	v_add_f32_e32 v18, v18, v66
	v_add_f32_e32 v19, v20, v21
	v_lshlrev_b32_e32 v84, 16, v37
	v_and_b32_e32 v85, 0xffff0000, v37
	v_pk_mul_f32 v[36:37], v[88:89], v[88:89]
	v_add_f32_e32 v18, v19, v18
	v_lshlrev_b32_e32 v82, 16, v38
	v_and_b32_e32 v83, 0xffff0000, v38
	v_pk_mul_f32 v[86:87], v[84:85], v[84:85]
	v_add_f32_e32 v0, v0, v18
	v_add_f32_e32 v18, v36, v37
	v_lshlrev_b32_e32 v78, 16, v39
	v_and_b32_e32 v79, 0xffff0000, v39
	v_pk_mul_f32 v[38:39], v[82:83], v[82:83]
	v_add_f32_e32 v0, v18, v0
	v_add_f32_e32 v18, v86, v87
	v_pk_mul_f32 v[80:81], v[78:79], v[78:79]
	v_add_f32_e32 v0, v18, v0
	v_add_f32_e32 v18, v38, v39
	v_lshlrev_b32_e32 v90, 16, v3
	v_and_b32_e32 v91, 0xffff0000, v3
	v_pk_mul_f32 v[2:3], v[94:95], v[94:95]
	v_add_f32_e32 v0, v18, v0
	v_add_f32_e32 v18, v80, v81
	v_and_b32_e32 v55, 0xffff0000, v5
	v_and_b32_e32 v54, 0xffff0000, v4
	v_pk_mul_f32 v[92:93], v[90:91], v[90:91]
	v_add_f32_e32 v0, v18, v0
	v_add_f32_e32 v2, v2, v3
	v_lshlrev_b32_e32 v33, 16, v5
	v_lshlrev_b32_e32 v32, 16, v4
	v_pk_mul_f32 v[4:5], v[54:55], v[54:55]
	v_add_f32_e32 v0, v2, v0
	v_add_f32_e32 v2, v92, v93
	v_pk_fma_f32 v[4:5], v[32:33], v[32:33], v[4:5]
	v_lshlrev_b32_e32 v57, 16, v7
	v_lshlrev_b32_e32 v56, 16, v6
	v_and_b32_e32 v7, 0xffff0000, v7
	v_and_b32_e32 v6, 0xffff0000, v6
	v_add_f32_e32 v0, v2, v0
	v_pk_mul_f32 v[58:59], v[6:7], v[6:7]
	v_add_f32_e32 v0, v4, v0
	v_pk_fma_f32 v[58:59], v[56:57], v[56:57], v[58:59]
	v_lshlrev_b32_e32 v61, 16, v9
	v_lshlrev_b32_e32 v60, 16, v8
	v_and_b32_e32 v9, 0xffff0000, v9
	v_and_b32_e32 v8, 0xffff0000, v8
	v_add_f32_e32 v0, v5, v0
	v_pk_mul_f32 v[62:63], v[8:9], v[8:9]
	v_add_f32_e32 v0, v58, v0
	v_pk_fma_f32 v[62:63], v[60:61], v[60:61], v[62:63]
	v_add_f32_e32 v0, v59, v0
	v_add_f32_e32 v0, v62, v0
	v_add_f32_e32 v0, v63, v0
	ds_bpermute_b32 v2, v226, v0
	s_waitcnt lgkmcnt(0)
	v_add_f32_e32 v0, v0, v2
	v_fmamk_f32 v0, v0, 0x3c800000, v211
	v_mul_f32_e32 v2, 0x4f800000, v0
	v_cmp_gt_f32_e32 vcc, s7, v0
	s_nop 1
	v_cndmask_b32_e32 v0, v0, v2, vcc
	v_sqrt_f32_e32 v2, v0
	s_nop 0
	v_add_u32_e32 v3, -1, v2
	v_fma_f32 v4, -v3, v2, v0
	v_cmp_ge_f32_e64 s[0:1], 0, v4
	v_add_u32_e32 v4, 1, v2
	s_nop 0
	v_cndmask_b32_e64 v3, v2, v3, s[0:1]
	v_fma_f32 v2, -v4, v2, v0
	v_cmp_lt_f32_e64 s[0:1], 0, v2
	s_nop 1
	v_cndmask_b32_e64 v2, v3, v4, s[0:1]
	v_mul_f32_e32 v3, 0x37800000, v2
	v_cndmask_b32_e32 v2, v2, v3, vcc
	v_cmp_class_f32_e32 vcc, v0, v212
	s_nop 1
	v_cndmask_b32_e32 v0, v2, v0, vcc
	v_div_scale_f32 v2, s[0:1], v0, v0, 1.0
	v_rcp_f32_e32 v3, v2
	s_movk_i32 s0, 0x100
	v_fma_f32 v4, -v2, v3, 1.0
	v_fmac_f32_e32 v3, v4, v3
	v_div_scale_f32 v4, vcc, 1.0, v0, 1.0
	v_mul_f32_e32 v5, v4, v3
	v_fma_f32 v18, -v2, v5, v4
	v_fmac_f32_e32 v5, v18, v3
	v_fma_f32 v2, -v2, v5, v4
	v_div_fmas_f32 v2, v2, v3, v5
	v_div_fixup_f32 v0, v2, v0, 1.0
	v_mul_f32_e32 v0, 0x3e38aa3b, v0
	v_pk_mul_f32 v[2:3], v[0:1], v[76:77] op_sel_hi:[0,1]
	v_pk_mul_f32 v[4:5], v[0:1], v[72:73] op_sel_hi:[0,1]
	v_pk_mul_f32 v[2:3], v[30:31], v[2:3]
	v_pk_mul_f32 v[4:5], v[28:29], v[4:5]
	v_cvt_pk_bf16_f32 v2, v2, v3
	v_cvt_pk_bf16_f32 v3, v4, v5
	v_pk_mul_f32 v[4:5], v[0:1], v[70:71] op_sel_hi:[0,1]
	v_pk_mul_f32 v[18:19], v[0:1], v[64:65] op_sel_hi:[0,1]
	v_pk_mul_f32 v[4:5], v[26:27], v[4:5]
	v_pk_mul_f32 v[18:19], v[34:35], v[18:19]
	v_cvt_pk_bf16_f32 v4, v4, v5
	v_cvt_pk_bf16_f32 v5, v18, v19
	ds_write_b128 v207, v[2:5] offset:4096
	v_pk_mul_f32 v[2:3], v[0:1], v[88:89] op_sel_hi:[0,1]
	v_pk_mul_f32 v[4:5], v[0:1], v[84:85] op_sel_hi:[0,1]
	v_pk_mul_f32 v[2:3], v[22:23], v[2:3]
	v_pk_mul_f32 v[4:5], v[24:25], v[4:5]
	v_cvt_pk_bf16_f32 v2, v2, v3
	v_cvt_pk_bf16_f32 v3, v4, v5
	v_pk_mul_f32 v[4:5], v[0:1], v[82:83] op_sel_hi:[0,1]
	v_pk_mul_f32 v[4:5], v[14:15], v[4:5]
	v_pk_mul_f32 v[14:15], v[0:1], v[78:79] op_sel_hi:[0,1]
	v_pk_mul_f32 v[14:15], v[16:17], v[14:15]
	v_cvt_pk_bf16_f32 v4, v4, v5
	v_cvt_pk_bf16_f32 v5, v14, v15
	ds_write_b128 v207, v[2:5] offset:5120
	v_pk_mul_f32 v[2:3], v[0:1], v[94:95] op_sel_hi:[0,1]
	v_pk_mul_f32 v[4:5], v[0:1], v[90:91] op_sel_hi:[0,1]
	v_pk_mul_f32 v[2:3], v[10:11], v[2:3]
	v_pk_mul_f32 v[4:5], v[12:13], v[4:5]
	v_cvt_pk_bf16_f32 v2, v2, v3
	v_cvt_pk_bf16_f32 v3, v4, v5
	v_mov_b32_e32 v4, v32
	v_mov_b32_e32 v5, v54
	v_mov_b32_e32 v54, v33
	v_pk_mul_f32 v[4:5], v[0:1], v[4:5] op_sel_hi:[0,1]
	v_pk_mul_f32 v[10:11], v[0:1], v[54:55] op_sel_hi:[0,1]
	v_pk_mul_f32 v[4:5], v[68:69], v[4:5]
	v_pk_mul_f32 v[10:11], v[44:45], v[10:11]
	v_cvt_pk_bf16_f32 v4, v4, v5
	v_cvt_pk_bf16_f32 v5, v10, v11
	ds_write_b128 v207, v[2:5] offset:6144
	v_mov_b32_e32 v2, v56
	v_mov_b32_e32 v3, v6
	v_mov_b32_e32 v6, v57
	v_pk_mul_f32 v[2:3], v[0:1], v[2:3] op_sel_hi:[0,1]
	v_pk_mul_f32 v[4:5], v[0:1], v[6:7] op_sel_hi:[0,1]
	v_pk_mul_f32 v[2:3], v[46:47], v[2:3]
	v_pk_mul_f32 v[4:5], v[40:41], v[4:5]
	v_cvt_pk_bf16_f32 v2, v2, v3
	v_cvt_pk_bf16_f32 v3, v4, v5
	v_mov_b32_e32 v4, v60
	v_mov_b32_e32 v5, v8
	v_mov_b32_e32 v8, v61
	v_pk_mul_f32 v[4:5], v[0:1], v[4:5] op_sel_hi:[0,1]
	v_pk_mul_f32 v[6:7], v[0:1], v[8:9] op_sel_hi:[0,1]
	v_pk_mul_f32 v[4:5], v[42:43], v[4:5]
	v_pk_mul_f32 v[6:7], v[52:53], v[6:7]
	v_cvt_pk_bf16_f32 v4, v4, v5
	v_cvt_pk_bf16_f32 v5, v6, v7
	v_cmp_gt_i32_e32 vcc, s0, v50
	ds_write_b128 v207, v[2:5] offset:7168
	s_and_saveexec_b64 s[0:1], vcc
	s_cbranch_execz .LBB0_494
	v_lshl_add_u32 v2, s6, 8, v50
	v_ashrrev_i32_e32 v3, 31, v2
	v_lshl_add_u64 v[2:3], v[2:3], 2, s[42:43]
	global_load_dword v0, v[2:3], off
	v_lshl_add_u32 v2, v50, 2, 0
	v_add_u32_e32 v2, 0x12a00, v2
	s_waitcnt vmcnt(0) lgkmcnt(0)
	ds_write_b32 v2, v0
; #define ATT_LOAD(jt) do { ATT_LOADK(jt); ATT_LOADV(jt); } while (0)
; template <int MODE>
; __device__ __forceinline__ void attn_item(const AttnP& p, int b, int h, int qb, LAS unsigned char* lds) {
;     ...
;     ATT_LOAD(jt_max);
;     ATT_STORE(0, jt_max);
;     __syncthreads();
.LBB0_494:
	s_or_b64 exec, exec, s[0:1]
	s_lshl_b32 s0, s5, 2
	v_ashrrev_i32_e32 v4, 3, v50
	s_or_b32 s10, s0, 3
	v_add_u32_e32 v229, s8, v4
	v_lshl_add_u32 v0, s10, 6, v229
	v_mov_b64_e32 v[2:3], s[46:47]
	v_mad_i64_i32 v[2:3], s[0:1], v0, s76, v[2:3]
	v_lshlrev_b32_e32 v0, 3, v50
	v_and_b32_e32 v34, 56, v0
	s_lshl_b32 s0, s9, 1
	s_mov_b32 s1, s93
	v_lshl_add_u64 v[2:3], v[2:3], 0, s[0:1]
	v_lshlrev_b32_e32 v0, 1, v34
	v_lshl_add_u64 v[2:3], v[2:3], 0, v[0:1]
	global_load_dwordx4 v[178:181], v[2:3], off offset:1024
	global_load_dwordx4 v[182:185], v[2:3], off offset:1152
	global_load_dwordx4 v[186:189], v[2:3], off offset:2048
	global_load_dwordx4 v[190:193], v[2:3], off offset:2176
	v_mul_lo_u32 v35, v4, 24
	s_movk_i32 s1, 0x88
	v_mad_u64_u32 v[4:5], s[6:7], v4, s1, v[34:35]
	v_lshlrev_b32_e32 v231, 1, v4
	v_add_lshl_u32 v232, v4, v35, 1
	v_add_u32_e32 v36, 64, v4
	v_add_lshl_u32 v234, v36, v35, 1
	v_add_u32_e32 v37, 0, v231
	v_lshlrev_b32_e32 v233, 1, v36
	v_add_u32_e32 v38, 0, v232
	v_add_u32_e32 v39, 0, v233
	v_lshlrev_b32_e32 v230, 2, v48
	v_and_b32_e32 v41, 16, v50
	s_or_b32 s5, s9, 0x200
	s_or_b32 s6, s9, 0x400
	s_or_b32 s1, s4, 31
	v_mul_u32_u24_e32 v235, 0x110, v49
	s_lshl_b32 s4, s2, 2
	v_mad_i32_i24 v236, v48, -4, v49
	s_lshl_b32 s2, s2, 8
	s_add_i32 s11, s3, 0xffffff01
	v_mov_b32_e32 v208, v1
	v_mov_b32_e32 v209, v1
	s_mov_b32 s12, 0
	s_sub_i32 s13, 64, s4
	s_sub_i32 s14, 0xf80, s2
	s_lshl_b32 s92, s5, 1
	s_lshl_b32 s4, s6, 1
	s_waitcnt vmcnt(0) lgkmcnt(0)
	v_and_b32_e32 v3, 0xffff0000, v181
	v_and_b32_e32 v5, 0xffff0000, v180
	v_and_b32_e32 v7, 0xffff0000, v179
	v_and_b32_e32 v9, 0xffff0000, v178
	v_lshlrev_b32_e32 v2, 16, v181
	v_lshlrev_b32_e32 v4, 16, v180
	v_lshlrev_b32_e32 v6, 16, v179
	v_lshlrev_b32_e32 v8, 16, v178
	v_and_b32_e32 v15, 0xffff0000, v183
	v_and_b32_e32 v17, 0xffff0000, v182
	v_mov_b32_e32 v20, v3
	v_mov_b32_e32 v21, v5
	v_mov_b32_e32 v24, v9
	v_mov_b32_e32 v25, v7
	v_and_b32_e32 v11, 0xffff0000, v185
	v_and_b32_e32 v13, 0xffff0000, v184
	v_lshlrev_b32_e32 v14, 16, v183
	v_lshlrev_b32_e32 v16, 16, v182
	v_mov_b32_e32 v18, v2
	v_mov_b32_e32 v19, v4
	v_mov_b32_e32 v22, v8
	v_mov_b32_e32 v23, v6
	v_mov_b32_e32 v32, v17
	v_mov_b32_e32 v33, v15
	v_pk_mul_f32 v[20:21], v[20:21], v[20:21]
	v_pk_mul_f32 v[24:25], v[24:25], v[24:25]
	v_lshlrev_b32_e32 v10, 16, v185
	v_lshlrev_b32_e32 v12, 16, v184
	v_mov_b32_e32 v28, v11
	v_mov_b32_e32 v29, v13
	v_mov_b32_e32 v30, v16
	v_mov_b32_e32 v31, v14
	v_pk_mul_f32 v[32:33], v[32:33], v[32:33]
	v_pk_fma_f32 v[18:19], v[18:19], v[18:19], v[20:21]
	v_pk_fma_f32 v[20:21], v[22:23], v[22:23], v[24:25]
	v_mov_b32_e32 v26, v10
	v_mov_b32_e32 v27, v12
	v_pk_mul_f32 v[28:29], v[28:29], v[28:29]
	v_pk_fma_f32 v[24:25], v[30:31], v[30:31], v[32:33]
	v_add_f32_e32 v0, v20, v21
	v_pk_fma_f32 v[22:23], v[26:27], v[26:27], v[28:29]
	v_add_f32_e32 v20, v24, v25
	v_add_f32_e32 v0, v19, v0
	v_add_f32_e32 v19, v23, v20
	v_add_f32_e32 v0, v18, v0
	v_add_f32_e32 v18, v22, v19
	s_nop 0
	v_add_f32_dpp v0, v0, v0 quad_perm:[1,0,3,2] row_mask:0xf bank_mask:0xf bound_ctrl:1
	v_add_f32_dpp v18, v18, v18 quad_perm:[1,0,3,2] row_mask:0xf bank_mask:0xf bound_ctrl:1
	s_nop 0
	v_add_f32_dpp v0, v0, v0 quad_perm:[2,3,0,1] row_mask:0xf bank_mask:0xf bound_ctrl:1
	v_add_f32_dpp v18, v18, v18 quad_perm:[2,3,0,1] row_mask:0xf bank_mask:0xf bound_ctrl:1
	s_nop 0
	v_add_f32_dpp v0, v0, v0 row_half_mirror row_mask:0xf bank_mask:0xf bound_ctrl:1
	v_fmamk_f32 v0, v0, 0x3c800000, v211
	v_add_f32_dpp v18, v18, v18 row_half_mirror row_mask:0xf bank_mask:0xf bound_ctrl:1
	v_rsq_f32_e32 v0, v0
	v_fmamk_f32 v18, v18, 0x3c800000, v211
	v_rsq_f32_e32 v18, v18
	v_pk_mul_f32 v[8:9], v[0:1], v[8:9] op_sel_hi:[0,1]
	v_pk_mul_f32 v[6:7], v[0:1], v[6:7] op_sel_hi:[0,1]
	v_pk_mul_f32 v[4:5], v[0:1], v[4:5] op_sel_hi:[0,1]
	v_pk_mul_f32 v[20:21], v[0:1], v[2:3] op_sel_hi:[0,1]
	v_pk_mul_f32 v[16:17], v[18:19], v[16:17] op_sel_hi:[0,1]
	v_pk_mul_f32 v[14:15], v[18:19], v[14:15] op_sel_hi:[0,1]
	v_pk_mul_f32 v[12:13], v[18:19], v[12:13] op_sel_hi:[0,1]
	v_pk_mul_f32 v[10:11], v[18:19], v[10:11] op_sel_hi:[0,1]
	v_cvt_pk_bf16_f32 v2, v8, v9
	v_cvt_pk_bf16_f32 v3, v6, v7
	v_cvt_pk_bf16_f32 v4, v4, v5
	v_cvt_pk_bf16_f32 v5, v20, v21
	v_add_u32_e32 v0, 0, v234
	v_cvt_pk_bf16_f32 v6, v16, v17
	v_cvt_pk_bf16_f32 v7, v14, v15
	v_cvt_pk_bf16_f32 v8, v12, v13
	v_cvt_pk_bf16_f32 v9, v10, v11
	ds_write_b128 v37, v[2:5]
	ds_write_b128 v38, v[186:189] offset:17408
	ds_write_b128 v39, v[6:9]
	ds_write_b128 v0, v[190:193] offset:17408
	v_lshlrev_b32_e32 v0, 2, v51
	s_waitcnt lgkmcnt(0)
	s_barrier
; #define LAS __attribute__((address_space(3)))
; template <int MODE>
; __device__ __forceinline__ void attn_item(const AttnP& p, int b, int h, int qb, LAS unsigned char* lds) {
;     ...
;     f32x16 O[NC][DV / 32];
; #pragma unroll
;     for (int c = 0; c < NC; ++c)
; #pragma unroll
;         for (int d = 0; d < DV / 32; ++d)
; #pragma unroll
;             for (int i = 0; i < 16; ++i) O[c][d][i] = 0.f;
;     float mrun[NC], lsum[NC];
; #pragma unroll
;     for (int c = 0; c < NC; ++c) { mrun[c] = -1e30f; lsum[c] = 0.f; }
;     ...
;     float mfix = 0.f;
;     if (MODE == 2) mfix = qk2;
;     if (MODE == 0) {
;         float gq_ = fabsf(p.qk_gain[lane]), gk_ = fabsf(p.qk_gain[64 + lane]);
;         const LAS float* tab_ = (const LAS float*)(lds + TAB_OFF);
;         float tm_ = fmaxf(fmaxf(fabsf(tab_[lane]), fabsf(tab_[64 + lane])), fmaxf(fabsf(tab_[128 + lane]), fabsf(tab_[192 + lane])));
; #pragma unroll
;         for (int o_ = 1; o_ < 64; o_ <<= 1) { gq_ = fmaxf(gq_, __shfl_xor(gq_, o_)); gk_ = fmaxf(gk_, __shfl_xor(gk_, o_)); tm_ = fmaxf(tm_, __shfl_xor(tm_, o_)); }
;         mfix = 8.0f * gq_ * gk_ * LOG2E * 1.02f + tm_;
;     }
	global_load_dword v35, v0, s[40:41]
	global_load_dword v40, v0, s[40:41] offset:256
	v_add_u32_e32 v0, 0, v0
	v_add_u32_e32 v0, 0x12a00, v0
	ds_read2st64_b32 v[36:37], v0 offset1:1
	ds_read2st64_b32 v[38:39], v0 offset0:2 offset1:3
	v_lshrrev_b32_e32 v18, 2, v50
	v_lshlrev_b32_e32 v19, 2, v50
	v_and_or_b32 v42, v18, 3, v230
	v_and_b32_e32 v43, 12, v19
	s_waitcnt lgkmcnt(0)
	v_max_f32_e64 v39, |v39|, |v39|
	v_max_f32_e64 v38, |v38|, |v38|
	v_max_f32_e32 v38, v38, v39
	v_max3_f32 v36, |v36|, |v37|, v38
	ds_bpermute_b32 v37, v221, v36
	v_mul_u32_u24_e32 v0, 0xa0, v42
	v_or3_b32 v0, v43, v41, v0
	v_lshlrev_b32_e32 v237, 1, v0
	v_mov_b32_e32 v16, v1
	s_waitcnt lgkmcnt(0)
	v_max_f32_e32 v0, v37, v37
	v_max_f32_e32 v0, v36, v0
	ds_bpermute_b32 v38, v222, v0
	v_mov_b32_e32 v17, v1
	v_mov_b32_e32 v2, v1
	v_mov_b32_e32 v3, v1
	v_mov_b32_e32 v4, v1
	s_waitcnt lgkmcnt(0)
	v_max_f32_e32 v38, v38, v38
	v_max_f32_e32 v0, v0, v38
	ds_bpermute_b32 v38, v223, v0
	v_mov_b32_e32 v5, v1
	v_mov_b32_e32 v6, v1
	v_mov_b32_e32 v7, v1
	v_mov_b32_e32 v8, v1
	s_waitcnt lgkmcnt(0)
	v_max_f32_e32 v38, v38, v38
	v_max_f32_e32 v0, v0, v38
	ds_bpermute_b32 v38, v224, v0
	v_mov_b32_e32 v9, v1
	v_mov_b32_e32 v10, v1
	v_mov_b32_e32 v11, v1
	v_mov_b32_e32 v12, v1
	s_waitcnt lgkmcnt(0)
	v_max_f32_e32 v38, v38, v38
	v_max_f32_e32 v0, v0, v38
	ds_bpermute_b32 v38, v225, v0
	v_mov_b32_e32 v13, v1
	v_mov_b32_e32 v14, v1
	v_mov_b32_e32 v15, v1
	v_mov_b64_e32 v[32:33], v[16:17]
	s_waitcnt lgkmcnt(0)
	v_max_f32_e32 v38, v38, v38
	v_max_f32_e32 v38, v0, v38
	v_mov_b64_e32 v[80:81], v[16:17]
	v_mov_b64_e32 v[112:113], v[16:17]
	v_mov_b64_e32 v[64:65], v[16:17]
	v_mov_b64_e32 v[96:97], v[16:17]
	v_mov_b64_e32 v[128:129], v[16:17]
	v_mov_b64_e32 v[30:31], v[14:15]
	v_mov_b64_e32 v[28:29], v[12:13]
	v_mov_b64_e32 v[26:27], v[10:11]
	v_mov_b64_e32 v[24:25], v[8:9]
	v_mov_b64_e32 v[22:23], v[6:7]
	v_mov_b64_e32 v[20:21], v[4:5]
	v_mov_b64_e32 v[18:19], v[2:3]
	v_mov_b64_e32 v[78:79], v[14:15]
	v_mov_b64_e32 v[76:77], v[12:13]
	v_mov_b64_e32 v[74:75], v[10:11]
	v_mov_b64_e32 v[72:73], v[8:9]
	v_mov_b64_e32 v[70:71], v[6:7]
	v_mov_b64_e32 v[68:69], v[4:5]
	v_mov_b64_e32 v[66:67], v[2:3]
	v_mov_b64_e32 v[110:111], v[14:15]
	v_mov_b64_e32 v[108:109], v[12:13]
	v_mov_b64_e32 v[106:107], v[10:11]
	v_mov_b64_e32 v[104:105], v[8:9]
	v_mov_b64_e32 v[102:103], v[6:7]
	v_mov_b64_e32 v[100:101], v[4:5]
	v_mov_b64_e32 v[98:99], v[2:3]
	v_add_u32_e32 v238, 0x2800, v237
	v_add_u32_e32 v239, 0x3c00, v237
	v_add_u32_e32 v240, 0x1400, v237
	v_mov_b64_e32 v[62:63], v[14:15]
	v_mov_b64_e32 v[60:61], v[12:13]
	v_mov_b64_e32 v[58:59], v[10:11]
	s_waitcnt vmcnt(1)
	v_and_b32_e32 v36, 0x7fffffff, v35
	s_waitcnt vmcnt(0)
	v_and_b32_e32 v37, 0x7fffffff, v40
	ds_bpermute_b32 v36, v221, v36
	ds_bpermute_b32 v37, v221, v37
	v_max_f32_e64 v35, |v35|, |v35|
	v_max_f32_e64 v39, |v40|, |v40|
	ds_bpermute_b32 v40, v226, v38
	s_waitcnt lgkmcnt(2)
	v_max_f32_e32 v36, v36, v36
	s_waitcnt lgkmcnt(1)
	v_max_f32_e32 v37, v37, v37
	v_max_f32_e32 v35, v35, v36
	v_max_f32_e32 v36, v39, v37
	ds_bpermute_b32 v37, v222, v35
	ds_bpermute_b32 v39, v222, v36
	v_mov_b64_e32 v[56:57], v[8:9]
	v_mov_b64_e32 v[54:55], v[6:7]
	v_mov_b64_e32 v[52:53], v[4:5]
	s_waitcnt lgkmcnt(1)
	v_max_f32_e32 v37, v37, v37
	s_waitcnt lgkmcnt(0)
	v_max_f32_e32 v39, v39, v39
	v_max_f32_e32 v35, v35, v37
	v_max_f32_e32 v36, v36, v39
	ds_bpermute_b32 v37, v223, v35
	ds_bpermute_b32 v39, v223, v36
	v_mov_b64_e32 v[50:51], v[2:3]
	v_mov_b64_e32 v[94:95], v[14:15]
	v_mov_b64_e32 v[92:93], v[12:13]
	s_waitcnt lgkmcnt(1)
	v_max_f32_e32 v37, v37, v37
	s_waitcnt lgkmcnt(0)
	v_max_f32_e32 v39, v39, v39
	v_max_f32_e32 v35, v35, v37
	v_max_f32_e32 v36, v36, v39
	ds_bpermute_b32 v37, v224, v35
	ds_bpermute_b32 v39, v224, v36
	v_mov_b64_e32 v[90:91], v[10:11]
	v_mov_b64_e32 v[88:89], v[8:9]
	v_mov_b64_e32 v[86:87], v[6:7]
	s_waitcnt lgkmcnt(1)
	v_max_f32_e32 v37, v37, v37
	s_waitcnt lgkmcnt(0)
	v_max_f32_e32 v39, v39, v39
	v_max_f32_e32 v35, v35, v37
	v_max_f32_e32 v36, v36, v39
	ds_bpermute_b32 v37, v225, v35
	ds_bpermute_b32 v39, v225, v36
	v_mov_b64_e32 v[84:85], v[4:5]
	v_mov_b64_e32 v[82:83], v[2:3]
	v_mov_b64_e32 v[126:127], v[14:15]
	s_waitcnt lgkmcnt(1)
	v_max_f32_e32 v0, v37, v37
	s_waitcnt lgkmcnt(0)
	v_max_f32_e32 v37, v39, v39
	v_max_f32_e32 v35, v35, v0
	v_max_f32_e32 v36, v36, v37
	ds_bpermute_b32 v37, v226, v35
	ds_bpermute_b32 v39, v226, v36
	v_lshlrev_b32_e32 v0, 1, v34
	v_max_f32_e32 v34, v40, v40
	v_max_f32_e32 v241, v38, v34
	s_waitcnt lgkmcnt(1)
	v_max_f32_e32 v34, v37, v37
	s_waitcnt lgkmcnt(0)
	v_max_f32_e32 v37, v39, v39
	v_max_f32_e32 v34, v35, v34
	v_max_f32_e32 v35, v36, v37
	v_mul_f32_e32 v34, 0x41000000, v34
	v_mul_f32_e32 v34, v35, v34
	v_mul_f32_e32 v34, 0x3fb8aa3b, v34
	v_fmac_f32_e32 v241, 0x3f828f5c, v34
	v_mov_b64_e32 v[48:49], v[16:17]
	v_mov_b64_e32 v[46:47], v[14:15]
	v_mov_b64_e32 v[44:45], v[12:13]
	v_mov_b64_e32 v[42:43], v[10:11]
	v_mov_b64_e32 v[40:41], v[8:9]
	v_mov_b64_e32 v[38:39], v[6:7]
	v_mov_b64_e32 v[36:37], v[4:5]
	v_mov_b64_e32 v[34:35], v[2:3]
	v_mov_b64_e32 v[124:125], v[12:13]
	v_mov_b64_e32 v[122:123], v[10:11]
	v_mov_b64_e32 v[120:121], v[8:9]
	v_mov_b64_e32 v[118:119], v[6:7]
	v_mov_b64_e32 v[116:117], v[4:5]
	v_mov_b64_e32 v[114:115], v[2:3]
	v_mov_b32_e32 v255, 0x12dfc
	ds_read_b32 v241, v255
	s_waitcnt lgkmcnt(0)
	s_branch .LBB0_496

; #define ATT_LOADK(jt) do { _Pragma("unroll") for (int i_ = 0; i_ < NC; ++i_) { const int key_ = tid >> 3, dch_ = (tid & 7) + 8 * i_; \
;             const bf16_t* rp_ = P + (size_t)(tok0 + (jt) * 64 + key_) * PP + dch_ * 8; kreg[i_] = *(const u32x4*)(rp_ + kcol); } \
;         if (MODE == 2 && w == 0) cfreg = p.misc[(size_t)(tok0 + (jt) * 64 + lane) * MISCP + 64 + h]; } while (0)
; #define ATT_LOADV(jt) do { _Pragma("unroll") for (int i_ = 0; i_ < NC; ++i_) { const int key_ = tid >> 3, dch_ = (tid & 7) + 8 * i_; \
;             const bf16_t* rp_ = P + (size_t)(tok0 + (jt) * 64 + key_) * PP + dch_ * 8; vreg[i_] = *(const u32x4*)(rp_ + vcol); } } while (0)
; template <int MODE>
; __device__ __forceinline__ void attn_item(const AttnP& p, int b, int h, int qb, LAS unsigned char* lds) {
;     ...
;     for (int it = 0; it <= jt_max; ++it) {
;         const int jt = jt_max - it, k0 = jt * 64, buf = it & 1;
;         const bool has_next = it < jt_max;
;         if (has_next) { ATT_LOADK(jt - 1); ATT_LOADV(jt - 1); }
.LBB0_496:
	s_cmp_lt_u32 s12, s10
	s_cselect_b64 s[6:7], -1, 0
	s_cmp_ge_u32 s12, s10
	s_cbranch_scc1 .LBB0_498
	v_add_u32_e32 v132, s14, v229
	v_mov_b64_e32 v[130:131], s[46:47]
	v_mad_i64_i32 v[130:131], s[2:3], v132, s76, v[130:131]
	v_lshl_add_u64 v[132:133], v[130:131], 0, s[92:93]
	v_lshl_add_u64 v[134:135], v[130:131], 0, v[0:1]
	v_lshl_add_u64 v[136:137], v[134:135], 0, s[92:93]
	v_lshl_add_u64 v[132:133], v[132:133], 0, v[0:1]
	s_mov_b32 s5, s93
	s_waitcnt vmcnt(0)
	global_load_dwordx4 v[178:181], v[136:137], off
	global_load_dwordx4 v[182:185], v[132:133], off offset:128
	v_lshl_add_u64 v[130:131], v[130:131], 0, s[4:5]
	v_lshl_add_u64 v[132:133], v[134:135], 0, s[4:5]
	v_lshl_add_u64 v[130:131], v[130:131], 0, v[0:1]
	global_load_dwordx4 v[186:189], v[132:133], off
	global_load_dwordx4 v[190:193], v[130:131], off offset:128

; #define LAS __attribute__((address_space(3)))
; template <int MODE>
; __device__ __forceinline__ void attn_item(const AttnP& p, int b, int h, int qb, LAS unsigned char* lds) {
;     ...
;                     if (MODE == 0) {
;                         const LAS float* tab = (const LAS float*)(lds + TAB_OFF);
;                         if (qw - (kp0 + 31) >= 128) {
;                             const float cb = tab[255] - mfix;
; #pragma unroll
;                             for (int c = 0; c < NC; ++c) { ATT_QK(c, cb); ATT_TAIL(c); }
;                         } else {
;                             float binit[16];
; #pragma unroll
;                             for (int i = 0; i < 16; ++i) {
;                                 const int dist = qrow - (kp0 + crow(i, hh));
;                                 binit[i] = (dist < 0) ? -3e38f : (tab[dist > 255 ? 255 : dist] - mfix);
;                             }
; #pragma unroll
;                             for (int c = 0; c < NC; ++c) { ATT_QK(c, binit[i]); ATT_TAIL(c); }
;                         }
;                     } else {
;                         float binit[16];
;                         const LAS float* bl = (const LAS float*)(vtb + VT_BYTES) + 32 * kb2 + 4 * hh;
; #pragma unroll
;                         for (int g = 0; g < 4; ++g) {
;                             const f32x4 t = *(const LAS f32x4*)(bl + 8 * g);
; #pragma unroll
;                             for (int e = 0; e < 4; ++e) binit[4 * g + e] = (need_mask && (kp0 + crow(4 * g + e, hh) > qrow)) ? -3e38f : (t[e] - mfix);
;                         }
;                         ATT_QK(0, binit[i]); ATT_TAIL(0);
;                     }
;     ...
;                 }
; #pragma unroll
;                 for (int t2 = 0; t2 < 2; ++t2)
; #pragma unroll
;                     for (int d = 0; d < DV / 32; ++d) {
;                         const LAS unsigned char* vp = vtb + ((32 * kb2 + 16 * t2 + 4 * hh + ((lane & 15) >> 2)) * VPT + d * 32 + 16 * ((lane >> 4) & 1) + 4 * (lane & 3)) * 2;
;                         const s16x4 lo = vtr(vp), hi = vtr(vp + 8 * VPT * 2);
;                         const bf16x8 va = __builtin_shufflevector(lo, hi, 0, 1, 2, 3, 4, 5, 6, 7);
; #pragma unroll
;                         for (int c = 0; c < NC; ++c) O[c][d] = MFMA32(va, pb[c][t2], O[c][d]);
;                     }
.LBB0_535:
.LBB0_537:
	s_nop 11
	v_exp_f32_e32 v130, v130
	v_exp_f32_e32 v131, v131
	v_exp_f32_e32 v132, v132
	v_exp_f32_e32 v133, v133
	v_add_f32_e32 v154, 0, v130
	v_exp_f32_e32 v156, v134
	v_add_f32_e32 v154, v131, v154
	v_exp_f32_e32 v157, v135
	v_add_f32_e32 v154, v132, v154
	v_exp_f32_e32 v158, v136
	v_add_f32_e32 v154, v133, v154
	v_exp_f32_e32 v137, v137
	v_add_f32_e32 v134, v156, v154
	v_exp_f32_e32 v138, v138
	v_add_f32_e32 v134, v157, v134
	v_exp_f32_e32 v139, v139
	v_add_f32_e32 v134, v158, v134
	v_exp_f32_e32 v140, v140
	v_add_f32_e32 v134, v137, v134
	v_exp_f32_e32 v141, v141
	v_add_f32_e32 v134, v138, v134
	v_exp_f32_e32 v142, v142
	v_add_f32_e32 v134, v139, v134
	v_exp_f32_e32 v143, v143
	v_add_f32_e32 v134, v140, v134
	v_exp_f32_e32 v144, v144
	v_add_f32_e32 v134, v141, v134
	v_exp_f32_e32 v145, v145
	v_add_f32_e32 v134, v142, v134
	v_add_f32_e32 v134, v143, v134
	v_add_f32_e32 v134, v144, v134
	v_cvt_pk_bf16_f32 v135, v132, v133
	v_cvt_pk_bf16_f32 v132, v142, v143
	v_add_u32_e32 v243, s15, v238
	v_add_f32_e32 v154, v145, v134
	v_cvt_pk_bf16_f32 v134, v130, v131
	v_cvt_pk_bf16_f32 v130, v138, v139
	v_cvt_pk_bf16_f32 v131, v140, v141
	v_cvt_pk_bf16_f32 v133, v144, v145
	ds_read_b64_tr_b16 v[244:245], v243 offset:17408
	ds_read_b64_tr_b16 v[246:247], v243 offset:19968
	ds_read_b64_tr_b16 v[248:249], v243 offset:17472
	ds_read_b64_tr_b16 v[250:251], v243 offset:20032
	ds_read_b64_tr_b16 v[138:139], v243 offset:17536
	ds_read_b64_tr_b16 v[140:141], v243 offset:20096
	ds_read_b64_tr_b16 v[142:143], v243 offset:17600
	ds_read_b64_tr_b16 v[144:145], v243 offset:20160
	v_cvt_pk_bf16_f32 v136, v156, v157
	v_cvt_pk_bf16_f32 v137, v158, v137
	v_add_u32_e32 v243, s15, v239
	v_add_f32_e64 v208, v208, v154
	v_add_f32_e64 v209, v209, v155
	s_waitcnt lgkmcnt(6)
	v_mfma_f32_32x32x16_bf16 v[114:129], v[244:247], v[150:153], v[114:129]
	v_mfma_f32_32x32x16_bf16 v[98:113], v[244:247], v[134:137], v[98:113]
	ds_read_b64_tr_b16 v[244:245], v243 offset:17408
	ds_read_b64_tr_b16 v[246:247], v243 offset:19968
	s_waitcnt lgkmcnt(6)
	v_mfma_f32_32x32x16_bf16 v[82:97], v[248:251], v[150:153], v[82:97]
	v_mfma_f32_32x32x16_bf16 v[66:81], v[248:251], v[134:137], v[66:81]
	ds_read_b64_tr_b16 v[248:249], v243 offset:17472
	ds_read_b64_tr_b16 v[250:251], v243 offset:20032
	s_waitcnt lgkmcnt(6)
	v_mfma_f32_32x32x16_bf16 v[50:65], v[138:141], v[150:153], v[50:65]
	v_mfma_f32_32x32x16_bf16 v[18:33], v[138:141], v[134:137], v[18:33]
	ds_read_b64_tr_b16 v[138:139], v243 offset:17536
	ds_read_b64_tr_b16 v[140:141], v243 offset:20096
	s_waitcnt lgkmcnt(6)
	v_mfma_f32_32x32x16_bf16 v[34:49], v[142:145], v[150:153], v[34:49]
	v_mfma_f32_32x32x16_bf16 v[2:17], v[142:145], v[134:137], v[2:17]
	ds_read_b64_tr_b16 v[142:143], v243 offset:17600
	ds_read_b64_tr_b16 v[144:145], v243 offset:20160
	s_waitcnt lgkmcnt(6)
	v_mfma_f32_32x32x16_bf16 v[114:129], v[244:247], v[146:149], v[114:129]
	v_mfma_f32_32x32x16_bf16 v[98:113], v[244:247], v[130:133], v[98:113]
	s_waitcnt lgkmcnt(4)
	v_mfma_f32_32x32x16_bf16 v[82:97], v[248:251], v[146:149], v[82:97]
	v_mfma_f32_32x32x16_bf16 v[66:81], v[248:251], v[130:133], v[66:81]
	s_waitcnt lgkmcnt(2)
	v_mfma_f32_32x32x16_bf16 v[50:65], v[138:141], v[146:149], v[50:65]
	v_mfma_f32_32x32x16_bf16 v[18:33], v[138:141], v[130:133], v[18:33]
	s_waitcnt lgkmcnt(0)
	v_mfma_f32_32x32x16_bf16 v[34:49], v[142:145], v[146:149], v[34:49]
	v_mfma_f32_32x32x16_bf16 v[2:17], v[142:145], v[130:133], v[2:17]
	s_add_i32 s2, s14, 64
	s_cmp_gt_i32 s2, s1
	s_cbranch_scc1 .LBB0_500

; #define LAS __attribute__((address_space(3)))
; template <int MODE>
; __device__ __forceinline__ void attn_item(const AttnP& p, int b, int h, int qb, LAS unsigned char* lds) {
;     ...
;                     if (MODE == 0) {
;                         const LAS float* tab = (const LAS float*)(lds + TAB_OFF);
;                         if (qw - (kp0 + 31) >= 128) {
;                             const float cb = tab[255] - mfix;
; #pragma unroll
;                             for (int c = 0; c < NC; ++c) { ATT_QK(c, cb); ATT_TAIL(c); }
;                         } else {
;                             float binit[16];
; #pragma unroll
;                             for (int i = 0; i < 16; ++i) {
;                                 const int dist = qrow - (kp0 + crow(i, hh));
;                                 binit[i] = (dist < 0) ? -3e38f : (tab[dist > 255 ? 255 : dist] - mfix);
;                             }
; #pragma unroll
;                             for (int c = 0; c < NC; ++c) { ATT_QK(c, binit[i]); ATT_TAIL(c); }
;                         }
;                     } else {
;                         float binit[16];
;                         const LAS float* bl = (const LAS float*)(vtb + VT_BYTES) + 32 * kb2 + 4 * hh;
; #pragma unroll
;                         for (int g = 0; g < 4; ++g) {
;                             const f32x4 t = *(const LAS f32x4*)(bl + 8 * g);
; #pragma unroll
;                             for (int e = 0; e < 4; ++e) binit[4 * g + e] = (need_mask && (kp0 + crow(4 * g + e, hh) > qrow)) ? -3e38f : (t[e] - mfix);
;                         }
;                         ATT_QK(0, binit[i]); ATT_TAIL(0);
;                     }
;     ...
;                 }
; #pragma unroll
;                 for (int t2 = 0; t2 < 2; ++t2)
; #pragma unroll
;                     for (int d = 0; d < DV / 32; ++d) {
;                         const LAS unsigned char* vp = vtb + ((32 * kb2 + 16 * t2 + 4 * hh + ((lane & 15) >> 2)) * VPT + d * 32 + 16 * ((lane >> 4) & 1) + 4 * (lane & 3)) * 2;
;                         const s16x4 lo = vtr(vp), hi = vtr(vp + 8 * VPT * 2);
;                         const bf16x8 va = __builtin_shufflevector(lo, hi, 0, 1, 2, 3, 4, 5, 6, 7);
; #pragma unroll
;                         for (int c = 0; c < NC; ++c) O[c][d] = MFMA32(va, pb[c][t2], O[c][d]);
;                     }
.LBB0_574:
	s_nop 11
	v_exp_f32_e32 v130, v130
	v_exp_f32_e32 v131, v131
	v_exp_f32_e32 v132, v132
	v_exp_f32_e32 v133, v133
	v_add_f32_e32 v154, 0, v130
	v_exp_f32_e32 v156, v134
	v_add_f32_e32 v154, v131, v154
	v_exp_f32_e32 v157, v135
	v_add_f32_e32 v154, v132, v154
	v_exp_f32_e32 v158, v136
	v_add_f32_e32 v154, v133, v154
	v_exp_f32_e32 v137, v137
	v_add_f32_e32 v134, v156, v154
	v_exp_f32_e32 v138, v138
	v_add_f32_e32 v134, v157, v134
	v_exp_f32_e32 v139, v139
	v_add_f32_e32 v134, v158, v134
	v_exp_f32_e32 v140, v140
	v_add_f32_e32 v134, v137, v134
	v_exp_f32_e32 v141, v141
	v_add_f32_e32 v134, v138, v134
	v_exp_f32_e32 v142, v142
	v_add_f32_e32 v134, v139, v134
	v_exp_f32_e32 v143, v143
	v_add_f32_e32 v134, v140, v134
	v_exp_f32_e32 v144, v144
	v_add_f32_e32 v134, v141, v134
	v_exp_f32_e32 v145, v145
	v_add_f32_e32 v134, v142, v134
	v_add_f32_e32 v134, v143, v134
	v_add_f32_e32 v134, v144, v134
	v_cvt_pk_bf16_f32 v135, v132, v133
	v_cvt_pk_bf16_f32 v132, v142, v143
	v_add_u32_e32 v243, s15, v237
	v_add_f32_e32 v154, v145, v134
	v_cvt_pk_bf16_f32 v134, v130, v131
	v_cvt_pk_bf16_f32 v130, v138, v139
	v_cvt_pk_bf16_f32 v131, v140, v141
	v_cvt_pk_bf16_f32 v133, v144, v145
	ds_read_b64_tr_b16 v[244:245], v243 offset:17408
	ds_read_b64_tr_b16 v[246:247], v243 offset:19968
	ds_read_b64_tr_b16 v[248:249], v243 offset:17472
	ds_read_b64_tr_b16 v[250:251], v243 offset:20032
	ds_read_b64_tr_b16 v[138:139], v243 offset:17536
	ds_read_b64_tr_b16 v[140:141], v243 offset:20096
	ds_read_b64_tr_b16 v[142:143], v243 offset:17600
	ds_read_b64_tr_b16 v[144:145], v243 offset:20160
	v_cvt_pk_bf16_f32 v136, v156, v157
	v_cvt_pk_bf16_f32 v137, v158, v137
	v_add_u32_e32 v243, s15, v240
	v_add_f32_e64 v208, v208, v154
	v_add_f32_e64 v209, v209, v155
	s_waitcnt lgkmcnt(6)
	v_mfma_f32_32x32x16_bf16 v[114:129], v[244:247], v[150:153], v[114:129]
	v_mfma_f32_32x32x16_bf16 v[98:113], v[244:247], v[134:137], v[98:113]
	ds_read_b64_tr_b16 v[244:245], v243 offset:17408
	ds_read_b64_tr_b16 v[246:247], v243 offset:19968
	s_waitcnt lgkmcnt(6)
	v_mfma_f32_32x32x16_bf16 v[82:97], v[248:251], v[150:153], v[82:97]
	v_mfma_f32_32x32x16_bf16 v[66:81], v[248:251], v[134:137], v[66:81]
	ds_read_b64_tr_b16 v[248:249], v243 offset:17472
	ds_read_b64_tr_b16 v[250:251], v243 offset:20032
	s_waitcnt lgkmcnt(6)
	v_mfma_f32_32x32x16_bf16 v[50:65], v[138:141], v[150:153], v[50:65]
	v_mfma_f32_32x32x16_bf16 v[18:33], v[138:141], v[134:137], v[18:33]
	ds_read_b64_tr_b16 v[138:139], v243 offset:17536
	ds_read_b64_tr_b16 v[140:141], v243 offset:20096
	s_waitcnt lgkmcnt(6)
	v_mfma_f32_32x32x16_bf16 v[34:49], v[142:145], v[150:153], v[34:49]
	v_mfma_f32_32x32x16_bf16 v[2:17], v[142:145], v[134:137], v[2:17]
	ds_read_b64_tr_b16 v[142:143], v243 offset:17600
	ds_read_b64_tr_b16 v[144:145], v243 offset:20160
	s_waitcnt lgkmcnt(6)
	v_mfma_f32_32x32x16_bf16 v[114:129], v[244:247], v[146:149], v[114:129]
	v_mfma_f32_32x32x16_bf16 v[98:113], v[244:247], v[130:133], v[98:113]
	s_waitcnt lgkmcnt(4)
	v_mfma_f32_32x32x16_bf16 v[82:97], v[248:251], v[146:149], v[82:97]
	v_mfma_f32_32x32x16_bf16 v[66:81], v[248:251], v[130:133], v[66:81]
	s_waitcnt lgkmcnt(2)
	v_mfma_f32_32x32x16_bf16 v[50:65], v[138:141], v[146:149], v[50:65]
	v_mfma_f32_32x32x16_bf16 v[18:33], v[138:141], v[130:133], v[18:33]
	s_waitcnt lgkmcnt(0)
	v_mfma_f32_32x32x16_bf16 v[34:49], v[142:145], v[146:149], v[34:49]
	v_mfma_f32_32x32x16_bf16 v[2:17], v[142:145], v[130:133], v[2:17]
	s_andn2_b64 vcc, exec, s[6:7]
	s_cbranch_vccnz .LBB0_495

; #define LAS __attribute__((address_space(3)))
; template <int MODE>
; __device__ __forceinline__ void attn_item(const AttnP& p, int b, int h, int qb, LAS unsigned char* lds) {
;     ...
;                     if (MODE == 0) {
;                         const LAS float* tab = (const LAS float*)(lds + TAB_OFF);
;                         if (qw - (kp0 + 31) >= 128) {
;                             const float cb = tab[255] - mfix;
; #pragma unroll
;                             for (int c = 0; c < NC; ++c) { ATT_QK(c, cb); ATT_TAIL(c); }
;                         } else {
;                             float binit[16];
; #pragma unroll
;                             for (int i = 0; i < 16; ++i) {
;                                 const int dist = qrow - (kp0 + crow(i, hh));
;                                 binit[i] = (dist < 0) ? -3e38f : (tab[dist > 255 ? 255 : dist] - mfix);
;                             }
; #pragma unroll
;                             for (int c = 0; c < NC; ++c) { ATT_QK(c, binit[i]); ATT_TAIL(c); }
;                         }
;                     } else {
;                         float binit[16];
;                         const LAS float* bl = (const LAS float*)(vtb + VT_BYTES) + 32 * kb2 + 4 * hh;
; #pragma unroll
;                         for (int g = 0; g < 4; ++g) {
;                             const f32x4 t = *(const LAS f32x4*)(bl + 8 * g);
; #pragma unroll
;                             for (int e = 0; e < 4; ++e) binit[4 * g + e] = (need_mask && (kp0 + crow(4 * g + e, hh) > qrow)) ? -3e38f : (t[e] - mfix);
;                         }
;                         ATT_QK(0, binit[i]); ATT_TAIL(0);
;                     }
;     ...
;                 }
; #pragma unroll
;                 for (int t2 = 0; t2 < 2; ++t2)
; #pragma unroll
;                     for (int d = 0; d < DV / 32; ++d) {
;                         const LAS unsigned char* vp = vtb + ((32 * kb2 + 16 * t2 + 4 * hh + ((lane & 15) >> 2)) * VPT + d * 32 + 16 * ((lane >> 4) & 1) + 4 * (lane & 3)) * 2;
;                         const s16x4 lo = vtr(vp), hi = vtr(vp + 8 * VPT * 2);
;                         const bf16x8 va = __builtin_shufflevector(lo, hi, 0, 1, 2, 3, 4, 5, 6, 7);
; #pragma unroll
;                         for (int c = 0; c < NC; ++c) O[c][d] = MFMA32(va, pb[c][t2], O[c][d]);
;                     }
.Lfar_tile:
	v_add_u32_e32 v243, v242, v235
	ds_read_b128 v[244:247], v243 offset:8704
	ds_read_b128 v[248:251], v243 offset:8736
	ds_read_b128 v[194:197], v243 offset:8768
	ds_read_b128 v[198:201], v243 offset:8800
	ds_read_b128 v[202:205], v243 offset:8832
	ds_read_b128 v[214:217], v207 offset:4096
	v_add_u32_e32 v218, s15, v238
	v_add_u32_e32 v219, s15, v239
	s_waitcnt lgkmcnt(5)
	v_mfma_f32_32x32x16_bf16 v[146:161], v[244:247], v[162:165], 0
	s_waitcnt lgkmcnt(4)
	v_mfma_f32_32x32x16_bf16 v[146:161], v[248:251], v[166:169], v[146:161]
	ds_read_b128 v[244:247], v243 offset:8864
	ds_read_b128 v[248:251], v207 offset:5120
	s_waitcnt lgkmcnt(5)
	v_mfma_f32_32x32x16_bf16 v[146:161], v[194:197], v[170:173], v[146:161]
	s_waitcnt lgkmcnt(4)
	v_mfma_f32_32x32x16_bf16 v[146:161], v[198:201], v[174:177], v[146:161]
	ds_read_b128 v[194:197], v243 offset:8896
	ds_read_b128 v[198:201], v207 offset:6144
	s_waitcnt lgkmcnt(4)
	v_mfma_f32_32x32x16_bf16 v[130:145], v[202:205], v[214:217], 0
	ds_read_b128 v[202:205], v243 offset:8928
	ds_read_b128 v[214:217], v207 offset:7168
	s_waitcnt lgkmcnt(4)
	v_mfma_f32_32x32x16_bf16 v[130:145], v[244:247], v[248:251], v[130:145]
	ds_read_b64_tr_b16 v[244:245], v218 offset:17408
	ds_read_b64_tr_b16 v[246:247], v218 offset:19968
	ds_read_b64_tr_b16 v[248:249], v218 offset:17472
	ds_read_b64_tr_b16 v[250:251], v218 offset:20032
	v_exp_f32_e32 v146, v146
	v_exp_f32_e32 v147, v147
	v_exp_f32_e32 v148, v148
	v_add_f32_e32 v220, v146, v147
	v_exp_f32_e32 v149, v149
	v_add_f32_e32 v220, v148, v220
	v_exp_f32_e32 v150, v150
	s_waitcnt lgkmcnt(6)
	v_mfma_f32_32x32x16_bf16 v[130:145], v[194:197], v[198:201], v[130:145]
	ds_read_b64_tr_b16 v[194:195], v218 offset:17536
	ds_read_b64_tr_b16 v[196:197], v218 offset:20096
	ds_read_b64_tr_b16 v[198:199], v218 offset:17600
	ds_read_b64_tr_b16 v[200:201], v218 offset:20160
	v_add_f32_e32 v220, v149, v220
	v_exp_f32_e32 v151, v151
	v_add_f32_e32 v220, v150, v220
	v_exp_f32_e32 v152, v152
	v_add_f32_e32 v220, v151, v220
	v_exp_f32_e32 v153, v153
	s_waitcnt lgkmcnt(8)
	v_mfma_f32_32x32x16_bf16 v[130:145], v[202:205], v[214:217], v[130:145]
	ds_read_b64_tr_b16 v[202:203], v219 offset:17408
	ds_read_b64_tr_b16 v[204:205], v219 offset:19968
	ds_read_b64_tr_b16 v[214:215], v219 offset:17472
	ds_read_b64_tr_b16 v[216:217], v219 offset:20032
	v_add_f32_e32 v220, v152, v220
	v_cvt_pk_bf16_f32 v146, v146, v147
	v_add_f32_e32 v220, v153, v220
	v_cvt_pk_bf16_f32 v147, v148, v149
	v_cvt_pk_bf16_f32 v148, v150, v151
	v_cvt_pk_bf16_f32 v149, v152, v153
	s_nop 1
	s_waitcnt lgkmcnt(10)
	v_mfma_f32_32x32x16_bf16 v[114:129], v[244:247], v[146:149], v[114:129]
	v_exp_f32_e32 v154, v154
	v_exp_f32_e32 v155, v155
	v_add_f32_e32 v220, v154, v220
	v_exp_f32_e32 v156, v156
	v_add_f32_e32 v220, v155, v220
	v_exp_f32_e32 v157, v157
	s_waitcnt lgkmcnt(8)
	v_mfma_f32_32x32x16_bf16 v[82:97], v[248:251], v[146:149], v[82:97]
	v_add_f32_e32 v220, v156, v220
	v_exp_f32_e32 v158, v158
	v_add_f32_e32 v220, v157, v220
	v_exp_f32_e32 v159, v159
	v_add_f32_e32 v220, v158, v220
	s_waitcnt lgkmcnt(6)
	v_mfma_f32_32x32x16_bf16 v[50:65], v[194:197], v[146:149], v[50:65]
	v_exp_f32_e32 v160, v160
	v_add_f32_e32 v220, v159, v220
	v_exp_f32_e32 v161, v161
	v_add_f32_e32 v220, v160, v220
	v_cvt_pk_bf16_f32 v150, v154, v155
	s_waitcnt lgkmcnt(4)
	v_mfma_f32_32x32x16_bf16 v[34:49], v[198:201], v[146:149], v[34:49]
	v_add_f32_e32 v220, v161, v220
	v_cvt_pk_bf16_f32 v151, v156, v157
	v_cvt_pk_bf16_f32 v152, v158, v159
	v_cvt_pk_bf16_f32 v153, v160, v161
	v_add_f32_e32 v209, v209, v220
	ds_read_b64_tr_b16 v[154:155], v219 offset:17536
	ds_read_b64_tr_b16 v[156:157], v219 offset:20096
	ds_read_b64_tr_b16 v[158:159], v219 offset:17600
	ds_read_b64_tr_b16 v[160:161], v219 offset:20160
	s_waitcnt lgkmcnt(6)
	v_mfma_f32_32x32x16_bf16 v[114:129], v[202:205], v[150:153], v[114:129]
	v_exp_f32_e32 v130, v130
	v_exp_f32_e32 v131, v131
	v_exp_f32_e32 v132, v132
	v_add_f32_e32 v213, v130, v131
	v_exp_f32_e32 v133, v133
	s_waitcnt lgkmcnt(4)
	v_mfma_f32_32x32x16_bf16 v[82:97], v[214:217], v[150:153], v[82:97]
	v_add_f32_e32 v213, v132, v213
	v_exp_f32_e32 v134, v134
	v_add_f32_e32 v213, v133, v213
	v_exp_f32_e32 v135, v135
	v_add_f32_e32 v213, v134, v213
	s_waitcnt lgkmcnt(2)
	v_mfma_f32_32x32x16_bf16 v[50:65], v[154:157], v[150:153], v[50:65]
	v_exp_f32_e32 v136, v136
	v_add_f32_e32 v213, v135, v213
	v_exp_f32_e32 v137, v137
	v_add_f32_e32 v213, v136, v213
	v_cvt_pk_bf16_f32 v130, v130, v131
	s_waitcnt lgkmcnt(0)
	v_mfma_f32_32x32x16_bf16 v[34:49], v[158:161], v[150:153], v[34:49]
	v_add_f32_e32 v213, v137, v213
	v_cvt_pk_bf16_f32 v131, v132, v133
	v_cvt_pk_bf16_f32 v132, v134, v135
	v_cvt_pk_bf16_f32 v133, v136, v137
	s_nop 1
	v_mfma_f32_32x32x16_bf16 v[98:113], v[244:247], v[130:133], v[98:113]
	v_exp_f32_e32 v138, v138
	v_exp_f32_e32 v139, v139
	v_add_f32_e32 v213, v138, v213
	v_exp_f32_e32 v140, v140
	v_add_f32_e32 v213, v139, v213
	v_exp_f32_e32 v141, v141
	ds_read_b128 v[244:247], v243 offset:0
	v_mfma_f32_32x32x16_bf16 v[66:81], v[248:251], v[130:133], v[66:81]
	v_add_f32_e32 v213, v140, v213
	v_exp_f32_e32 v142, v142
	v_add_f32_e32 v213, v141, v213
	v_exp_f32_e32 v143, v143
	v_add_f32_e32 v213, v142, v213
	ds_read_b128 v[248:251], v243 offset:32
	v_mfma_f32_32x32x16_bf16 v[18:33], v[194:197], v[130:133], v[18:33]
	v_exp_f32_e32 v144, v144
	v_add_f32_e32 v213, v143, v213
	v_exp_f32_e32 v145, v145
	v_add_f32_e32 v213, v144, v213
	v_cvt_pk_bf16_f32 v134, v138, v139
	ds_read_b128 v[194:197], v243 offset:64
	v_mfma_f32_32x32x16_bf16 v[2:17], v[198:201], v[130:133], v[2:17]
	v_add_f32_e32 v213, v145, v213
	v_cvt_pk_bf16_f32 v135, v140, v141
	v_cvt_pk_bf16_f32 v136, v142, v143
	v_cvt_pk_bf16_f32 v137, v144, v145
	v_add_f32_e32 v208, v208, v213
	ds_read_b128 v[198:201], v243 offset:96
	s_nop 1
	v_mfma_f32_32x32x16_bf16 v[98:113], v[202:205], v[134:137], v[98:113]
	ds_read_b128 v[202:205], v243 offset:128
	v_mfma_f32_32x32x16_bf16 v[66:81], v[214:217], v[134:137], v[66:81]
	ds_read_b128 v[214:217], v207 offset:4096
	v_mfma_f32_32x32x16_bf16 v[18:33], v[154:157], v[134:137], v[18:33]
	v_mfma_f32_32x32x16_bf16 v[2:17], v[158:161], v[134:137], v[2:17]
	v_add_u32_e32 v218, s15, v237
	v_add_u32_e32 v219, s15, v240
	s_waitcnt lgkmcnt(5)
; #define LAS __attribute__((address_space(3)))
; template <int MODE>
; __device__ __forceinline__ void attn_item(const AttnP& p, int b, int h, int qb, LAS unsigned char* lds) {
;     ...
;                     if (MODE == 0) {
;                         const LAS float* tab = (const LAS float*)(lds + TAB_OFF);
;                         if (qw - (kp0 + 31) >= 128) {
;                             const float cb = tab[255] - mfix;
; #pragma unroll
;                             for (int c = 0; c < NC; ++c) { ATT_QK(c, cb); ATT_TAIL(c); }
;                         } else {
;                             float binit[16];
; #pragma unroll
;                             for (int i = 0; i < 16; ++i) {
;                                 const int dist = qrow - (kp0 + crow(i, hh));
;                                 binit[i] = (dist < 0) ? -3e38f : (tab[dist > 255 ? 255 : dist] - mfix);
;                             }
; #pragma unroll
;                             for (int c = 0; c < NC; ++c) { ATT_QK(c, binit[i]); ATT_TAIL(c); }
;                         }
;                     } else {
;                         float binit[16];
;                         const LAS float* bl = (const LAS float*)(vtb + VT_BYTES) + 32 * kb2 + 4 * hh;
; #pragma unroll
;                         for (int g = 0; g < 4; ++g) {
;                             const f32x4 t = *(const LAS f32x4*)(bl + 8 * g);
; #pragma unroll
;                             for (int e = 0; e < 4; ++e) binit[4 * g + e] = (need_mask && (kp0 + crow(4 * g + e, hh) > qrow)) ? -3e38f : (t[e] - mfix);
;                         }
;                         ATT_QK(0, binit[i]); ATT_TAIL(0);
;                     }
;     ...
;                 }
; #pragma unroll
;                 for (int t2 = 0; t2 < 2; ++t2)
; #pragma unroll
;                     for (int d = 0; d < DV / 32; ++d) {
;                         const LAS unsigned char* vp = vtb + ((32 * kb2 + 16 * t2 + 4 * hh + ((lane & 15) >> 2)) * VPT + d * 32 + 16 * ((lane >> 4) & 1) + 4 * (lane & 3)) * 2;
;                         const s16x4 lo = vtr(vp), hi = vtr(vp + 8 * VPT * 2);
;                         const bf16x8 va = __builtin_shufflevector(lo, hi, 0, 1, 2, 3, 4, 5, 6, 7);
; #pragma unroll
;                         for (int c = 0; c < NC; ++c) O[c][d] = MFMA32(va, pb[c][t2], O[c][d]);
;                     }
	v_mfma_f32_32x32x16_bf16 v[146:161], v[244:247], v[162:165], 0
	s_waitcnt lgkmcnt(4)
	v_mfma_f32_32x32x16_bf16 v[146:161], v[248:251], v[166:169], v[146:161]
	ds_read_b128 v[244:247], v243 offset:160
	ds_read_b128 v[248:251], v207 offset:5120
	s_waitcnt lgkmcnt(5)
	v_mfma_f32_32x32x16_bf16 v[146:161], v[194:197], v[170:173], v[146:161]
	s_waitcnt lgkmcnt(4)
	v_mfma_f32_32x32x16_bf16 v[146:161], v[198:201], v[174:177], v[146:161]
	ds_read_b128 v[194:197], v243 offset:192
	ds_read_b128 v[198:201], v207 offset:6144
	s_waitcnt lgkmcnt(4)
	v_mfma_f32_32x32x16_bf16 v[130:145], v[202:205], v[214:217], 0
	ds_read_b128 v[202:205], v243 offset:224
	ds_read_b128 v[214:217], v207 offset:7168
	s_waitcnt lgkmcnt(4)
	v_mfma_f32_32x32x16_bf16 v[130:145], v[244:247], v[248:251], v[130:145]
	ds_read_b64_tr_b16 v[244:245], v218 offset:17408
	ds_read_b64_tr_b16 v[246:247], v218 offset:19968
	ds_read_b64_tr_b16 v[248:249], v218 offset:17472
	ds_read_b64_tr_b16 v[250:251], v218 offset:20032
	v_exp_f32_e32 v146, v146
	v_exp_f32_e32 v147, v147
	v_exp_f32_e32 v148, v148
	v_add_f32_e32 v220, v146, v147
	v_exp_f32_e32 v149, v149
	v_add_f32_e32 v220, v148, v220
	v_exp_f32_e32 v150, v150
	s_waitcnt lgkmcnt(6)
	v_mfma_f32_32x32x16_bf16 v[130:145], v[194:197], v[198:201], v[130:145]
	ds_read_b64_tr_b16 v[194:195], v218 offset:17536
	ds_read_b64_tr_b16 v[196:197], v218 offset:20096
	ds_read_b64_tr_b16 v[198:199], v218 offset:17600
	ds_read_b64_tr_b16 v[200:201], v218 offset:20160
	v_add_f32_e32 v220, v149, v220
	v_exp_f32_e32 v151, v151
	v_add_f32_e32 v220, v150, v220
	v_exp_f32_e32 v152, v152
	v_add_f32_e32 v220, v151, v220
	v_exp_f32_e32 v153, v153
	s_waitcnt lgkmcnt(8)
	v_mfma_f32_32x32x16_bf16 v[130:145], v[202:205], v[214:217], v[130:145]
	ds_read_b64_tr_b16 v[202:203], v219 offset:17408
	ds_read_b64_tr_b16 v[204:205], v219 offset:19968
	ds_read_b64_tr_b16 v[214:215], v219 offset:17472
	ds_read_b64_tr_b16 v[216:217], v219 offset:20032
	v_add_f32_e32 v220, v152, v220
	v_cvt_pk_bf16_f32 v146, v146, v147
	v_add_f32_e32 v220, v153, v220
	v_cvt_pk_bf16_f32 v147, v148, v149
	v_cvt_pk_bf16_f32 v148, v150, v151
	v_cvt_pk_bf16_f32 v149, v152, v153
	s_nop 1
	s_waitcnt lgkmcnt(10)
	v_mfma_f32_32x32x16_bf16 v[114:129], v[244:247], v[146:149], v[114:129]
	v_exp_f32_e32 v154, v154
	v_exp_f32_e32 v155, v155
	v_add_f32_e32 v220, v154, v220
	v_exp_f32_e32 v156, v156
	v_add_f32_e32 v220, v155, v220
	v_exp_f32_e32 v157, v157
	s_waitcnt lgkmcnt(8)
	v_mfma_f32_32x32x16_bf16 v[82:97], v[248:251], v[146:149], v[82:97]
	v_add_f32_e32 v220, v156, v220
	v_exp_f32_e32 v158, v158
	v_add_f32_e32 v220, v157, v220
	v_exp_f32_e32 v159, v159
	v_add_f32_e32 v220, v158, v220
	s_waitcnt lgkmcnt(6)
	v_mfma_f32_32x32x16_bf16 v[50:65], v[194:197], v[146:149], v[50:65]
	v_exp_f32_e32 v160, v160
	v_add_f32_e32 v220, v159, v220
	v_exp_f32_e32 v161, v161
	v_add_f32_e32 v220, v160, v220
	v_cvt_pk_bf16_f32 v150, v154, v155
	s_waitcnt lgkmcnt(4)
	v_mfma_f32_32x32x16_bf16 v[34:49], v[198:201], v[146:149], v[34:49]
	v_add_f32_e32 v220, v161, v220
	v_cvt_pk_bf16_f32 v151, v156, v157
	v_cvt_pk_bf16_f32 v152, v158, v159
	v_cvt_pk_bf16_f32 v153, v160, v161
	v_add_f32_e32 v209, v209, v220
	ds_read_b64_tr_b16 v[154:155], v219 offset:17536
	ds_read_b64_tr_b16 v[156:157], v219 offset:20096
	ds_read_b64_tr_b16 v[158:159], v219 offset:17600
	ds_read_b64_tr_b16 v[160:161], v219 offset:20160
	s_waitcnt lgkmcnt(6)
	v_mfma_f32_32x32x16_bf16 v[114:129], v[202:205], v[150:153], v[114:129]
	v_exp_f32_e32 v130, v130
	v_exp_f32_e32 v131, v131
	v_exp_f32_e32 v132, v132
	v_add_f32_e32 v213, v130, v131
	v_exp_f32_e32 v133, v133
	s_waitcnt lgkmcnt(4)
	v_mfma_f32_32x32x16_bf16 v[82:97], v[214:217], v[150:153], v[82:97]
	v_add_f32_e32 v213, v132, v213
	v_exp_f32_e32 v134, v134
	v_add_f32_e32 v213, v133, v213
	v_exp_f32_e32 v135, v135
	v_add_f32_e32 v213, v134, v213
	s_waitcnt lgkmcnt(2)
	v_mfma_f32_32x32x16_bf16 v[50:65], v[154:157], v[150:153], v[50:65]
	v_exp_f32_e32 v136, v136
	v_add_f32_e32 v213, v135, v213
	v_exp_f32_e32 v137, v137
	v_add_f32_e32 v213, v136, v213
	v_cvt_pk_bf16_f32 v130, v130, v131
	s_waitcnt lgkmcnt(0)
	v_mfma_f32_32x32x16_bf16 v[34:49], v[158:161], v[150:153], v[34:49]
	v_add_f32_e32 v213, v137, v213
	v_cvt_pk_bf16_f32 v131, v132, v133
	v_cvt_pk_bf16_f32 v132, v134, v135
	v_cvt_pk_bf16_f32 v133, v136, v137
	s_nop 1
	v_mfma_f32_32x32x16_bf16 v[98:113], v[244:247], v[130:133], v[98:113]
	v_exp_f32_e32 v138, v138
	v_exp_f32_e32 v139, v139
	v_add_f32_e32 v213, v138, v213
	v_exp_f32_e32 v140, v140
	v_add_f32_e32 v213, v139, v213
	v_exp_f32_e32 v141, v141
	v_mfma_f32_32x32x16_bf16 v[66:81], v[248:251], v[130:133], v[66:81]
	v_add_f32_e32 v213, v140, v213
	v_exp_f32_e32 v142, v142
	v_add_f32_e32 v213, v141, v213
	v_exp_f32_e32 v143, v143
	v_add_f32_e32 v213, v142, v213
	v_mfma_f32_32x32x16_bf16 v[18:33], v[194:197], v[130:133], v[18:33]
	v_exp_f32_e32 v144, v144
	v_add_f32_e32 v213, v143, v213
	v_exp_f32_e32 v145, v145
	v_add_f32_e32 v213, v144, v213
	v_cvt_pk_bf16_f32 v134, v138, v139
	v_mfma_f32_32x32x16_bf16 v[2:17], v[198:201], v[130:133], v[2:17]
	v_add_f32_e32 v213, v145, v213
	v_cvt_pk_bf16_f32 v135, v140, v141
	v_cvt_pk_bf16_f32 v136, v142, v143
	v_cvt_pk_bf16_f32 v137, v144, v145
	v_add_f32_e32 v208, v208, v213
	s_nop 1
	v_mfma_f32_32x32x16_bf16 v[98:113], v[202:205], v[134:137], v[98:113]
	v_mfma_f32_32x32x16_bf16 v[66:81], v[214:217], v[134:137], v[66:81]
	v_mfma_f32_32x32x16_bf16 v[18:33], v[154:157], v[134:137], v[18:33]
	v_mfma_f32_32x32x16_bf16 v[2:17], v[158:161], v[134:137], v[2:17]
	s_andn2_b64 vcc, exec, s[6:7]
	s_cbranch_vccnz .LBB0_495
	s_branch .LBB0_575

; __device__ __forceinline__ unsigned cvt_pk_bf16(float lo, float hi) { unsigned r; asm volatile("v_cvt_pk_bf16_f32 %0, %1, %2" : "=v"(r) : "v"(lo), "v"(hi)); return r; }
;     __device__ __forceinline__ void operator()(const f32x4 (&acc)[2][2][4][2], const Unit& u, int wr, int wc, int fr, int fq) const {
;     ...
;                 const int row = u.pm * BM + ai * HALF + wr * 64 + m * 16 + fr;
;                 const size_t off = (size_t)row * 1024 + col0;
;                 float ss = 0.f;
; #pragma unroll
;                 for (int bj = 0; bj < 2; ++bj)
; #pragma unroll
;                     for (int n = 0; n < 2; ++n) {
;                         const f32x4 o = *(const f32x4*)(res + off + bj * HALF + n * 16) + acc[ai][bj][m][n];
;                         *(f32x4*)(out + off + bj * HALF + n * 16) = o;
;                         if (write_hb) {
;                             u32x2 w; w.x = cvt_pk_bf16(o[0], o[1]); w.y = cvt_pk_bf16(o[2], o[3]);
;                             *(u32x2*)(hb + off + bj * HALF + n * 16) = w;
;                             ss += (o[0] * o[0] + o[1] * o[1]) + (o[2] * o[2] + o[3] * o[3]);
;                         }
;                     }
;                 if (write_hb) {
;                     ss += __shfl_xor(ss, 16); ss += __shfl_xor(ss, 32);
;                     if (fq == 0) hss[(size_t)row * 16 + u.pn * 4 + wc] = ss;
.LBB0_604:
	v_lshl_add_u32 v138, s33, 8, v144
	v_lshl_or_b32 v136, s20, 8, v146
	v_ashrrev_i32_e32 v139, 31, v138
	v_ashrrev_i32_e32 v137, 31, v136
	v_lshlrev_b64 v[140:141], 10, v[138:139]
	v_lshl_add_u64 v[142:143], v[140:141], 0, v[136:137]
	v_lshl_add_u64 v[140:141], v[142:143], 2, s[12:13]
	global_load_dwordx4 v[148:151], v[140:141], off
	v_readlane_b32 s2, v254, 38
	v_readlane_b32 s3, v254, 39
	s_lshl_b32 s34, s20, 2
	s_ashr_i32 s35, s34, 31
	v_cndmask_b32_e64 v152, 0, 1, s[2:3]
	v_cmp_ne_u32_e64 s[6:7], 1, v152
	s_andn2_b64 vcc, exec, s[2:3]
	s_mov_b64 s[2:3], -1
	s_mov_b32 s55, 0xf800000
	s_waitcnt vmcnt(0) lgkmcnt(0)
	v_pk_add_f32 v[128:129], v[128:129], v[150:151]
	v_pk_add_f32 v[126:127], v[126:127], v[148:149]
	global_store_dwordx4 v[140:141], v[126:129], off
	s_cbranch_vccnz .LBB0_608
	v_cvt_pk_bf16_f32 v148, v126, v127
	s_nop 0
	v_mul_f32_e32 v127, v127, v127
	v_lshl_add_u64 v[142:143], v[142:143], 1, s[16:17]
	v_fmac_f32_e32 v127, v126, v126
	v_mul_f32_e32 v126, v129, v129
	v_cvt_pk_bf16_f32 v149, v128, v129
	global_store_dwordx2 v[142:143], v[148:149], off
	v_fmac_f32_e32 v126, v128, v128
	v_add_f32_e32 v150, v127, v126
	global_load_dwordx4 v[126:129], v[140:141], off offset:64
	s_waitcnt vmcnt(0) lgkmcnt(0)
	v_pk_add_f32 v[128:129], v[124:125], v[128:129]
	v_pk_add_f32 v[126:127], v[122:123], v[126:127]
	global_store_dwordx4 v[140:141], v[126:129], off offset:64
	v_cvt_pk_bf16_f32 v148, v126, v127
	v_cvt_pk_bf16_f32 v149, v128, v129
	global_store_dwordx2 v[142:143], v[148:149], off offset:32
	s_nop 0
	v_mul_f32_e32 v127, v127, v127
	v_fmac_f32_e32 v127, v126, v126
	v_mul_f32_e32 v126, v129, v129
	v_fmac_f32_e32 v126, v128, v128
	v_add_f32_e32 v126, v127, v126
	v_add_f32_e32 v150, v150, v126
	global_load_dwordx4 v[126:129], v[140:141], off offset:512
	s_waitcnt vmcnt(0) lgkmcnt(0)
	v_pk_add_f32 v[128:129], v[120:121], v[128:129]
	v_pk_add_f32 v[126:127], v[118:119], v[126:127]
	global_store_dwordx4 v[140:141], v[126:129], off offset:512
	v_cvt_pk_bf16_f32 v148, v126, v127
	v_cvt_pk_bf16_f32 v149, v128, v129
	global_store_dwordx2 v[142:143], v[148:149], off offset:256
	s_nop 0
	v_mul_f32_e32 v127, v127, v127
	v_fmac_f32_e32 v127, v126, v126
	v_mul_f32_e32 v126, v129, v129
	v_fmac_f32_e32 v126, v128, v128
	v_add_f32_e32 v126, v127, v126
	v_add_f32_e32 v150, v150, v126
	global_load_dwordx4 v[126:129], v[140:141], off offset:576
	s_waitcnt vmcnt(0) lgkmcnt(0)
	v_pk_add_f32 v[128:129], v[116:117], v[128:129]
	v_pk_add_f32 v[126:127], v[114:115], v[126:127]
	global_store_dwordx4 v[140:141], v[126:129], off offset:576
	v_cvt_pk_bf16_f32 v148, v126, v127
	v_cvt_pk_bf16_f32 v149, v128, v129
	global_store_dwordx2 v[142:143], v[148:149], off offset:288
	s_nop 0
	v_mul_f32_e32 v127, v127, v127
	v_fmac_f32_e32 v127, v126, v126
	v_mul_f32_e32 v126, v129, v129
	v_fmac_f32_e32 v126, v128, v128
	v_and_b32_e32 v128, 64, v216
	v_add_f32_e32 v126, v127, v126
	v_xor_b32_e32 v127, 16, v216
	v_add_u32_e32 v128, 64, v128
	v_cmp_lt_i32_e32 vcc, v127, v128
	v_add_f32_e32 v126, v150, v126
	s_nop 0
	v_cndmask_b32_e32 v127, v216, v127, vcc
	v_lshlrev_b32_e32 v127, 2, v127
	ds_bpermute_b32 v127, v127, v126
	s_waitcnt lgkmcnt(0)
	v_add_f32_e32 v126, v126, v127
	v_xor_b32_e32 v127, 32, v216
	v_cmp_lt_i32_e32 vcc, v127, v128
	s_nop 1
	v_cndmask_b32_e32 v127, v216, v127, vcc
	v_lshlrev_b32_e32 v127, 2, v127
	ds_bpermute_b32 v127, v127, v126
	s_and_saveexec_b64 s[2:3], s[0:1]
	s_cbranch_execz .LBB0_607
	v_lshlrev_b64 v[128:129], 6, v[138:139]
	v_lshl_add_u64 v[128:129], s[18:19], 0, v[128:129]
	v_lshl_add_u64 v[128:129], s[34:35], 2, v[128:129]
	s_lshl_b32 s92, s46, 2
	v_lshl_add_u64 v[128:129], v[128:129], 0, s[92:93]
	s_waitcnt lgkmcnt(0)
	v_add_f32_e32 v126, v126, v127
	global_store_dword v[128:129], v126, off

; __device__ __forceinline__ unsigned cvt_pk_bf16(float lo, float hi) { unsigned r; asm volatile("v_cvt_pk_bf16_f32 %0, %1, %2" : "=v"(r) : "v"(lo), "v"(hi)); return r; }
;     __device__ __forceinline__ void operator()(const f32x4 (&acc)[2][2][4][2], const Unit& u, int wr, int wc, int fr, int fq) const {
;     ...
;                 const int row = u.pm * BM + ai * HALF + wr * 64 + m * 16 + fr;
;                 const size_t off = (size_t)row * 1024 + col0;
;                 float ss = 0.f;
; #pragma unroll
;                 for (int bj = 0; bj < 2; ++bj)
; #pragma unroll
;                     for (int n = 0; n < 2; ++n) {
;                         const f32x4 o = *(const f32x4*)(res + off + bj * HALF + n * 16) + acc[ai][bj][m][n];
;                         *(f32x4*)(out + off + bj * HALF + n * 16) = o;
;                         if (write_hb) {
;                             u32x2 w; w.x = cvt_pk_bf16(o[0], o[1]); w.y = cvt_pk_bf16(o[2], o[3]);
;                             *(u32x2*)(hb + off + bj * HALF + n * 16) = w;
;                             ss += (o[0] * o[0] + o[1] * o[1]) + (o[2] * o[2] + o[3] * o[3]);
;                         }
;                     }
;                 if (write_hb) {
;                     ss += __shfl_xor(ss, 16); ss += __shfl_xor(ss, 32);
;                     if (fq == 0) hss[(size_t)row * 16 + u.pn * 4 + wc] = ss;
.LBB0_608:
	s_andn2_b64 vcc, exec, s[2:3]
	s_cbranch_vccnz .LBB0_610
	s_waitcnt lgkmcnt(0)
	global_load_dwordx4 v[126:129], v[140:141], off offset:64
	s_waitcnt vmcnt(0) lgkmcnt(0)
	v_pk_add_f32 v[124:125], v[124:125], v[128:129]
	v_pk_add_f32 v[122:123], v[122:123], v[126:127]
	global_store_dwordx4 v[140:141], v[122:125], off offset:64
	global_load_dwordx4 v[122:125], v[140:141], off offset:512
	s_waitcnt vmcnt(0) lgkmcnt(0)
	v_pk_add_f32 v[120:121], v[120:121], v[124:125]
	v_pk_add_f32 v[118:119], v[118:119], v[122:123]
	global_store_dwordx4 v[140:141], v[118:121], off offset:512
	global_load_dwordx4 v[118:121], v[140:141], off offset:576
	s_waitcnt vmcnt(0) lgkmcnt(0)
	v_pk_add_f32 v[116:117], v[116:117], v[120:121]
	v_pk_add_f32 v[114:115], v[114:115], v[118:119]
	global_store_dwordx4 v[140:141], v[114:117], off offset:576
.LBB0_610:
	s_nop 1
	v_or_b32_e32 v116, 16, v138
	v_ashrrev_i32_e32 v117, 31, v116
	v_lshlrev_b64 v[114:115], 10, v[116:117]
	v_lshl_add_u64 v[118:119], v[114:115], 0, v[136:137]
	v_lshl_add_u64 v[114:115], v[118:119], 2, s[12:13]
	global_load_dwordx4 v[120:123], v[114:115], off
	s_and_b64 vcc, exec, s[6:7]
	s_mov_b64 s[2:3], -1
	s_waitcnt vmcnt(0) lgkmcnt(0)
	v_pk_add_f32 v[112:113], v[112:113], v[122:123]
	v_pk_add_f32 v[110:111], v[110:111], v[120:121]
	global_store_dwordx4 v[114:115], v[110:113], off
	s_cbranch_vccnz .LBB0_614
	v_cvt_pk_bf16_f32 v120, v110, v111
	s_nop 0
	v_mul_f32_e32 v111, v111, v111
	v_lshl_add_u64 v[118:119], v[118:119], 1, s[16:17]
	v_fmac_f32_e32 v111, v110, v110
	v_mul_f32_e32 v110, v113, v113
	v_cvt_pk_bf16_f32 v121, v112, v113
	global_store_dwordx2 v[118:119], v[120:121], off
	v_fmac_f32_e32 v110, v112, v112
	v_add_f32_e32 v122, v111, v110
	global_load_dwordx4 v[110:113], v[114:115], off offset:64
	s_waitcnt vmcnt(0) lgkmcnt(0)
	v_pk_add_f32 v[112:113], v[108:109], v[112:113]
	v_pk_add_f32 v[110:111], v[106:107], v[110:111]
	global_store_dwordx4 v[114:115], v[110:113], off offset:64
	v_cvt_pk_bf16_f32 v120, v110, v111
	v_cvt_pk_bf16_f32 v121, v112, v113
	global_store_dwordx2 v[118:119], v[120:121], off offset:32
	s_nop 0
	v_mul_f32_e32 v111, v111, v111
	v_fmac_f32_e32 v111, v110, v110
	v_mul_f32_e32 v110, v113, v113
	v_fmac_f32_e32 v110, v112, v112
	v_add_f32_e32 v110, v111, v110
	v_add_f32_e32 v122, v122, v110
	global_load_dwordx4 v[110:113], v[114:115], off offset:512
	s_waitcnt vmcnt(0) lgkmcnt(0)
	v_pk_add_f32 v[112:113], v[104:105], v[112:113]
	v_pk_add_f32 v[110:111], v[102:103], v[110:111]
	global_store_dwordx4 v[114:115], v[110:113], off offset:512
	v_cvt_pk_bf16_f32 v120, v110, v111
	v_cvt_pk_bf16_f32 v121, v112, v113
	global_store_dwordx2 v[118:119], v[120:121], off offset:256
	s_nop 0
	v_mul_f32_e32 v111, v111, v111
	v_fmac_f32_e32 v111, v110, v110
	v_mul_f32_e32 v110, v113, v113
	v_fmac_f32_e32 v110, v112, v112
	v_add_f32_e32 v110, v111, v110
	v_add_f32_e32 v122, v122, v110
	global_load_dwordx4 v[110:113], v[114:115], off offset:576
	s_waitcnt vmcnt(0) lgkmcnt(0)
	v_pk_add_f32 v[112:113], v[100:101], v[112:113]
	v_pk_add_f32 v[110:111], v[98:99], v[110:111]
	global_store_dwordx4 v[114:115], v[110:113], off offset:576
	v_cvt_pk_bf16_f32 v120, v110, v111
	v_cvt_pk_bf16_f32 v121, v112, v113
	global_store_dwordx2 v[118:119], v[120:121], off offset:288
	s_nop 0
	v_mul_f32_e32 v111, v111, v111
	v_fmac_f32_e32 v111, v110, v110
	v_mul_f32_e32 v110, v113, v113
	v_fmac_f32_e32 v110, v112, v112
	v_and_b32_e32 v112, 64, v216
	v_add_f32_e32 v110, v111, v110
	v_xor_b32_e32 v111, 16, v216
	v_add_u32_e32 v112, 64, v112
	v_cmp_lt_i32_e32 vcc, v111, v112
	v_add_f32_e32 v110, v122, v110
	s_nop 0
	v_cndmask_b32_e32 v111, v216, v111, vcc
	v_lshlrev_b32_e32 v111, 2, v111
	ds_bpermute_b32 v111, v111, v110
	s_waitcnt lgkmcnt(0)
	v_add_f32_e32 v110, v110, v111
	v_xor_b32_e32 v111, 32, v216
	v_cmp_lt_i32_e32 vcc, v111, v112
	s_nop 1
	v_cndmask_b32_e32 v111, v216, v111, vcc
	v_lshlrev_b32_e32 v111, 2, v111
	ds_bpermute_b32 v111, v111, v110
	s_and_saveexec_b64 s[2:3], s[0:1]
	s_cbranch_execz .LBB0_613
	v_lshlrev_b64 v[112:113], 6, v[116:117]
	v_lshl_add_u64 v[112:113], s[18:19], 0, v[112:113]
	v_lshl_add_u64 v[112:113], s[34:35], 2, v[112:113]
	s_lshl_b32 s92, s46, 2
	v_lshl_add_u64 v[112:113], v[112:113], 0, s[92:93]
	s_waitcnt lgkmcnt(0)
	v_add_f32_e32 v110, v110, v111
	global_store_dword v[112:113], v110, off

; __device__ __forceinline__ unsigned cvt_pk_bf16(float lo, float hi) { unsigned r; asm volatile("v_cvt_pk_bf16_f32 %0, %1, %2" : "=v"(r) : "v"(lo), "v"(hi)); return r; }
;     __device__ __forceinline__ void operator()(const f32x4 (&acc)[2][2][4][2], const Unit& u, int wr, int wc, int fr, int fq) const {
;     ...
;                 const int row = u.pm * BM + ai * HALF + wr * 64 + m * 16 + fr;
;                 const size_t off = (size_t)row * 1024 + col0;
;                 float ss = 0.f;
; #pragma unroll
;                 for (int bj = 0; bj < 2; ++bj)
; #pragma unroll
;                     for (int n = 0; n < 2; ++n) {
;                         const f32x4 o = *(const f32x4*)(res + off + bj * HALF + n * 16) + acc[ai][bj][m][n];
;                         *(f32x4*)(out + off + bj * HALF + n * 16) = o;
;                         if (write_hb) {
;                             u32x2 w; w.x = cvt_pk_bf16(o[0], o[1]); w.y = cvt_pk_bf16(o[2], o[3]);
;                             *(u32x2*)(hb + off + bj * HALF + n * 16) = w;
;                             ss += (o[0] * o[0] + o[1] * o[1]) + (o[2] * o[2] + o[3] * o[3]);
;                         }
;                     }
;                 if (write_hb) {
;                     ss += __shfl_xor(ss, 16); ss += __shfl_xor(ss, 32);
;                     if (fq == 0) hss[(size_t)row * 16 + u.pn * 4 + wc] = ss;
.LBB0_614:
	s_andn2_b64 vcc, exec, s[2:3]
	s_cbranch_vccnz .LBB0_616
	s_waitcnt lgkmcnt(0)
	global_load_dwordx4 v[110:113], v[114:115], off offset:64
	s_waitcnt vmcnt(0) lgkmcnt(0)
	v_pk_add_f32 v[108:109], v[108:109], v[112:113]
	v_pk_add_f32 v[106:107], v[106:107], v[110:111]
	global_store_dwordx4 v[114:115], v[106:109], off offset:64
	global_load_dwordx4 v[106:109], v[114:115], off offset:512
	s_waitcnt vmcnt(0) lgkmcnt(0)
	v_pk_add_f32 v[104:105], v[104:105], v[108:109]
	v_pk_add_f32 v[102:103], v[102:103], v[106:107]
	global_store_dwordx4 v[114:115], v[102:105], off offset:512
	global_load_dwordx4 v[102:105], v[114:115], off offset:576
	s_waitcnt vmcnt(0) lgkmcnt(0)
	v_pk_add_f32 v[100:101], v[100:101], v[104:105]
	v_pk_add_f32 v[98:99], v[98:99], v[102:103]
	global_store_dwordx4 v[114:115], v[98:101], off offset:576
.LBB0_616:
	s_nop 1
	v_or_b32_e32 v100, 32, v138
	v_ashrrev_i32_e32 v101, 31, v100
	v_lshlrev_b64 v[98:99], 10, v[100:101]
	v_lshl_add_u64 v[102:103], v[98:99], 0, v[136:137]
	v_lshl_add_u64 v[98:99], v[102:103], 2, s[12:13]
	global_load_dwordx4 v[104:107], v[98:99], off
	s_and_b64 vcc, exec, s[6:7]
	s_mov_b64 s[2:3], -1
	s_waitcnt vmcnt(0) lgkmcnt(0)
	v_pk_add_f32 v[96:97], v[96:97], v[106:107]
	v_pk_add_f32 v[94:95], v[94:95], v[104:105]
	global_store_dwordx4 v[98:99], v[94:97], off
	s_cbranch_vccnz .LBB0_620
	v_cvt_pk_bf16_f32 v104, v94, v95
	s_nop 0
	v_mul_f32_e32 v95, v95, v95
	v_lshl_add_u64 v[102:103], v[102:103], 1, s[16:17]
	v_fmac_f32_e32 v95, v94, v94
	v_mul_f32_e32 v94, v97, v97
	v_cvt_pk_bf16_f32 v105, v96, v97
	global_store_dwordx2 v[102:103], v[104:105], off
	v_fmac_f32_e32 v94, v96, v96
	v_add_f32_e32 v106, v95, v94
	global_load_dwordx4 v[94:97], v[98:99], off offset:64
	s_waitcnt vmcnt(0) lgkmcnt(0)
	v_pk_add_f32 v[96:97], v[92:93], v[96:97]
	v_pk_add_f32 v[94:95], v[90:91], v[94:95]
	global_store_dwordx4 v[98:99], v[94:97], off offset:64
	v_cvt_pk_bf16_f32 v104, v94, v95
	v_cvt_pk_bf16_f32 v105, v96, v97
	global_store_dwordx2 v[102:103], v[104:105], off offset:32
	s_nop 0
	v_mul_f32_e32 v95, v95, v95
	v_fmac_f32_e32 v95, v94, v94
	v_mul_f32_e32 v94, v97, v97
	v_fmac_f32_e32 v94, v96, v96
	v_add_f32_e32 v94, v95, v94
	v_add_f32_e32 v106, v106, v94
	global_load_dwordx4 v[94:97], v[98:99], off offset:512
	s_waitcnt vmcnt(0) lgkmcnt(0)
	v_pk_add_f32 v[96:97], v[88:89], v[96:97]
	v_pk_add_f32 v[94:95], v[86:87], v[94:95]
	global_store_dwordx4 v[98:99], v[94:97], off offset:512
	v_cvt_pk_bf16_f32 v104, v94, v95
	v_cvt_pk_bf16_f32 v105, v96, v97
	global_store_dwordx2 v[102:103], v[104:105], off offset:256
	s_nop 0
	v_mul_f32_e32 v95, v95, v95
	v_fmac_f32_e32 v95, v94, v94
	v_mul_f32_e32 v94, v97, v97
	v_fmac_f32_e32 v94, v96, v96
	v_add_f32_e32 v94, v95, v94
	v_add_f32_e32 v106, v106, v94
	global_load_dwordx4 v[94:97], v[98:99], off offset:576
	s_waitcnt vmcnt(0) lgkmcnt(0)
	v_pk_add_f32 v[96:97], v[84:85], v[96:97]
	v_pk_add_f32 v[94:95], v[82:83], v[94:95]
	global_store_dwordx4 v[98:99], v[94:97], off offset:576
	v_cvt_pk_bf16_f32 v104, v94, v95
	v_cvt_pk_bf16_f32 v105, v96, v97
	global_store_dwordx2 v[102:103], v[104:105], off offset:288
	s_nop 0
	v_mul_f32_e32 v95, v95, v95
	v_fmac_f32_e32 v95, v94, v94
	v_mul_f32_e32 v94, v97, v97
	v_fmac_f32_e32 v94, v96, v96
	v_and_b32_e32 v96, 64, v216
	v_add_f32_e32 v94, v95, v94
	v_xor_b32_e32 v95, 16, v216
	v_add_u32_e32 v96, 64, v96
	v_cmp_lt_i32_e32 vcc, v95, v96
	v_add_f32_e32 v94, v106, v94
	s_nop 0
	v_cndmask_b32_e32 v95, v216, v95, vcc
	v_lshlrev_b32_e32 v95, 2, v95
	ds_bpermute_b32 v95, v95, v94
	s_waitcnt lgkmcnt(0)
	v_add_f32_e32 v94, v94, v95
	v_xor_b32_e32 v95, 32, v216
	v_cmp_lt_i32_e32 vcc, v95, v96
	s_nop 1
	v_cndmask_b32_e32 v95, v216, v95, vcc
	v_lshlrev_b32_e32 v95, 2, v95
	ds_bpermute_b32 v95, v95, v94
	s_and_saveexec_b64 s[2:3], s[0:1]
	s_cbranch_execz .LBB0_619
	v_lshlrev_b64 v[96:97], 6, v[100:101]
	v_lshl_add_u64 v[96:97], s[18:19], 0, v[96:97]
	v_lshl_add_u64 v[96:97], s[34:35], 2, v[96:97]
	s_lshl_b32 s92, s46, 2
	v_lshl_add_u64 v[96:97], v[96:97], 0, s[92:93]
	s_waitcnt lgkmcnt(0)
	v_add_f32_e32 v94, v94, v95
	global_store_dword v[96:97], v94, off

; __device__ __forceinline__ unsigned cvt_pk_bf16(float lo, float hi) { unsigned r; asm volatile("v_cvt_pk_bf16_f32 %0, %1, %2" : "=v"(r) : "v"(lo), "v"(hi)); return r; }
;     __device__ __forceinline__ void operator()(const f32x4 (&acc)[2][2][4][2], const Unit& u, int wr, int wc, int fr, int fq) const {
;     ...
;                 const int row = u.pm * BM + ai * HALF + wr * 64 + m * 16 + fr;
;                 const size_t off = (size_t)row * 1024 + col0;
;                 float ss = 0.f;
; #pragma unroll
;                 for (int bj = 0; bj < 2; ++bj)
; #pragma unroll
;                     for (int n = 0; n < 2; ++n) {
;                         const f32x4 o = *(const f32x4*)(res + off + bj * HALF + n * 16) + acc[ai][bj][m][n];
;                         *(f32x4*)(out + off + bj * HALF + n * 16) = o;
;                         if (write_hb) {
;                             u32x2 w; w.x = cvt_pk_bf16(o[0], o[1]); w.y = cvt_pk_bf16(o[2], o[3]);
;                             *(u32x2*)(hb + off + bj * HALF + n * 16) = w;
;                             ss += (o[0] * o[0] + o[1] * o[1]) + (o[2] * o[2] + o[3] * o[3]);
;                         }
;                     }
;                 if (write_hb) {
;                     ss += __shfl_xor(ss, 16); ss += __shfl_xor(ss, 32);
;                     if (fq == 0) hss[(size_t)row * 16 + u.pn * 4 + wc] = ss;
.LBB0_620:
	s_andn2_b64 vcc, exec, s[2:3]
	s_cbranch_vccnz .LBB0_622
	s_waitcnt lgkmcnt(0)
	global_load_dwordx4 v[94:97], v[98:99], off offset:64
	s_waitcnt vmcnt(0) lgkmcnt(0)
	v_pk_add_f32 v[92:93], v[92:93], v[96:97]
	v_pk_add_f32 v[90:91], v[90:91], v[94:95]
	global_store_dwordx4 v[98:99], v[90:93], off offset:64
	global_load_dwordx4 v[90:93], v[98:99], off offset:512
	s_waitcnt vmcnt(0) lgkmcnt(0)
	v_pk_add_f32 v[88:89], v[88:89], v[92:93]
	v_pk_add_f32 v[86:87], v[86:87], v[90:91]
	global_store_dwordx4 v[98:99], v[86:89], off offset:512
	global_load_dwordx4 v[86:89], v[98:99], off offset:576
	s_waitcnt vmcnt(0) lgkmcnt(0)
	v_pk_add_f32 v[84:85], v[84:85], v[88:89]
	v_pk_add_f32 v[82:83], v[82:83], v[86:87]
	global_store_dwordx4 v[98:99], v[82:85], off offset:576
.LBB0_622:
	s_nop 1
	v_or_b32_e32 v84, 48, v138
	v_ashrrev_i32_e32 v85, 31, v84
	v_lshlrev_b64 v[82:83], 10, v[84:85]
	v_lshl_add_u64 v[86:87], v[82:83], 0, v[136:137]
	v_lshl_add_u64 v[82:83], v[86:87], 2, s[12:13]
	global_load_dwordx4 v[88:91], v[82:83], off
	s_and_b64 vcc, exec, s[6:7]
	s_mov_b64 s[2:3], -1
	s_waitcnt vmcnt(0) lgkmcnt(0)
	v_pk_add_f32 v[80:81], v[80:81], v[90:91]
	v_pk_add_f32 v[78:79], v[78:79], v[88:89]
	global_store_dwordx4 v[82:83], v[78:81], off
	s_cbranch_vccnz .LBB0_626
	v_cvt_pk_bf16_f32 v88, v78, v79
	s_nop 0
	v_mul_f32_e32 v79, v79, v79
	v_lshl_add_u64 v[86:87], v[86:87], 1, s[16:17]
	v_fmac_f32_e32 v79, v78, v78
	v_mul_f32_e32 v78, v81, v81
	v_cvt_pk_bf16_f32 v89, v80, v81
	global_store_dwordx2 v[86:87], v[88:89], off
	v_fmac_f32_e32 v78, v80, v80
	v_add_f32_e32 v90, v79, v78
	global_load_dwordx4 v[78:81], v[82:83], off offset:64
	s_waitcnt vmcnt(0) lgkmcnt(0)
	v_pk_add_f32 v[80:81], v[76:77], v[80:81]
	v_pk_add_f32 v[78:79], v[74:75], v[78:79]
	global_store_dwordx4 v[82:83], v[78:81], off offset:64
	v_cvt_pk_bf16_f32 v88, v78, v79
	v_cvt_pk_bf16_f32 v89, v80, v81
	global_store_dwordx2 v[86:87], v[88:89], off offset:32
	s_nop 0
	v_mul_f32_e32 v79, v79, v79
	v_fmac_f32_e32 v79, v78, v78
	v_mul_f32_e32 v78, v81, v81
	v_fmac_f32_e32 v78, v80, v80
	v_add_f32_e32 v78, v79, v78
	v_add_f32_e32 v90, v90, v78
	global_load_dwordx4 v[78:81], v[82:83], off offset:512
	s_waitcnt vmcnt(0) lgkmcnt(0)
	v_pk_add_f32 v[80:81], v[72:73], v[80:81]
	v_pk_add_f32 v[78:79], v[70:71], v[78:79]
	global_store_dwordx4 v[82:83], v[78:81], off offset:512
	v_cvt_pk_bf16_f32 v88, v78, v79
	v_cvt_pk_bf16_f32 v89, v80, v81
	global_store_dwordx2 v[86:87], v[88:89], off offset:256
	s_nop 0
	v_mul_f32_e32 v79, v79, v79
	v_fmac_f32_e32 v79, v78, v78
	v_mul_f32_e32 v78, v81, v81
	v_fmac_f32_e32 v78, v80, v80
	v_add_f32_e32 v78, v79, v78
	v_add_f32_e32 v90, v90, v78
	global_load_dwordx4 v[78:81], v[82:83], off offset:576
	s_waitcnt vmcnt(0) lgkmcnt(0)
	v_pk_add_f32 v[80:81], v[68:69], v[80:81]
	v_pk_add_f32 v[78:79], v[66:67], v[78:79]
	global_store_dwordx4 v[82:83], v[78:81], off offset:576
	v_cvt_pk_bf16_f32 v88, v78, v79
	v_cvt_pk_bf16_f32 v89, v80, v81
	global_store_dwordx2 v[86:87], v[88:89], off offset:288
	s_nop 0
	v_mul_f32_e32 v79, v79, v79
	v_fmac_f32_e32 v79, v78, v78
	v_mul_f32_e32 v78, v81, v81
	v_fmac_f32_e32 v78, v80, v80
	v_and_b32_e32 v80, 64, v216
	v_add_f32_e32 v78, v79, v78
	v_xor_b32_e32 v79, 16, v216
	v_add_u32_e32 v80, 64, v80
	v_cmp_lt_i32_e32 vcc, v79, v80
	v_add_f32_e32 v78, v90, v78
	s_nop 0
	v_cndmask_b32_e32 v79, v216, v79, vcc
	v_lshlrev_b32_e32 v79, 2, v79
	ds_bpermute_b32 v79, v79, v78
	s_waitcnt lgkmcnt(0)
	v_add_f32_e32 v78, v78, v79
	v_xor_b32_e32 v79, 32, v216
	v_cmp_lt_i32_e32 vcc, v79, v80
	s_nop 1
	v_cndmask_b32_e32 v79, v216, v79, vcc
	v_lshlrev_b32_e32 v79, 2, v79
	ds_bpermute_b32 v79, v79, v78
	s_and_saveexec_b64 s[2:3], s[0:1]
	s_cbranch_execz .LBB0_625
	v_lshlrev_b64 v[80:81], 6, v[84:85]
	v_lshl_add_u64 v[80:81], s[18:19], 0, v[80:81]
	v_lshl_add_u64 v[80:81], s[34:35], 2, v[80:81]
	s_lshl_b32 s92, s46, 2
	v_lshl_add_u64 v[80:81], v[80:81], 0, s[92:93]
	s_waitcnt lgkmcnt(0)
	v_add_f32_e32 v78, v78, v79
	global_store_dword v[80:81], v78, off

; __device__ __forceinline__ unsigned cvt_pk_bf16(float lo, float hi) { unsigned r; asm volatile("v_cvt_pk_bf16_f32 %0, %1, %2" : "=v"(r) : "v"(lo), "v"(hi)); return r; }
;     __device__ __forceinline__ void operator()(const f32x4 (&acc)[2][2][4][2], const Unit& u, int wr, int wc, int fr, int fq) const {
;     ...
;                 const int row = u.pm * BM + ai * HALF + wr * 64 + m * 16 + fr;
;                 const size_t off = (size_t)row * 1024 + col0;
;                 float ss = 0.f;
; #pragma unroll
;                 for (int bj = 0; bj < 2; ++bj)
; #pragma unroll
;                     for (int n = 0; n < 2; ++n) {
;                         const f32x4 o = *(const f32x4*)(res + off + bj * HALF + n * 16) + acc[ai][bj][m][n];
;                         *(f32x4*)(out + off + bj * HALF + n * 16) = o;
;                         if (write_hb) {
;                             u32x2 w; w.x = cvt_pk_bf16(o[0], o[1]); w.y = cvt_pk_bf16(o[2], o[3]);
;                             *(u32x2*)(hb + off + bj * HALF + n * 16) = w;
;                             ss += (o[0] * o[0] + o[1] * o[1]) + (o[2] * o[2] + o[3] * o[3]);
;                         }
;                     }
;                 if (write_hb) {
;                     ss += __shfl_xor(ss, 16); ss += __shfl_xor(ss, 32);
;                     if (fq == 0) hss[(size_t)row * 16 + u.pn * 4 + wc] = ss;
.LBB0_626:
	s_andn2_b64 vcc, exec, s[2:3]
	s_cbranch_vccnz .LBB0_628
	s_waitcnt lgkmcnt(0)
	global_load_dwordx4 v[78:81], v[82:83], off offset:64
	s_waitcnt vmcnt(0) lgkmcnt(0)
	v_pk_add_f32 v[76:77], v[76:77], v[80:81]
	v_pk_add_f32 v[74:75], v[74:75], v[78:79]
	global_store_dwordx4 v[82:83], v[74:77], off offset:64
	global_load_dwordx4 v[74:77], v[82:83], off offset:512
	s_waitcnt vmcnt(0) lgkmcnt(0)
	v_pk_add_f32 v[72:73], v[72:73], v[76:77]
	v_pk_add_f32 v[70:71], v[70:71], v[74:75]
	global_store_dwordx4 v[82:83], v[70:73], off offset:512
	global_load_dwordx4 v[70:73], v[82:83], off offset:576
	s_waitcnt vmcnt(0) lgkmcnt(0)
	v_pk_add_f32 v[68:69], v[68:69], v[72:73]
	v_pk_add_f32 v[66:67], v[66:67], v[70:71]
	global_store_dwordx4 v[82:83], v[66:69], off offset:576
.LBB0_628:
	s_nop 1
	v_add_u32_e32 v68, 0x80, v138
	v_ashrrev_i32_e32 v69, 31, v68
	v_lshlrev_b64 v[66:67], 10, v[68:69]
	v_lshl_add_u64 v[70:71], v[66:67], 0, v[136:137]
	v_lshl_add_u64 v[66:67], v[70:71], 2, s[12:13]
	global_load_dwordx4 v[72:75], v[66:67], off
	s_and_b64 vcc, exec, s[6:7]
	s_mov_b64 s[2:3], -1
	s_waitcnt vmcnt(0) lgkmcnt(0)
	v_pk_add_f32 v[64:65], v[64:65], v[74:75]
	v_pk_add_f32 v[62:63], v[62:63], v[72:73]
	global_store_dwordx4 v[66:67], v[62:65], off
	s_cbranch_vccnz .LBB0_632
	v_cvt_pk_bf16_f32 v72, v62, v63
	s_nop 0
	v_mul_f32_e32 v63, v63, v63
	v_lshl_add_u64 v[70:71], v[70:71], 1, s[16:17]
	v_fmac_f32_e32 v63, v62, v62
	v_mul_f32_e32 v62, v65, v65
	v_cvt_pk_bf16_f32 v73, v64, v65
	global_store_dwordx2 v[70:71], v[72:73], off
	v_fmac_f32_e32 v62, v64, v64
	v_add_f32_e32 v74, v63, v62
	global_load_dwordx4 v[62:65], v[66:67], off offset:64
	s_waitcnt vmcnt(0) lgkmcnt(0)
	v_pk_add_f32 v[64:65], v[60:61], v[64:65]
	v_pk_add_f32 v[62:63], v[58:59], v[62:63]
	global_store_dwordx4 v[66:67], v[62:65], off offset:64
	v_cvt_pk_bf16_f32 v72, v62, v63
	v_cvt_pk_bf16_f32 v73, v64, v65
	global_store_dwordx2 v[70:71], v[72:73], off offset:32
	s_nop 0
	v_mul_f32_e32 v63, v63, v63
	v_fmac_f32_e32 v63, v62, v62
	v_mul_f32_e32 v62, v65, v65
	v_fmac_f32_e32 v62, v64, v64
	v_add_f32_e32 v62, v63, v62
	v_add_f32_e32 v74, v74, v62
	global_load_dwordx4 v[62:65], v[66:67], off offset:512
	s_waitcnt vmcnt(0) lgkmcnt(0)
	v_pk_add_f32 v[64:65], v[56:57], v[64:65]
	v_pk_add_f32 v[62:63], v[54:55], v[62:63]
	global_store_dwordx4 v[66:67], v[62:65], off offset:512
	v_cvt_pk_bf16_f32 v72, v62, v63
	v_cvt_pk_bf16_f32 v73, v64, v65
	global_store_dwordx2 v[70:71], v[72:73], off offset:256
	s_nop 0
	v_mul_f32_e32 v63, v63, v63
	v_fmac_f32_e32 v63, v62, v62
	v_mul_f32_e32 v62, v65, v65
	v_fmac_f32_e32 v62, v64, v64
	v_add_f32_e32 v62, v63, v62
	v_add_f32_e32 v74, v74, v62
	global_load_dwordx4 v[62:65], v[66:67], off offset:576
	s_waitcnt vmcnt(0) lgkmcnt(0)
	v_pk_add_f32 v[64:65], v[52:53], v[64:65]
	v_pk_add_f32 v[62:63], v[50:51], v[62:63]
	global_store_dwordx4 v[66:67], v[62:65], off offset:576
	v_cvt_pk_bf16_f32 v72, v62, v63
	v_cvt_pk_bf16_f32 v73, v64, v65
	global_store_dwordx2 v[70:71], v[72:73], off offset:288
	s_nop 0
	v_mul_f32_e32 v63, v63, v63
	v_fmac_f32_e32 v63, v62, v62
	v_mul_f32_e32 v62, v65, v65
	v_fmac_f32_e32 v62, v64, v64
	v_and_b32_e32 v64, 64, v216
	v_add_f32_e32 v62, v63, v62
	v_xor_b32_e32 v63, 16, v216
	v_add_u32_e32 v64, 64, v64
	v_cmp_lt_i32_e32 vcc, v63, v64
	v_add_f32_e32 v62, v74, v62
	s_nop 0
	v_cndmask_b32_e32 v63, v216, v63, vcc
	v_lshlrev_b32_e32 v63, 2, v63
	ds_bpermute_b32 v63, v63, v62
	s_waitcnt lgkmcnt(0)
	v_add_f32_e32 v62, v62, v63
	v_xor_b32_e32 v63, 32, v216
	v_cmp_lt_i32_e32 vcc, v63, v64
	s_nop 1
	v_cndmask_b32_e32 v63, v216, v63, vcc
	v_lshlrev_b32_e32 v63, 2, v63
	ds_bpermute_b32 v63, v63, v62
	s_and_saveexec_b64 s[2:3], s[0:1]
	s_cbranch_execz .LBB0_631
	v_lshlrev_b64 v[64:65], 6, v[68:69]
	v_lshl_add_u64 v[64:65], s[18:19], 0, v[64:65]
	v_lshl_add_u64 v[64:65], s[34:35], 2, v[64:65]
	s_lshl_b32 s92, s46, 2
	v_lshl_add_u64 v[64:65], v[64:65], 0, s[92:93]
	s_waitcnt lgkmcnt(0)
	v_add_f32_e32 v62, v62, v63
	global_store_dword v[64:65], v62, off

; __device__ __forceinline__ unsigned cvt_pk_bf16(float lo, float hi) { unsigned r; asm volatile("v_cvt_pk_bf16_f32 %0, %1, %2" : "=v"(r) : "v"(lo), "v"(hi)); return r; }
;     __device__ __forceinline__ void operator()(const f32x4 (&acc)[2][2][4][2], const Unit& u, int wr, int wc, int fr, int fq) const {
;     ...
;                 const int row = u.pm * BM + ai * HALF + wr * 64 + m * 16 + fr;
;                 const size_t off = (size_t)row * 1024 + col0;
;                 float ss = 0.f;
; #pragma unroll
;                 for (int bj = 0; bj < 2; ++bj)
; #pragma unroll
;                     for (int n = 0; n < 2; ++n) {
;                         const f32x4 o = *(const f32x4*)(res + off + bj * HALF + n * 16) + acc[ai][bj][m][n];
;                         *(f32x4*)(out + off + bj * HALF + n * 16) = o;
;                         if (write_hb) {
;                             u32x2 w; w.x = cvt_pk_bf16(o[0], o[1]); w.y = cvt_pk_bf16(o[2], o[3]);
;                             *(u32x2*)(hb + off + bj * HALF + n * 16) = w;
;                             ss += (o[0] * o[0] + o[1] * o[1]) + (o[2] * o[2] + o[3] * o[3]);
;                         }
;                     }
;                 if (write_hb) {
;                     ss += __shfl_xor(ss, 16); ss += __shfl_xor(ss, 32);
;                     if (fq == 0) hss[(size_t)row * 16 + u.pn * 4 + wc] = ss;
.LBB0_632:
	s_andn2_b64 vcc, exec, s[2:3]
	s_cbranch_vccnz .LBB0_634
	s_waitcnt lgkmcnt(0)
	global_load_dwordx4 v[62:65], v[66:67], off offset:64
	s_waitcnt vmcnt(0) lgkmcnt(0)
	v_pk_add_f32 v[60:61], v[60:61], v[64:65]
	v_pk_add_f32 v[58:59], v[58:59], v[62:63]
	global_store_dwordx4 v[66:67], v[58:61], off offset:64
	global_load_dwordx4 v[58:61], v[66:67], off offset:512
	s_waitcnt vmcnt(0) lgkmcnt(0)
	v_pk_add_f32 v[56:57], v[56:57], v[60:61]
	v_pk_add_f32 v[54:55], v[54:55], v[58:59]
	global_store_dwordx4 v[66:67], v[54:57], off offset:512
	global_load_dwordx4 v[54:57], v[66:67], off offset:576
	s_waitcnt vmcnt(0) lgkmcnt(0)
	v_pk_add_f32 v[52:53], v[52:53], v[56:57]
	v_pk_add_f32 v[50:51], v[50:51], v[54:55]
	global_store_dwordx4 v[66:67], v[50:53], off offset:576
.LBB0_634:
	s_nop 1
	v_add_u32_e32 v52, 0x90, v138
	v_ashrrev_i32_e32 v53, 31, v52
	v_lshlrev_b64 v[50:51], 10, v[52:53]
	v_lshl_add_u64 v[54:55], v[50:51], 0, v[136:137]
	v_lshl_add_u64 v[50:51], v[54:55], 2, s[12:13]
	global_load_dwordx4 v[56:59], v[50:51], off
	s_and_b64 vcc, exec, s[6:7]
	s_mov_b64 s[2:3], -1
	s_waitcnt vmcnt(0) lgkmcnt(0)
	v_pk_add_f32 v[48:49], v[48:49], v[58:59]
	v_pk_add_f32 v[46:47], v[46:47], v[56:57]
	global_store_dwordx4 v[50:51], v[46:49], off
	s_cbranch_vccnz .LBB0_638
	v_cvt_pk_bf16_f32 v56, v46, v47
	s_nop 0
	v_mul_f32_e32 v47, v47, v47
	v_lshl_add_u64 v[54:55], v[54:55], 1, s[16:17]
	v_fmac_f32_e32 v47, v46, v46
	v_mul_f32_e32 v46, v49, v49
	v_cvt_pk_bf16_f32 v57, v48, v49
	global_store_dwordx2 v[54:55], v[56:57], off
	v_fmac_f32_e32 v46, v48, v48
	v_add_f32_e32 v58, v47, v46
	global_load_dwordx4 v[46:49], v[50:51], off offset:64
	s_waitcnt vmcnt(0) lgkmcnt(0)
	v_pk_add_f32 v[48:49], v[44:45], v[48:49]
	v_pk_add_f32 v[46:47], v[42:43], v[46:47]
	global_store_dwordx4 v[50:51], v[46:49], off offset:64
	v_cvt_pk_bf16_f32 v56, v46, v47
	v_cvt_pk_bf16_f32 v57, v48, v49
	global_store_dwordx2 v[54:55], v[56:57], off offset:32
	s_nop 0
	v_mul_f32_e32 v47, v47, v47
	v_fmac_f32_e32 v47, v46, v46
	v_mul_f32_e32 v46, v49, v49
	v_fmac_f32_e32 v46, v48, v48
	v_add_f32_e32 v46, v47, v46
	v_add_f32_e32 v58, v58, v46
	global_load_dwordx4 v[46:49], v[50:51], off offset:512
	s_waitcnt vmcnt(0) lgkmcnt(0)
	v_pk_add_f32 v[48:49], v[40:41], v[48:49]
	v_pk_add_f32 v[46:47], v[38:39], v[46:47]
	global_store_dwordx4 v[50:51], v[46:49], off offset:512
	v_cvt_pk_bf16_f32 v56, v46, v47
	v_cvt_pk_bf16_f32 v57, v48, v49
	global_store_dwordx2 v[54:55], v[56:57], off offset:256
	s_nop 0
	v_mul_f32_e32 v47, v47, v47
	v_fmac_f32_e32 v47, v46, v46
	v_mul_f32_e32 v46, v49, v49
	v_fmac_f32_e32 v46, v48, v48
	v_add_f32_e32 v46, v47, v46
	v_add_f32_e32 v58, v58, v46
	global_load_dwordx4 v[46:49], v[50:51], off offset:576
	s_waitcnt vmcnt(0) lgkmcnt(0)
	v_pk_add_f32 v[48:49], v[36:37], v[48:49]
	v_pk_add_f32 v[46:47], v[34:35], v[46:47]
	global_store_dwordx4 v[50:51], v[46:49], off offset:576
	v_cvt_pk_bf16_f32 v56, v46, v47
	v_cvt_pk_bf16_f32 v57, v48, v49
	global_store_dwordx2 v[54:55], v[56:57], off offset:288
	s_nop 0
	v_mul_f32_e32 v47, v47, v47
	v_fmac_f32_e32 v47, v46, v46
	v_mul_f32_e32 v46, v49, v49
	v_fmac_f32_e32 v46, v48, v48
	v_and_b32_e32 v48, 64, v216
	v_add_f32_e32 v46, v47, v46
	v_xor_b32_e32 v47, 16, v216
	v_add_u32_e32 v48, 64, v48
	v_cmp_lt_i32_e32 vcc, v47, v48
	v_add_f32_e32 v46, v58, v46
	s_nop 0
	v_cndmask_b32_e32 v47, v216, v47, vcc
	v_lshlrev_b32_e32 v47, 2, v47
	ds_bpermute_b32 v47, v47, v46
	s_waitcnt lgkmcnt(0)
	v_add_f32_e32 v46, v46, v47
	v_xor_b32_e32 v47, 32, v216
	v_cmp_lt_i32_e32 vcc, v47, v48
	s_nop 1
	v_cndmask_b32_e32 v47, v216, v47, vcc
	v_lshlrev_b32_e32 v47, 2, v47
	ds_bpermute_b32 v47, v47, v46
	s_and_saveexec_b64 s[2:3], s[0:1]
	s_cbranch_execz .LBB0_637
	v_lshlrev_b64 v[48:49], 6, v[52:53]
	v_lshl_add_u64 v[48:49], s[18:19], 0, v[48:49]
	v_lshl_add_u64 v[48:49], s[34:35], 2, v[48:49]
	s_lshl_b32 s92, s46, 2
	v_lshl_add_u64 v[48:49], v[48:49], 0, s[92:93]
	s_waitcnt lgkmcnt(0)
	v_add_f32_e32 v46, v46, v47
	global_store_dword v[48:49], v46, off

; __device__ __forceinline__ unsigned cvt_pk_bf16(float lo, float hi) { unsigned r; asm volatile("v_cvt_pk_bf16_f32 %0, %1, %2" : "=v"(r) : "v"(lo), "v"(hi)); return r; }
;     __device__ __forceinline__ void operator()(const f32x4 (&acc)[2][2][4][2], const Unit& u, int wr, int wc, int fr, int fq) const {
;     ...
;                 const int row = u.pm * BM + ai * HALF + wr * 64 + m * 16 + fr;
;                 const size_t off = (size_t)row * 1024 + col0;
;                 float ss = 0.f;
; #pragma unroll
;                 for (int bj = 0; bj < 2; ++bj)
; #pragma unroll
;                     for (int n = 0; n < 2; ++n) {
;                         const f32x4 o = *(const f32x4*)(res + off + bj * HALF + n * 16) + acc[ai][bj][m][n];
;                         *(f32x4*)(out + off + bj * HALF + n * 16) = o;
;                         if (write_hb) {
;                             u32x2 w; w.x = cvt_pk_bf16(o[0], o[1]); w.y = cvt_pk_bf16(o[2], o[3]);
;                             *(u32x2*)(hb + off + bj * HALF + n * 16) = w;
;                             ss += (o[0] * o[0] + o[1] * o[1]) + (o[2] * o[2] + o[3] * o[3]);
;                         }
;                     }
;                 if (write_hb) {
;                     ss += __shfl_xor(ss, 16); ss += __shfl_xor(ss, 32);
;                     if (fq == 0) hss[(size_t)row * 16 + u.pn * 4 + wc] = ss;
.LBB0_638:
	s_andn2_b64 vcc, exec, s[2:3]
	s_cbranch_vccnz .LBB0_640
	s_waitcnt lgkmcnt(0)
	global_load_dwordx4 v[46:49], v[50:51], off offset:64
	s_waitcnt vmcnt(0) lgkmcnt(0)
	v_pk_add_f32 v[44:45], v[44:45], v[48:49]
	v_pk_add_f32 v[42:43], v[42:43], v[46:47]
	global_store_dwordx4 v[50:51], v[42:45], off offset:64
	global_load_dwordx4 v[42:45], v[50:51], off offset:512
	s_waitcnt vmcnt(0) lgkmcnt(0)
	v_pk_add_f32 v[40:41], v[40:41], v[44:45]
	v_pk_add_f32 v[38:39], v[38:39], v[42:43]
	global_store_dwordx4 v[50:51], v[38:41], off offset:512
	global_load_dwordx4 v[38:41], v[50:51], off offset:576
	s_waitcnt vmcnt(0) lgkmcnt(0)
	v_pk_add_f32 v[36:37], v[36:37], v[40:41]
	v_pk_add_f32 v[34:35], v[34:35], v[38:39]
	global_store_dwordx4 v[50:51], v[34:37], off offset:576
.LBB0_640:
	s_nop 1
	v_add_u32_e32 v36, 0xa0, v138
	v_ashrrev_i32_e32 v37, 31, v36
	v_lshlrev_b64 v[34:35], 10, v[36:37]
	v_lshl_add_u64 v[38:39], v[34:35], 0, v[136:137]
	v_lshl_add_u64 v[34:35], v[38:39], 2, s[12:13]
	global_load_dwordx4 v[40:43], v[34:35], off
	s_and_b64 vcc, exec, s[6:7]
	s_mov_b64 s[2:3], -1
	s_waitcnt vmcnt(0) lgkmcnt(0)
	v_pk_add_f32 v[32:33], v[32:33], v[42:43]
	v_pk_add_f32 v[30:31], v[30:31], v[40:41]
	global_store_dwordx4 v[34:35], v[30:33], off
	s_cbranch_vccnz .LBB0_644
	v_cvt_pk_bf16_f32 v40, v30, v31
	s_nop 0
	v_mul_f32_e32 v31, v31, v31
	v_lshl_add_u64 v[38:39], v[38:39], 1, s[16:17]
	v_fmac_f32_e32 v31, v30, v30
	v_mul_f32_e32 v30, v33, v33
	v_cvt_pk_bf16_f32 v41, v32, v33
	global_store_dwordx2 v[38:39], v[40:41], off
	v_fmac_f32_e32 v30, v32, v32
	v_add_f32_e32 v42, v31, v30
	global_load_dwordx4 v[30:33], v[34:35], off offset:64
	s_waitcnt vmcnt(0) lgkmcnt(0)
	v_pk_add_f32 v[32:33], v[28:29], v[32:33]
	v_pk_add_f32 v[30:31], v[26:27], v[30:31]
	global_store_dwordx4 v[34:35], v[30:33], off offset:64
	v_cvt_pk_bf16_f32 v40, v30, v31
	v_cvt_pk_bf16_f32 v41, v32, v33
	global_store_dwordx2 v[38:39], v[40:41], off offset:32
	s_nop 0
	v_mul_f32_e32 v31, v31, v31
	v_fmac_f32_e32 v31, v30, v30
	v_mul_f32_e32 v30, v33, v33
	v_fmac_f32_e32 v30, v32, v32
	v_add_f32_e32 v30, v31, v30
	v_add_f32_e32 v42, v42, v30
	global_load_dwordx4 v[30:33], v[34:35], off offset:512
	s_waitcnt vmcnt(0) lgkmcnt(0)
	v_pk_add_f32 v[32:33], v[24:25], v[32:33]
	v_pk_add_f32 v[30:31], v[22:23], v[30:31]
	global_store_dwordx4 v[34:35], v[30:33], off offset:512
	v_cvt_pk_bf16_f32 v40, v30, v31
	v_cvt_pk_bf16_f32 v41, v32, v33
	global_store_dwordx2 v[38:39], v[40:41], off offset:256
	s_nop 0
	v_mul_f32_e32 v31, v31, v31
	v_fmac_f32_e32 v31, v30, v30
	v_mul_f32_e32 v30, v33, v33
	v_fmac_f32_e32 v30, v32, v32
	v_add_f32_e32 v30, v31, v30
	v_add_f32_e32 v42, v42, v30
	global_load_dwordx4 v[30:33], v[34:35], off offset:576
	s_waitcnt vmcnt(0) lgkmcnt(0)
	v_pk_add_f32 v[32:33], v[20:21], v[32:33]
	v_pk_add_f32 v[30:31], v[18:19], v[30:31]
	global_store_dwordx4 v[34:35], v[30:33], off offset:576
	v_cvt_pk_bf16_f32 v40, v30, v31
	v_cvt_pk_bf16_f32 v41, v32, v33
	global_store_dwordx2 v[38:39], v[40:41], off offset:288
	s_nop 0
	v_mul_f32_e32 v31, v31, v31
	v_fmac_f32_e32 v31, v30, v30
	v_mul_f32_e32 v30, v33, v33
	v_fmac_f32_e32 v30, v32, v32
	v_and_b32_e32 v32, 64, v216
	v_add_f32_e32 v30, v31, v30
	v_xor_b32_e32 v31, 16, v216
	v_add_u32_e32 v32, 64, v32
	v_cmp_lt_i32_e32 vcc, v31, v32
	v_add_f32_e32 v30, v42, v30
	s_nop 0
	v_cndmask_b32_e32 v31, v216, v31, vcc
	v_lshlrev_b32_e32 v31, 2, v31
	ds_bpermute_b32 v31, v31, v30
	s_waitcnt lgkmcnt(0)
	v_add_f32_e32 v30, v30, v31
	v_xor_b32_e32 v31, 32, v216
	v_cmp_lt_i32_e32 vcc, v31, v32
	s_nop 1
	v_cndmask_b32_e32 v31, v216, v31, vcc
	v_lshlrev_b32_e32 v31, 2, v31
	ds_bpermute_b32 v31, v31, v30
	s_and_saveexec_b64 s[2:3], s[0:1]
	s_cbranch_execz .LBB0_643
	v_lshlrev_b64 v[32:33], 6, v[36:37]
	v_lshl_add_u64 v[32:33], s[18:19], 0, v[32:33]
	v_lshl_add_u64 v[32:33], s[34:35], 2, v[32:33]
	s_lshl_b32 s92, s46, 2
	v_lshl_add_u64 v[32:33], v[32:33], 0, s[92:93]
	s_waitcnt lgkmcnt(0)
	v_add_f32_e32 v30, v30, v31
	global_store_dword v[32:33], v30, off

; __device__ __forceinline__ unsigned cvt_pk_bf16(float lo, float hi) { unsigned r; asm volatile("v_cvt_pk_bf16_f32 %0, %1, %2" : "=v"(r) : "v"(lo), "v"(hi)); return r; }
;     __device__ __forceinline__ void operator()(const f32x4 (&acc)[2][2][4][2], const Unit& u, int wr, int wc, int fr, int fq) const {
;     ...
;                 const int row = u.pm * BM + ai * HALF + wr * 64 + m * 16 + fr;
;                 const size_t off = (size_t)row * 1024 + col0;
;                 float ss = 0.f;
; #pragma unroll
;                 for (int bj = 0; bj < 2; ++bj)
; #pragma unroll
;                     for (int n = 0; n < 2; ++n) {
;                         const f32x4 o = *(const f32x4*)(res + off + bj * HALF + n * 16) + acc[ai][bj][m][n];
;                         *(f32x4*)(out + off + bj * HALF + n * 16) = o;
;                         if (write_hb) {
;                             u32x2 w; w.x = cvt_pk_bf16(o[0], o[1]); w.y = cvt_pk_bf16(o[2], o[3]);
;                             *(u32x2*)(hb + off + bj * HALF + n * 16) = w;
;                             ss += (o[0] * o[0] + o[1] * o[1]) + (o[2] * o[2] + o[3] * o[3]);
;                         }
;                     }
;                 if (write_hb) {
;                     ss += __shfl_xor(ss, 16); ss += __shfl_xor(ss, 32);
;                     if (fq == 0) hss[(size_t)row * 16 + u.pn * 4 + wc] = ss;
.LBB0_644:
	s_andn2_b64 vcc, exec, s[2:3]
	s_cbranch_vccnz .LBB0_646
	s_waitcnt lgkmcnt(0)
	global_load_dwordx4 v[30:33], v[34:35], off offset:64
	s_waitcnt vmcnt(0) lgkmcnt(0)
	v_pk_add_f32 v[28:29], v[28:29], v[32:33]
	v_pk_add_f32 v[26:27], v[26:27], v[30:31]
	global_store_dwordx4 v[34:35], v[26:29], off offset:64
	global_load_dwordx4 v[26:29], v[34:35], off offset:512
	s_waitcnt vmcnt(0) lgkmcnt(0)
	v_pk_add_f32 v[24:25], v[24:25], v[28:29]
	v_pk_add_f32 v[22:23], v[22:23], v[26:27]
	global_store_dwordx4 v[34:35], v[22:25], off offset:512
	global_load_dwordx4 v[22:25], v[34:35], off offset:576
	s_waitcnt vmcnt(0) lgkmcnt(0)
	v_pk_add_f32 v[20:21], v[20:21], v[24:25]
	v_pk_add_f32 v[18:19], v[18:19], v[22:23]
	global_store_dwordx4 v[34:35], v[18:21], off offset:576
.LBB0_646:
	s_nop 1
	v_add_u32_e32 v20, 0xb0, v138
	v_ashrrev_i32_e32 v21, 31, v20
	v_lshlrev_b64 v[18:19], 10, v[20:21]
	v_lshl_add_u64 v[22:23], v[18:19], 0, v[136:137]
	v_lshl_add_u64 v[18:19], v[22:23], 2, s[12:13]
	global_load_dwordx4 v[24:27], v[18:19], off
	s_and_b64 vcc, exec, s[6:7]
	s_mov_b64 s[2:3], -1
	s_waitcnt vmcnt(0) lgkmcnt(0)
	v_pk_add_f32 v[16:17], v[16:17], v[26:27]
	v_pk_add_f32 v[14:15], v[14:15], v[24:25]
	global_store_dwordx4 v[18:19], v[14:17], off
	s_cbranch_vccnz .LBB0_650
	v_cvt_pk_bf16_f32 v24, v14, v15
	s_nop 0
	v_mul_f32_e32 v15, v15, v15
	v_lshl_add_u64 v[22:23], v[22:23], 1, s[16:17]
	v_fmac_f32_e32 v15, v14, v14
	v_mul_f32_e32 v14, v17, v17
	v_cvt_pk_bf16_f32 v25, v16, v17
	global_store_dwordx2 v[22:23], v[24:25], off
	v_fmac_f32_e32 v14, v16, v16
	v_add_f32_e32 v26, v15, v14
	global_load_dwordx4 v[14:17], v[18:19], off offset:64
	s_waitcnt vmcnt(0) lgkmcnt(0)
	v_pk_add_f32 v[16:17], v[12:13], v[16:17]
	v_pk_add_f32 v[14:15], v[10:11], v[14:15]
	global_store_dwordx4 v[18:19], v[14:17], off offset:64
	v_cvt_pk_bf16_f32 v24, v14, v15
	v_cvt_pk_bf16_f32 v25, v16, v17
	global_store_dwordx2 v[22:23], v[24:25], off offset:32
	s_nop 0
	v_mul_f32_e32 v15, v15, v15
	v_fmac_f32_e32 v15, v14, v14
	v_mul_f32_e32 v14, v17, v17
	v_fmac_f32_e32 v14, v16, v16
	v_add_f32_e32 v14, v15, v14
	v_add_f32_e32 v26, v26, v14
	global_load_dwordx4 v[14:17], v[18:19], off offset:512
	s_waitcnt vmcnt(0) lgkmcnt(0)
	v_pk_add_f32 v[16:17], v[8:9], v[16:17]
	v_pk_add_f32 v[14:15], v[6:7], v[14:15]
	global_store_dwordx4 v[18:19], v[14:17], off offset:512
	v_cvt_pk_bf16_f32 v24, v14, v15
	v_cvt_pk_bf16_f32 v25, v16, v17
	global_store_dwordx2 v[22:23], v[24:25], off offset:256
	s_nop 0
	v_mul_f32_e32 v15, v15, v15
	v_fmac_f32_e32 v15, v14, v14
	v_mul_f32_e32 v14, v17, v17
	v_fmac_f32_e32 v14, v16, v16
	v_add_f32_e32 v14, v15, v14
	v_add_f32_e32 v26, v26, v14
	global_load_dwordx4 v[14:17], v[18:19], off offset:576
	s_waitcnt vmcnt(0) lgkmcnt(0)
	v_pk_add_f32 v[16:17], v[4:5], v[16:17]
	v_pk_add_f32 v[14:15], v[2:3], v[14:15]
	global_store_dwordx4 v[18:19], v[14:17], off offset:576
	v_cvt_pk_bf16_f32 v24, v14, v15
	v_cvt_pk_bf16_f32 v25, v16, v17
	global_store_dwordx2 v[22:23], v[24:25], off offset:288
	s_nop 0
	v_mul_f32_e32 v15, v15, v15
	v_fmac_f32_e32 v15, v14, v14
	v_mul_f32_e32 v14, v17, v17
	v_fmac_f32_e32 v14, v16, v16
	v_and_b32_e32 v16, 64, v216
	v_add_f32_e32 v14, v15, v14
	v_xor_b32_e32 v15, 16, v216
	v_add_u32_e32 v16, 64, v16
	v_cmp_lt_i32_e32 vcc, v15, v16
	v_add_f32_e32 v14, v26, v14
	s_nop 0
	v_cndmask_b32_e32 v15, v216, v15, vcc
	v_lshlrev_b32_e32 v15, 2, v15
	ds_bpermute_b32 v15, v15, v14
	s_waitcnt lgkmcnt(0)
	v_add_f32_e32 v14, v14, v15
	v_xor_b32_e32 v15, 32, v216
	v_cmp_lt_i32_e32 vcc, v15, v16
	s_nop 1
	v_cndmask_b32_e32 v15, v216, v15, vcc
	v_lshlrev_b32_e32 v15, 2, v15
	ds_bpermute_b32 v15, v15, v14
	s_and_saveexec_b64 s[2:3], s[0:1]
	s_cbranch_execz .LBB0_649
	v_lshlrev_b64 v[16:17], 6, v[20:21]
	v_lshl_add_u64 v[16:17], s[18:19], 0, v[16:17]
	v_lshl_add_u64 v[16:17], s[34:35], 2, v[16:17]
	s_lshl_b32 s92, s46, 2
	v_lshl_add_u64 v[16:17], v[16:17], 0, s[92:93]
	s_waitcnt lgkmcnt(0)
	v_add_f32_e32 v14, v14, v15
	global_store_dword v[16:17], v14, off

;     __device__ __forceinline__ void operator()(const f32x4 (&acc)[2][2][4][2], const Unit& u, int wr, int wc, int fr, int fq) const {
;     ...
;                 for (int bj = 0; bj < 2; ++bj)
; #pragma unroll
;                     for (int n = 0; n < 2; ++n) {
;                         const f32x4 o = *(const f32x4*)(res + off + bj * HALF + n * 16) + acc[ai][bj][m][n];
;                         *(f32x4*)(out + off + bj * HALF + n * 16) = o;
.LBB0_650:
	s_andn2_b64 vcc, exec, s[2:3]
	s_cbranch_vccnz .LBB0_652
	s_waitcnt lgkmcnt(0)
	global_load_dwordx4 v[14:17], v[18:19], off offset:64
	s_waitcnt vmcnt(0) lgkmcnt(0)
	v_pk_add_f32 v[12:13], v[12:13], v[16:17]
	v_pk_add_f32 v[10:11], v[10:11], v[14:15]
	global_store_dwordx4 v[18:19], v[10:13], off offset:64
	global_load_dwordx4 v[10:13], v[18:19], off offset:512
	s_waitcnt vmcnt(0) lgkmcnt(0)
	v_pk_add_f32 v[8:9], v[8:9], v[12:13]
	v_pk_add_f32 v[6:7], v[6:7], v[10:11]
	global_store_dwordx4 v[18:19], v[6:9], off offset:512
	global_load_dwordx4 v[6:9], v[18:19], off offset:576
	s_waitcnt vmcnt(0) lgkmcnt(0)
	v_pk_add_f32 v[4:5], v[4:5], v[8:9]
	v_pk_add_f32 v[2:3], v[2:3], v[6:7]
	global_store_dwordx4 v[18:19], v[2:5], off offset:576

; #define LAS __attribute__((address_space(3)))
; __global__ void __launch_bounds__(512) hymba_fwd(Args a) {
;     extern __shared__ __attribute__((aligned(16))) unsigned char lds_raw[];
;     LAS unsigned char* lds = (LAS unsigned char*)lds_raw;
	.amdhsa_kernel _Z9hymba_fwd4Args
		.amdhsa_group_segment_fixed_size 0
		.amdhsa_private_segment_fixed_size 0
		.amdhsa_kernarg_size 416
		.amdhsa_user_sgpr_count 2
		.amdhsa_user_sgpr_dispatch_ptr 0
		.amdhsa_user_sgpr_queue_ptr 0
		.amdhsa_user_sgpr_kernarg_segment_ptr 1
		.amdhsa_user_sgpr_dispatch_id 0
		.amdhsa_user_sgpr_kernarg_preload_length 0
		.amdhsa_user_sgpr_kernarg_preload_offset 0
		.amdhsa_user_sgpr_private_segment_size 0
		.amdhsa_uses_dynamic_stack 0
		.amdhsa_enable_private_segment 0
		.amdhsa_system_sgpr_workgroup_id_x 1
		.amdhsa_system_sgpr_workgroup_id_y 0
		.amdhsa_system_sgpr_workgroup_id_z 0
		.amdhsa_system_sgpr_workgroup_info 0
		.amdhsa_system_vgpr_workitem_id 2
		.amdhsa_next_free_vgpr 256
		.amdhsa_next_free_sgpr 100
		.amdhsa_accum_offset 256
		.amdhsa_reserve_vcc 1
		.amdhsa_float_round_mode_32 0
		.amdhsa_float_round_mode_16_64 0
		.amdhsa_float_denorm_mode_32 3
		.amdhsa_float_denorm_mode_16_64 3
		.amdhsa_dx10_clamp 1
		.amdhsa_ieee_mode 1
		.amdhsa_fp16_overflow 0
		.amdhsa_tg_split 0
		.amdhsa_exception_fp_ieee_invalid_op 0
		.amdhsa_exception_fp_denorm_src 0
		.amdhsa_exception_fp_ieee_div_zero 0
		.amdhsa_exception_fp_ieee_overflow 0
		.amdhsa_exception_fp_ieee_underflow 0
		.amdhsa_exception_fp_ieee_inexact 0
		.amdhsa_exception_int_div_zero 0
	.end_amdhsa_kernel

; #define LAS __attribute__((address_space(3)))
; __global__ void __launch_bounds__(512) hymba_fwd(Args a) {
;     extern __shared__ __attribute__((aligned(16))) unsigned char lds_raw[];
;     LAS unsigned char* lds = (LAS unsigned char*)lds_raw;
amdhsa.kernels:
  - .agpr_count:     0
    .args:
      - .offset:         0
        .size:           160
        .value_kind:     by_value
      - .offset:         160
        .size:           4
        .value_kind:     hidden_block_count_x
      - .offset:         164
        .size:           4
        .value_kind:     hidden_block_count_y
      - .offset:         168
        .size:           4
        .value_kind:     hidden_block_count_z
      - .offset:         172
        .size:           2
        .value_kind:     hidden_group_size_x
      - .offset:         174
        .size:           2
        .value_kind:     hidden_group_size_y
      - .offset:         176
        .size:           2
        .value_kind:     hidden_group_size_z
      - .offset:         178
        .size:           2
        .value_kind:     hidden_remainder_x
      - .offset:         180
        .size:           2
        .value_kind:     hidden_remainder_y
      - .offset:         182
        .size:           2
        .value_kind:     hidden_remainder_z
      - .offset:         200
        .size:           8
        .value_kind:     hidden_global_offset_x
      - .offset:         208
        .size:           8
        .value_kind:     hidden_global_offset_y
      - .offset:         216
        .size:           8
        .value_kind:     hidden_global_offset_z
      - .offset:         224
        .size:           2
        .value_kind:     hidden_grid_dims
      - .offset:         248
        .size:           8
        .value_kind:     hidden_multigrid_sync_arg
      - .offset:         280
        .size:           4
        .value_kind:     hidden_dynamic_lds_size
    .group_segment_fixed_size: 0
    .kernarg_segment_align: 8
    .kernarg_segment_size: 416
    .language:       OpenCL C
    .language_version:
      - 2
      - 0
    .max_flat_workgroup_size: 512
    .name:           _Z9hymba_fwd4Args
    .private_segment_fixed_size: 0
    .sgpr_count:     106
    .sgpr_spill_count: 144
    .symbol:         _Z9hymba_fwd4Args.kd
    .uniform_work_group_size: 1
    .uses_dynamic_stack: false
    .vgpr_count:     256
    .vgpr_spill_count: 0
    .wavefront_size: 64
